# peeled first K-iteration per GEMM unit with srcC=0 (drops 128 acc-zeroing v_mov per unit), removed hipcc's per-unit vmcnt(0) drain, static prio 1 for waves 4-7 in attention, 64B-aligned hot loops, rem
# speedup vs baseline: 1.0034x; 1.0022x over previous
; #define PG8_STAGE(bufoff, gbase, voff) do { _Pragma("unroll") for (int _i = 0; _i < 2; ++_i) \
;         __builtin_amdgcn_global_load_lds((const unsigned*)((const char*)(gbase) + (voff)[_i]), (PG8_LAS unsigned*)(lds + (bufoff) + ldsw + _i * 8192), 16, 0, 0); } while (0)
; #define PG8_LDA(dst, b, h) do { _Pragma("unroll") for (int m = 0; m < 4; ++m) _Pragma("unroll") for (int k = 0; k < 2; ++k) dst[m][k] = *(const PG8_LAS bf16x8*)(lds + PG8_SA(b, h) + aoff + m * 2048 + k * 1024); } while (0)
; #define PG8_LDB(dst, b, h) do { _Pragma("unroll") for (int n = 0; n < 2; ++n) _Pragma("unroll") for (int k = 0; k < 2; ++k) dst[n][k] = *(const PG8_LAS bf16x8*)(lds + PG8_SB(b, h) + boff + n * 2048 + k * 1024); } while (0)
; template <class Epi, class Sched, bool ALIGN_EPI = false, bool SP2 = false>
; __device__ __forceinline__ void gemm_phase(PG8_LAS unsigned char* lds, const Gemm g, const Sched& S, const Epi& E, const int tid_in) {
;     ...
;         const bool has_next = S.next(ui + 1, nxt);
;         const char* nA = has_next ? (const char*)g.A + (size_t)nxt.pm * tstepA : cA; const char* nB = has_next ? (const char*)g.Bt + (size_t)nxt.pn * tstepB : cB;
;         for (int t = 0; t < nt; t += 2) {
;             const bool last = (t == nt - 2);
;             const char* a1 = cA + (size_t)(t + 1) * kstep;
;             const char* a2 = last ? nA : cA + (size_t)(t + 2) * kstep; const char* b2 = last ? nB : cB + (size_t)(t + 2) * kstep;
;             const char* a3 = a2 + kstep; const char* b3 = b2 + kstep;
;             if (last && has_next) S.a_ready(nxt);
;             if constexpr (SP2) {
;             PG8_LDB(B0, 0, 0); PG8_LDB(B1, 0, 1); PG8_SCHED; PG8_LDA(At, 0, 0); PG8_STAGE(PG8_SA(1, 1), a1 + hstepA, voffA);
;             PG8_WAIT_V(8); PG8_WAIT_L(0); PG8_BAR; PG8_MMA(0, 0, At, B0); PG8_MMA(0, 1, At, B1); PG8_BAR; PG8_SCHED;
;             PG8_LDA(At, 0, 1); PG8_STAGE(PG8_SB(0, 0), b2, voffB); PG8_STAGE(PG8_SB(0, 1), b2 + hstepB, voffB); PG8_STAGE(PG8_SA(0, 0), a2, voffA);
;             PG8_WAIT_V(8); PG8_WAIT_L(0); PG8_BAR; PG8_MMA(1, 0, At, B0); PG8_MMA(1, 1, At, B1); PG8_BAR; PG8_SCHED;
;     ...
;         for (int a = 0; a < 2; ++a)
; #pragma unroll
;             for (int b = 0; b < 2; ++b)
; #pragma unroll
;                 for (int m = 0; m < 4; ++m)
; #pragma unroll
;                     for (int n = 0; n < 2; ++n) acc[a][b][m][n] = (f32x4){0.f, 0.f, 0.f, 0.f};
.LBB0_288:
	s_ashr_i32 s41, s40, 31
	s_lshl_b64 s[12:13], s[40:41], 20
	s_add_u32 s42, s10, s12
	s_addc_u32 s43, s11, s13
	s_and_b64 s[12:13], s[34:35], exec
	s_cselect_b32 s41, s43, s47
	s_cselect_b32 s63, s42, s46
	s_ashr_i32 s39, s38, 31
	s_lshl_b64 s[12:13], s[38:39], 20
	s_add_u32 s44, s18, s12
	s_addc_u32 s45, s52, s13
	s_and_b64 s[12:13], s[34:35], exec
	s_cselect_b32 s39, s45, s49
	s_cselect_b32 s64, s44, s48
	s_add_u32 s46, s46, 0x80080
	s_addc_u32 s47, s47, 0
	s_add_u32 s65, s48, 0x100
	s_addc_u32 s66, s49, 0
	s_mov_b32 s67, -2
	s_add_u32 s12, s46, 0xfff80080
	s_addc_u32 s13, s47, -1
	s_add_i32 s68, 0, 0x10000
	s_cmp_eq_u32 s67, 28
	s_cselect_b32 s51, s41, s13
	s_cselect_b32 s50, s63, s12
	v_add_u32_e32 v138, s68, v141
	s_cselect_b32 s49, s39, s66
	s_cselect_b32 s48, s64, s65
	s_add_i32 s69, 0, 0x14000
	ds_read_b128 v[142:145], v138
	ds_read_b128 v[150:153], v138 offset:1024
	ds_read_b128 v[154:157], v138 offset:2048
	ds_read_b128 v[158:161], v138 offset:3072
	v_add_u32_e32 v138, s69, v141
	ds_read_b128 v[162:165], v138
	ds_read_b128 v[166:169], v138 offset:1024
	ds_read_b128 v[170:173], v138 offset:2048
	ds_read_b128 v[174:177], v138 offset:3072
	v_lshl_add_u64 v[190:191], s[46:47], 0, v[134:135]
	s_add_i32 m0, s54, 0xc000
	ds_read_b128 v[178:181], v149
	ds_read_b128 v[182:185], v149 offset:1024
	ds_read_b128 v[186:189], v149 offset:2048
	ds_read_b128 v[194:197], v149 offset:3072
	ds_read_b128 v[198:201], v149 offset:4096
	ds_read_b128 v[202:205], v149 offset:5120
	ds_read_b128 v[206:209], v149 offset:6144
	ds_read_b128 v[210:213], v149 offset:7168
	global_load_lds_dwordx4 v[190:191], off
	v_lshl_add_u64 v[190:191], s[46:47], 0, v[136:137]
	s_add_i32 m0, s54, 0xe000
	s_nop 0
	global_load_lds_dwordx4 v[190:191], off
	s_waitcnt vmcnt(8)
	s_waitcnt lgkmcnt(0)
	s_barrier
	s_setprio 1
	s_waitcnt lgkmcnt(0)
	v_mfma_f32_16x16x32_bf16 v[124:127], v[142:145], v[178:181], 0
	v_mfma_f32_16x16x32_bf16 v[120:123], v[154:157], v[178:181], 0
	v_mfma_f32_16x16x32_bf16 v[108:111], v[142:145], v[186:189], 0
	v_mfma_f32_16x16x32_bf16 v[104:107], v[154:157], v[186:189], 0
	v_mfma_f32_16x16x32_bf16 v[92:95], v[142:145], v[198:201], 0
	v_mfma_f32_16x16x32_bf16 v[88:91], v[154:157], v[198:201], 0
	v_mfma_f32_16x16x32_bf16 v[76:79], v[142:145], v[206:209], 0
	v_mfma_f32_16x16x32_bf16 v[72:75], v[154:157], v[206:209], 0
	v_mfma_f32_16x16x32_bf16 v[124:127], v[150:153], v[182:185], v[124:127]
	v_mfma_f32_16x16x32_bf16 v[120:123], v[158:161], v[182:185], v[120:123]
	v_mfma_f32_16x16x32_bf16 v[108:111], v[150:153], v[194:197], v[108:111]
	v_mfma_f32_16x16x32_bf16 v[104:107], v[158:161], v[194:197], v[104:107]
	v_mfma_f32_16x16x32_bf16 v[92:95], v[150:153], v[202:205], v[92:95]
	v_mfma_f32_16x16x32_bf16 v[88:91], v[158:161], v[202:205], v[88:91]
	v_mfma_f32_16x16x32_bf16 v[76:79], v[150:153], v[210:213], v[76:79]
	v_mfma_f32_16x16x32_bf16 v[72:75], v[158:161], v[210:213], v[72:75]
	s_setprio 0
	s_setprio 1
	v_mfma_f32_16x16x32_bf16 v[116:119], v[162:165], v[178:181], 0
	v_mfma_f32_16x16x32_bf16 v[112:115], v[170:173], v[178:181], 0
	v_mfma_f32_16x16x32_bf16 v[100:103], v[162:165], v[186:189], 0
	v_mfma_f32_16x16x32_bf16 v[96:99], v[170:173], v[186:189], 0
	v_mfma_f32_16x16x32_bf16 v[84:87], v[162:165], v[198:201], 0
	v_mfma_f32_16x16x32_bf16 v[80:83], v[170:173], v[198:201], 0
	v_mfma_f32_16x16x32_bf16 v[68:71], v[162:165], v[206:209], 0
	v_mfma_f32_16x16x32_bf16 v[64:67], v[170:173], v[206:209], 0
	v_mfma_f32_16x16x32_bf16 v[116:119], v[166:169], v[182:185], v[116:119]
	v_mfma_f32_16x16x32_bf16 v[112:115], v[174:177], v[182:185], v[112:115]
	v_mfma_f32_16x16x32_bf16 v[100:103], v[166:169], v[194:197], v[100:103]
	v_mfma_f32_16x16x32_bf16 v[96:99], v[174:177], v[194:197], v[96:99]
	v_mfma_f32_16x16x32_bf16 v[84:87], v[166:169], v[202:205], v[84:87]
	v_mfma_f32_16x16x32_bf16 v[80:83], v[174:177], v[202:205], v[80:83]
	v_mfma_f32_16x16x32_bf16 v[68:71], v[166:169], v[210:213], v[68:71]
	v_mfma_f32_16x16x32_bf16 v[64:67], v[174:177], v[210:213], v[64:67]
	s_setprio 0
	s_barrier
	s_add_i32 s12, s68, s53
	v_lshl_add_u64 v[190:191], s[48:49], 0, v[192:193]
	s_mov_b32 m0, s12
	ds_read_b128 v[178:181], v149 offset:16384
	ds_read_b128 v[182:185], v149 offset:17408
	ds_read_b128 v[186:189], v149 offset:18432
	ds_read_b128 v[194:197], v149 offset:19456
	ds_read_b128 v[198:201], v149 offset:20480
	ds_read_b128 v[202:205], v149 offset:21504
	ds_read_b128 v[206:209], v149 offset:22528
	ds_read_b128 v[210:213], v149 offset:23552
	global_load_lds_dwordx4 v[190:191], off
	s_add_i32 m0, s12, 0x2000
	s_add_u32 s12, s48, 0x80000
	v_lshl_add_u64 v[214:215], s[48:49], 0, v[132:133]
	s_addc_u32 s13, s49, 0
	s_add_i32 s68, s69, s53
	global_load_lds_dwordx4 v[214:215], off
	v_lshl_add_u64 v[216:217], s[12:13], 0, v[192:193]
	s_mov_b32 m0, s68
	v_lshl_add_u64 v[218:219], s[50:51], 0, v[130:131]
	global_load_lds_dwordx4 v[216:217], off
	v_lshl_add_u64 v[216:217], s[12:13], 0, v[132:133]
	s_add_i32 m0, s68, 0x2000
	s_nop 0
	global_load_lds_dwordx4 v[216:217], off
	v_lshl_add_u64 v[216:217], s[50:51], 0, v[128:129]
	s_mov_b32 m0, s54
	s_nop 0
	global_load_lds_dwordx4 v[216:217], off
	s_mov_b32 m0, s55
	s_nop 0
	global_load_lds_dwordx4 v[218:219], off
	s_waitcnt vmcnt(8)
	s_waitcnt lgkmcnt(0)
	s_barrier
; #define PG8_STAGE(bufoff, gbase, voff) do { _Pragma("unroll") for (int _i = 0; _i < 2; ++_i) \
;         __builtin_amdgcn_global_load_lds((const unsigned*)((const char*)(gbase) + (voff)[_i]), (PG8_LAS unsigned*)(lds + (bufoff) + ldsw + _i * 8192), 16, 0, 0); } while (0)
; #define PG8_LDA(dst, b, h) do { _Pragma("unroll") for (int m = 0; m < 4; ++m) _Pragma("unroll") for (int k = 0; k < 2; ++k) dst[m][k] = *(const PG8_LAS bf16x8*)(lds + PG8_SA(b, h) + aoff + m * 2048 + k * 1024); } while (0)
; #define PG8_LDB(dst, b, h) do { _Pragma("unroll") for (int n = 0; n < 2; ++n) _Pragma("unroll") for (int k = 0; k < 2; ++k) dst[n][k] = *(const PG8_LAS bf16x8*)(lds + PG8_SB(b, h) + boff + n * 2048 + k * 1024); } while (0)
; #define PG8_MMA(ai, bj, At, Bt) do { __builtin_amdgcn_s_setprio(1); _Pragma("unroll") for (int m = 0; m < 4; ++m) _Pragma("unroll") for (int n = 0; n < 2; ++n) _Pragma("unroll") for (int k = 0; k < 2; ++k) \
;         acc[ai][bj][m][n] = __builtin_amdgcn_mfma_f32_16x16x32_bf16(Bt[n][k], At[m][k], acc[ai][bj][m][n], 0, 0, 0); __builtin_amdgcn_s_setprio(0); } while (0)
; #define PG8_WAIT_V(n) asm volatile("s_waitcnt vmcnt(" #n ")" ::: "memory")
; #define PG8_WAIT_L(n) asm volatile("s_waitcnt lgkmcnt(" #n ")" ::: "memory")
; #define PG8_BAR __builtin_amdgcn_s_barrier()
; #define PG8_SCHED __builtin_amdgcn_sched_barrier(0)
; template <class Epi, class Sched, bool ALIGN_EPI = false, bool SP2 = false>
; __device__ __forceinline__ void gemm_phase(PG8_LAS unsigned char* lds, const Gemm g, const Sched& S, const Epi& E, const int tid_in) {
;     ...
;             PG8_WAIT_V(8); PG8_WAIT_L(0); PG8_BAR; PG8_MMA(1, 0, At, B0); PG8_MMA(1, 1, At, B1); PG8_BAR; PG8_SCHED;
;             PG8_LDB(B0, 1, 0); PG8_LDB(B1, 1, 1); PG8_SCHED; PG8_LDA(At, 1, 0); PG8_STAGE(PG8_SA(0, 1), a2 + hstepA, voffA);
;             PG8_WAIT_V(8); PG8_WAIT_L(0); PG8_BAR; PG8_MMA(0, 0, At, B0); PG8_MMA(0, 1, At, B1); PG8_BAR; PG8_SCHED;
	s_setprio 1
	s_waitcnt lgkmcnt(0)
	v_mfma_f32_16x16x32_bf16 v[60:63], v[142:145], v[178:181], 0
	v_mfma_f32_16x16x32_bf16 v[56:59], v[154:157], v[178:181], 0
	v_mfma_f32_16x16x32_bf16 v[48:51], v[142:145], v[186:189], 0
	v_mfma_f32_16x16x32_bf16 v[40:43], v[154:157], v[186:189], 0
	v_mfma_f32_16x16x32_bf16 v[32:35], v[142:145], v[198:201], 0
	v_mfma_f32_16x16x32_bf16 v[24:27], v[154:157], v[198:201], 0
	v_mfma_f32_16x16x32_bf16 v[16:19], v[142:145], v[206:209], 0
	v_mfma_f32_16x16x32_bf16 v[8:11], v[154:157], v[206:209], 0
	v_mfma_f32_16x16x32_bf16 v[60:63], v[150:153], v[182:185], v[60:63]
	v_mfma_f32_16x16x32_bf16 v[56:59], v[158:161], v[182:185], v[56:59]
	v_mfma_f32_16x16x32_bf16 v[48:51], v[150:153], v[194:197], v[48:51]
	v_mfma_f32_16x16x32_bf16 v[40:43], v[158:161], v[194:197], v[40:43]
	v_mfma_f32_16x16x32_bf16 v[32:35], v[150:153], v[202:205], v[32:35]
	v_mfma_f32_16x16x32_bf16 v[24:27], v[158:161], v[202:205], v[24:27]
	v_mfma_f32_16x16x32_bf16 v[16:19], v[150:153], v[210:213], v[16:19]
	v_mfma_f32_16x16x32_bf16 v[8:11], v[158:161], v[210:213], v[8:11]
	s_setprio 0
	s_setprio 1
	v_mfma_f32_16x16x32_bf16 v[52:55], v[162:165], v[178:181], 0
	v_mfma_f32_16x16x32_bf16 v[44:47], v[170:173], v[178:181], 0
	v_mfma_f32_16x16x32_bf16 v[36:39], v[162:165], v[186:189], 0
	v_mfma_f32_16x16x32_bf16 v[28:31], v[170:173], v[186:189], 0
	v_mfma_f32_16x16x32_bf16 v[20:23], v[162:165], v[198:201], 0
	v_mfma_f32_16x16x32_bf16 v[12:15], v[170:173], v[198:201], 0
	v_mfma_f32_16x16x32_bf16 v[4:7], v[162:165], v[206:209], 0
	v_mfma_f32_16x16x32_bf16 v[0:3], v[170:173], v[206:209], 0
	v_mfma_f32_16x16x32_bf16 v[52:55], v[166:169], v[182:185], v[52:55]
	v_mfma_f32_16x16x32_bf16 v[44:47], v[174:177], v[182:185], v[44:47]
	v_mfma_f32_16x16x32_bf16 v[36:39], v[166:169], v[194:197], v[36:39]
	v_mfma_f32_16x16x32_bf16 v[28:31], v[174:177], v[194:197], v[28:31]
	v_mfma_f32_16x16x32_bf16 v[20:23], v[166:169], v[202:205], v[20:23]
	v_mfma_f32_16x16x32_bf16 v[12:15], v[174:177], v[202:205], v[12:15]
	v_mfma_f32_16x16x32_bf16 v[4:7], v[166:169], v[210:213], v[4:7]
	v_mfma_f32_16x16x32_bf16 v[0:3], v[174:177], v[210:213], v[0:3]
	s_setprio 0
	s_barrier
	s_add_i32 s68, 0, 0x18000
	v_add_u32_e32 v138, s68, v141
	s_add_i32 s69, 0, 0x1c000
	ds_read_b128 v[142:145], v138
	ds_read_b128 v[150:153], v138 offset:1024
	ds_read_b128 v[154:157], v138 offset:2048
	ds_read_b128 v[158:161], v138 offset:3072
	v_add_u32_e32 v138, s69, v141
	ds_read_b128 v[162:165], v138
	ds_read_b128 v[166:169], v138 offset:1024
	ds_read_b128 v[170:173], v138 offset:2048
	ds_read_b128 v[174:177], v138 offset:3072
	s_add_u32 s12, s50, 0x80000
	s_addc_u32 s13, s51, 0
	s_mov_b32 m0, s56
	v_lshl_add_u64 v[220:221], s[12:13], 0, v[128:129]
	ds_read_b128 v[178:181], v149 offset:32768
	ds_read_b128 v[182:185], v149 offset:33792
	ds_read_b128 v[186:189], v149 offset:34816
	ds_read_b128 v[194:197], v149 offset:35840
	ds_read_b128 v[198:201], v149 offset:36864
	ds_read_b128 v[202:205], v149 offset:37888
	ds_read_b128 v[206:209], v149 offset:38912
	ds_read_b128 v[210:213], v149 offset:39936
	global_load_lds_dwordx4 v[220:221], off
	v_lshl_add_u64 v[220:221], s[12:13], 0, v[130:131]
	s_mov_b32 m0, s57
	s_nop 0
	global_load_lds_dwordx4 v[220:221], off
	s_waitcnt vmcnt(8)
	s_waitcnt lgkmcnt(0)
	s_barrier
	s_setprio 1
	s_waitcnt lgkmcnt(0)
	v_mfma_f32_16x16x32_bf16 v[124:127], v[142:145], v[178:181], v[124:127]
	v_mfma_f32_16x16x32_bf16 v[120:123], v[154:157], v[178:181], v[120:123]
	v_mfma_f32_16x16x32_bf16 v[108:111], v[142:145], v[186:189], v[108:111]
	v_mfma_f32_16x16x32_bf16 v[104:107], v[154:157], v[186:189], v[104:107]
	v_mfma_f32_16x16x32_bf16 v[92:95], v[142:145], v[198:201], v[92:95]
	v_mfma_f32_16x16x32_bf16 v[88:91], v[154:157], v[198:201], v[88:91]
	v_mfma_f32_16x16x32_bf16 v[76:79], v[142:145], v[206:209], v[76:79]
	v_mfma_f32_16x16x32_bf16 v[72:75], v[154:157], v[206:209], v[72:75]
	v_mfma_f32_16x16x32_bf16 v[124:127], v[150:153], v[182:185], v[124:127]
	v_mfma_f32_16x16x32_bf16 v[120:123], v[158:161], v[182:185], v[120:123]
	v_mfma_f32_16x16x32_bf16 v[108:111], v[150:153], v[194:197], v[108:111]
	v_mfma_f32_16x16x32_bf16 v[104:107], v[158:161], v[194:197], v[104:107]
	v_mfma_f32_16x16x32_bf16 v[92:95], v[150:153], v[202:205], v[92:95]
	v_mfma_f32_16x16x32_bf16 v[88:91], v[158:161], v[202:205], v[88:91]
	v_mfma_f32_16x16x32_bf16 v[76:79], v[150:153], v[210:213], v[76:79]
	v_mfma_f32_16x16x32_bf16 v[72:75], v[158:161], v[210:213], v[72:75]
	s_setprio 0
	s_setprio 1
	v_mfma_f32_16x16x32_bf16 v[116:119], v[162:165], v[178:181], v[116:119]
	v_mfma_f32_16x16x32_bf16 v[112:115], v[170:173], v[178:181], v[112:115]
	v_mfma_f32_16x16x32_bf16 v[100:103], v[162:165], v[186:189], v[100:103]
	v_mfma_f32_16x16x32_bf16 v[96:99], v[170:173], v[186:189], v[96:99]
	v_mfma_f32_16x16x32_bf16 v[84:87], v[162:165], v[198:201], v[84:87]
	v_mfma_f32_16x16x32_bf16 v[80:83], v[170:173], v[198:201], v[80:83]
	v_mfma_f32_16x16x32_bf16 v[68:71], v[162:165], v[206:209], v[68:71]
	v_mfma_f32_16x16x32_bf16 v[64:67], v[170:173], v[206:209], v[64:67]
	v_mfma_f32_16x16x32_bf16 v[116:119], v[166:169], v[182:185], v[116:119]
	v_mfma_f32_16x16x32_bf16 v[112:115], v[174:177], v[182:185], v[112:115]
	v_mfma_f32_16x16x32_bf16 v[100:103], v[166:169], v[194:197], v[100:103]
	v_mfma_f32_16x16x32_bf16 v[96:99], v[174:177], v[194:197], v[96:99]
	v_mfma_f32_16x16x32_bf16 v[84:87], v[166:169], v[202:205], v[84:87]
	v_mfma_f32_16x16x32_bf16 v[80:83], v[174:177], v[202:205], v[80:83]
	v_mfma_f32_16x16x32_bf16 v[68:71], v[166:169], v[210:213], v[68:71]
	v_mfma_f32_16x16x32_bf16 v[64:67], v[174:177], v[210:213], v[64:67]
	s_setprio 0
	s_barrier
; #define PG8_STAGE(bufoff, gbase, voff) do { _Pragma("unroll") for (int _i = 0; _i < 2; ++_i) \
;         __builtin_amdgcn_global_load_lds((const unsigned*)((const char*)(gbase) + (voff)[_i]), (PG8_LAS unsigned*)(lds + (bufoff) + ldsw + _i * 8192), 16, 0, 0); } while (0)
; #define PG8_LDA(dst, b, h) do { _Pragma("unroll") for (int m = 0; m < 4; ++m) _Pragma("unroll") for (int k = 0; k < 2; ++k) dst[m][k] = *(const PG8_LAS bf16x8*)(lds + PG8_SA(b, h) + aoff + m * 2048 + k * 1024); } while (0)
; #define PG8_WAIT_V(n) asm volatile("s_waitcnt vmcnt(" #n ")" ::: "memory")
; #define PG8_WAIT_L(n) asm volatile("s_waitcnt lgkmcnt(" #n ")" ::: "memory")
; #define PG8_BAR __builtin_amdgcn_s_barrier()
; template <class Epi, class Sched, bool ALIGN_EPI = false, bool SP2 = false>
; __device__ __forceinline__ void gemm_phase(PG8_LAS unsigned char* lds, const Gemm g, const Sched& S, const Epi& E, const int tid_in) {
;     ...
;         for (int t = 0; t < nt; t += 2) {
;             const bool last = (t == nt - 2);
;             const char* a1 = cA + (size_t)(t + 1) * kstep;
;             const char* a2 = last ? nA : cA + (size_t)(t + 2) * kstep; const char* b2 = last ? nB : cB + (size_t)(t + 2) * kstep;
;             const char* a3 = a2 + kstep; const char* b3 = b2 + kstep;
;             if (last && has_next) S.a_ready(nxt);
;             if constexpr (SP2) {
;             PG8_LDB(B0, 0, 0); PG8_LDB(B1, 0, 1); PG8_SCHED; PG8_LDA(At, 0, 0); PG8_STAGE(PG8_SA(1, 1), a1 + hstepA, voffA);
;             PG8_WAIT_V(8); PG8_WAIT_L(0); PG8_BAR; PG8_MMA(0, 0, At, B0); PG8_MMA(0, 1, At, B1); PG8_BAR; PG8_SCHED;
;             PG8_LDA(At, 0, 1); PG8_STAGE(PG8_SB(0, 0), b2, voffB); PG8_STAGE(PG8_SB(0, 1), b2 + hstepB, voffB); PG8_STAGE(PG8_SA(0, 0), a2, voffA);
;             PG8_WAIT_V(8); PG8_WAIT_L(0); PG8_BAR; PG8_MMA(1, 0, At, B0); PG8_MMA(1, 1, At, B1); PG8_BAR; PG8_SCHED;
;             PG8_LDB(B0, 1, 0); PG8_LDB(B1, 1, 1); PG8_SCHED; PG8_LDA(At, 1, 0); PG8_STAGE(PG8_SA(0, 1), a2 + hstepA, voffA);
;             PG8_WAIT_V(8); PG8_WAIT_L(0); PG8_BAR; PG8_MMA(0, 0, At, B0); PG8_MMA(0, 1, At, B1); PG8_BAR; PG8_SCHED;
;             PG8_LDA(At, 1, 1); PG8_STAGE(PG8_SB(1, 0), b3, voffB); PG8_STAGE(PG8_SB(1, 1), b3 + hstepB, voffB); PG8_STAGE(PG8_SA(1, 0), a3, voffA);
;             PG8_WAIT_V(8); PG8_WAIT_L(0); PG8_BAR; PG8_MMA(1, 0, At, B0); PG8_MMA(1, 1, At, B1); PG8_BAR; PG8_SCHED;
	s_add_i32 s12, s68, s53
	v_lshl_add_u64 v[190:191], v[190:191], 0, s[26:27]
	s_mov_b32 m0, s12
	ds_read_b128 v[178:181], v149 offset:49152
	ds_read_b128 v[182:185], v149 offset:50176
	ds_read_b128 v[186:189], v149 offset:51200
	ds_read_b128 v[194:197], v149 offset:52224
	ds_read_b128 v[198:201], v149 offset:53248
	ds_read_b128 v[202:205], v149 offset:54272
	ds_read_b128 v[206:209], v149 offset:55296
	ds_read_b128 v[210:213], v149 offset:56320
	global_load_lds_dwordx4 v[190:191], off
	s_add_i32 m0, s12, 0x2000
	s_add_u32 s12, s48, 0x80080
	v_lshl_add_u64 v[190:191], v[214:215], 0, s[26:27]
	s_addc_u32 s13, s49, 0
	s_add_i32 s48, s69, s53
	global_load_lds_dwordx4 v[190:191], off
	v_lshl_add_u64 v[190:191], s[12:13], 0, v[192:193]
	s_mov_b32 m0, s48
	s_nop 0
	global_load_lds_dwordx4 v[190:191], off
	v_lshl_add_u64 v[190:191], s[12:13], 0, v[132:133]
	s_add_i32 m0, s48, 0x2000
	s_nop 0
	global_load_lds_dwordx4 v[190:191], off
	v_lshl_add_u64 v[190:191], v[216:217], 0, s[26:27]
	s_mov_b32 m0, s58
	s_nop 0
	global_load_lds_dwordx4 v[190:191], off
	v_lshl_add_u64 v[190:191], v[218:219], 0, s[26:27]
	s_mov_b32 m0, s59
	s_nop 0
	global_load_lds_dwordx4 v[190:191], off
	s_waitcnt vmcnt(8)
	s_waitcnt lgkmcnt(0)
	s_barrier
	s_setprio 1
	s_waitcnt lgkmcnt(0)
	v_mfma_f32_16x16x32_bf16 v[60:63], v[142:145], v[178:181], v[60:63]
	v_mfma_f32_16x16x32_bf16 v[56:59], v[154:157], v[178:181], v[56:59]
	v_mfma_f32_16x16x32_bf16 v[48:51], v[142:145], v[186:189], v[48:51]
	v_mfma_f32_16x16x32_bf16 v[40:43], v[154:157], v[186:189], v[40:43]
	v_mfma_f32_16x16x32_bf16 v[32:35], v[142:145], v[198:201], v[32:35]
	v_mfma_f32_16x16x32_bf16 v[24:27], v[154:157], v[198:201], v[24:27]
	v_mfma_f32_16x16x32_bf16 v[16:19], v[142:145], v[206:209], v[16:19]
	v_mfma_f32_16x16x32_bf16 v[8:11], v[154:157], v[206:209], v[8:11]
	v_mfma_f32_16x16x32_bf16 v[60:63], v[150:153], v[182:185], v[60:63]
	v_mfma_f32_16x16x32_bf16 v[56:59], v[158:161], v[182:185], v[56:59]
	v_mfma_f32_16x16x32_bf16 v[48:51], v[150:153], v[194:197], v[48:51]
	v_mfma_f32_16x16x32_bf16 v[40:43], v[158:161], v[194:197], v[40:43]
	v_mfma_f32_16x16x32_bf16 v[32:35], v[150:153], v[202:205], v[32:35]
	v_mfma_f32_16x16x32_bf16 v[24:27], v[158:161], v[202:205], v[24:27]
	v_mfma_f32_16x16x32_bf16 v[16:19], v[150:153], v[210:213], v[16:19]
	v_mfma_f32_16x16x32_bf16 v[8:11], v[158:161], v[210:213], v[8:11]
	s_setprio 0
	s_setprio 1
	v_mfma_f32_16x16x32_bf16 v[52:55], v[162:165], v[178:181], v[52:55]
	v_mfma_f32_16x16x32_bf16 v[44:47], v[170:173], v[178:181], v[44:47]
	v_mfma_f32_16x16x32_bf16 v[36:39], v[162:165], v[186:189], v[36:39]
	v_mfma_f32_16x16x32_bf16 v[28:31], v[170:173], v[186:189], v[28:31]
	v_mfma_f32_16x16x32_bf16 v[20:23], v[162:165], v[198:201], v[20:23]
	v_mfma_f32_16x16x32_bf16 v[12:15], v[170:173], v[198:201], v[12:15]
	v_mfma_f32_16x16x32_bf16 v[4:7], v[162:165], v[206:209], v[4:7]
	v_mfma_f32_16x16x32_bf16 v[0:3], v[170:173], v[206:209], v[0:3]
	v_mfma_f32_16x16x32_bf16 v[52:55], v[166:169], v[182:185], v[52:55]
	v_mfma_f32_16x16x32_bf16 v[44:47], v[174:177], v[182:185], v[44:47]
	v_mfma_f32_16x16x32_bf16 v[36:39], v[166:169], v[194:197], v[36:39]
	v_mfma_f32_16x16x32_bf16 v[28:31], v[174:177], v[194:197], v[28:31]
	v_mfma_f32_16x16x32_bf16 v[20:23], v[166:169], v[202:205], v[20:23]
	v_mfma_f32_16x16x32_bf16 v[12:15], v[174:177], v[202:205], v[12:15]
	v_mfma_f32_16x16x32_bf16 v[4:7], v[166:169], v[210:213], v[4:7]
	v_mfma_f32_16x16x32_bf16 v[0:3], v[174:177], v[210:213], v[0:3]
	s_setprio 0
	s_barrier
	s_add_i32 s67, s67, 2
	s_add_u32 s46, s46, 0x100
	s_addc_u32 s47, s47, 0
	s_add_u32 s65, s65, 0x100
	s_addc_u32 s66, s66, 0
	s_cmp_gt_u32 s67, 29
	.p2align 6
.LBB0_289:
	s_add_u32 s12, s46, 0xfff80080
	s_addc_u32 s13, s47, -1
	s_add_i32 s68, 0, 0x10000
	s_cmp_eq_u32 s67, 28
	s_cselect_b32 s51, s41, s13
	s_cselect_b32 s50, s63, s12
	v_add_u32_e32 v138, s68, v141
	s_cselect_b32 s49, s39, s66
	s_cselect_b32 s48, s64, s65
	s_add_i32 s69, 0, 0x14000
	ds_read_b128 v[142:145], v138
	ds_read_b128 v[150:153], v138 offset:1024
	ds_read_b128 v[154:157], v138 offset:2048
	ds_read_b128 v[158:161], v138 offset:3072
	v_add_u32_e32 v138, s69, v141
	ds_read_b128 v[162:165], v138
	ds_read_b128 v[166:169], v138 offset:1024
	ds_read_b128 v[170:173], v138 offset:2048
	ds_read_b128 v[174:177], v138 offset:3072
	v_lshl_add_u64 v[190:191], s[46:47], 0, v[134:135]
	s_add_i32 m0, s54, 0xc000
	ds_read_b128 v[178:181], v149
	ds_read_b128 v[182:185], v149 offset:1024
	ds_read_b128 v[186:189], v149 offset:2048
	ds_read_b128 v[194:197], v149 offset:3072
	ds_read_b128 v[198:201], v149 offset:4096
	ds_read_b128 v[202:205], v149 offset:5120
	ds_read_b128 v[206:209], v149 offset:6144
	ds_read_b128 v[210:213], v149 offset:7168
	global_load_lds_dwordx4 v[190:191], off
	v_lshl_add_u64 v[190:191], s[46:47], 0, v[136:137]
	s_add_i32 m0, s54, 0xe000
	s_nop 0
	global_load_lds_dwordx4 v[190:191], off
	s_waitcnt vmcnt(8)
	s_waitcnt lgkmcnt(0)
	s_barrier
; #define PG8_STAGE(bufoff, gbase, voff) do { _Pragma("unroll") for (int _i = 0; _i < 2; ++_i) \
;         __builtin_amdgcn_global_load_lds((const unsigned*)((const char*)(gbase) + (voff)[_i]), (PG8_LAS unsigned*)(lds + (bufoff) + ldsw + _i * 8192), 16, 0, 0); } while (0)
; #define PG8_LDA(dst, b, h) do { _Pragma("unroll") for (int m = 0; m < 4; ++m) _Pragma("unroll") for (int k = 0; k < 2; ++k) dst[m][k] = *(const PG8_LAS bf16x8*)(lds + PG8_SA(b, h) + aoff + m * 2048 + k * 1024); } while (0)
; #define PG8_MMA(ai, bj, At, Bt) do { __builtin_amdgcn_s_setprio(1); _Pragma("unroll") for (int m = 0; m < 4; ++m) _Pragma("unroll") for (int n = 0; n < 2; ++n) _Pragma("unroll") for (int k = 0; k < 2; ++k) \
;         acc[ai][bj][m][n] = __builtin_amdgcn_mfma_f32_16x16x32_bf16(Bt[n][k], At[m][k], acc[ai][bj][m][n], 0, 0, 0); __builtin_amdgcn_s_setprio(0); } while (0)
; #define PG8_WAIT_V(n) asm volatile("s_waitcnt vmcnt(" #n ")" ::: "memory")
; #define PG8_WAIT_L(n) asm volatile("s_waitcnt lgkmcnt(" #n ")" ::: "memory")
; #define PG8_BAR __builtin_amdgcn_s_barrier()
; #define PG8_SCHED __builtin_amdgcn_sched_barrier(0)
; template <class Epi, class Sched, bool ALIGN_EPI = false, bool SP2 = false>
; __device__ __forceinline__ void gemm_phase(PG8_LAS unsigned char* lds, const Gemm g, const Sched& S, const Epi& E, const int tid_in) {
;     ...
;             PG8_WAIT_V(8); PG8_WAIT_L(0); PG8_BAR; PG8_MMA(0, 0, At, B0); PG8_MMA(0, 1, At, B1); PG8_BAR; PG8_SCHED;
;             PG8_LDA(At, 0, 1); PG8_STAGE(PG8_SB(0, 0), b2, voffB); PG8_STAGE(PG8_SB(0, 1), b2 + hstepB, voffB); PG8_STAGE(PG8_SA(0, 0), a2, voffA);
;             PG8_WAIT_V(8); PG8_WAIT_L(0); PG8_BAR; PG8_MMA(1, 0, At, B0); PG8_MMA(1, 1, At, B1); PG8_BAR; PG8_SCHED;
	s_setprio 1
	s_waitcnt lgkmcnt(0)
	v_mfma_f32_16x16x32_bf16 v[124:127], v[142:145], v[178:181], v[124:127]
	v_mfma_f32_16x16x32_bf16 v[120:123], v[154:157], v[178:181], v[120:123]
	v_mfma_f32_16x16x32_bf16 v[108:111], v[142:145], v[186:189], v[108:111]
	v_mfma_f32_16x16x32_bf16 v[104:107], v[154:157], v[186:189], v[104:107]
	v_mfma_f32_16x16x32_bf16 v[92:95], v[142:145], v[198:201], v[92:95]
	v_mfma_f32_16x16x32_bf16 v[88:91], v[154:157], v[198:201], v[88:91]
	v_mfma_f32_16x16x32_bf16 v[76:79], v[142:145], v[206:209], v[76:79]
	v_mfma_f32_16x16x32_bf16 v[72:75], v[154:157], v[206:209], v[72:75]
	v_mfma_f32_16x16x32_bf16 v[124:127], v[150:153], v[182:185], v[124:127]
	v_mfma_f32_16x16x32_bf16 v[120:123], v[158:161], v[182:185], v[120:123]
	v_mfma_f32_16x16x32_bf16 v[108:111], v[150:153], v[194:197], v[108:111]
	v_mfma_f32_16x16x32_bf16 v[104:107], v[158:161], v[194:197], v[104:107]
	v_mfma_f32_16x16x32_bf16 v[92:95], v[150:153], v[202:205], v[92:95]
	v_mfma_f32_16x16x32_bf16 v[88:91], v[158:161], v[202:205], v[88:91]
	v_mfma_f32_16x16x32_bf16 v[76:79], v[150:153], v[210:213], v[76:79]
	v_mfma_f32_16x16x32_bf16 v[72:75], v[158:161], v[210:213], v[72:75]
	v_mfma_f32_16x16x32_bf16 v[116:119], v[162:165], v[178:181], v[116:119]
	v_mfma_f32_16x16x32_bf16 v[112:115], v[170:173], v[178:181], v[112:115]
	v_mfma_f32_16x16x32_bf16 v[100:103], v[162:165], v[186:189], v[100:103]
	v_mfma_f32_16x16x32_bf16 v[96:99], v[170:173], v[186:189], v[96:99]
	v_mfma_f32_16x16x32_bf16 v[84:87], v[162:165], v[198:201], v[84:87]
	v_mfma_f32_16x16x32_bf16 v[80:83], v[170:173], v[198:201], v[80:83]
	v_mfma_f32_16x16x32_bf16 v[68:71], v[162:165], v[206:209], v[68:71]
	v_mfma_f32_16x16x32_bf16 v[64:67], v[170:173], v[206:209], v[64:67]
	v_mfma_f32_16x16x32_bf16 v[116:119], v[166:169], v[182:185], v[116:119]
	v_mfma_f32_16x16x32_bf16 v[112:115], v[174:177], v[182:185], v[112:115]
	v_mfma_f32_16x16x32_bf16 v[100:103], v[166:169], v[194:197], v[100:103]
	v_mfma_f32_16x16x32_bf16 v[96:99], v[174:177], v[194:197], v[96:99]
	v_mfma_f32_16x16x32_bf16 v[84:87], v[166:169], v[202:205], v[84:87]
	v_mfma_f32_16x16x32_bf16 v[80:83], v[174:177], v[202:205], v[80:83]
	v_mfma_f32_16x16x32_bf16 v[68:71], v[166:169], v[210:213], v[68:71]
	v_mfma_f32_16x16x32_bf16 v[64:67], v[174:177], v[210:213], v[64:67]
	s_setprio 0
	s_barrier
	s_add_i32 s12, s68, s53
	v_lshl_add_u64 v[190:191], s[48:49], 0, v[192:193]
	s_mov_b32 m0, s12
	ds_read_b128 v[178:181], v149 offset:16384
	ds_read_b128 v[182:185], v149 offset:17408
	ds_read_b128 v[186:189], v149 offset:18432
	ds_read_b128 v[194:197], v149 offset:19456
	ds_read_b128 v[198:201], v149 offset:20480
	ds_read_b128 v[202:205], v149 offset:21504
	ds_read_b128 v[206:209], v149 offset:22528
	ds_read_b128 v[210:213], v149 offset:23552
	global_load_lds_dwordx4 v[190:191], off
	s_add_i32 m0, s12, 0x2000
	s_add_u32 s12, s48, 0x80000
	v_lshl_add_u64 v[214:215], s[48:49], 0, v[132:133]
	s_addc_u32 s13, s49, 0
	s_add_i32 s68, s69, s53
	global_load_lds_dwordx4 v[214:215], off
	v_lshl_add_u64 v[216:217], s[12:13], 0, v[192:193]
	s_mov_b32 m0, s68
	v_lshl_add_u64 v[218:219], s[50:51], 0, v[130:131]
	global_load_lds_dwordx4 v[216:217], off
	v_lshl_add_u64 v[216:217], s[12:13], 0, v[132:133]
	s_add_i32 m0, s68, 0x2000
	s_nop 0
	global_load_lds_dwordx4 v[216:217], off
	v_lshl_add_u64 v[216:217], s[50:51], 0, v[128:129]
	s_mov_b32 m0, s54
	s_nop 0
	global_load_lds_dwordx4 v[216:217], off
	s_mov_b32 m0, s55
	s_nop 0
	global_load_lds_dwordx4 v[218:219], off
	s_waitcnt vmcnt(8)
	s_waitcnt lgkmcnt(0)
	s_barrier
	s_setprio 1
	s_waitcnt lgkmcnt(0)
	v_mfma_f32_16x16x32_bf16 v[60:63], v[142:145], v[178:181], v[60:63]
	v_mfma_f32_16x16x32_bf16 v[56:59], v[154:157], v[178:181], v[56:59]
	v_mfma_f32_16x16x32_bf16 v[48:51], v[142:145], v[186:189], v[48:51]
	v_mfma_f32_16x16x32_bf16 v[40:43], v[154:157], v[186:189], v[40:43]
	v_mfma_f32_16x16x32_bf16 v[32:35], v[142:145], v[198:201], v[32:35]
	v_mfma_f32_16x16x32_bf16 v[24:27], v[154:157], v[198:201], v[24:27]
	v_mfma_f32_16x16x32_bf16 v[16:19], v[142:145], v[206:209], v[16:19]
	v_mfma_f32_16x16x32_bf16 v[8:11], v[154:157], v[206:209], v[8:11]
	v_mfma_f32_16x16x32_bf16 v[60:63], v[150:153], v[182:185], v[60:63]
	v_mfma_f32_16x16x32_bf16 v[56:59], v[158:161], v[182:185], v[56:59]
	v_mfma_f32_16x16x32_bf16 v[48:51], v[150:153], v[194:197], v[48:51]
	v_mfma_f32_16x16x32_bf16 v[40:43], v[158:161], v[194:197], v[40:43]
	v_mfma_f32_16x16x32_bf16 v[32:35], v[150:153], v[202:205], v[32:35]
	v_mfma_f32_16x16x32_bf16 v[24:27], v[158:161], v[202:205], v[24:27]
	v_mfma_f32_16x16x32_bf16 v[16:19], v[150:153], v[210:213], v[16:19]
	v_mfma_f32_16x16x32_bf16 v[8:11], v[158:161], v[210:213], v[8:11]
	v_mfma_f32_16x16x32_bf16 v[52:55], v[162:165], v[178:181], v[52:55]
	v_mfma_f32_16x16x32_bf16 v[44:47], v[170:173], v[178:181], v[44:47]
	v_mfma_f32_16x16x32_bf16 v[36:39], v[162:165], v[186:189], v[36:39]
	v_mfma_f32_16x16x32_bf16 v[28:31], v[170:173], v[186:189], v[28:31]
	v_mfma_f32_16x16x32_bf16 v[20:23], v[162:165], v[198:201], v[20:23]
	v_mfma_f32_16x16x32_bf16 v[12:15], v[170:173], v[198:201], v[12:15]
	v_mfma_f32_16x16x32_bf16 v[4:7], v[162:165], v[206:209], v[4:7]
	v_mfma_f32_16x16x32_bf16 v[0:3], v[170:173], v[206:209], v[0:3]
	v_mfma_f32_16x16x32_bf16 v[52:55], v[166:169], v[182:185], v[52:55]
	v_mfma_f32_16x16x32_bf16 v[44:47], v[174:177], v[182:185], v[44:47]
	v_mfma_f32_16x16x32_bf16 v[36:39], v[166:169], v[194:197], v[36:39]
	v_mfma_f32_16x16x32_bf16 v[28:31], v[174:177], v[194:197], v[28:31]
	v_mfma_f32_16x16x32_bf16 v[20:23], v[166:169], v[202:205], v[20:23]
	v_mfma_f32_16x16x32_bf16 v[12:15], v[174:177], v[202:205], v[12:15]
	v_mfma_f32_16x16x32_bf16 v[4:7], v[166:169], v[210:213], v[4:7]
	v_mfma_f32_16x16x32_bf16 v[0:3], v[174:177], v[210:213], v[0:3]
	s_setprio 0
	s_barrier
; #define PG8_STAGE(bufoff, gbase, voff) do { _Pragma("unroll") for (int _i = 0; _i < 2; ++_i) \
;         __builtin_amdgcn_global_load_lds((const unsigned*)((const char*)(gbase) + (voff)[_i]), (PG8_LAS unsigned*)(lds + (bufoff) + ldsw + _i * 8192), 16, 0, 0); } while (0)
; #define PG8_LDA(dst, b, h) do { _Pragma("unroll") for (int m = 0; m < 4; ++m) _Pragma("unroll") for (int k = 0; k < 2; ++k) dst[m][k] = *(const PG8_LAS bf16x8*)(lds + PG8_SA(b, h) + aoff + m * 2048 + k * 1024); } while (0)
; #define PG8_LDB(dst, b, h) do { _Pragma("unroll") for (int n = 0; n < 2; ++n) _Pragma("unroll") for (int k = 0; k < 2; ++k) dst[n][k] = *(const PG8_LAS bf16x8*)(lds + PG8_SB(b, h) + boff + n * 2048 + k * 1024); } while (0)
; #define PG8_MMA(ai, bj, At, Bt) do { __builtin_amdgcn_s_setprio(1); _Pragma("unroll") for (int m = 0; m < 4; ++m) _Pragma("unroll") for (int n = 0; n < 2; ++n) _Pragma("unroll") for (int k = 0; k < 2; ++k) \
;         acc[ai][bj][m][n] = __builtin_amdgcn_mfma_f32_16x16x32_bf16(Bt[n][k], At[m][k], acc[ai][bj][m][n], 0, 0, 0); __builtin_amdgcn_s_setprio(0); } while (0)
; #define PG8_WAIT_V(n) asm volatile("s_waitcnt vmcnt(" #n ")" ::: "memory")
; #define PG8_WAIT_L(n) asm volatile("s_waitcnt lgkmcnt(" #n ")" ::: "memory")
; #define PG8_BAR __builtin_amdgcn_s_barrier()
; #define PG8_SCHED __builtin_amdgcn_sched_barrier(0)
; template <class Epi, class Sched, bool ALIGN_EPI = false, bool SP2 = false>
; __device__ __forceinline__ void gemm_phase(PG8_LAS unsigned char* lds, const Gemm g, const Sched& S, const Epi& E, const int tid_in) {
;     ...
;             PG8_LDB(B0, 1, 0); PG8_LDB(B1, 1, 1); PG8_SCHED; PG8_LDA(At, 1, 0); PG8_STAGE(PG8_SA(0, 1), a2 + hstepA, voffA);
;             PG8_WAIT_V(8); PG8_WAIT_L(0); PG8_BAR; PG8_MMA(0, 0, At, B0); PG8_MMA(0, 1, At, B1); PG8_BAR; PG8_SCHED;
	s_add_i32 s68, 0, 0x18000
	v_add_u32_e32 v138, s68, v141
	s_add_i32 s69, 0, 0x1c000
	ds_read_b128 v[142:145], v138
	ds_read_b128 v[150:153], v138 offset:1024
	ds_read_b128 v[154:157], v138 offset:2048
	ds_read_b128 v[158:161], v138 offset:3072
	v_add_u32_e32 v138, s69, v141
	ds_read_b128 v[162:165], v138
	ds_read_b128 v[166:169], v138 offset:1024
	ds_read_b128 v[170:173], v138 offset:2048
	ds_read_b128 v[174:177], v138 offset:3072
	s_add_u32 s12, s50, 0x80000
	s_addc_u32 s13, s51, 0
	s_mov_b32 m0, s56
	v_lshl_add_u64 v[220:221], s[12:13], 0, v[128:129]
	ds_read_b128 v[178:181], v149 offset:32768
	ds_read_b128 v[182:185], v149 offset:33792
	ds_read_b128 v[186:189], v149 offset:34816
	ds_read_b128 v[194:197], v149 offset:35840
	ds_read_b128 v[198:201], v149 offset:36864
	ds_read_b128 v[202:205], v149 offset:37888
	ds_read_b128 v[206:209], v149 offset:38912
	ds_read_b128 v[210:213], v149 offset:39936
	global_load_lds_dwordx4 v[220:221], off
	v_lshl_add_u64 v[220:221], s[12:13], 0, v[130:131]
	s_mov_b32 m0, s57
	s_nop 0
	global_load_lds_dwordx4 v[220:221], off
	s_waitcnt vmcnt(8)
	s_waitcnt lgkmcnt(0)
	s_barrier
	s_setprio 1
	s_waitcnt lgkmcnt(0)
	v_mfma_f32_16x16x32_bf16 v[124:127], v[142:145], v[178:181], v[124:127]
	v_mfma_f32_16x16x32_bf16 v[120:123], v[154:157], v[178:181], v[120:123]
	v_mfma_f32_16x16x32_bf16 v[108:111], v[142:145], v[186:189], v[108:111]
	v_mfma_f32_16x16x32_bf16 v[104:107], v[154:157], v[186:189], v[104:107]
	v_mfma_f32_16x16x32_bf16 v[92:95], v[142:145], v[198:201], v[92:95]
	v_mfma_f32_16x16x32_bf16 v[88:91], v[154:157], v[198:201], v[88:91]
	v_mfma_f32_16x16x32_bf16 v[76:79], v[142:145], v[206:209], v[76:79]
	v_mfma_f32_16x16x32_bf16 v[72:75], v[154:157], v[206:209], v[72:75]
	v_mfma_f32_16x16x32_bf16 v[124:127], v[150:153], v[182:185], v[124:127]
	v_mfma_f32_16x16x32_bf16 v[120:123], v[158:161], v[182:185], v[120:123]
	v_mfma_f32_16x16x32_bf16 v[108:111], v[150:153], v[194:197], v[108:111]
	v_mfma_f32_16x16x32_bf16 v[104:107], v[158:161], v[194:197], v[104:107]
	v_mfma_f32_16x16x32_bf16 v[92:95], v[150:153], v[202:205], v[92:95]
	v_mfma_f32_16x16x32_bf16 v[88:91], v[158:161], v[202:205], v[88:91]
	v_mfma_f32_16x16x32_bf16 v[76:79], v[150:153], v[210:213], v[76:79]
	v_mfma_f32_16x16x32_bf16 v[72:75], v[158:161], v[210:213], v[72:75]
	v_mfma_f32_16x16x32_bf16 v[116:119], v[162:165], v[178:181], v[116:119]
	v_mfma_f32_16x16x32_bf16 v[112:115], v[170:173], v[178:181], v[112:115]
	v_mfma_f32_16x16x32_bf16 v[100:103], v[162:165], v[186:189], v[100:103]
	v_mfma_f32_16x16x32_bf16 v[96:99], v[170:173], v[186:189], v[96:99]
	v_mfma_f32_16x16x32_bf16 v[84:87], v[162:165], v[198:201], v[84:87]
	v_mfma_f32_16x16x32_bf16 v[80:83], v[170:173], v[198:201], v[80:83]
	v_mfma_f32_16x16x32_bf16 v[68:71], v[162:165], v[206:209], v[68:71]
	v_mfma_f32_16x16x32_bf16 v[64:67], v[170:173], v[206:209], v[64:67]
	v_mfma_f32_16x16x32_bf16 v[116:119], v[166:169], v[182:185], v[116:119]
	v_mfma_f32_16x16x32_bf16 v[112:115], v[174:177], v[182:185], v[112:115]
	v_mfma_f32_16x16x32_bf16 v[100:103], v[166:169], v[194:197], v[100:103]
	v_mfma_f32_16x16x32_bf16 v[96:99], v[174:177], v[194:197], v[96:99]
	v_mfma_f32_16x16x32_bf16 v[84:87], v[166:169], v[202:205], v[84:87]
	v_mfma_f32_16x16x32_bf16 v[80:83], v[174:177], v[202:205], v[80:83]
	v_mfma_f32_16x16x32_bf16 v[68:71], v[166:169], v[210:213], v[68:71]
	v_mfma_f32_16x16x32_bf16 v[64:67], v[174:177], v[210:213], v[64:67]
	s_setprio 0
	s_barrier
; #define PG8_STAGE(bufoff, gbase, voff) do { _Pragma("unroll") for (int _i = 0; _i < 2; ++_i) \
;         __builtin_amdgcn_global_load_lds((const unsigned*)((const char*)(gbase) + (voff)[_i]), (PG8_LAS unsigned*)(lds + (bufoff) + ldsw + _i * 8192), 16, 0, 0); } while (0)
; #define PG8_LDA(dst, b, h) do { _Pragma("unroll") for (int m = 0; m < 4; ++m) _Pragma("unroll") for (int k = 0; k < 2; ++k) dst[m][k] = *(const PG8_LAS bf16x8*)(lds + PG8_SA(b, h) + aoff + m * 2048 + k * 1024); } while (0)
; #define PG8_MMA(ai, bj, At, Bt) do { __builtin_amdgcn_s_setprio(1); _Pragma("unroll") for (int m = 0; m < 4; ++m) _Pragma("unroll") for (int n = 0; n < 2; ++n) _Pragma("unroll") for (int k = 0; k < 2; ++k) \
;         acc[ai][bj][m][n] = __builtin_amdgcn_mfma_f32_16x16x32_bf16(Bt[n][k], At[m][k], acc[ai][bj][m][n], 0, 0, 0); __builtin_amdgcn_s_setprio(0); } while (0)
; #define PG8_WAIT_V(n) asm volatile("s_waitcnt vmcnt(" #n ")" ::: "memory")
; #define PG8_WAIT_L(n) asm volatile("s_waitcnt lgkmcnt(" #n ")" ::: "memory")
; #define PG8_BAR __builtin_amdgcn_s_barrier()
; #define PG8_SCHED __builtin_amdgcn_sched_barrier(0)
; template <class Epi, class Sched, bool ALIGN_EPI = false, bool SP2 = false>
; __device__ __forceinline__ void gemm_phase(PG8_LAS unsigned char* lds, const Gemm g, const Sched& S, const Epi& E, const int tid_in) {
;     ...
;             PG8_LDA(At, 1, 1); PG8_STAGE(PG8_SB(1, 0), b3, voffB); PG8_STAGE(PG8_SB(1, 1), b3 + hstepB, voffB); PG8_STAGE(PG8_SA(1, 0), a3, voffA);
;             PG8_WAIT_V(8); PG8_WAIT_L(0); PG8_BAR; PG8_MMA(1, 0, At, B0); PG8_MMA(1, 1, At, B1); PG8_BAR; PG8_SCHED;
;     ...
;         if constexpr (ALIGN_EPI) { if (wr == 0) PG8_BAR; }
	s_add_i32 s12, s68, s53
	v_lshl_add_u64 v[190:191], v[190:191], 0, s[26:27]
	s_mov_b32 m0, s12
	ds_read_b128 v[178:181], v149 offset:49152
	ds_read_b128 v[182:185], v149 offset:50176
	ds_read_b128 v[186:189], v149 offset:51200
	ds_read_b128 v[194:197], v149 offset:52224
	ds_read_b128 v[198:201], v149 offset:53248
	ds_read_b128 v[202:205], v149 offset:54272
	ds_read_b128 v[206:209], v149 offset:55296
	ds_read_b128 v[210:213], v149 offset:56320
	global_load_lds_dwordx4 v[190:191], off
	s_add_i32 m0, s12, 0x2000
	s_add_u32 s12, s48, 0x80080
	v_lshl_add_u64 v[190:191], v[214:215], 0, s[26:27]
	s_addc_u32 s13, s49, 0
	s_add_i32 s48, s69, s53
	global_load_lds_dwordx4 v[190:191], off
	v_lshl_add_u64 v[190:191], s[12:13], 0, v[192:193]
	s_mov_b32 m0, s48
	s_nop 0
	global_load_lds_dwordx4 v[190:191], off
	v_lshl_add_u64 v[190:191], s[12:13], 0, v[132:133]
	s_add_i32 m0, s48, 0x2000
	s_nop 0
	global_load_lds_dwordx4 v[190:191], off
	v_lshl_add_u64 v[190:191], v[216:217], 0, s[26:27]
	s_mov_b32 m0, s58
	s_nop 0
	global_load_lds_dwordx4 v[190:191], off
	v_lshl_add_u64 v[190:191], v[218:219], 0, s[26:27]
	s_mov_b32 m0, s59
	s_nop 0
	global_load_lds_dwordx4 v[190:191], off
	s_waitcnt vmcnt(8)
	s_waitcnt lgkmcnt(0)
	s_barrier
	s_setprio 1
	s_waitcnt lgkmcnt(0)
	v_mfma_f32_16x16x32_bf16 v[60:63], v[142:145], v[178:181], v[60:63]
	v_mfma_f32_16x16x32_bf16 v[56:59], v[154:157], v[178:181], v[56:59]
	v_mfma_f32_16x16x32_bf16 v[48:51], v[142:145], v[186:189], v[48:51]
	v_mfma_f32_16x16x32_bf16 v[40:43], v[154:157], v[186:189], v[40:43]
	v_mfma_f32_16x16x32_bf16 v[32:35], v[142:145], v[198:201], v[32:35]
	v_mfma_f32_16x16x32_bf16 v[24:27], v[154:157], v[198:201], v[24:27]
	v_mfma_f32_16x16x32_bf16 v[16:19], v[142:145], v[206:209], v[16:19]
	v_mfma_f32_16x16x32_bf16 v[8:11], v[154:157], v[206:209], v[8:11]
	v_mfma_f32_16x16x32_bf16 v[60:63], v[150:153], v[182:185], v[60:63]
	v_mfma_f32_16x16x32_bf16 v[56:59], v[158:161], v[182:185], v[56:59]
	v_mfma_f32_16x16x32_bf16 v[48:51], v[150:153], v[194:197], v[48:51]
	v_mfma_f32_16x16x32_bf16 v[40:43], v[158:161], v[194:197], v[40:43]
	v_mfma_f32_16x16x32_bf16 v[32:35], v[150:153], v[202:205], v[32:35]
	v_mfma_f32_16x16x32_bf16 v[24:27], v[158:161], v[202:205], v[24:27]
	v_mfma_f32_16x16x32_bf16 v[16:19], v[150:153], v[210:213], v[16:19]
	v_mfma_f32_16x16x32_bf16 v[8:11], v[158:161], v[210:213], v[8:11]
	v_mfma_f32_16x16x32_bf16 v[52:55], v[162:165], v[178:181], v[52:55]
	v_mfma_f32_16x16x32_bf16 v[44:47], v[170:173], v[178:181], v[44:47]
	v_mfma_f32_16x16x32_bf16 v[36:39], v[162:165], v[186:189], v[36:39]
	v_mfma_f32_16x16x32_bf16 v[28:31], v[170:173], v[186:189], v[28:31]
	v_mfma_f32_16x16x32_bf16 v[20:23], v[162:165], v[198:201], v[20:23]
	v_mfma_f32_16x16x32_bf16 v[12:15], v[170:173], v[198:201], v[12:15]
	v_mfma_f32_16x16x32_bf16 v[4:7], v[162:165], v[206:209], v[4:7]
	v_mfma_f32_16x16x32_bf16 v[0:3], v[170:173], v[206:209], v[0:3]
	v_mfma_f32_16x16x32_bf16 v[52:55], v[166:169], v[182:185], v[52:55]
	v_mfma_f32_16x16x32_bf16 v[44:47], v[174:177], v[182:185], v[44:47]
	v_mfma_f32_16x16x32_bf16 v[36:39], v[166:169], v[194:197], v[36:39]
	v_mfma_f32_16x16x32_bf16 v[28:31], v[174:177], v[194:197], v[28:31]
	v_mfma_f32_16x16x32_bf16 v[20:23], v[166:169], v[202:205], v[20:23]
	v_mfma_f32_16x16x32_bf16 v[12:15], v[174:177], v[202:205], v[12:15]
	v_mfma_f32_16x16x32_bf16 v[4:7], v[166:169], v[210:213], v[4:7]
	v_mfma_f32_16x16x32_bf16 v[0:3], v[174:177], v[210:213], v[0:3]
	s_setprio 0
	s_barrier
	s_add_i32 s67, s67, 2
	s_add_u32 s46, s46, 0x100
	s_addc_u32 s47, s47, 0
	s_add_u32 s65, s65, 0x100
	s_addc_u32 s66, s66, 0
	s_cmp_gt_u32 s67, 29
	s_cbranch_scc0 .LBB0_289
	s_and_b64 vcc, exec, s[36:37]
	s_cbranch_vccz .LBB0_292
	s_barrier

; #define PG8_STAGE(bufoff, gbase, voff) do { _Pragma("unroll") for (int _i = 0; _i < 2; ++_i) \
;         __builtin_amdgcn_global_load_lds((const unsigned*)((const char*)(gbase) + (voff)[_i]), (PG8_LAS unsigned*)(lds + (bufoff) + ldsw + _i * 8192), 16, 0, 0); } while (0)
; #define PG8_LDA(dst, b, h) do { _Pragma("unroll") for (int m = 0; m < 4; ++m) _Pragma("unroll") for (int k = 0; k < 2; ++k) dst[m][k] = *(const PG8_LAS bf16x8*)(lds + PG8_SA(b, h) + aoff + m * 2048 + k * 1024); } while (0)
; #define PG8_LDB(dst, b, h) do { _Pragma("unroll") for (int n = 0; n < 2; ++n) _Pragma("unroll") for (int k = 0; k < 2; ++k) dst[n][k] = *(const PG8_LAS bf16x8*)(lds + PG8_SB(b, h) + boff + n * 2048 + k * 1024); } while (0)
; template <class Epi, class Sched, bool ALIGN_EPI = false, bool SP2 = false>
; __device__ __forceinline__ void gemm_phase(PG8_LAS unsigned char* lds, const Gemm g, const Sched& S, const Epi& E, const int tid_in) {
;     ...
;         const bool has_next = S.next(ui + 1, nxt);
;         const char* nA = has_next ? (const char*)g.A + (size_t)nxt.pm * tstepA : cA; const char* nB = has_next ? (const char*)g.Bt + (size_t)nxt.pn * tstepB : cB;
;         for (int t = 0; t < nt; t += 2) {
;             const bool last = (t == nt - 2);
;             const char* a1 = cA + (size_t)(t + 1) * kstep;
;             const char* a2 = last ? nA : cA + (size_t)(t + 2) * kstep; const char* b2 = last ? nB : cB + (size_t)(t + 2) * kstep;
;             const char* a3 = a2 + kstep; const char* b3 = b2 + kstep;
;             if (last && has_next) S.a_ready(nxt);
;             if constexpr (SP2) {
;             PG8_LDB(B0, 0, 0); PG8_LDB(B1, 0, 1); PG8_SCHED; PG8_LDA(At, 0, 0); PG8_STAGE(PG8_SA(1, 1), a1 + hstepA, voffA);
;             PG8_WAIT_V(8); PG8_WAIT_L(0); PG8_BAR; PG8_MMA(0, 0, At, B0); PG8_MMA(0, 1, At, B1); PG8_BAR; PG8_SCHED;
;             PG8_LDA(At, 0, 1); PG8_STAGE(PG8_SB(0, 0), b2, voffB); PG8_STAGE(PG8_SB(0, 1), b2 + hstepB, voffB); PG8_STAGE(PG8_SA(0, 0), a2, voffA);
;             PG8_WAIT_V(8); PG8_WAIT_L(0); PG8_BAR; PG8_MMA(1, 0, At, B0); PG8_MMA(1, 1, At, B1); PG8_BAR; PG8_SCHED;
;     ...
;         for (int a = 0; a < 2; ++a)
; #pragma unroll
;             for (int b = 0; b < 2; ++b)
; #pragma unroll
;                 for (int m = 0; m < 4; ++m)
; #pragma unroll
;                     for (int n = 0; n < 2; ++n) acc[a][b][m][n] = (f32x4){0.f, 0.f, 0.f, 0.f};
.LBB0_426:
	s_ashr_i32 s47, s46, 31
	s_lshl_b64 s[12:13], s[46:47], 19
	s_add_u32 s48, s10, s12
	s_addc_u32 s49, s11, s13
	s_and_b64 s[12:13], s[34:35], exec
	s_cselect_b32 s1, s49, s53
	s_cselect_b32 s37, s48, s52
	s_ashr_i32 s45, s44, 31
	s_lshl_b64 s[12:13], s[44:45], 18
	s_add_u32 s50, s18, s12
	s_addc_u32 s51, s58, s13
	s_and_b64 s[12:13], s[34:35], exec
	s_cselect_b32 s45, s51, s55
	s_cselect_b32 s47, s50, s54
	s_add_u32 s52, s52, 0x40080
	s_addc_u32 s53, s53, 0
	s_add_u32 s67, s54, 0x100
	s_addc_u32 s68, s55, 0
	s_mov_b32 s69, -2
	s_add_u32 s12, s52, 0xfffc0080
	s_addc_u32 s13, s53, -1
	s_add_i32 s70, 0, 0x10000
	s_cmp_eq_u32 s69, 4
	s_cselect_b32 s57, s1, s13
	s_cselect_b32 s56, s37, s12
	s_cselect_b32 s55, s45, s68
	s_cselect_b32 s54, s47, s67
	s_add_i32 s71, 0, 0x14000
	v_add_u32_e32 v140, s70, v242
	v_add_u32_e32 v156, s71, v242
	ds_read_b128 v[128:131], v140
	ds_read_b128 v[132:135], v140 offset:1024
	ds_read_b128 v[136:139], v140 offset:2048
	ds_read_b128 v[140:143], v140 offset:3072
	ds_read_b128 v[144:147], v156
	ds_read_b128 v[148:151], v156 offset:1024
	ds_read_b128 v[152:155], v156 offset:2048
	ds_read_b128 v[156:159], v156 offset:3072
	v_lshl_add_u64 v[194:195], s[52:53], 0, v[206:207]
	s_add_i32 m0, s60, 0xc000
	ds_read_b128 v[160:163], v244
	ds_read_b128 v[164:167], v244 offset:1024
	ds_read_b128 v[168:171], v244 offset:2048
	ds_read_b128 v[172:175], v244 offset:3072
	ds_read_b128 v[176:179], v244 offset:4096
	ds_read_b128 v[180:183], v244 offset:5120
	ds_read_b128 v[184:187], v244 offset:6144
	ds_read_b128 v[188:191], v244 offset:7168
	global_load_lds_dwordx4 v[194:195], off
	v_lshl_add_u64 v[194:195], s[52:53], 0, v[208:209]
	s_add_i32 m0, s60, 0xe000
	s_nop 0
	global_load_lds_dwordx4 v[194:195], off
	s_waitcnt vmcnt(8)
	s_waitcnt lgkmcnt(0)
	s_barrier
	s_setprio 1
	s_waitcnt lgkmcnt(0)
	v_mfma_f32_16x16x32_bf16 v[124:127], v[128:131], v[160:163], 0
	v_mfma_f32_16x16x32_bf16 v[120:123], v[136:139], v[160:163], 0
	v_mfma_f32_16x16x32_bf16 v[108:111], v[128:131], v[168:171], 0
	v_mfma_f32_16x16x32_bf16 v[104:107], v[136:139], v[168:171], 0
	v_mfma_f32_16x16x32_bf16 v[92:95], v[128:131], v[176:179], 0
	v_mfma_f32_16x16x32_bf16 v[88:91], v[136:139], v[176:179], 0
	v_mfma_f32_16x16x32_bf16 v[76:79], v[128:131], v[184:187], 0
	v_mfma_f32_16x16x32_bf16 v[72:75], v[136:139], v[184:187], 0
	v_mfma_f32_16x16x32_bf16 v[124:127], v[132:135], v[164:167], v[124:127]
	v_mfma_f32_16x16x32_bf16 v[120:123], v[140:143], v[164:167], v[120:123]
	v_mfma_f32_16x16x32_bf16 v[108:111], v[132:135], v[172:175], v[108:111]
	v_mfma_f32_16x16x32_bf16 v[104:107], v[140:143], v[172:175], v[104:107]
	v_mfma_f32_16x16x32_bf16 v[92:95], v[132:135], v[180:183], v[92:95]
	v_mfma_f32_16x16x32_bf16 v[88:91], v[140:143], v[180:183], v[88:91]
	v_mfma_f32_16x16x32_bf16 v[76:79], v[132:135], v[188:191], v[76:79]
	v_mfma_f32_16x16x32_bf16 v[72:75], v[140:143], v[188:191], v[72:75]
	s_setprio 0
	s_setprio 1
	v_mfma_f32_16x16x32_bf16 v[116:119], v[144:147], v[160:163], 0
	v_mfma_f32_16x16x32_bf16 v[112:115], v[152:155], v[160:163], 0
	v_mfma_f32_16x16x32_bf16 v[100:103], v[144:147], v[168:171], 0
	v_mfma_f32_16x16x32_bf16 v[96:99], v[152:155], v[168:171], 0
	v_mfma_f32_16x16x32_bf16 v[84:87], v[144:147], v[176:179], 0
	v_mfma_f32_16x16x32_bf16 v[80:83], v[152:155], v[176:179], 0
	v_mfma_f32_16x16x32_bf16 v[68:71], v[144:147], v[184:187], 0
	v_mfma_f32_16x16x32_bf16 v[64:67], v[152:155], v[184:187], 0
	v_mfma_f32_16x16x32_bf16 v[116:119], v[148:151], v[164:167], v[116:119]
	v_mfma_f32_16x16x32_bf16 v[112:115], v[156:159], v[164:167], v[112:115]
	v_mfma_f32_16x16x32_bf16 v[100:103], v[148:151], v[172:175], v[100:103]
	v_mfma_f32_16x16x32_bf16 v[96:99], v[156:159], v[172:175], v[96:99]
	v_mfma_f32_16x16x32_bf16 v[84:87], v[148:151], v[180:183], v[84:87]
	v_mfma_f32_16x16x32_bf16 v[80:83], v[156:159], v[180:183], v[80:83]
	v_mfma_f32_16x16x32_bf16 v[68:71], v[148:151], v[188:191], v[68:71]
	v_mfma_f32_16x16x32_bf16 v[64:67], v[156:159], v[188:191], v[64:67]
	s_setprio 0
	s_barrier
	s_add_i32 s12, s70, s59
	v_lshl_add_u64 v[194:195], s[54:55], 0, v[200:201]
	s_mov_b32 m0, s12
	ds_read_b128 v[160:163], v244 offset:16384
	ds_read_b128 v[164:167], v244 offset:17408
	ds_read_b128 v[168:171], v244 offset:18432
	ds_read_b128 v[172:175], v244 offset:19456
	ds_read_b128 v[176:179], v244 offset:20480
	ds_read_b128 v[180:183], v244 offset:21504
	ds_read_b128 v[184:187], v244 offset:22528
	ds_read_b128 v[188:191], v244 offset:23552
	global_load_lds_dwordx4 v[194:195], off
	s_add_i32 m0, s12, 0x2000
	s_add_u32 s12, s54, 0x20000
	v_lshl_add_u64 v[196:197], s[54:55], 0, v[204:205]
	s_addc_u32 s13, s55, 0
	s_add_i32 s70, s71, s59
	global_load_lds_dwordx4 v[196:197], off
	v_lshl_add_u64 v[210:211], s[12:13], 0, v[200:201]
	s_mov_b32 m0, s70
	v_lshl_add_u64 v[212:213], s[56:57], 0, v[202:203]
	global_load_lds_dwordx4 v[210:211], off
	v_lshl_add_u64 v[210:211], s[12:13], 0, v[204:205]
	s_add_i32 m0, s70, 0x2000
	s_nop 0
	global_load_lds_dwordx4 v[210:211], off
	v_lshl_add_u64 v[210:211], s[56:57], 0, v[198:199]
	s_mov_b32 m0, s60
	s_nop 0
	global_load_lds_dwordx4 v[210:211], off
	s_mov_b32 m0, s61
	s_nop 0
	global_load_lds_dwordx4 v[212:213], off
	s_waitcnt vmcnt(8)
	s_waitcnt lgkmcnt(0)
	s_barrier
; #define PG8_STAGE(bufoff, gbase, voff) do { _Pragma("unroll") for (int _i = 0; _i < 2; ++_i) \
;         __builtin_amdgcn_global_load_lds((const unsigned*)((const char*)(gbase) + (voff)[_i]), (PG8_LAS unsigned*)(lds + (bufoff) + ldsw + _i * 8192), 16, 0, 0); } while (0)
; #define PG8_LDA(dst, b, h) do { _Pragma("unroll") for (int m = 0; m < 4; ++m) _Pragma("unroll") for (int k = 0; k < 2; ++k) dst[m][k] = *(const PG8_LAS bf16x8*)(lds + PG8_SA(b, h) + aoff + m * 2048 + k * 1024); } while (0)
; #define PG8_LDB(dst, b, h) do { _Pragma("unroll") for (int n = 0; n < 2; ++n) _Pragma("unroll") for (int k = 0; k < 2; ++k) dst[n][k] = *(const PG8_LAS bf16x8*)(lds + PG8_SB(b, h) + boff + n * 2048 + k * 1024); } while (0)
; #define PG8_MMA(ai, bj, At, Bt) do { __builtin_amdgcn_s_setprio(1); _Pragma("unroll") for (int m = 0; m < 4; ++m) _Pragma("unroll") for (int n = 0; n < 2; ++n) _Pragma("unroll") for (int k = 0; k < 2; ++k) \
;         acc[ai][bj][m][n] = __builtin_amdgcn_mfma_f32_16x16x32_bf16(Bt[n][k], At[m][k], acc[ai][bj][m][n], 0, 0, 0); __builtin_amdgcn_s_setprio(0); } while (0)
; #define PG8_WAIT_V(n) asm volatile("s_waitcnt vmcnt(" #n ")" ::: "memory")
; #define PG8_WAIT_L(n) asm volatile("s_waitcnt lgkmcnt(" #n ")" ::: "memory")
; #define PG8_BAR __builtin_amdgcn_s_barrier()
; #define PG8_SCHED __builtin_amdgcn_sched_barrier(0)
; template <class Epi, class Sched, bool ALIGN_EPI = false, bool SP2 = false>
; __device__ __forceinline__ void gemm_phase(PG8_LAS unsigned char* lds, const Gemm g, const Sched& S, const Epi& E, const int tid_in) {
;     ...
;             PG8_WAIT_V(8); PG8_WAIT_L(0); PG8_BAR; PG8_MMA(1, 0, At, B0); PG8_MMA(1, 1, At, B1); PG8_BAR; PG8_SCHED;
;             PG8_LDB(B0, 1, 0); PG8_LDB(B1, 1, 1); PG8_SCHED; PG8_LDA(At, 1, 0); PG8_STAGE(PG8_SA(0, 1), a2 + hstepA, voffA);
;             PG8_WAIT_V(8); PG8_WAIT_L(0); PG8_BAR; PG8_MMA(0, 0, At, B0); PG8_MMA(0, 1, At, B1); PG8_BAR; PG8_SCHED;
	s_setprio 1
	s_waitcnt lgkmcnt(0)
	v_mfma_f32_16x16x32_bf16 v[60:63], v[128:131], v[160:163], 0
	v_mfma_f32_16x16x32_bf16 v[56:59], v[136:139], v[160:163], 0
	v_mfma_f32_16x16x32_bf16 v[44:47], v[128:131], v[168:171], 0
	v_mfma_f32_16x16x32_bf16 v[40:43], v[136:139], v[168:171], 0
	v_mfma_f32_16x16x32_bf16 v[28:31], v[128:131], v[176:179], 0
	v_mfma_f32_16x16x32_bf16 v[24:27], v[136:139], v[176:179], 0
	v_mfma_f32_16x16x32_bf16 v[12:15], v[128:131], v[184:187], 0
	v_mfma_f32_16x16x32_bf16 v[8:11], v[136:139], v[184:187], 0
	v_mfma_f32_16x16x32_bf16 v[60:63], v[132:135], v[164:167], v[60:63]
	v_mfma_f32_16x16x32_bf16 v[56:59], v[140:143], v[164:167], v[56:59]
	v_mfma_f32_16x16x32_bf16 v[44:47], v[132:135], v[172:175], v[44:47]
	v_mfma_f32_16x16x32_bf16 v[40:43], v[140:143], v[172:175], v[40:43]
	v_mfma_f32_16x16x32_bf16 v[28:31], v[132:135], v[180:183], v[28:31]
	v_mfma_f32_16x16x32_bf16 v[24:27], v[140:143], v[180:183], v[24:27]
	v_mfma_f32_16x16x32_bf16 v[12:15], v[132:135], v[188:191], v[12:15]
	v_mfma_f32_16x16x32_bf16 v[8:11], v[140:143], v[188:191], v[8:11]
	s_setprio 0
	s_setprio 1
	v_mfma_f32_16x16x32_bf16 v[52:55], v[144:147], v[160:163], 0
	v_mfma_f32_16x16x32_bf16 v[48:51], v[152:155], v[160:163], 0
	v_mfma_f32_16x16x32_bf16 v[36:39], v[144:147], v[168:171], 0
	v_mfma_f32_16x16x32_bf16 v[32:35], v[152:155], v[168:171], 0
	v_mfma_f32_16x16x32_bf16 v[20:23], v[144:147], v[176:179], 0
	v_mfma_f32_16x16x32_bf16 v[16:19], v[152:155], v[176:179], 0
	v_mfma_f32_16x16x32_bf16 v[4:7], v[144:147], v[184:187], 0
	v_mfma_f32_16x16x32_bf16 v[0:3], v[152:155], v[184:187], 0
	v_mfma_f32_16x16x32_bf16 v[52:55], v[148:151], v[164:167], v[52:55]
	v_mfma_f32_16x16x32_bf16 v[48:51], v[156:159], v[164:167], v[48:51]
	v_mfma_f32_16x16x32_bf16 v[36:39], v[148:151], v[172:175], v[36:39]
	v_mfma_f32_16x16x32_bf16 v[32:35], v[156:159], v[172:175], v[32:35]
	v_mfma_f32_16x16x32_bf16 v[20:23], v[148:151], v[180:183], v[20:23]
	v_mfma_f32_16x16x32_bf16 v[16:19], v[156:159], v[180:183], v[16:19]
	v_mfma_f32_16x16x32_bf16 v[4:7], v[148:151], v[188:191], v[4:7]
	v_mfma_f32_16x16x32_bf16 v[0:3], v[156:159], v[188:191], v[0:3]
	s_setprio 0
	s_barrier
	s_add_i32 s70, 0, 0x18000
	s_add_i32 s71, 0, 0x1c000
	v_add_u32_e32 v140, s70, v242
	v_add_u32_e32 v156, s71, v242
	ds_read_b128 v[128:131], v140
	ds_read_b128 v[132:135], v140 offset:1024
	ds_read_b128 v[136:139], v140 offset:2048
	ds_read_b128 v[140:143], v140 offset:3072
	ds_read_b128 v[144:147], v156
	ds_read_b128 v[148:151], v156 offset:1024
	ds_read_b128 v[152:155], v156 offset:2048
	ds_read_b128 v[156:159], v156 offset:3072
	s_add_u32 s12, s56, 0x40000
	s_addc_u32 s13, s57, 0
	s_mov_b32 m0, s62
	v_lshl_add_u64 v[214:215], s[12:13], 0, v[198:199]
	ds_read_b128 v[160:163], v244 offset:32768
	ds_read_b128 v[164:167], v244 offset:33792
	ds_read_b128 v[168:171], v244 offset:34816
	ds_read_b128 v[172:175], v244 offset:35840
	ds_read_b128 v[176:179], v244 offset:36864
	ds_read_b128 v[180:183], v244 offset:37888
	ds_read_b128 v[184:187], v244 offset:38912
	ds_read_b128 v[188:191], v244 offset:39936
	global_load_lds_dwordx4 v[214:215], off
	v_lshl_add_u64 v[214:215], s[12:13], 0, v[202:203]
	s_mov_b32 m0, s63
	s_nop 0
	global_load_lds_dwordx4 v[214:215], off
	s_waitcnt vmcnt(8)
	s_waitcnt lgkmcnt(0)
	s_barrier
	s_setprio 1
	s_waitcnt lgkmcnt(0)
	v_mfma_f32_16x16x32_bf16 v[124:127], v[128:131], v[160:163], v[124:127]
	v_mfma_f32_16x16x32_bf16 v[120:123], v[136:139], v[160:163], v[120:123]
	v_mfma_f32_16x16x32_bf16 v[108:111], v[128:131], v[168:171], v[108:111]
	v_mfma_f32_16x16x32_bf16 v[104:107], v[136:139], v[168:171], v[104:107]
	v_mfma_f32_16x16x32_bf16 v[92:95], v[128:131], v[176:179], v[92:95]
	v_mfma_f32_16x16x32_bf16 v[88:91], v[136:139], v[176:179], v[88:91]
	v_mfma_f32_16x16x32_bf16 v[76:79], v[128:131], v[184:187], v[76:79]
	v_mfma_f32_16x16x32_bf16 v[72:75], v[136:139], v[184:187], v[72:75]
	v_mfma_f32_16x16x32_bf16 v[124:127], v[132:135], v[164:167], v[124:127]
	v_mfma_f32_16x16x32_bf16 v[120:123], v[140:143], v[164:167], v[120:123]
	v_mfma_f32_16x16x32_bf16 v[108:111], v[132:135], v[172:175], v[108:111]
	v_mfma_f32_16x16x32_bf16 v[104:107], v[140:143], v[172:175], v[104:107]
	v_mfma_f32_16x16x32_bf16 v[92:95], v[132:135], v[180:183], v[92:95]
	v_mfma_f32_16x16x32_bf16 v[88:91], v[140:143], v[180:183], v[88:91]
	v_mfma_f32_16x16x32_bf16 v[76:79], v[132:135], v[188:191], v[76:79]
	v_mfma_f32_16x16x32_bf16 v[72:75], v[140:143], v[188:191], v[72:75]
	s_setprio 0
	s_setprio 1
	v_mfma_f32_16x16x32_bf16 v[116:119], v[144:147], v[160:163], v[116:119]
	v_mfma_f32_16x16x32_bf16 v[112:115], v[152:155], v[160:163], v[112:115]
	v_mfma_f32_16x16x32_bf16 v[100:103], v[144:147], v[168:171], v[100:103]
	v_mfma_f32_16x16x32_bf16 v[96:99], v[152:155], v[168:171], v[96:99]
	v_mfma_f32_16x16x32_bf16 v[84:87], v[144:147], v[176:179], v[84:87]
	v_mfma_f32_16x16x32_bf16 v[80:83], v[152:155], v[176:179], v[80:83]
	v_mfma_f32_16x16x32_bf16 v[68:71], v[144:147], v[184:187], v[68:71]
	v_mfma_f32_16x16x32_bf16 v[64:67], v[152:155], v[184:187], v[64:67]
	v_mfma_f32_16x16x32_bf16 v[116:119], v[148:151], v[164:167], v[116:119]
	v_mfma_f32_16x16x32_bf16 v[112:115], v[156:159], v[164:167], v[112:115]
	v_mfma_f32_16x16x32_bf16 v[100:103], v[148:151], v[172:175], v[100:103]
	v_mfma_f32_16x16x32_bf16 v[96:99], v[156:159], v[172:175], v[96:99]
	v_mfma_f32_16x16x32_bf16 v[84:87], v[148:151], v[180:183], v[84:87]
	v_mfma_f32_16x16x32_bf16 v[80:83], v[156:159], v[180:183], v[80:83]
	v_mfma_f32_16x16x32_bf16 v[68:71], v[148:151], v[188:191], v[68:71]
	v_mfma_f32_16x16x32_bf16 v[64:67], v[156:159], v[188:191], v[64:67]
	s_setprio 0
	s_barrier
; #define PG8_STAGE(bufoff, gbase, voff) do { _Pragma("unroll") for (int _i = 0; _i < 2; ++_i) \
;         __builtin_amdgcn_global_load_lds((const unsigned*)((const char*)(gbase) + (voff)[_i]), (PG8_LAS unsigned*)(lds + (bufoff) + ldsw + _i * 8192), 16, 0, 0); } while (0)
; #define PG8_LDA(dst, b, h) do { _Pragma("unroll") for (int m = 0; m < 4; ++m) _Pragma("unroll") for (int k = 0; k < 2; ++k) dst[m][k] = *(const PG8_LAS bf16x8*)(lds + PG8_SA(b, h) + aoff + m * 2048 + k * 1024); } while (0)
; #define PG8_WAIT_V(n) asm volatile("s_waitcnt vmcnt(" #n ")" ::: "memory")
; #define PG8_WAIT_L(n) asm volatile("s_waitcnt lgkmcnt(" #n ")" ::: "memory")
; #define PG8_BAR __builtin_amdgcn_s_barrier()
; template <class Epi, class Sched, bool ALIGN_EPI = false, bool SP2 = false>
; __device__ __forceinline__ void gemm_phase(PG8_LAS unsigned char* lds, const Gemm g, const Sched& S, const Epi& E, const int tid_in) {
;     ...
;         for (int t = 0; t < nt; t += 2) {
;             const bool last = (t == nt - 2);
;             const char* a1 = cA + (size_t)(t + 1) * kstep;
;             const char* a2 = last ? nA : cA + (size_t)(t + 2) * kstep; const char* b2 = last ? nB : cB + (size_t)(t + 2) * kstep;
;             const char* a3 = a2 + kstep; const char* b3 = b2 + kstep;
;             if (last && has_next) S.a_ready(nxt);
;             if constexpr (SP2) {
;             PG8_LDB(B0, 0, 0); PG8_LDB(B1, 0, 1); PG8_SCHED; PG8_LDA(At, 0, 0); PG8_STAGE(PG8_SA(1, 1), a1 + hstepA, voffA);
;             PG8_WAIT_V(8); PG8_WAIT_L(0); PG8_BAR; PG8_MMA(0, 0, At, B0); PG8_MMA(0, 1, At, B1); PG8_BAR; PG8_SCHED;
;             PG8_LDA(At, 0, 1); PG8_STAGE(PG8_SB(0, 0), b2, voffB); PG8_STAGE(PG8_SB(0, 1), b2 + hstepB, voffB); PG8_STAGE(PG8_SA(0, 0), a2, voffA);
;             PG8_WAIT_V(8); PG8_WAIT_L(0); PG8_BAR; PG8_MMA(1, 0, At, B0); PG8_MMA(1, 1, At, B1); PG8_BAR; PG8_SCHED;
;             PG8_LDB(B0, 1, 0); PG8_LDB(B1, 1, 1); PG8_SCHED; PG8_LDA(At, 1, 0); PG8_STAGE(PG8_SA(0, 1), a2 + hstepA, voffA);
;             PG8_WAIT_V(8); PG8_WAIT_L(0); PG8_BAR; PG8_MMA(0, 0, At, B0); PG8_MMA(0, 1, At, B1); PG8_BAR; PG8_SCHED;
;             PG8_LDA(At, 1, 1); PG8_STAGE(PG8_SB(1, 0), b3, voffB); PG8_STAGE(PG8_SB(1, 1), b3 + hstepB, voffB); PG8_STAGE(PG8_SA(1, 0), a3, voffA);
;             PG8_WAIT_V(8); PG8_WAIT_L(0); PG8_BAR; PG8_MMA(1, 0, At, B0); PG8_MMA(1, 1, At, B1); PG8_BAR; PG8_SCHED;
	s_add_i32 s12, s70, s59
	v_lshl_add_u64 v[194:195], v[194:195], 0, s[26:27]
	s_mov_b32 m0, s12
	ds_read_b128 v[160:163], v244 offset:49152
	ds_read_b128 v[164:167], v244 offset:50176
	ds_read_b128 v[168:171], v244 offset:51200
	ds_read_b128 v[172:175], v244 offset:52224
	ds_read_b128 v[176:179], v244 offset:53248
	ds_read_b128 v[180:183], v244 offset:54272
	ds_read_b128 v[184:187], v244 offset:55296
	ds_read_b128 v[188:191], v244 offset:56320
	global_load_lds_dwordx4 v[194:195], off
	s_add_i32 m0, s12, 0x2000
	s_add_u32 s12, s54, 0x20080
	v_lshl_add_u64 v[194:195], v[196:197], 0, s[26:27]
	s_addc_u32 s13, s55, 0
	s_add_i32 s54, s71, s59
	global_load_lds_dwordx4 v[194:195], off
	v_lshl_add_u64 v[194:195], s[12:13], 0, v[200:201]
	s_mov_b32 m0, s54
	s_nop 0
	global_load_lds_dwordx4 v[194:195], off
	v_lshl_add_u64 v[194:195], s[12:13], 0, v[204:205]
	s_add_i32 m0, s54, 0x2000
	s_nop 0
	global_load_lds_dwordx4 v[194:195], off
	v_lshl_add_u64 v[194:195], v[210:211], 0, s[26:27]
	s_mov_b32 m0, s64
	s_nop 0
	global_load_lds_dwordx4 v[194:195], off
	v_lshl_add_u64 v[194:195], v[212:213], 0, s[26:27]
	s_mov_b32 m0, s65
	s_nop 0
	global_load_lds_dwordx4 v[194:195], off
	s_waitcnt vmcnt(8)
	s_waitcnt lgkmcnt(0)
	s_barrier
	s_setprio 1
	s_waitcnt lgkmcnt(0)
	v_mfma_f32_16x16x32_bf16 v[60:63], v[128:131], v[160:163], v[60:63]
	v_mfma_f32_16x16x32_bf16 v[56:59], v[136:139], v[160:163], v[56:59]
	v_mfma_f32_16x16x32_bf16 v[44:47], v[128:131], v[168:171], v[44:47]
	v_mfma_f32_16x16x32_bf16 v[40:43], v[136:139], v[168:171], v[40:43]
	v_mfma_f32_16x16x32_bf16 v[28:31], v[128:131], v[176:179], v[28:31]
	v_mfma_f32_16x16x32_bf16 v[24:27], v[136:139], v[176:179], v[24:27]
	v_mfma_f32_16x16x32_bf16 v[12:15], v[128:131], v[184:187], v[12:15]
	v_mfma_f32_16x16x32_bf16 v[8:11], v[136:139], v[184:187], v[8:11]
	v_mfma_f32_16x16x32_bf16 v[60:63], v[132:135], v[164:167], v[60:63]
	v_mfma_f32_16x16x32_bf16 v[56:59], v[140:143], v[164:167], v[56:59]
	v_mfma_f32_16x16x32_bf16 v[44:47], v[132:135], v[172:175], v[44:47]
	v_mfma_f32_16x16x32_bf16 v[40:43], v[140:143], v[172:175], v[40:43]
	v_mfma_f32_16x16x32_bf16 v[28:31], v[132:135], v[180:183], v[28:31]
	v_mfma_f32_16x16x32_bf16 v[24:27], v[140:143], v[180:183], v[24:27]
	v_mfma_f32_16x16x32_bf16 v[12:15], v[132:135], v[188:191], v[12:15]
	v_mfma_f32_16x16x32_bf16 v[8:11], v[140:143], v[188:191], v[8:11]
	s_setprio 0
	s_setprio 1
	v_mfma_f32_16x16x32_bf16 v[52:55], v[144:147], v[160:163], v[52:55]
	v_mfma_f32_16x16x32_bf16 v[48:51], v[152:155], v[160:163], v[48:51]
	v_mfma_f32_16x16x32_bf16 v[36:39], v[144:147], v[168:171], v[36:39]
	v_mfma_f32_16x16x32_bf16 v[32:35], v[152:155], v[168:171], v[32:35]
	v_mfma_f32_16x16x32_bf16 v[20:23], v[144:147], v[176:179], v[20:23]
	v_mfma_f32_16x16x32_bf16 v[16:19], v[152:155], v[176:179], v[16:19]
	v_mfma_f32_16x16x32_bf16 v[4:7], v[144:147], v[184:187], v[4:7]
	v_mfma_f32_16x16x32_bf16 v[0:3], v[152:155], v[184:187], v[0:3]
	v_mfma_f32_16x16x32_bf16 v[52:55], v[148:151], v[164:167], v[52:55]
	v_mfma_f32_16x16x32_bf16 v[48:51], v[156:159], v[164:167], v[48:51]
	v_mfma_f32_16x16x32_bf16 v[36:39], v[148:151], v[172:175], v[36:39]
	v_mfma_f32_16x16x32_bf16 v[32:35], v[156:159], v[172:175], v[32:35]
	v_mfma_f32_16x16x32_bf16 v[20:23], v[148:151], v[180:183], v[20:23]
	v_mfma_f32_16x16x32_bf16 v[16:19], v[156:159], v[180:183], v[16:19]
	v_mfma_f32_16x16x32_bf16 v[4:7], v[148:151], v[188:191], v[4:7]
	v_mfma_f32_16x16x32_bf16 v[0:3], v[156:159], v[188:191], v[0:3]
	s_setprio 0
	s_barrier
	s_add_i32 s69, s69, 2
	s_add_u32 s52, s52, 0x100
	s_addc_u32 s53, s53, 0
	s_add_u32 s67, s67, 0x100
	s_addc_u32 s68, s68, 0
	s_cmp_gt_u32 s69, 5
	.p2align 6
.LBB0_427:
	s_add_u32 s12, s52, 0xfffc0080
	s_addc_u32 s13, s53, -1
	s_add_i32 s70, 0, 0x10000
	s_cmp_eq_u32 s69, 4
	s_cselect_b32 s57, s1, s13
	s_cselect_b32 s56, s37, s12
	s_cselect_b32 s55, s45, s68
	s_cselect_b32 s54, s47, s67
	s_add_i32 s71, 0, 0x14000
	v_add_u32_e32 v140, s70, v242
	v_add_u32_e32 v156, s71, v242
	ds_read_b128 v[128:131], v140
	ds_read_b128 v[132:135], v140 offset:1024
	ds_read_b128 v[136:139], v140 offset:2048
	ds_read_b128 v[140:143], v140 offset:3072
	ds_read_b128 v[144:147], v156
	ds_read_b128 v[148:151], v156 offset:1024
	ds_read_b128 v[152:155], v156 offset:2048
	ds_read_b128 v[156:159], v156 offset:3072
	v_lshl_add_u64 v[194:195], s[52:53], 0, v[206:207]
	s_add_i32 m0, s60, 0xc000
	ds_read_b128 v[160:163], v244
	ds_read_b128 v[164:167], v244 offset:1024
	ds_read_b128 v[168:171], v244 offset:2048
	ds_read_b128 v[172:175], v244 offset:3072
	ds_read_b128 v[176:179], v244 offset:4096
	ds_read_b128 v[180:183], v244 offset:5120
	ds_read_b128 v[184:187], v244 offset:6144
	ds_read_b128 v[188:191], v244 offset:7168
	global_load_lds_dwordx4 v[194:195], off
	v_lshl_add_u64 v[194:195], s[52:53], 0, v[208:209]
	s_add_i32 m0, s60, 0xe000
	s_nop 0
	global_load_lds_dwordx4 v[194:195], off
	s_waitcnt vmcnt(8)
	s_waitcnt lgkmcnt(0)
	s_barrier
; #define PG8_STAGE(bufoff, gbase, voff) do { _Pragma("unroll") for (int _i = 0; _i < 2; ++_i) \
;         __builtin_amdgcn_global_load_lds((const unsigned*)((const char*)(gbase) + (voff)[_i]), (PG8_LAS unsigned*)(lds + (bufoff) + ldsw + _i * 8192), 16, 0, 0); } while (0)
; #define PG8_LDA(dst, b, h) do { _Pragma("unroll") for (int m = 0; m < 4; ++m) _Pragma("unroll") for (int k = 0; k < 2; ++k) dst[m][k] = *(const PG8_LAS bf16x8*)(lds + PG8_SA(b, h) + aoff + m * 2048 + k * 1024); } while (0)
; #define PG8_MMA(ai, bj, At, Bt) do { __builtin_amdgcn_s_setprio(1); _Pragma("unroll") for (int m = 0; m < 4; ++m) _Pragma("unroll") for (int n = 0; n < 2; ++n) _Pragma("unroll") for (int k = 0; k < 2; ++k) \
;         acc[ai][bj][m][n] = __builtin_amdgcn_mfma_f32_16x16x32_bf16(Bt[n][k], At[m][k], acc[ai][bj][m][n], 0, 0, 0); __builtin_amdgcn_s_setprio(0); } while (0)
; #define PG8_WAIT_V(n) asm volatile("s_waitcnt vmcnt(" #n ")" ::: "memory")
; #define PG8_WAIT_L(n) asm volatile("s_waitcnt lgkmcnt(" #n ")" ::: "memory")
; #define PG8_BAR __builtin_amdgcn_s_barrier()
; #define PG8_SCHED __builtin_amdgcn_sched_barrier(0)
; template <class Epi, class Sched, bool ALIGN_EPI = false, bool SP2 = false>
; __device__ __forceinline__ void gemm_phase(PG8_LAS unsigned char* lds, const Gemm g, const Sched& S, const Epi& E, const int tid_in) {
;     ...
;             PG8_WAIT_V(8); PG8_WAIT_L(0); PG8_BAR; PG8_MMA(0, 0, At, B0); PG8_MMA(0, 1, At, B1); PG8_BAR; PG8_SCHED;
;             PG8_LDA(At, 0, 1); PG8_STAGE(PG8_SB(0, 0), b2, voffB); PG8_STAGE(PG8_SB(0, 1), b2 + hstepB, voffB); PG8_STAGE(PG8_SA(0, 0), a2, voffA);
;             PG8_WAIT_V(8); PG8_WAIT_L(0); PG8_BAR; PG8_MMA(1, 0, At, B0); PG8_MMA(1, 1, At, B1); PG8_BAR; PG8_SCHED;
	s_setprio 1
	s_waitcnt lgkmcnt(0)
	v_mfma_f32_16x16x32_bf16 v[124:127], v[128:131], v[160:163], v[124:127]
	v_mfma_f32_16x16x32_bf16 v[120:123], v[136:139], v[160:163], v[120:123]
	v_mfma_f32_16x16x32_bf16 v[108:111], v[128:131], v[168:171], v[108:111]
	v_mfma_f32_16x16x32_bf16 v[104:107], v[136:139], v[168:171], v[104:107]
	v_mfma_f32_16x16x32_bf16 v[92:95], v[128:131], v[176:179], v[92:95]
	v_mfma_f32_16x16x32_bf16 v[88:91], v[136:139], v[176:179], v[88:91]
	v_mfma_f32_16x16x32_bf16 v[76:79], v[128:131], v[184:187], v[76:79]
	v_mfma_f32_16x16x32_bf16 v[72:75], v[136:139], v[184:187], v[72:75]
	v_mfma_f32_16x16x32_bf16 v[124:127], v[132:135], v[164:167], v[124:127]
	v_mfma_f32_16x16x32_bf16 v[120:123], v[140:143], v[164:167], v[120:123]
	v_mfma_f32_16x16x32_bf16 v[108:111], v[132:135], v[172:175], v[108:111]
	v_mfma_f32_16x16x32_bf16 v[104:107], v[140:143], v[172:175], v[104:107]
	v_mfma_f32_16x16x32_bf16 v[92:95], v[132:135], v[180:183], v[92:95]
	v_mfma_f32_16x16x32_bf16 v[88:91], v[140:143], v[180:183], v[88:91]
	v_mfma_f32_16x16x32_bf16 v[76:79], v[132:135], v[188:191], v[76:79]
	v_mfma_f32_16x16x32_bf16 v[72:75], v[140:143], v[188:191], v[72:75]
	v_mfma_f32_16x16x32_bf16 v[116:119], v[144:147], v[160:163], v[116:119]
	v_mfma_f32_16x16x32_bf16 v[112:115], v[152:155], v[160:163], v[112:115]
	v_mfma_f32_16x16x32_bf16 v[100:103], v[144:147], v[168:171], v[100:103]
	v_mfma_f32_16x16x32_bf16 v[96:99], v[152:155], v[168:171], v[96:99]
	v_mfma_f32_16x16x32_bf16 v[84:87], v[144:147], v[176:179], v[84:87]
	v_mfma_f32_16x16x32_bf16 v[80:83], v[152:155], v[176:179], v[80:83]
	v_mfma_f32_16x16x32_bf16 v[68:71], v[144:147], v[184:187], v[68:71]
	v_mfma_f32_16x16x32_bf16 v[64:67], v[152:155], v[184:187], v[64:67]
	v_mfma_f32_16x16x32_bf16 v[116:119], v[148:151], v[164:167], v[116:119]
	v_mfma_f32_16x16x32_bf16 v[112:115], v[156:159], v[164:167], v[112:115]
	v_mfma_f32_16x16x32_bf16 v[100:103], v[148:151], v[172:175], v[100:103]
	v_mfma_f32_16x16x32_bf16 v[96:99], v[156:159], v[172:175], v[96:99]
	v_mfma_f32_16x16x32_bf16 v[84:87], v[148:151], v[180:183], v[84:87]
	v_mfma_f32_16x16x32_bf16 v[80:83], v[156:159], v[180:183], v[80:83]
	v_mfma_f32_16x16x32_bf16 v[68:71], v[148:151], v[188:191], v[68:71]
	v_mfma_f32_16x16x32_bf16 v[64:67], v[156:159], v[188:191], v[64:67]
	s_setprio 0
	s_barrier
	s_add_i32 s12, s70, s59
	v_lshl_add_u64 v[194:195], s[54:55], 0, v[200:201]
	s_mov_b32 m0, s12
	ds_read_b128 v[160:163], v244 offset:16384
	ds_read_b128 v[164:167], v244 offset:17408
	ds_read_b128 v[168:171], v244 offset:18432
	ds_read_b128 v[172:175], v244 offset:19456
	ds_read_b128 v[176:179], v244 offset:20480
	ds_read_b128 v[180:183], v244 offset:21504
	ds_read_b128 v[184:187], v244 offset:22528
	ds_read_b128 v[188:191], v244 offset:23552
	global_load_lds_dwordx4 v[194:195], off
	s_add_i32 m0, s12, 0x2000
	s_add_u32 s12, s54, 0x20000
	v_lshl_add_u64 v[196:197], s[54:55], 0, v[204:205]
	s_addc_u32 s13, s55, 0
	s_add_i32 s70, s71, s59
	global_load_lds_dwordx4 v[196:197], off
	v_lshl_add_u64 v[210:211], s[12:13], 0, v[200:201]
	s_mov_b32 m0, s70
	v_lshl_add_u64 v[212:213], s[56:57], 0, v[202:203]
	global_load_lds_dwordx4 v[210:211], off
	v_lshl_add_u64 v[210:211], s[12:13], 0, v[204:205]
	s_add_i32 m0, s70, 0x2000
	s_nop 0
	global_load_lds_dwordx4 v[210:211], off
	v_lshl_add_u64 v[210:211], s[56:57], 0, v[198:199]
	s_mov_b32 m0, s60
	s_nop 0
	global_load_lds_dwordx4 v[210:211], off
	s_mov_b32 m0, s61
	s_nop 0
	global_load_lds_dwordx4 v[212:213], off
	s_waitcnt vmcnt(8)
	s_waitcnt lgkmcnt(0)
	s_barrier
	s_setprio 1
	s_waitcnt lgkmcnt(0)
	v_mfma_f32_16x16x32_bf16 v[60:63], v[128:131], v[160:163], v[60:63]
	v_mfma_f32_16x16x32_bf16 v[56:59], v[136:139], v[160:163], v[56:59]
	v_mfma_f32_16x16x32_bf16 v[44:47], v[128:131], v[168:171], v[44:47]
	v_mfma_f32_16x16x32_bf16 v[40:43], v[136:139], v[168:171], v[40:43]
	v_mfma_f32_16x16x32_bf16 v[28:31], v[128:131], v[176:179], v[28:31]
	v_mfma_f32_16x16x32_bf16 v[24:27], v[136:139], v[176:179], v[24:27]
	v_mfma_f32_16x16x32_bf16 v[12:15], v[128:131], v[184:187], v[12:15]
	v_mfma_f32_16x16x32_bf16 v[8:11], v[136:139], v[184:187], v[8:11]
	v_mfma_f32_16x16x32_bf16 v[60:63], v[132:135], v[164:167], v[60:63]
	v_mfma_f32_16x16x32_bf16 v[56:59], v[140:143], v[164:167], v[56:59]
	v_mfma_f32_16x16x32_bf16 v[44:47], v[132:135], v[172:175], v[44:47]
	v_mfma_f32_16x16x32_bf16 v[40:43], v[140:143], v[172:175], v[40:43]
	v_mfma_f32_16x16x32_bf16 v[28:31], v[132:135], v[180:183], v[28:31]
	v_mfma_f32_16x16x32_bf16 v[24:27], v[140:143], v[180:183], v[24:27]
	v_mfma_f32_16x16x32_bf16 v[12:15], v[132:135], v[188:191], v[12:15]
	v_mfma_f32_16x16x32_bf16 v[8:11], v[140:143], v[188:191], v[8:11]
	v_mfma_f32_16x16x32_bf16 v[52:55], v[144:147], v[160:163], v[52:55]
	v_mfma_f32_16x16x32_bf16 v[48:51], v[152:155], v[160:163], v[48:51]
	v_mfma_f32_16x16x32_bf16 v[36:39], v[144:147], v[168:171], v[36:39]
	v_mfma_f32_16x16x32_bf16 v[32:35], v[152:155], v[168:171], v[32:35]
	v_mfma_f32_16x16x32_bf16 v[20:23], v[144:147], v[176:179], v[20:23]
	v_mfma_f32_16x16x32_bf16 v[16:19], v[152:155], v[176:179], v[16:19]
	v_mfma_f32_16x16x32_bf16 v[4:7], v[144:147], v[184:187], v[4:7]
	v_mfma_f32_16x16x32_bf16 v[0:3], v[152:155], v[184:187], v[0:3]
	v_mfma_f32_16x16x32_bf16 v[52:55], v[148:151], v[164:167], v[52:55]
	v_mfma_f32_16x16x32_bf16 v[48:51], v[156:159], v[164:167], v[48:51]
	v_mfma_f32_16x16x32_bf16 v[36:39], v[148:151], v[172:175], v[36:39]
	v_mfma_f32_16x16x32_bf16 v[32:35], v[156:159], v[172:175], v[32:35]
	v_mfma_f32_16x16x32_bf16 v[20:23], v[148:151], v[180:183], v[20:23]
	v_mfma_f32_16x16x32_bf16 v[16:19], v[156:159], v[180:183], v[16:19]
	v_mfma_f32_16x16x32_bf16 v[4:7], v[148:151], v[188:191], v[4:7]
	v_mfma_f32_16x16x32_bf16 v[0:3], v[156:159], v[188:191], v[0:3]
	s_setprio 0
	s_barrier
; #define PG8_STAGE(bufoff, gbase, voff) do { _Pragma("unroll") for (int _i = 0; _i < 2; ++_i) \
;         __builtin_amdgcn_global_load_lds((const unsigned*)((const char*)(gbase) + (voff)[_i]), (PG8_LAS unsigned*)(lds + (bufoff) + ldsw + _i * 8192), 16, 0, 0); } while (0)
; #define PG8_LDA(dst, b, h) do { _Pragma("unroll") for (int m = 0; m < 4; ++m) _Pragma("unroll") for (int k = 0; k < 2; ++k) dst[m][k] = *(const PG8_LAS bf16x8*)(lds + PG8_SA(b, h) + aoff + m * 2048 + k * 1024); } while (0)
; #define PG8_LDB(dst, b, h) do { _Pragma("unroll") for (int n = 0; n < 2; ++n) _Pragma("unroll") for (int k = 0; k < 2; ++k) dst[n][k] = *(const PG8_LAS bf16x8*)(lds + PG8_SB(b, h) + boff + n * 2048 + k * 1024); } while (0)
; #define PG8_MMA(ai, bj, At, Bt) do { __builtin_amdgcn_s_setprio(1); _Pragma("unroll") for (int m = 0; m < 4; ++m) _Pragma("unroll") for (int n = 0; n < 2; ++n) _Pragma("unroll") for (int k = 0; k < 2; ++k) \
;         acc[ai][bj][m][n] = __builtin_amdgcn_mfma_f32_16x16x32_bf16(Bt[n][k], At[m][k], acc[ai][bj][m][n], 0, 0, 0); __builtin_amdgcn_s_setprio(0); } while (0)
; #define PG8_WAIT_V(n) asm volatile("s_waitcnt vmcnt(" #n ")" ::: "memory")
; #define PG8_WAIT_L(n) asm volatile("s_waitcnt lgkmcnt(" #n ")" ::: "memory")
; #define PG8_BAR __builtin_amdgcn_s_barrier()
; #define PG8_SCHED __builtin_amdgcn_sched_barrier(0)
; template <class Epi, class Sched, bool ALIGN_EPI = false, bool SP2 = false>
; __device__ __forceinline__ void gemm_phase(PG8_LAS unsigned char* lds, const Gemm g, const Sched& S, const Epi& E, const int tid_in) {
;     ...
;             PG8_LDB(B0, 1, 0); PG8_LDB(B1, 1, 1); PG8_SCHED; PG8_LDA(At, 1, 0); PG8_STAGE(PG8_SA(0, 1), a2 + hstepA, voffA);
;             PG8_WAIT_V(8); PG8_WAIT_L(0); PG8_BAR; PG8_MMA(0, 0, At, B0); PG8_MMA(0, 1, At, B1); PG8_BAR; PG8_SCHED;
	s_add_i32 s70, 0, 0x18000
	s_add_i32 s71, 0, 0x1c000
	v_add_u32_e32 v140, s70, v242
	v_add_u32_e32 v156, s71, v242
	ds_read_b128 v[128:131], v140
	ds_read_b128 v[132:135], v140 offset:1024
	ds_read_b128 v[136:139], v140 offset:2048
	ds_read_b128 v[140:143], v140 offset:3072
	ds_read_b128 v[144:147], v156
	ds_read_b128 v[148:151], v156 offset:1024
	ds_read_b128 v[152:155], v156 offset:2048
	ds_read_b128 v[156:159], v156 offset:3072
	s_add_u32 s12, s56, 0x40000
	s_addc_u32 s13, s57, 0
	s_mov_b32 m0, s62
	v_lshl_add_u64 v[214:215], s[12:13], 0, v[198:199]
	ds_read_b128 v[160:163], v244 offset:32768
	ds_read_b128 v[164:167], v244 offset:33792
	ds_read_b128 v[168:171], v244 offset:34816
	ds_read_b128 v[172:175], v244 offset:35840
	ds_read_b128 v[176:179], v244 offset:36864
	ds_read_b128 v[180:183], v244 offset:37888
	ds_read_b128 v[184:187], v244 offset:38912
	ds_read_b128 v[188:191], v244 offset:39936
	global_load_lds_dwordx4 v[214:215], off
	v_lshl_add_u64 v[214:215], s[12:13], 0, v[202:203]
	s_mov_b32 m0, s63
	s_nop 0
	global_load_lds_dwordx4 v[214:215], off
	s_waitcnt vmcnt(8)
	s_waitcnt lgkmcnt(0)
	s_barrier
	s_setprio 1
	s_waitcnt lgkmcnt(0)
	v_mfma_f32_16x16x32_bf16 v[124:127], v[128:131], v[160:163], v[124:127]
	v_mfma_f32_16x16x32_bf16 v[120:123], v[136:139], v[160:163], v[120:123]
	v_mfma_f32_16x16x32_bf16 v[108:111], v[128:131], v[168:171], v[108:111]
	v_mfma_f32_16x16x32_bf16 v[104:107], v[136:139], v[168:171], v[104:107]
	v_mfma_f32_16x16x32_bf16 v[92:95], v[128:131], v[176:179], v[92:95]
	v_mfma_f32_16x16x32_bf16 v[88:91], v[136:139], v[176:179], v[88:91]
	v_mfma_f32_16x16x32_bf16 v[76:79], v[128:131], v[184:187], v[76:79]
	v_mfma_f32_16x16x32_bf16 v[72:75], v[136:139], v[184:187], v[72:75]
	v_mfma_f32_16x16x32_bf16 v[124:127], v[132:135], v[164:167], v[124:127]
	v_mfma_f32_16x16x32_bf16 v[120:123], v[140:143], v[164:167], v[120:123]
	v_mfma_f32_16x16x32_bf16 v[108:111], v[132:135], v[172:175], v[108:111]
	v_mfma_f32_16x16x32_bf16 v[104:107], v[140:143], v[172:175], v[104:107]
	v_mfma_f32_16x16x32_bf16 v[92:95], v[132:135], v[180:183], v[92:95]
	v_mfma_f32_16x16x32_bf16 v[88:91], v[140:143], v[180:183], v[88:91]
	v_mfma_f32_16x16x32_bf16 v[76:79], v[132:135], v[188:191], v[76:79]
	v_mfma_f32_16x16x32_bf16 v[72:75], v[140:143], v[188:191], v[72:75]
	v_mfma_f32_16x16x32_bf16 v[116:119], v[144:147], v[160:163], v[116:119]
	v_mfma_f32_16x16x32_bf16 v[112:115], v[152:155], v[160:163], v[112:115]
	v_mfma_f32_16x16x32_bf16 v[100:103], v[144:147], v[168:171], v[100:103]
	v_mfma_f32_16x16x32_bf16 v[96:99], v[152:155], v[168:171], v[96:99]
	v_mfma_f32_16x16x32_bf16 v[84:87], v[144:147], v[176:179], v[84:87]
	v_mfma_f32_16x16x32_bf16 v[80:83], v[152:155], v[176:179], v[80:83]
	v_mfma_f32_16x16x32_bf16 v[68:71], v[144:147], v[184:187], v[68:71]
	v_mfma_f32_16x16x32_bf16 v[64:67], v[152:155], v[184:187], v[64:67]
	v_mfma_f32_16x16x32_bf16 v[116:119], v[148:151], v[164:167], v[116:119]
	v_mfma_f32_16x16x32_bf16 v[112:115], v[156:159], v[164:167], v[112:115]
	v_mfma_f32_16x16x32_bf16 v[100:103], v[148:151], v[172:175], v[100:103]
	v_mfma_f32_16x16x32_bf16 v[96:99], v[156:159], v[172:175], v[96:99]
	v_mfma_f32_16x16x32_bf16 v[84:87], v[148:151], v[180:183], v[84:87]
	v_mfma_f32_16x16x32_bf16 v[80:83], v[156:159], v[180:183], v[80:83]
	v_mfma_f32_16x16x32_bf16 v[68:71], v[148:151], v[188:191], v[68:71]
	v_mfma_f32_16x16x32_bf16 v[64:67], v[156:159], v[188:191], v[64:67]
	s_setprio 0
	s_barrier
; #define PG8_STAGE(bufoff, gbase, voff) do { _Pragma("unroll") for (int _i = 0; _i < 2; ++_i) \
;         __builtin_amdgcn_global_load_lds((const unsigned*)((const char*)(gbase) + (voff)[_i]), (PG8_LAS unsigned*)(lds + (bufoff) + ldsw + _i * 8192), 16, 0, 0); } while (0)
; #define PG8_LDA(dst, b, h) do { _Pragma("unroll") for (int m = 0; m < 4; ++m) _Pragma("unroll") for (int k = 0; k < 2; ++k) dst[m][k] = *(const PG8_LAS bf16x8*)(lds + PG8_SA(b, h) + aoff + m * 2048 + k * 1024); } while (0)
; #define PG8_MMA(ai, bj, At, Bt) do { __builtin_amdgcn_s_setprio(1); _Pragma("unroll") for (int m = 0; m < 4; ++m) _Pragma("unroll") for (int n = 0; n < 2; ++n) _Pragma("unroll") for (int k = 0; k < 2; ++k) \
;         acc[ai][bj][m][n] = __builtin_amdgcn_mfma_f32_16x16x32_bf16(Bt[n][k], At[m][k], acc[ai][bj][m][n], 0, 0, 0); __builtin_amdgcn_s_setprio(0); } while (0)
; #define PG8_WAIT_V(n) asm volatile("s_waitcnt vmcnt(" #n ")" ::: "memory")
; #define PG8_WAIT_L(n) asm volatile("s_waitcnt lgkmcnt(" #n ")" ::: "memory")
; #define PG8_BAR __builtin_amdgcn_s_barrier()
; #define PG8_SCHED __builtin_amdgcn_sched_barrier(0)
; template <class Epi, class Sched, bool ALIGN_EPI = false, bool SP2 = false>
; __device__ __forceinline__ void gemm_phase(PG8_LAS unsigned char* lds, const Gemm g, const Sched& S, const Epi& E, const int tid_in) {
;     ...
;             PG8_LDA(At, 1, 1); PG8_STAGE(PG8_SB(1, 0), b3, voffB); PG8_STAGE(PG8_SB(1, 1), b3 + hstepB, voffB); PG8_STAGE(PG8_SA(1, 0), a3, voffA);
;             PG8_WAIT_V(8); PG8_WAIT_L(0); PG8_BAR; PG8_MMA(1, 0, At, B0); PG8_MMA(1, 1, At, B1); PG8_BAR; PG8_SCHED;
;     ...
;         if constexpr (ALIGN_EPI) { if (wr == 0) PG8_BAR; }
	s_add_i32 s12, s70, s59
	v_lshl_add_u64 v[194:195], v[194:195], 0, s[26:27]
	s_mov_b32 m0, s12
	ds_read_b128 v[160:163], v244 offset:49152
	ds_read_b128 v[164:167], v244 offset:50176
	ds_read_b128 v[168:171], v244 offset:51200
	ds_read_b128 v[172:175], v244 offset:52224
	ds_read_b128 v[176:179], v244 offset:53248
	ds_read_b128 v[180:183], v244 offset:54272
	ds_read_b128 v[184:187], v244 offset:55296
	ds_read_b128 v[188:191], v244 offset:56320
	global_load_lds_dwordx4 v[194:195], off
	s_add_i32 m0, s12, 0x2000
	s_add_u32 s12, s54, 0x20080
	v_lshl_add_u64 v[194:195], v[196:197], 0, s[26:27]
	s_addc_u32 s13, s55, 0
	s_add_i32 s54, s71, s59
	global_load_lds_dwordx4 v[194:195], off
	v_lshl_add_u64 v[194:195], s[12:13], 0, v[200:201]
	s_mov_b32 m0, s54
	s_nop 0
	global_load_lds_dwordx4 v[194:195], off
	v_lshl_add_u64 v[194:195], s[12:13], 0, v[204:205]
	s_add_i32 m0, s54, 0x2000
	s_nop 0
	global_load_lds_dwordx4 v[194:195], off
	v_lshl_add_u64 v[194:195], v[210:211], 0, s[26:27]
	s_mov_b32 m0, s64
	s_nop 0
	global_load_lds_dwordx4 v[194:195], off
	v_lshl_add_u64 v[194:195], v[212:213], 0, s[26:27]
	s_mov_b32 m0, s65
	s_nop 0
	global_load_lds_dwordx4 v[194:195], off
	s_waitcnt vmcnt(8)
	s_waitcnt lgkmcnt(0)
	s_barrier
	s_setprio 1
	s_waitcnt lgkmcnt(0)
	v_mfma_f32_16x16x32_bf16 v[60:63], v[128:131], v[160:163], v[60:63]
	v_mfma_f32_16x16x32_bf16 v[56:59], v[136:139], v[160:163], v[56:59]
	v_mfma_f32_16x16x32_bf16 v[44:47], v[128:131], v[168:171], v[44:47]
	v_mfma_f32_16x16x32_bf16 v[40:43], v[136:139], v[168:171], v[40:43]
	v_mfma_f32_16x16x32_bf16 v[28:31], v[128:131], v[176:179], v[28:31]
	v_mfma_f32_16x16x32_bf16 v[24:27], v[136:139], v[176:179], v[24:27]
	v_mfma_f32_16x16x32_bf16 v[12:15], v[128:131], v[184:187], v[12:15]
	v_mfma_f32_16x16x32_bf16 v[8:11], v[136:139], v[184:187], v[8:11]
	v_mfma_f32_16x16x32_bf16 v[60:63], v[132:135], v[164:167], v[60:63]
	v_mfma_f32_16x16x32_bf16 v[56:59], v[140:143], v[164:167], v[56:59]
	v_mfma_f32_16x16x32_bf16 v[44:47], v[132:135], v[172:175], v[44:47]
	v_mfma_f32_16x16x32_bf16 v[40:43], v[140:143], v[172:175], v[40:43]
	v_mfma_f32_16x16x32_bf16 v[28:31], v[132:135], v[180:183], v[28:31]
	v_mfma_f32_16x16x32_bf16 v[24:27], v[140:143], v[180:183], v[24:27]
	v_mfma_f32_16x16x32_bf16 v[12:15], v[132:135], v[188:191], v[12:15]
	v_mfma_f32_16x16x32_bf16 v[8:11], v[140:143], v[188:191], v[8:11]
	v_mfma_f32_16x16x32_bf16 v[52:55], v[144:147], v[160:163], v[52:55]
	v_mfma_f32_16x16x32_bf16 v[48:51], v[152:155], v[160:163], v[48:51]
	v_mfma_f32_16x16x32_bf16 v[36:39], v[144:147], v[168:171], v[36:39]
	v_mfma_f32_16x16x32_bf16 v[32:35], v[152:155], v[168:171], v[32:35]
	v_mfma_f32_16x16x32_bf16 v[20:23], v[144:147], v[176:179], v[20:23]
	v_mfma_f32_16x16x32_bf16 v[16:19], v[152:155], v[176:179], v[16:19]
	v_mfma_f32_16x16x32_bf16 v[4:7], v[144:147], v[184:187], v[4:7]
	v_mfma_f32_16x16x32_bf16 v[0:3], v[152:155], v[184:187], v[0:3]
	v_mfma_f32_16x16x32_bf16 v[52:55], v[148:151], v[164:167], v[52:55]
	v_mfma_f32_16x16x32_bf16 v[48:51], v[156:159], v[164:167], v[48:51]
	v_mfma_f32_16x16x32_bf16 v[36:39], v[148:151], v[172:175], v[36:39]
	v_mfma_f32_16x16x32_bf16 v[32:35], v[156:159], v[172:175], v[32:35]
	v_mfma_f32_16x16x32_bf16 v[20:23], v[148:151], v[180:183], v[20:23]
	v_mfma_f32_16x16x32_bf16 v[16:19], v[156:159], v[180:183], v[16:19]
	v_mfma_f32_16x16x32_bf16 v[4:7], v[148:151], v[188:191], v[4:7]
	v_mfma_f32_16x16x32_bf16 v[0:3], v[156:159], v[188:191], v[0:3]
	s_setprio 0
	s_barrier
	s_add_i32 s69, s69, 2
	s_add_u32 s52, s52, 0x100
	s_addc_u32 s53, s53, 0
	s_add_u32 s67, s67, 0x100
	s_addc_u32 s68, s68, 0
	s_cmp_gt_u32 s69, 5
	s_cbranch_scc0 .LBB0_427
	s_and_b64 vcc, exec, s[42:43]
	s_cbranch_vccz .LBB0_430
	s_barrier

; #define PG8_STAGE(bufoff, gbase, voff) do { _Pragma("unroll") for (int _i = 0; _i < 2; ++_i) \
;         __builtin_amdgcn_global_load_lds((const unsigned*)((const char*)(gbase) + (voff)[_i]), (PG8_LAS unsigned*)(lds + (bufoff) + ldsw + _i * 8192), 16, 0, 0); } while (0)
; #define PG8_LDA(dst, b, h) do { _Pragma("unroll") for (int m = 0; m < 4; ++m) _Pragma("unroll") for (int k = 0; k < 2; ++k) dst[m][k] = *(const PG8_LAS bf16x8*)(lds + PG8_SA(b, h) + aoff + m * 2048 + k * 1024); } while (0)
; #define PG8_LDB(dst, b, h) do { _Pragma("unroll") for (int n = 0; n < 2; ++n) _Pragma("unroll") for (int k = 0; k < 2; ++k) dst[n][k] = *(const PG8_LAS bf16x8*)(lds + PG8_SB(b, h) + boff + n * 2048 + k * 1024); } while (0)
; template <class Epi, class Sched, bool ALIGN_EPI = false, bool SP2 = false>
; __device__ __forceinline__ void gemm_phase(PG8_LAS unsigned char* lds, const Gemm g, const Sched& S, const Epi& E, const int tid_in) {
;     ...
;         const bool has_next = S.next(ui + 1, nxt);
;         const char* nA = has_next ? (const char*)g.A + (size_t)nxt.pm * tstepA : cA; const char* nB = has_next ? (const char*)g.Bt + (size_t)nxt.pn * tstepB : cB;
;         for (int t = 0; t < nt; t += 2) {
;             const bool last = (t == nt - 2);
;             const char* a1 = cA + (size_t)(t + 1) * kstep;
;             const char* a2 = last ? nA : cA + (size_t)(t + 2) * kstep; const char* b2 = last ? nB : cB + (size_t)(t + 2) * kstep;
;             const char* a3 = a2 + kstep; const char* b3 = b2 + kstep;
;             if (last && has_next) S.a_ready(nxt);
;             if constexpr (SP2) {
;             PG8_LDB(B0, 0, 0); PG8_LDB(B1, 0, 1); PG8_SCHED; PG8_LDA(At, 0, 0); PG8_STAGE(PG8_SA(1, 1), a1 + hstepA, voffA);
;             PG8_WAIT_V(8); PG8_WAIT_L(0); PG8_BAR; PG8_MMA(0, 0, At, B0); PG8_MMA(0, 1, At, B1); PG8_BAR; PG8_SCHED;
;             PG8_LDA(At, 0, 1); PG8_STAGE(PG8_SB(0, 0), b2, voffB); PG8_STAGE(PG8_SB(0, 1), b2 + hstepB, voffB); PG8_STAGE(PG8_SA(0, 0), a2, voffA);
;             PG8_WAIT_V(8); PG8_WAIT_L(0); PG8_BAR; PG8_MMA(1, 0, At, B0); PG8_MMA(1, 1, At, B1); PG8_BAR; PG8_SCHED;
;     ...
;         for (int a = 0; a < 2; ++a)
; #pragma unroll
;             for (int b = 0; b < 2; ++b)
; #pragma unroll
;                 for (int m = 0; m < 4; ++m)
; #pragma unroll
;                     for (int n = 0; n < 2; ++n) acc[a][b][m][n] = (f32x4){0.f, 0.f, 0.f, 0.f};
.LBB0_538:
	s_ashr_i32 s37, s36, 31
	s_lshl_b64 s[12:13], s[36:37], 19
	s_add_u32 s38, s18, s12
	s_addc_u32 s39, s48, s13
	s_and_b64 s[12:13], s[34:35], exec
	s_cselect_b32 s37, s39, s43
	s_cselect_b32 s63, s38, s42
	s_ashr_i32 s31, s30, 31
	s_lshl_b64 s[12:13], s[30:31], 18
	s_add_u32 s40, s49, s12
	s_addc_u32 s41, s50, s13
	s_and_b64 s[12:13], s[34:35], exec
	s_cselect_b32 s31, s41, s45
	s_cselect_b32 s64, s40, s44
	s_add_u32 s42, s42, 0x40080
	s_addc_u32 s43, s43, 0
	s_add_u32 s65, s44, 0x100
	s_addc_u32 s66, s45, 0
	s_mov_b32 s67, -2
	s_add_u32 s12, s42, 0xfffc0080
	s_addc_u32 s13, s43, -1
	s_add_i32 s68, 0, 0x10000
	s_cmp_eq_u32 s67, 4
	s_cselect_b32 s47, s37, s13
	s_cselect_b32 s46, s63, s12
	v_add_u32_e32 v130, s68, v133
	s_cselect_b32 s45, s31, s66
	s_cselect_b32 s44, s64, s65
	s_add_i32 s69, 0, 0x14000
	ds_read_b128 v[136:139], v130
	ds_read_b128 v[140:143], v130 offset:1024
	ds_read_b128 v[144:147], v130 offset:2048
	ds_read_b128 v[148:151], v130 offset:3072
	v_add_u32_e32 v130, s69, v133
	ds_read_b128 v[152:155], v130
	ds_read_b128 v[156:159], v130 offset:1024
	ds_read_b128 v[160:163], v130 offset:2048
	ds_read_b128 v[164:167], v130 offset:3072
	v_lshl_add_u64 v[130:131], s[42:43], 0, v[192:193]
	s_add_i32 m0, s52, 0xc000
	ds_read_b128 v[168:171], v135
	ds_read_b128 v[172:175], v135 offset:1024
	ds_read_b128 v[176:179], v135 offset:2048
	ds_read_b128 v[180:183], v135 offset:3072
	ds_read_b128 v[184:187], v135 offset:4096
	ds_read_b128 v[188:191], v135 offset:5120
	ds_read_b128 v[194:197], v135 offset:6144
	ds_read_b128 v[206:209], v135 offset:7168
	global_load_lds_dwordx4 v[130:131], off
	v_lshl_add_u64 v[130:131], s[42:43], 0, v[128:129]
	s_add_i32 m0, s52, 0xe000
	s_nop 0
	global_load_lds_dwordx4 v[130:131], off
	s_waitcnt vmcnt(8)
	s_waitcnt lgkmcnt(0)
	s_barrier
	s_setprio 1
	s_waitcnt lgkmcnt(0)
	v_mfma_f32_16x16x32_bf16 v[124:127], v[136:139], v[168:171], 0
	v_mfma_f32_16x16x32_bf16 v[120:123], v[144:147], v[168:171], 0
	v_mfma_f32_16x16x32_bf16 v[116:119], v[136:139], v[176:179], 0
	v_mfma_f32_16x16x32_bf16 v[108:111], v[144:147], v[176:179], 0
	v_mfma_f32_16x16x32_bf16 v[100:103], v[136:139], v[184:187], 0
	v_mfma_f32_16x16x32_bf16 v[92:95], v[144:147], v[184:187], 0
	v_mfma_f32_16x16x32_bf16 v[84:87], v[136:139], v[194:197], 0
	v_mfma_f32_16x16x32_bf16 v[76:79], v[144:147], v[194:197], 0
	v_mfma_f32_16x16x32_bf16 v[124:127], v[140:143], v[172:175], v[124:127]
	v_mfma_f32_16x16x32_bf16 v[120:123], v[148:151], v[172:175], v[120:123]
	v_mfma_f32_16x16x32_bf16 v[116:119], v[140:143], v[180:183], v[116:119]
	v_mfma_f32_16x16x32_bf16 v[108:111], v[148:151], v[180:183], v[108:111]
	v_mfma_f32_16x16x32_bf16 v[100:103], v[140:143], v[188:191], v[100:103]
	v_mfma_f32_16x16x32_bf16 v[92:95], v[148:151], v[188:191], v[92:95]
	v_mfma_f32_16x16x32_bf16 v[84:87], v[140:143], v[206:209], v[84:87]
	v_mfma_f32_16x16x32_bf16 v[76:79], v[148:151], v[206:209], v[76:79]
	s_setprio 0
	s_setprio 1
	v_mfma_f32_16x16x32_bf16 v[112:115], v[152:155], v[168:171], 0
	v_mfma_f32_16x16x32_bf16 v[104:107], v[160:163], v[168:171], 0
	v_mfma_f32_16x16x32_bf16 v[96:99], v[152:155], v[176:179], 0
	v_mfma_f32_16x16x32_bf16 v[88:91], v[160:163], v[176:179], 0
	v_mfma_f32_16x16x32_bf16 v[80:83], v[152:155], v[184:187], 0
	v_mfma_f32_16x16x32_bf16 v[72:75], v[160:163], v[184:187], 0
	v_mfma_f32_16x16x32_bf16 v[68:71], v[152:155], v[194:197], 0
	v_mfma_f32_16x16x32_bf16 v[64:67], v[160:163], v[194:197], 0
	v_mfma_f32_16x16x32_bf16 v[112:115], v[156:159], v[172:175], v[112:115]
	v_mfma_f32_16x16x32_bf16 v[104:107], v[164:167], v[172:175], v[104:107]
	v_mfma_f32_16x16x32_bf16 v[96:99], v[156:159], v[180:183], v[96:99]
	v_mfma_f32_16x16x32_bf16 v[88:91], v[164:167], v[180:183], v[88:91]
	v_mfma_f32_16x16x32_bf16 v[80:83], v[156:159], v[188:191], v[80:83]
	v_mfma_f32_16x16x32_bf16 v[72:75], v[164:167], v[188:191], v[72:75]
	v_mfma_f32_16x16x32_bf16 v[68:71], v[156:159], v[206:209], v[68:71]
	v_mfma_f32_16x16x32_bf16 v[64:67], v[164:167], v[206:209], v[64:67]
	s_setprio 0
	s_barrier
	s_add_i32 s12, s68, s51
	v_lshl_add_u64 v[130:131], s[44:45], 0, v[200:201]
	s_mov_b32 m0, s12
	ds_read_b128 v[168:171], v135 offset:16384
	ds_read_b128 v[172:175], v135 offset:17408
	ds_read_b128 v[176:179], v135 offset:18432
	ds_read_b128 v[180:183], v135 offset:19456
	ds_read_b128 v[184:187], v135 offset:20480
	ds_read_b128 v[188:191], v135 offset:21504
	ds_read_b128 v[194:197], v135 offset:22528
	ds_read_b128 v[206:209], v135 offset:23552
	global_load_lds_dwordx4 v[130:131], off
	s_add_i32 m0, s12, 0x2000
	s_add_u32 s12, s44, 0x20000
	v_lshl_add_u64 v[210:211], s[44:45], 0, v[204:205]
	s_addc_u32 s13, s45, 0
	s_add_i32 s68, s69, s51
	global_load_lds_dwordx4 v[210:211], off
	v_lshl_add_u64 v[212:213], s[12:13], 0, v[200:201]
	s_mov_b32 m0, s68
	v_lshl_add_u64 v[214:215], s[46:47], 0, v[202:203]
	global_load_lds_dwordx4 v[212:213], off
	v_lshl_add_u64 v[212:213], s[12:13], 0, v[204:205]
	s_add_i32 m0, s68, 0x2000
	s_nop 0
	global_load_lds_dwordx4 v[212:213], off
	v_lshl_add_u64 v[212:213], s[46:47], 0, v[198:199]
	s_mov_b32 m0, s52
	s_nop 0
	global_load_lds_dwordx4 v[212:213], off
	s_mov_b32 m0, s53
	s_nop 0
	global_load_lds_dwordx4 v[214:215], off
	s_waitcnt vmcnt(8)
	s_waitcnt lgkmcnt(0)
	s_barrier
; #define PG8_STAGE(bufoff, gbase, voff) do { _Pragma("unroll") for (int _i = 0; _i < 2; ++_i) \
;         __builtin_amdgcn_global_load_lds((const unsigned*)((const char*)(gbase) + (voff)[_i]), (PG8_LAS unsigned*)(lds + (bufoff) + ldsw + _i * 8192), 16, 0, 0); } while (0)
; #define PG8_LDA(dst, b, h) do { _Pragma("unroll") for (int m = 0; m < 4; ++m) _Pragma("unroll") for (int k = 0; k < 2; ++k) dst[m][k] = *(const PG8_LAS bf16x8*)(lds + PG8_SA(b, h) + aoff + m * 2048 + k * 1024); } while (0)
; #define PG8_LDB(dst, b, h) do { _Pragma("unroll") for (int n = 0; n < 2; ++n) _Pragma("unroll") for (int k = 0; k < 2; ++k) dst[n][k] = *(const PG8_LAS bf16x8*)(lds + PG8_SB(b, h) + boff + n * 2048 + k * 1024); } while (0)
; #define PG8_MMA(ai, bj, At, Bt) do { __builtin_amdgcn_s_setprio(1); _Pragma("unroll") for (int m = 0; m < 4; ++m) _Pragma("unroll") for (int n = 0; n < 2; ++n) _Pragma("unroll") for (int k = 0; k < 2; ++k) \
;         acc[ai][bj][m][n] = __builtin_amdgcn_mfma_f32_16x16x32_bf16(Bt[n][k], At[m][k], acc[ai][bj][m][n], 0, 0, 0); __builtin_amdgcn_s_setprio(0); } while (0)
; #define PG8_WAIT_V(n) asm volatile("s_waitcnt vmcnt(" #n ")" ::: "memory")
; #define PG8_WAIT_L(n) asm volatile("s_waitcnt lgkmcnt(" #n ")" ::: "memory")
; #define PG8_BAR __builtin_amdgcn_s_barrier()
; #define PG8_SCHED __builtin_amdgcn_sched_barrier(0)
; template <class Epi, class Sched, bool ALIGN_EPI = false, bool SP2 = false>
; __device__ __forceinline__ void gemm_phase(PG8_LAS unsigned char* lds, const Gemm g, const Sched& S, const Epi& E, const int tid_in) {
;     ...
;             PG8_WAIT_V(8); PG8_WAIT_L(0); PG8_BAR; PG8_MMA(1, 0, At, B0); PG8_MMA(1, 1, At, B1); PG8_BAR; PG8_SCHED;
;             PG8_LDB(B0, 1, 0); PG8_LDB(B1, 1, 1); PG8_SCHED; PG8_LDA(At, 1, 0); PG8_STAGE(PG8_SA(0, 1), a2 + hstepA, voffA);
;             PG8_WAIT_V(8); PG8_WAIT_L(0); PG8_BAR; PG8_MMA(0, 0, At, B0); PG8_MMA(0, 1, At, B1); PG8_BAR; PG8_SCHED;
	s_setprio 1
	s_waitcnt lgkmcnt(0)
	v_mfma_f32_16x16x32_bf16 v[60:63], v[136:139], v[168:171], 0
	v_mfma_f32_16x16x32_bf16 v[56:59], v[144:147], v[168:171], 0
	v_mfma_f32_16x16x32_bf16 v[52:55], v[136:139], v[176:179], 0
	v_mfma_f32_16x16x32_bf16 v[44:47], v[144:147], v[176:179], 0
	v_mfma_f32_16x16x32_bf16 v[36:39], v[136:139], v[184:187], 0
	v_mfma_f32_16x16x32_bf16 v[28:31], v[144:147], v[184:187], 0
	v_mfma_f32_16x16x32_bf16 v[20:23], v[136:139], v[194:197], 0
	v_mfma_f32_16x16x32_bf16 v[12:15], v[144:147], v[194:197], 0
	v_mfma_f32_16x16x32_bf16 v[60:63], v[140:143], v[172:175], v[60:63]
	v_mfma_f32_16x16x32_bf16 v[56:59], v[148:151], v[172:175], v[56:59]
	v_mfma_f32_16x16x32_bf16 v[52:55], v[140:143], v[180:183], v[52:55]
	v_mfma_f32_16x16x32_bf16 v[44:47], v[148:151], v[180:183], v[44:47]
	v_mfma_f32_16x16x32_bf16 v[36:39], v[140:143], v[188:191], v[36:39]
	v_mfma_f32_16x16x32_bf16 v[28:31], v[148:151], v[188:191], v[28:31]
	v_mfma_f32_16x16x32_bf16 v[20:23], v[140:143], v[206:209], v[20:23]
	v_mfma_f32_16x16x32_bf16 v[12:15], v[148:151], v[206:209], v[12:15]
	s_setprio 0
	s_setprio 1
	v_mfma_f32_16x16x32_bf16 v[48:51], v[152:155], v[168:171], 0
	v_mfma_f32_16x16x32_bf16 v[40:43], v[160:163], v[168:171], 0
	v_mfma_f32_16x16x32_bf16 v[32:35], v[152:155], v[176:179], 0
	v_mfma_f32_16x16x32_bf16 v[24:27], v[160:163], v[176:179], 0
	v_mfma_f32_16x16x32_bf16 v[16:19], v[152:155], v[184:187], 0
	v_mfma_f32_16x16x32_bf16 v[8:11], v[160:163], v[184:187], 0
	v_mfma_f32_16x16x32_bf16 v[4:7], v[152:155], v[194:197], 0
	v_mfma_f32_16x16x32_bf16 v[0:3], v[160:163], v[194:197], 0
	v_mfma_f32_16x16x32_bf16 v[48:51], v[156:159], v[172:175], v[48:51]
	v_mfma_f32_16x16x32_bf16 v[40:43], v[164:167], v[172:175], v[40:43]
	v_mfma_f32_16x16x32_bf16 v[32:35], v[156:159], v[180:183], v[32:35]
	v_mfma_f32_16x16x32_bf16 v[24:27], v[164:167], v[180:183], v[24:27]
	v_mfma_f32_16x16x32_bf16 v[16:19], v[156:159], v[188:191], v[16:19]
	v_mfma_f32_16x16x32_bf16 v[8:11], v[164:167], v[188:191], v[8:11]
	v_mfma_f32_16x16x32_bf16 v[4:7], v[156:159], v[206:209], v[4:7]
	v_mfma_f32_16x16x32_bf16 v[0:3], v[164:167], v[206:209], v[0:3]
	s_setprio 0
	s_barrier
	s_add_i32 s68, 0, 0x18000
	s_add_i32 s69, 0, 0x1c000
	v_add_u32_e32 v148, s68, v133
	v_add_u32_e32 v164, s69, v133
	ds_read_b128 v[136:139], v148
	ds_read_b128 v[140:143], v148 offset:1024
	ds_read_b128 v[144:147], v148 offset:2048
	ds_read_b128 v[148:151], v148 offset:3072
	ds_read_b128 v[152:155], v164
	ds_read_b128 v[156:159], v164 offset:1024
	ds_read_b128 v[160:163], v164 offset:2048
	ds_read_b128 v[164:167], v164 offset:3072
	s_add_u32 s12, s46, 0x40000
	s_addc_u32 s13, s47, 0
	s_mov_b32 m0, s54
	v_lshl_add_u64 v[216:217], s[12:13], 0, v[198:199]
	ds_read_b128 v[168:171], v135 offset:32768
	ds_read_b128 v[172:175], v135 offset:33792
	ds_read_b128 v[176:179], v135 offset:34816
	ds_read_b128 v[180:183], v135 offset:35840
	ds_read_b128 v[184:187], v135 offset:36864
	ds_read_b128 v[188:191], v135 offset:37888
	ds_read_b128 v[194:197], v135 offset:38912
	ds_read_b128 v[206:209], v135 offset:39936
	global_load_lds_dwordx4 v[216:217], off
	v_lshl_add_u64 v[216:217], s[12:13], 0, v[202:203]
	s_mov_b32 m0, s55
	s_nop 0
	global_load_lds_dwordx4 v[216:217], off
	s_waitcnt vmcnt(8)
	s_waitcnt lgkmcnt(0)
	s_barrier
	s_setprio 1
	s_waitcnt lgkmcnt(0)
	v_mfma_f32_16x16x32_bf16 v[124:127], v[136:139], v[168:171], v[124:127]
	v_mfma_f32_16x16x32_bf16 v[120:123], v[144:147], v[168:171], v[120:123]
	v_mfma_f32_16x16x32_bf16 v[116:119], v[136:139], v[176:179], v[116:119]
	v_mfma_f32_16x16x32_bf16 v[108:111], v[144:147], v[176:179], v[108:111]
	v_mfma_f32_16x16x32_bf16 v[100:103], v[136:139], v[184:187], v[100:103]
	v_mfma_f32_16x16x32_bf16 v[92:95], v[144:147], v[184:187], v[92:95]
	v_mfma_f32_16x16x32_bf16 v[84:87], v[136:139], v[194:197], v[84:87]
	v_mfma_f32_16x16x32_bf16 v[76:79], v[144:147], v[194:197], v[76:79]
	v_mfma_f32_16x16x32_bf16 v[124:127], v[140:143], v[172:175], v[124:127]
	v_mfma_f32_16x16x32_bf16 v[120:123], v[148:151], v[172:175], v[120:123]
	v_mfma_f32_16x16x32_bf16 v[116:119], v[140:143], v[180:183], v[116:119]
	v_mfma_f32_16x16x32_bf16 v[108:111], v[148:151], v[180:183], v[108:111]
	v_mfma_f32_16x16x32_bf16 v[100:103], v[140:143], v[188:191], v[100:103]
	v_mfma_f32_16x16x32_bf16 v[92:95], v[148:151], v[188:191], v[92:95]
	v_mfma_f32_16x16x32_bf16 v[84:87], v[140:143], v[206:209], v[84:87]
	v_mfma_f32_16x16x32_bf16 v[76:79], v[148:151], v[206:209], v[76:79]
	s_setprio 0
	s_setprio 1
	v_mfma_f32_16x16x32_bf16 v[112:115], v[152:155], v[168:171], v[112:115]
	v_mfma_f32_16x16x32_bf16 v[104:107], v[160:163], v[168:171], v[104:107]
	v_mfma_f32_16x16x32_bf16 v[96:99], v[152:155], v[176:179], v[96:99]
	v_mfma_f32_16x16x32_bf16 v[88:91], v[160:163], v[176:179], v[88:91]
	v_mfma_f32_16x16x32_bf16 v[80:83], v[152:155], v[184:187], v[80:83]
	v_mfma_f32_16x16x32_bf16 v[72:75], v[160:163], v[184:187], v[72:75]
	v_mfma_f32_16x16x32_bf16 v[68:71], v[152:155], v[194:197], v[68:71]
	v_mfma_f32_16x16x32_bf16 v[64:67], v[160:163], v[194:197], v[64:67]
	v_mfma_f32_16x16x32_bf16 v[112:115], v[156:159], v[172:175], v[112:115]
	v_mfma_f32_16x16x32_bf16 v[104:107], v[164:167], v[172:175], v[104:107]
	v_mfma_f32_16x16x32_bf16 v[96:99], v[156:159], v[180:183], v[96:99]
	v_mfma_f32_16x16x32_bf16 v[88:91], v[164:167], v[180:183], v[88:91]
	v_mfma_f32_16x16x32_bf16 v[80:83], v[156:159], v[188:191], v[80:83]
	v_mfma_f32_16x16x32_bf16 v[72:75], v[164:167], v[188:191], v[72:75]
	v_mfma_f32_16x16x32_bf16 v[68:71], v[156:159], v[206:209], v[68:71]
	v_mfma_f32_16x16x32_bf16 v[64:67], v[164:167], v[206:209], v[64:67]
	s_setprio 0
	s_barrier
; #define PG8_STAGE(bufoff, gbase, voff) do { _Pragma("unroll") for (int _i = 0; _i < 2; ++_i) \
;         __builtin_amdgcn_global_load_lds((const unsigned*)((const char*)(gbase) + (voff)[_i]), (PG8_LAS unsigned*)(lds + (bufoff) + ldsw + _i * 8192), 16, 0, 0); } while (0)
; #define PG8_LDA(dst, b, h) do { _Pragma("unroll") for (int m = 0; m < 4; ++m) _Pragma("unroll") for (int k = 0; k < 2; ++k) dst[m][k] = *(const PG8_LAS bf16x8*)(lds + PG8_SA(b, h) + aoff + m * 2048 + k * 1024); } while (0)
; #define PG8_WAIT_V(n) asm volatile("s_waitcnt vmcnt(" #n ")" ::: "memory")
; #define PG8_WAIT_L(n) asm volatile("s_waitcnt lgkmcnt(" #n ")" ::: "memory")
; #define PG8_BAR __builtin_amdgcn_s_barrier()
; template <class Epi, class Sched, bool ALIGN_EPI = false, bool SP2 = false>
; __device__ __forceinline__ void gemm_phase(PG8_LAS unsigned char* lds, const Gemm g, const Sched& S, const Epi& E, const int tid_in) {
;     ...
;         for (int t = 0; t < nt; t += 2) {
;             const bool last = (t == nt - 2);
;             const char* a1 = cA + (size_t)(t + 1) * kstep;
;             const char* a2 = last ? nA : cA + (size_t)(t + 2) * kstep; const char* b2 = last ? nB : cB + (size_t)(t + 2) * kstep;
;             const char* a3 = a2 + kstep; const char* b3 = b2 + kstep;
;             if (last && has_next) S.a_ready(nxt);
;             if constexpr (SP2) {
;             PG8_LDB(B0, 0, 0); PG8_LDB(B1, 0, 1); PG8_SCHED; PG8_LDA(At, 0, 0); PG8_STAGE(PG8_SA(1, 1), a1 + hstepA, voffA);
;             PG8_WAIT_V(8); PG8_WAIT_L(0); PG8_BAR; PG8_MMA(0, 0, At, B0); PG8_MMA(0, 1, At, B1); PG8_BAR; PG8_SCHED;
;             PG8_LDA(At, 0, 1); PG8_STAGE(PG8_SB(0, 0), b2, voffB); PG8_STAGE(PG8_SB(0, 1), b2 + hstepB, voffB); PG8_STAGE(PG8_SA(0, 0), a2, voffA);
;             PG8_WAIT_V(8); PG8_WAIT_L(0); PG8_BAR; PG8_MMA(1, 0, At, B0); PG8_MMA(1, 1, At, B1); PG8_BAR; PG8_SCHED;
;             PG8_LDB(B0, 1, 0); PG8_LDB(B1, 1, 1); PG8_SCHED; PG8_LDA(At, 1, 0); PG8_STAGE(PG8_SA(0, 1), a2 + hstepA, voffA);
;             PG8_WAIT_V(8); PG8_WAIT_L(0); PG8_BAR; PG8_MMA(0, 0, At, B0); PG8_MMA(0, 1, At, B1); PG8_BAR; PG8_SCHED;
;             PG8_LDA(At, 1, 1); PG8_STAGE(PG8_SB(1, 0), b3, voffB); PG8_STAGE(PG8_SB(1, 1), b3 + hstepB, voffB); PG8_STAGE(PG8_SA(1, 0), a3, voffA);
;             PG8_WAIT_V(8); PG8_WAIT_L(0); PG8_BAR; PG8_MMA(1, 0, At, B0); PG8_MMA(1, 1, At, B1); PG8_BAR; PG8_SCHED;
	s_add_i32 s12, s68, s51
	v_lshl_add_u64 v[130:131], v[130:131], 0, s[26:27]
	s_mov_b32 m0, s12
	ds_read_b128 v[168:171], v135 offset:49152
	ds_read_b128 v[172:175], v135 offset:50176
	ds_read_b128 v[176:179], v135 offset:51200
	ds_read_b128 v[180:183], v135 offset:52224
	ds_read_b128 v[184:187], v135 offset:53248
	ds_read_b128 v[188:191], v135 offset:54272
	ds_read_b128 v[194:197], v135 offset:55296
	ds_read_b128 v[206:209], v135 offset:56320
	global_load_lds_dwordx4 v[130:131], off
	s_add_i32 m0, s12, 0x2000
	s_add_u32 s12, s44, 0x20080
	v_lshl_add_u64 v[130:131], v[210:211], 0, s[26:27]
	s_addc_u32 s13, s45, 0
	s_add_i32 s44, s69, s51
	global_load_lds_dwordx4 v[130:131], off
	v_lshl_add_u64 v[130:131], s[12:13], 0, v[200:201]
	s_mov_b32 m0, s44
	s_nop 0
	global_load_lds_dwordx4 v[130:131], off
	v_lshl_add_u64 v[130:131], s[12:13], 0, v[204:205]
	s_add_i32 m0, s44, 0x2000
	s_nop 0
	global_load_lds_dwordx4 v[130:131], off
	v_lshl_add_u64 v[130:131], v[212:213], 0, s[26:27]
	s_mov_b32 m0, s58
	s_nop 0
	global_load_lds_dwordx4 v[130:131], off
	v_lshl_add_u64 v[130:131], v[214:215], 0, s[26:27]
	s_mov_b32 m0, s59
	s_nop 0
	global_load_lds_dwordx4 v[130:131], off
	s_waitcnt vmcnt(8)
	s_waitcnt lgkmcnt(0)
	s_barrier
	s_setprio 1
	s_waitcnt lgkmcnt(0)
	v_mfma_f32_16x16x32_bf16 v[60:63], v[136:139], v[168:171], v[60:63]
	v_mfma_f32_16x16x32_bf16 v[56:59], v[144:147], v[168:171], v[56:59]
	v_mfma_f32_16x16x32_bf16 v[52:55], v[136:139], v[176:179], v[52:55]
	v_mfma_f32_16x16x32_bf16 v[44:47], v[144:147], v[176:179], v[44:47]
	v_mfma_f32_16x16x32_bf16 v[36:39], v[136:139], v[184:187], v[36:39]
	v_mfma_f32_16x16x32_bf16 v[28:31], v[144:147], v[184:187], v[28:31]
	v_mfma_f32_16x16x32_bf16 v[20:23], v[136:139], v[194:197], v[20:23]
	v_mfma_f32_16x16x32_bf16 v[12:15], v[144:147], v[194:197], v[12:15]
	v_mfma_f32_16x16x32_bf16 v[60:63], v[140:143], v[172:175], v[60:63]
	v_mfma_f32_16x16x32_bf16 v[56:59], v[148:151], v[172:175], v[56:59]
	v_mfma_f32_16x16x32_bf16 v[52:55], v[140:143], v[180:183], v[52:55]
	v_mfma_f32_16x16x32_bf16 v[44:47], v[148:151], v[180:183], v[44:47]
	v_mfma_f32_16x16x32_bf16 v[36:39], v[140:143], v[188:191], v[36:39]
	v_mfma_f32_16x16x32_bf16 v[28:31], v[148:151], v[188:191], v[28:31]
	v_mfma_f32_16x16x32_bf16 v[20:23], v[140:143], v[206:209], v[20:23]
	v_mfma_f32_16x16x32_bf16 v[12:15], v[148:151], v[206:209], v[12:15]
	s_setprio 0
	s_setprio 1
	v_mfma_f32_16x16x32_bf16 v[48:51], v[152:155], v[168:171], v[48:51]
	v_mfma_f32_16x16x32_bf16 v[40:43], v[160:163], v[168:171], v[40:43]
	v_mfma_f32_16x16x32_bf16 v[32:35], v[152:155], v[176:179], v[32:35]
	v_mfma_f32_16x16x32_bf16 v[24:27], v[160:163], v[176:179], v[24:27]
	v_mfma_f32_16x16x32_bf16 v[16:19], v[152:155], v[184:187], v[16:19]
	v_mfma_f32_16x16x32_bf16 v[8:11], v[160:163], v[184:187], v[8:11]
	v_mfma_f32_16x16x32_bf16 v[4:7], v[152:155], v[194:197], v[4:7]
	v_mfma_f32_16x16x32_bf16 v[0:3], v[160:163], v[194:197], v[0:3]
	v_mfma_f32_16x16x32_bf16 v[48:51], v[156:159], v[172:175], v[48:51]
	v_mfma_f32_16x16x32_bf16 v[40:43], v[164:167], v[172:175], v[40:43]
	v_mfma_f32_16x16x32_bf16 v[32:35], v[156:159], v[180:183], v[32:35]
	v_mfma_f32_16x16x32_bf16 v[24:27], v[164:167], v[180:183], v[24:27]
	v_mfma_f32_16x16x32_bf16 v[16:19], v[156:159], v[188:191], v[16:19]
	v_mfma_f32_16x16x32_bf16 v[8:11], v[164:167], v[188:191], v[8:11]
	v_mfma_f32_16x16x32_bf16 v[4:7], v[156:159], v[206:209], v[4:7]
	v_mfma_f32_16x16x32_bf16 v[0:3], v[164:167], v[206:209], v[0:3]
	s_setprio 0
	s_barrier
	s_add_i32 s67, s67, 2
	s_add_u32 s42, s42, 0x100
	s_addc_u32 s43, s43, 0
	s_add_u32 s65, s65, 0x100
	s_addc_u32 s66, s66, 0
	s_cmp_gt_u32 s67, 5
	.p2align 6
.LBB0_539:
	s_add_u32 s12, s42, 0xfffc0080
	s_addc_u32 s13, s43, -1
	s_add_i32 s68, 0, 0x10000
	s_cmp_eq_u32 s67, 4
	s_cselect_b32 s47, s37, s13
	s_cselect_b32 s46, s63, s12
	v_add_u32_e32 v130, s68, v133
	s_cselect_b32 s45, s31, s66
	s_cselect_b32 s44, s64, s65
	s_add_i32 s69, 0, 0x14000
	ds_read_b128 v[136:139], v130
	ds_read_b128 v[140:143], v130 offset:1024
	ds_read_b128 v[144:147], v130 offset:2048
	ds_read_b128 v[148:151], v130 offset:3072
	v_add_u32_e32 v130, s69, v133
	ds_read_b128 v[152:155], v130
	ds_read_b128 v[156:159], v130 offset:1024
	ds_read_b128 v[160:163], v130 offset:2048
	ds_read_b128 v[164:167], v130 offset:3072
	v_lshl_add_u64 v[130:131], s[42:43], 0, v[192:193]
	s_add_i32 m0, s52, 0xc000
	ds_read_b128 v[168:171], v135
	ds_read_b128 v[172:175], v135 offset:1024
	ds_read_b128 v[176:179], v135 offset:2048
	ds_read_b128 v[180:183], v135 offset:3072
	ds_read_b128 v[184:187], v135 offset:4096
	ds_read_b128 v[188:191], v135 offset:5120
	ds_read_b128 v[194:197], v135 offset:6144
	ds_read_b128 v[206:209], v135 offset:7168
	global_load_lds_dwordx4 v[130:131], off
	v_lshl_add_u64 v[130:131], s[42:43], 0, v[128:129]
	s_add_i32 m0, s52, 0xe000
	s_nop 0
	global_load_lds_dwordx4 v[130:131], off
	s_waitcnt vmcnt(8)
	s_waitcnt lgkmcnt(0)
	s_barrier
; #define PG8_STAGE(bufoff, gbase, voff) do { _Pragma("unroll") for (int _i = 0; _i < 2; ++_i) \
;         __builtin_amdgcn_global_load_lds((const unsigned*)((const char*)(gbase) + (voff)[_i]), (PG8_LAS unsigned*)(lds + (bufoff) + ldsw + _i * 8192), 16, 0, 0); } while (0)
; #define PG8_LDA(dst, b, h) do { _Pragma("unroll") for (int m = 0; m < 4; ++m) _Pragma("unroll") for (int k = 0; k < 2; ++k) dst[m][k] = *(const PG8_LAS bf16x8*)(lds + PG8_SA(b, h) + aoff + m * 2048 + k * 1024); } while (0)
; #define PG8_MMA(ai, bj, At, Bt) do { __builtin_amdgcn_s_setprio(1); _Pragma("unroll") for (int m = 0; m < 4; ++m) _Pragma("unroll") for (int n = 0; n < 2; ++n) _Pragma("unroll") for (int k = 0; k < 2; ++k) \
;         acc[ai][bj][m][n] = __builtin_amdgcn_mfma_f32_16x16x32_bf16(Bt[n][k], At[m][k], acc[ai][bj][m][n], 0, 0, 0); __builtin_amdgcn_s_setprio(0); } while (0)
; #define PG8_WAIT_V(n) asm volatile("s_waitcnt vmcnt(" #n ")" ::: "memory")
; #define PG8_WAIT_L(n) asm volatile("s_waitcnt lgkmcnt(" #n ")" ::: "memory")
; #define PG8_BAR __builtin_amdgcn_s_barrier()
; #define PG8_SCHED __builtin_amdgcn_sched_barrier(0)
; template <class Epi, class Sched, bool ALIGN_EPI = false, bool SP2 = false>
; __device__ __forceinline__ void gemm_phase(PG8_LAS unsigned char* lds, const Gemm g, const Sched& S, const Epi& E, const int tid_in) {
;     ...
;             PG8_WAIT_V(8); PG8_WAIT_L(0); PG8_BAR; PG8_MMA(0, 0, At, B0); PG8_MMA(0, 1, At, B1); PG8_BAR; PG8_SCHED;
;             PG8_LDA(At, 0, 1); PG8_STAGE(PG8_SB(0, 0), b2, voffB); PG8_STAGE(PG8_SB(0, 1), b2 + hstepB, voffB); PG8_STAGE(PG8_SA(0, 0), a2, voffA);
;             PG8_WAIT_V(8); PG8_WAIT_L(0); PG8_BAR; PG8_MMA(1, 0, At, B0); PG8_MMA(1, 1, At, B1); PG8_BAR; PG8_SCHED;
	s_setprio 1
	s_waitcnt lgkmcnt(0)
	v_mfma_f32_16x16x32_bf16 v[124:127], v[136:139], v[168:171], v[124:127]
	v_mfma_f32_16x16x32_bf16 v[120:123], v[144:147], v[168:171], v[120:123]
	v_mfma_f32_16x16x32_bf16 v[116:119], v[136:139], v[176:179], v[116:119]
	v_mfma_f32_16x16x32_bf16 v[108:111], v[144:147], v[176:179], v[108:111]
	v_mfma_f32_16x16x32_bf16 v[100:103], v[136:139], v[184:187], v[100:103]
	v_mfma_f32_16x16x32_bf16 v[92:95], v[144:147], v[184:187], v[92:95]
	v_mfma_f32_16x16x32_bf16 v[84:87], v[136:139], v[194:197], v[84:87]
	v_mfma_f32_16x16x32_bf16 v[76:79], v[144:147], v[194:197], v[76:79]
	v_mfma_f32_16x16x32_bf16 v[124:127], v[140:143], v[172:175], v[124:127]
	v_mfma_f32_16x16x32_bf16 v[120:123], v[148:151], v[172:175], v[120:123]
	v_mfma_f32_16x16x32_bf16 v[116:119], v[140:143], v[180:183], v[116:119]
	v_mfma_f32_16x16x32_bf16 v[108:111], v[148:151], v[180:183], v[108:111]
	v_mfma_f32_16x16x32_bf16 v[100:103], v[140:143], v[188:191], v[100:103]
	v_mfma_f32_16x16x32_bf16 v[92:95], v[148:151], v[188:191], v[92:95]
	v_mfma_f32_16x16x32_bf16 v[84:87], v[140:143], v[206:209], v[84:87]
	v_mfma_f32_16x16x32_bf16 v[76:79], v[148:151], v[206:209], v[76:79]
	v_mfma_f32_16x16x32_bf16 v[112:115], v[152:155], v[168:171], v[112:115]
	v_mfma_f32_16x16x32_bf16 v[104:107], v[160:163], v[168:171], v[104:107]
	v_mfma_f32_16x16x32_bf16 v[96:99], v[152:155], v[176:179], v[96:99]
	v_mfma_f32_16x16x32_bf16 v[88:91], v[160:163], v[176:179], v[88:91]
	v_mfma_f32_16x16x32_bf16 v[80:83], v[152:155], v[184:187], v[80:83]
	v_mfma_f32_16x16x32_bf16 v[72:75], v[160:163], v[184:187], v[72:75]
	v_mfma_f32_16x16x32_bf16 v[68:71], v[152:155], v[194:197], v[68:71]
	v_mfma_f32_16x16x32_bf16 v[64:67], v[160:163], v[194:197], v[64:67]
	v_mfma_f32_16x16x32_bf16 v[112:115], v[156:159], v[172:175], v[112:115]
	v_mfma_f32_16x16x32_bf16 v[104:107], v[164:167], v[172:175], v[104:107]
	v_mfma_f32_16x16x32_bf16 v[96:99], v[156:159], v[180:183], v[96:99]
	v_mfma_f32_16x16x32_bf16 v[88:91], v[164:167], v[180:183], v[88:91]
	v_mfma_f32_16x16x32_bf16 v[80:83], v[156:159], v[188:191], v[80:83]
	v_mfma_f32_16x16x32_bf16 v[72:75], v[164:167], v[188:191], v[72:75]
	v_mfma_f32_16x16x32_bf16 v[68:71], v[156:159], v[206:209], v[68:71]
	v_mfma_f32_16x16x32_bf16 v[64:67], v[164:167], v[206:209], v[64:67]
	s_setprio 0
	s_barrier
	s_add_i32 s12, s68, s51
	v_lshl_add_u64 v[130:131], s[44:45], 0, v[200:201]
	s_mov_b32 m0, s12
	ds_read_b128 v[168:171], v135 offset:16384
	ds_read_b128 v[172:175], v135 offset:17408
	ds_read_b128 v[176:179], v135 offset:18432
	ds_read_b128 v[180:183], v135 offset:19456
	ds_read_b128 v[184:187], v135 offset:20480
	ds_read_b128 v[188:191], v135 offset:21504
	ds_read_b128 v[194:197], v135 offset:22528
	ds_read_b128 v[206:209], v135 offset:23552
	global_load_lds_dwordx4 v[130:131], off
	s_add_i32 m0, s12, 0x2000
	s_add_u32 s12, s44, 0x20000
	v_lshl_add_u64 v[210:211], s[44:45], 0, v[204:205]
	s_addc_u32 s13, s45, 0
	s_add_i32 s68, s69, s51
	global_load_lds_dwordx4 v[210:211], off
	v_lshl_add_u64 v[212:213], s[12:13], 0, v[200:201]
	s_mov_b32 m0, s68
	v_lshl_add_u64 v[214:215], s[46:47], 0, v[202:203]
	global_load_lds_dwordx4 v[212:213], off
	v_lshl_add_u64 v[212:213], s[12:13], 0, v[204:205]
	s_add_i32 m0, s68, 0x2000
	s_nop 0
	global_load_lds_dwordx4 v[212:213], off
	v_lshl_add_u64 v[212:213], s[46:47], 0, v[198:199]
	s_mov_b32 m0, s52
	s_nop 0
	global_load_lds_dwordx4 v[212:213], off
	s_mov_b32 m0, s53
	s_nop 0
	global_load_lds_dwordx4 v[214:215], off
	s_waitcnt vmcnt(8)
	s_waitcnt lgkmcnt(0)
	s_barrier
	s_setprio 1
	s_waitcnt lgkmcnt(0)
	v_mfma_f32_16x16x32_bf16 v[60:63], v[136:139], v[168:171], v[60:63]
	v_mfma_f32_16x16x32_bf16 v[56:59], v[144:147], v[168:171], v[56:59]
	v_mfma_f32_16x16x32_bf16 v[52:55], v[136:139], v[176:179], v[52:55]
	v_mfma_f32_16x16x32_bf16 v[44:47], v[144:147], v[176:179], v[44:47]
	v_mfma_f32_16x16x32_bf16 v[36:39], v[136:139], v[184:187], v[36:39]
	v_mfma_f32_16x16x32_bf16 v[28:31], v[144:147], v[184:187], v[28:31]
	v_mfma_f32_16x16x32_bf16 v[20:23], v[136:139], v[194:197], v[20:23]
	v_mfma_f32_16x16x32_bf16 v[12:15], v[144:147], v[194:197], v[12:15]
	v_mfma_f32_16x16x32_bf16 v[60:63], v[140:143], v[172:175], v[60:63]
	v_mfma_f32_16x16x32_bf16 v[56:59], v[148:151], v[172:175], v[56:59]
	v_mfma_f32_16x16x32_bf16 v[52:55], v[140:143], v[180:183], v[52:55]
	v_mfma_f32_16x16x32_bf16 v[44:47], v[148:151], v[180:183], v[44:47]
	v_mfma_f32_16x16x32_bf16 v[36:39], v[140:143], v[188:191], v[36:39]
	v_mfma_f32_16x16x32_bf16 v[28:31], v[148:151], v[188:191], v[28:31]
	v_mfma_f32_16x16x32_bf16 v[20:23], v[140:143], v[206:209], v[20:23]
	v_mfma_f32_16x16x32_bf16 v[12:15], v[148:151], v[206:209], v[12:15]
	v_mfma_f32_16x16x32_bf16 v[48:51], v[152:155], v[168:171], v[48:51]
	v_mfma_f32_16x16x32_bf16 v[40:43], v[160:163], v[168:171], v[40:43]
	v_mfma_f32_16x16x32_bf16 v[32:35], v[152:155], v[176:179], v[32:35]
	v_mfma_f32_16x16x32_bf16 v[24:27], v[160:163], v[176:179], v[24:27]
	v_mfma_f32_16x16x32_bf16 v[16:19], v[152:155], v[184:187], v[16:19]
	v_mfma_f32_16x16x32_bf16 v[8:11], v[160:163], v[184:187], v[8:11]
	v_mfma_f32_16x16x32_bf16 v[4:7], v[152:155], v[194:197], v[4:7]
	v_mfma_f32_16x16x32_bf16 v[0:3], v[160:163], v[194:197], v[0:3]
	v_mfma_f32_16x16x32_bf16 v[48:51], v[156:159], v[172:175], v[48:51]
	v_mfma_f32_16x16x32_bf16 v[40:43], v[164:167], v[172:175], v[40:43]
	v_mfma_f32_16x16x32_bf16 v[32:35], v[156:159], v[180:183], v[32:35]
	v_mfma_f32_16x16x32_bf16 v[24:27], v[164:167], v[180:183], v[24:27]
	v_mfma_f32_16x16x32_bf16 v[16:19], v[156:159], v[188:191], v[16:19]
	v_mfma_f32_16x16x32_bf16 v[8:11], v[164:167], v[188:191], v[8:11]
	v_mfma_f32_16x16x32_bf16 v[4:7], v[156:159], v[206:209], v[4:7]
	v_mfma_f32_16x16x32_bf16 v[0:3], v[164:167], v[206:209], v[0:3]
	s_setprio 0
	s_barrier
; #define PG8_STAGE(bufoff, gbase, voff) do { _Pragma("unroll") for (int _i = 0; _i < 2; ++_i) \
;         __builtin_amdgcn_global_load_lds((const unsigned*)((const char*)(gbase) + (voff)[_i]), (PG8_LAS unsigned*)(lds + (bufoff) + ldsw + _i * 8192), 16, 0, 0); } while (0)
; #define PG8_LDA(dst, b, h) do { _Pragma("unroll") for (int m = 0; m < 4; ++m) _Pragma("unroll") for (int k = 0; k < 2; ++k) dst[m][k] = *(const PG8_LAS bf16x8*)(lds + PG8_SA(b, h) + aoff + m * 2048 + k * 1024); } while (0)
; #define PG8_LDB(dst, b, h) do { _Pragma("unroll") for (int n = 0; n < 2; ++n) _Pragma("unroll") for (int k = 0; k < 2; ++k) dst[n][k] = *(const PG8_LAS bf16x8*)(lds + PG8_SB(b, h) + boff + n * 2048 + k * 1024); } while (0)
; #define PG8_MMA(ai, bj, At, Bt) do { __builtin_amdgcn_s_setprio(1); _Pragma("unroll") for (int m = 0; m < 4; ++m) _Pragma("unroll") for (int n = 0; n < 2; ++n) _Pragma("unroll") for (int k = 0; k < 2; ++k) \
;         acc[ai][bj][m][n] = __builtin_amdgcn_mfma_f32_16x16x32_bf16(Bt[n][k], At[m][k], acc[ai][bj][m][n], 0, 0, 0); __builtin_amdgcn_s_setprio(0); } while (0)
; #define PG8_WAIT_V(n) asm volatile("s_waitcnt vmcnt(" #n ")" ::: "memory")
; #define PG8_WAIT_L(n) asm volatile("s_waitcnt lgkmcnt(" #n ")" ::: "memory")
; #define PG8_BAR __builtin_amdgcn_s_barrier()
; #define PG8_SCHED __builtin_amdgcn_sched_barrier(0)
; template <class Epi, class Sched, bool ALIGN_EPI = false, bool SP2 = false>
; __device__ __forceinline__ void gemm_phase(PG8_LAS unsigned char* lds, const Gemm g, const Sched& S, const Epi& E, const int tid_in) {
;     ...
;             PG8_LDB(B0, 1, 0); PG8_LDB(B1, 1, 1); PG8_SCHED; PG8_LDA(At, 1, 0); PG8_STAGE(PG8_SA(0, 1), a2 + hstepA, voffA);
;             PG8_WAIT_V(8); PG8_WAIT_L(0); PG8_BAR; PG8_MMA(0, 0, At, B0); PG8_MMA(0, 1, At, B1); PG8_BAR; PG8_SCHED;
	s_add_i32 s68, 0, 0x18000
	s_add_i32 s69, 0, 0x1c000
	v_add_u32_e32 v148, s68, v133
	v_add_u32_e32 v164, s69, v133
	ds_read_b128 v[136:139], v148
	ds_read_b128 v[140:143], v148 offset:1024
	ds_read_b128 v[144:147], v148 offset:2048
	ds_read_b128 v[148:151], v148 offset:3072
	ds_read_b128 v[152:155], v164
	ds_read_b128 v[156:159], v164 offset:1024
	ds_read_b128 v[160:163], v164 offset:2048
	ds_read_b128 v[164:167], v164 offset:3072
	s_add_u32 s12, s46, 0x40000
	s_addc_u32 s13, s47, 0
	s_mov_b32 m0, s54
	v_lshl_add_u64 v[216:217], s[12:13], 0, v[198:199]
	ds_read_b128 v[168:171], v135 offset:32768
	ds_read_b128 v[172:175], v135 offset:33792
	ds_read_b128 v[176:179], v135 offset:34816
	ds_read_b128 v[180:183], v135 offset:35840
	ds_read_b128 v[184:187], v135 offset:36864
	ds_read_b128 v[188:191], v135 offset:37888
	ds_read_b128 v[194:197], v135 offset:38912
	ds_read_b128 v[206:209], v135 offset:39936
	global_load_lds_dwordx4 v[216:217], off
	v_lshl_add_u64 v[216:217], s[12:13], 0, v[202:203]
	s_mov_b32 m0, s55
	s_nop 0
	global_load_lds_dwordx4 v[216:217], off
	s_waitcnt vmcnt(8)
	s_waitcnt lgkmcnt(0)
	s_barrier
	s_setprio 1
	s_waitcnt lgkmcnt(0)
	v_mfma_f32_16x16x32_bf16 v[124:127], v[136:139], v[168:171], v[124:127]
	v_mfma_f32_16x16x32_bf16 v[120:123], v[144:147], v[168:171], v[120:123]
	v_mfma_f32_16x16x32_bf16 v[116:119], v[136:139], v[176:179], v[116:119]
	v_mfma_f32_16x16x32_bf16 v[108:111], v[144:147], v[176:179], v[108:111]
	v_mfma_f32_16x16x32_bf16 v[100:103], v[136:139], v[184:187], v[100:103]
	v_mfma_f32_16x16x32_bf16 v[92:95], v[144:147], v[184:187], v[92:95]
	v_mfma_f32_16x16x32_bf16 v[84:87], v[136:139], v[194:197], v[84:87]
	v_mfma_f32_16x16x32_bf16 v[76:79], v[144:147], v[194:197], v[76:79]
	v_mfma_f32_16x16x32_bf16 v[124:127], v[140:143], v[172:175], v[124:127]
	v_mfma_f32_16x16x32_bf16 v[120:123], v[148:151], v[172:175], v[120:123]
	v_mfma_f32_16x16x32_bf16 v[116:119], v[140:143], v[180:183], v[116:119]
	v_mfma_f32_16x16x32_bf16 v[108:111], v[148:151], v[180:183], v[108:111]
	v_mfma_f32_16x16x32_bf16 v[100:103], v[140:143], v[188:191], v[100:103]
	v_mfma_f32_16x16x32_bf16 v[92:95], v[148:151], v[188:191], v[92:95]
	v_mfma_f32_16x16x32_bf16 v[84:87], v[140:143], v[206:209], v[84:87]
	v_mfma_f32_16x16x32_bf16 v[76:79], v[148:151], v[206:209], v[76:79]
	v_mfma_f32_16x16x32_bf16 v[112:115], v[152:155], v[168:171], v[112:115]
	v_mfma_f32_16x16x32_bf16 v[104:107], v[160:163], v[168:171], v[104:107]
	v_mfma_f32_16x16x32_bf16 v[96:99], v[152:155], v[176:179], v[96:99]
	v_mfma_f32_16x16x32_bf16 v[88:91], v[160:163], v[176:179], v[88:91]
	v_mfma_f32_16x16x32_bf16 v[80:83], v[152:155], v[184:187], v[80:83]
	v_mfma_f32_16x16x32_bf16 v[72:75], v[160:163], v[184:187], v[72:75]
	v_mfma_f32_16x16x32_bf16 v[68:71], v[152:155], v[194:197], v[68:71]
	v_mfma_f32_16x16x32_bf16 v[64:67], v[160:163], v[194:197], v[64:67]
	v_mfma_f32_16x16x32_bf16 v[112:115], v[156:159], v[172:175], v[112:115]
	v_mfma_f32_16x16x32_bf16 v[104:107], v[164:167], v[172:175], v[104:107]
	v_mfma_f32_16x16x32_bf16 v[96:99], v[156:159], v[180:183], v[96:99]
	v_mfma_f32_16x16x32_bf16 v[88:91], v[164:167], v[180:183], v[88:91]
	v_mfma_f32_16x16x32_bf16 v[80:83], v[156:159], v[188:191], v[80:83]
	v_mfma_f32_16x16x32_bf16 v[72:75], v[164:167], v[188:191], v[72:75]
	v_mfma_f32_16x16x32_bf16 v[68:71], v[156:159], v[206:209], v[68:71]
	v_mfma_f32_16x16x32_bf16 v[64:67], v[164:167], v[206:209], v[64:67]
	s_setprio 0
	s_barrier
; #define PG8_STAGE(bufoff, gbase, voff) do { _Pragma("unroll") for (int _i = 0; _i < 2; ++_i) \
;         __builtin_amdgcn_global_load_lds((const unsigned*)((const char*)(gbase) + (voff)[_i]), (PG8_LAS unsigned*)(lds + (bufoff) + ldsw + _i * 8192), 16, 0, 0); } while (0)
; #define PG8_LDA(dst, b, h) do { _Pragma("unroll") for (int m = 0; m < 4; ++m) _Pragma("unroll") for (int k = 0; k < 2; ++k) dst[m][k] = *(const PG8_LAS bf16x8*)(lds + PG8_SA(b, h) + aoff + m * 2048 + k * 1024); } while (0)
; #define PG8_MMA(ai, bj, At, Bt) do { __builtin_amdgcn_s_setprio(1); _Pragma("unroll") for (int m = 0; m < 4; ++m) _Pragma("unroll") for (int n = 0; n < 2; ++n) _Pragma("unroll") for (int k = 0; k < 2; ++k) \
;         acc[ai][bj][m][n] = __builtin_amdgcn_mfma_f32_16x16x32_bf16(Bt[n][k], At[m][k], acc[ai][bj][m][n], 0, 0, 0); __builtin_amdgcn_s_setprio(0); } while (0)
; #define PG8_WAIT_V(n) asm volatile("s_waitcnt vmcnt(" #n ")" ::: "memory")
; #define PG8_WAIT_L(n) asm volatile("s_waitcnt lgkmcnt(" #n ")" ::: "memory")
; #define PG8_BAR __builtin_amdgcn_s_barrier()
; #define PG8_SCHED __builtin_amdgcn_sched_barrier(0)
; template <class Epi, class Sched, bool ALIGN_EPI = false, bool SP2 = false>
; __device__ __forceinline__ void gemm_phase(PG8_LAS unsigned char* lds, const Gemm g, const Sched& S, const Epi& E, const int tid_in) {
;     ...
;             PG8_LDA(At, 1, 1); PG8_STAGE(PG8_SB(1, 0), b3, voffB); PG8_STAGE(PG8_SB(1, 1), b3 + hstepB, voffB); PG8_STAGE(PG8_SA(1, 0), a3, voffA);
;             PG8_WAIT_V(8); PG8_WAIT_L(0); PG8_BAR; PG8_MMA(1, 0, At, B0); PG8_MMA(1, 1, At, B1); PG8_BAR; PG8_SCHED;
;     ...
;         if constexpr (ALIGN_EPI) { if (wr == 0) PG8_BAR; }
	s_add_i32 s12, s68, s51
	v_lshl_add_u64 v[130:131], v[130:131], 0, s[26:27]
	s_mov_b32 m0, s12
	ds_read_b128 v[168:171], v135 offset:49152
	ds_read_b128 v[172:175], v135 offset:50176
	ds_read_b128 v[176:179], v135 offset:51200
	ds_read_b128 v[180:183], v135 offset:52224
	ds_read_b128 v[184:187], v135 offset:53248
	ds_read_b128 v[188:191], v135 offset:54272
	ds_read_b128 v[194:197], v135 offset:55296
	ds_read_b128 v[206:209], v135 offset:56320
	global_load_lds_dwordx4 v[130:131], off
	s_add_i32 m0, s12, 0x2000
	s_add_u32 s12, s44, 0x20080
	v_lshl_add_u64 v[130:131], v[210:211], 0, s[26:27]
	s_addc_u32 s13, s45, 0
	s_add_i32 s44, s69, s51
	global_load_lds_dwordx4 v[130:131], off
	v_lshl_add_u64 v[130:131], s[12:13], 0, v[200:201]
	s_mov_b32 m0, s44
	s_nop 0
	global_load_lds_dwordx4 v[130:131], off
	v_lshl_add_u64 v[130:131], s[12:13], 0, v[204:205]
	s_add_i32 m0, s44, 0x2000
	s_nop 0
	global_load_lds_dwordx4 v[130:131], off
	v_lshl_add_u64 v[130:131], v[212:213], 0, s[26:27]
	s_mov_b32 m0, s58
	s_nop 0
	global_load_lds_dwordx4 v[130:131], off
	v_lshl_add_u64 v[130:131], v[214:215], 0, s[26:27]
	s_mov_b32 m0, s59
	s_nop 0
	global_load_lds_dwordx4 v[130:131], off
	s_waitcnt vmcnt(8)
	s_waitcnt lgkmcnt(0)
	s_barrier
	s_setprio 1
	s_waitcnt lgkmcnt(0)
	v_mfma_f32_16x16x32_bf16 v[60:63], v[136:139], v[168:171], v[60:63]
	v_mfma_f32_16x16x32_bf16 v[56:59], v[144:147], v[168:171], v[56:59]
	v_mfma_f32_16x16x32_bf16 v[52:55], v[136:139], v[176:179], v[52:55]
	v_mfma_f32_16x16x32_bf16 v[44:47], v[144:147], v[176:179], v[44:47]
	v_mfma_f32_16x16x32_bf16 v[36:39], v[136:139], v[184:187], v[36:39]
	v_mfma_f32_16x16x32_bf16 v[28:31], v[144:147], v[184:187], v[28:31]
	v_mfma_f32_16x16x32_bf16 v[20:23], v[136:139], v[194:197], v[20:23]
	v_mfma_f32_16x16x32_bf16 v[12:15], v[144:147], v[194:197], v[12:15]
	v_mfma_f32_16x16x32_bf16 v[60:63], v[140:143], v[172:175], v[60:63]
	v_mfma_f32_16x16x32_bf16 v[56:59], v[148:151], v[172:175], v[56:59]
	v_mfma_f32_16x16x32_bf16 v[52:55], v[140:143], v[180:183], v[52:55]
	v_mfma_f32_16x16x32_bf16 v[44:47], v[148:151], v[180:183], v[44:47]
	v_mfma_f32_16x16x32_bf16 v[36:39], v[140:143], v[188:191], v[36:39]
	v_mfma_f32_16x16x32_bf16 v[28:31], v[148:151], v[188:191], v[28:31]
	v_mfma_f32_16x16x32_bf16 v[20:23], v[140:143], v[206:209], v[20:23]
	v_mfma_f32_16x16x32_bf16 v[12:15], v[148:151], v[206:209], v[12:15]
	v_mfma_f32_16x16x32_bf16 v[48:51], v[152:155], v[168:171], v[48:51]
	v_mfma_f32_16x16x32_bf16 v[40:43], v[160:163], v[168:171], v[40:43]
	v_mfma_f32_16x16x32_bf16 v[32:35], v[152:155], v[176:179], v[32:35]
	v_mfma_f32_16x16x32_bf16 v[24:27], v[160:163], v[176:179], v[24:27]
	v_mfma_f32_16x16x32_bf16 v[16:19], v[152:155], v[184:187], v[16:19]
	v_mfma_f32_16x16x32_bf16 v[8:11], v[160:163], v[184:187], v[8:11]
	v_mfma_f32_16x16x32_bf16 v[4:7], v[152:155], v[194:197], v[4:7]
	v_mfma_f32_16x16x32_bf16 v[0:3], v[160:163], v[194:197], v[0:3]
	v_mfma_f32_16x16x32_bf16 v[48:51], v[156:159], v[172:175], v[48:51]
	v_mfma_f32_16x16x32_bf16 v[40:43], v[164:167], v[172:175], v[40:43]
	v_mfma_f32_16x16x32_bf16 v[32:35], v[156:159], v[180:183], v[32:35]
	v_mfma_f32_16x16x32_bf16 v[24:27], v[164:167], v[180:183], v[24:27]
	v_mfma_f32_16x16x32_bf16 v[16:19], v[156:159], v[188:191], v[16:19]
	v_mfma_f32_16x16x32_bf16 v[8:11], v[164:167], v[188:191], v[8:11]
	v_mfma_f32_16x16x32_bf16 v[4:7], v[156:159], v[206:209], v[4:7]
	v_mfma_f32_16x16x32_bf16 v[0:3], v[164:167], v[206:209], v[0:3]
	s_setprio 0
	s_barrier
	s_add_i32 s67, s67, 2
	s_add_u32 s42, s42, 0x100
	s_addc_u32 s43, s43, 0
	s_add_u32 s65, s65, 0x100
	s_addc_u32 s66, s66, 0
	s_cmp_gt_u32 s67, 5
	s_cbranch_scc0 .LBB0_539
	s_and_b64 vcc, exec, s[22:23]
	s_cbranch_vccz .LBB0_542
	s_barrier

; __device__ __forceinline__ void attn_unit(const bf16_t* __restrict__ Qs, const bf16_t* __restrict__ Kn, const bf16_t* __restrict__ Kr, const bf16_t* __restrict__ Vs, bf16_t* Os, int q0, int Lp, char* lds, const int tid) {
;     const int wid = tid >> 6, lane = tid & 63, r32 = lane & 31, hi = lane >> 5; const int wu = __builtin_amdgcn_readfirstlane(wid);
;     char* V_lds = lds; char* K_lds = lds + 2 * SHM_V;
;     float* ws = (float*)(lds + 2 * SHM_V + 2 * SHM_K) + wid * 64; float* li_l = ws; float* al_l = ws + 32;
;     float m_reg = -1e30f, l_reg = 0; f32x16 o[4] = {}; bf16x8 qr[12 - NQL];
;     char* qslot = lds + SHM_QR + wid * (NQL * 1024) + lane * 16;
;     int kb[4];
; #pragma unroll
;     for (int c = 0; c < 4; ++c) kb[c] = KSWZ(r32, c * 32 + hi * 16);
;     const bf16_t* ksrc[3];
; #pragma unroll
;     for (int n = 0; n < 3; ++n) { const int p = (wid * 3 + n) * 64 + lane, row = p / 24, cp = p % 24, c = (cp & 24) | ((cp ^ row) & 7);
;         ksrc[n] = c < 16 ? Kn + (size_t)row * 2048 + c * 8 : Kr + (size_t)row * 64 + (c - 16) * 8; }
;     unsigned vsrc[2];
; #pragma unroll
;     for (int n = 0; n < 2; ++n) { const int p = (wid * 2 + n) * 64 + lane, sub = p >> 5, elt = (p & 31) * 8, kk = (sub >> 2) * 8 + (elt >> 5), k = (kk & ~0xC) | ((kk & 4) << 1) | ((kk & 8) >> 1), c = (sub & 3) * 32 + (elt & 31);
;         vsrc[n] = (unsigned)(k * 2048 + c) * 2u; }
;     const unsigned lK = (unsigned)(uintptr_t)K_lds + wu * 3072, lV = (unsigned)(uintptr_t)V_lds + wu * 2048;
;     bool krope[3];
; #pragma unroll
; __device__ __forceinline__ void attn_phase(const Frame& F, const bf16_t* Q, const bf16_t* KN, const bf16_t* KR, const bf16_t* V, bf16_t* O) {
;     ...
;         if (exact) { smp = i >= np; u = !smp ? (i < 8 ? c + 256 * i : 2048 + c) : (c < 64 ? c + 64 * (i - np) : 448 + (c - 64) + 192 * (i - np)); }
;         else { const int g = c + F.G * i; smp = g >= NUP; u = smp ? g - NUP : g; }
;         const int nqb = smp ? NQS : NQP, Lp = smp ? LP_S : LP_P;
;         const int qb = u % nqb, sh = u / nqb, head = sh % MH, seq = sh / MH; const size_t rb = (smp ? (size_t)ROWS0 : 0) + (size_t)seq * Lp;
;         attn_unit(Q + rb * 3072 + head * MQK, KN + rb * 2048 + head * MNOPE, KR + rb * 64, V + rb * 2048 + head * MV, O + rb * 2048 + head * MV, qb * 256, Lp, F.ldsg, F.tid);
.LBB0_621:
	s_and_b64 s[22:23], s[0:1], exec
	s_cselect_b32 s13, 17, 33
	v_cvt_f32_ubyte0_e32 v0, s13
	v_rcp_iflag_f32_e32 v0, v0
	s_movk_i32 s22, 0x2080
	s_cselect_b32 s62, 0x1080, s22
	s_sub_i32 s30, 0, s13
	v_mul_f32_e32 v0, 0x4f7ffffe, v0
	v_cvt_u32_f32_e32 v0, v0
	s_abs_i32 s23, s12
	s_ashr_i32 s22, s12, 31
	s_movk_i32 s64, 0xff00
	v_readfirstlane_b32 s31, v0
	s_mul_i32 s30, s30, s31
	s_mul_hi_u32 s30, s31, s30
	s_add_i32 s31, s31, s30
	s_mul_hi_u32 s30, s23, s31
	s_mul_i32 s31, s30, s13
	s_sub_i32 s23, s23, s31
	s_add_i32 s42, s30, 1
	s_sub_i32 s31, s23, s13
	s_cmp_ge_u32 s23, s13
	s_cselect_b32 s30, s42, s30
	s_cselect_b32 s23, s31, s23
	s_add_i32 s31, s30, 1
	s_cmp_ge_u32 s23, s13
	s_cselect_b32 s23, s31, s30
	s_xor_b32 s23, s23, s22
	s_sub_i32 s22, s23, s22
	s_mul_i32 s13, s22, s13
	s_sub_i32 s48, s12, s13
	s_ashr_i32 s12, s22, 31
	s_lshr_b32 s12, s12, 28
	s_add_i32 s12, s22, s12
	s_ashr_i32 s13, s12, 4
	s_and_b32 s12, s12, -16
	s_sub_i32 s46, s22, s12
	s_and_b64 s[0:1], s[0:1], exec
	s_cselect_b32 s0, 0x8200, 0
	s_mul_hi_i32 s1, s13, s62
	s_mul_i32 s13, s13, s62
	s_add_u32 s12, s13, s0
	s_addc_u32 s13, s1, 0
	s_mul_i32 s0, s13, 0x1800
	s_mul_hi_u32 s1, s12, 0x1800
	s_add_i32 s1, s1, s0
	s_mul_i32 s0, s12, 0x1800
	s_add_u32 s22, s52, s0
	s_mul_i32 s0, s46, 0xc0
	s_addc_u32 s23, s53, s1
	s_ashr_i32 s1, s0, 31
	s_lshl_b64 s[0:1], s[0:1], 1
	s_add_u32 s42, s22, s0
	s_addc_u32 s43, s23, s1
	s_lshl_b64 s[22:23], s[12:13], 11
	s_lshl_b64 s[30:31], s[12:13], 12
	s_add_u32 s47, s54, s30
	s_addc_u32 s49, s55, s31
	s_lshl_b32 s0, s46, 7
	s_ashr_i32 s1, s0, 31
	s_lshl_b64 s[0:1], s[0:1], 1
	s_add_u32 s46, s47, s0
	s_addc_u32 s47, s49, s1
	s_lshl_b64 s[12:13], s[12:13], 7
	s_add_u32 s12, s60, s12
	s_addc_u32 s13, s61, s13
	v_lshl_add_u64 v[2:3], s[12:13], 0, v[198:199]
	v_lshl_add_u64 v[0:1], s[46:47], 0, v[200:201]
	v_lshl_add_u64 v[2:3], v[2:3], 0, v[192:193]
	s_mov_b32 s65, -1
	v_lshl_add_u64 v[0:1], v[0:1], 0, v[192:193]
	v_lshl_add_u64 v[2:3], v[2:3], 0, s[64:65]
	s_add_u32 s30, s11, s30
	v_cndmask_b32_e64 v229, v3, v1, s[34:35]
	v_cndmask_b32_e64 v228, v2, v0, s[34:35]
	v_mov_b32_e32 v217, v193
	v_lshl_add_u64 v[2:3], s[12:13], 0, v[202:203]
	s_addc_u32 s31, s18, s31
	v_lshl_add_u64 v[0:1], s[46:47], 0, v[204:205]
	v_lshl_add_u64 v[2:3], v[2:3], 0, v[216:217]
	s_add_u32 s30, s30, s0
	v_readfirstlane_b32 s49, v191
	v_lshl_add_u64 v[0:1], v[0:1], 0, v[216:217]
	v_lshl_add_u64 v[2:3], v[2:3], 0, s[64:65]
	s_addc_u32 s31, s31, s1
	v_cndmask_b32_e64 v231, v3, v1, s[36:37]
	v_cndmask_b32_e64 v230, v2, v0, s[36:37]
	v_mov_b32_e32 v219, v193
	v_lshl_add_u64 v[2:3], s[12:13], 0, v[206:207]
	s_lshl_b32 s12, s49, 11
	s_add_i32 s13, 0, 0x8000
	v_lshl_add_u64 v[0:1], s[46:47], 0, v[208:209]
	v_lshl_add_u64 v[2:3], v[2:3], 0, v[218:219]
	s_cmp_lg_u32 s13, -1
	v_lshl_add_u64 v[0:1], v[0:1], 0, v[218:219]
	v_lshl_add_u64 v[2:3], v[2:3], 0, s[64:65]
	s_mul_i32 s65, s49, 0xc00
	s_cselect_b32 s13, s13, 0
	v_mov_b32_e32 v221, v193
	v_cndmask_b32_e64 v233, v3, v1, s[38:39]
	v_cndmask_b32_e64 v232, v2, v0, s[38:39]
	s_add_i32 s65, s65, s13
	v_lshl_add_u64 v[0:1], v[228:229], 0, v[220:221]
	v_mov_b32_e32 v223, v193
	s_add_i32 s66, s65, 0x6000
	s_mov_b32 s13, m0
	s_mov_b32 m0, s66
	s_nop 0
	global_load_lds_dwordx4 v[0:1], off
	s_mov_b32 m0, s13
	v_lshl_add_u64 v[0:1], v[230:231], 0, v[222:223]
	v_mov_b32_e32 v225, v193
	s_add_i32 s67, s65, 0x6400
	s_mov_b32 s13, m0
	s_mov_b32 m0, s67
	s_nop 0
	global_load_lds_dwordx4 v[0:1], off
	s_mov_b32 m0, s13
	v_lshl_add_u64 v[0:1], v[232:233], 0, v[224:225]
	s_add_i32 s68, s65, 0x6800
	s_mov_b32 s13, m0
	s_mov_b32 m0, s68
	s_nop 0
	global_load_lds_dwordx4 v[0:1], off
	s_mov_b32 m0, s13
	v_lshlrev_b32_e32 v0, 5, v191
	s_cmp_lg_u32 0, -1
	v_lshl_add_u32 v217, s48, 8, v0
	s_cselect_b32 s13, 0, 0
	v_or_b32_e32 v2, v217, v190
	v_mov_b64_e32 v[0:1], s[42:43]
	s_add_i32 s69, s12, s13
	s_mov_b32 s12, m0
	s_mov_b32 m0, s69
	s_nop 0
	global_load_lds_dwordx4 v211, s[30:31]
	s_mov_b32 m0, s12
	v_mov_b32_e32 v227, v193
	v_mad_i64_i32 v[0:1], s[12:13], v2, s77, v[0:1]
	s_add_i32 s70, s69, 0x400
	s_mov_b32 s12, m0
	s_mov_b32 m0, s70
	s_nop 0
	global_load_lds_dwordx4 v213, s[30:31]
	s_mov_b32 m0, s12
	v_lshl_add_u64 v[0:1], v[0:1], 0, v[226:227]
	global_load_dwordx4 v[186:189], v[0:1], off
	global_load_dwordx4 v[182:185], v[0:1], off offset:32
	global_load_dwordx4 v[178:181], v[0:1], off offset:64
	global_load_dwordx4 v[174:177], v[0:1], off offset:96
	global_load_dwordx4 v[170:173], v[0:1], off offset:128
	global_load_dwordx4 v[166:169], v[0:1], off offset:160
	global_load_dwordx4 v[162:165], v[0:1], off offset:192
	global_load_dwordx4 v[158:161], v[0:1], off offset:224
	global_load_dwordx4 v[154:157], v[0:1], off offset:256
	global_load_dwordx4 v[150:153], v[0:1], off offset:288
	global_load_dwordx4 v[146:149], v[0:1], off offset:320
	global_load_dwordx4 v[142:145], v[0:1], off offset:352
	s_waitcnt vmcnt(0)
	s_lshr_b32 s71, s62, 6
	s_waitcnt lgkmcnt(0)
	s_barrier
; #define WAITV(N) asm volatile("s_waitcnt vmcnt(" #N ")" ::: "memory")
; #define LBAR() asm volatile("s_waitcnt lgkmcnt(0)\n\ts_barrier" ::: "memory")
; __device__ __forceinline__ void attn_unit(const bf16_t* __restrict__ Qs, const bf16_t* __restrict__ Kn, const bf16_t* __restrict__ Kr, const bf16_t* __restrict__ Vs, bf16_t* Os, int q0, int Lp, char* lds, const int tid) {
;     ...
;     float m_reg = -1e30f, l_reg = 0; f32x16 o[4] = {}; bf16x8 qr[12 - NQL];
;     ...
;     f32x16 pA0, pA1, pB0, pB1; float alA = 1.f, alB; bf16x8 pa[4]; s16x4 vl[4], vh[4]; const int NT = Lp / KVBLK;
;     static_assert(PADF >= KVBLK && PADF < 2 * KVBLK, "tile 0 fully masked, tile 1 partly");
;     ...
;     pA0 = f32x16{};
; #pragma unroll
;     for (int r = 0; r < 16; ++r) pA1[r] = -INFINITY;
;     WAITV(0); LBAR();
;     for (int j = 1; j + 1 < NT; j += 2) {
	s_add_i32 s72, s65, 0x400
	s_add_i32 s73, s65, 0x800
	s_add_i32 s64, s69, 0x4000
	s_add_i32 s63, s69, 0x4400
	v_mov_b32_e32 v14, v193
	v_mov_b32_e32 v15, v193
	s_add_u32 s42, s30, 0x80000
	v_mov_b32_e32 v0, v193
	v_mov_b32_e32 v1, v193
	v_mov_b32_e32 v2, v193
	v_mov_b32_e32 v3, v193
	v_mov_b32_e32 v4, v193
	v_mov_b32_e32 v5, v193
	v_mov_b32_e32 v6, v193
	v_mov_b32_e32 v7, v193
	v_mov_b32_e32 v8, v193
	v_mov_b32_e32 v9, v193
	v_mov_b32_e32 v10, v193
	v_mov_b32_e32 v11, v193
	v_mov_b32_e32 v12, v193
	v_mov_b32_e32 v13, v193
	s_waitcnt vmcnt(0) lgkmcnt(0)
	v_mov_b32_e32 v64, 0xff800000
	v_mov_b32_e32 v219, 0
	v_mov_b64_e32 v[62:63], v[14:15]
	v_mov_b64_e32 v[46:47], v[14:15]
	v_mov_b64_e32 v[30:31], v[14:15]
	s_addc_u32 s43, s31, 0
	v_mov_b32_e32 v221, 1.0
	v_mov_b32_e32 v130, 0xf149f2ca
	s_mov_b64 s[46:47], 2
	v_mov_b64_e32 v[60:61], v[12:13]
	v_mov_b64_e32 v[58:59], v[10:11]
	v_mov_b64_e32 v[56:57], v[8:9]
	v_mov_b64_e32 v[54:55], v[6:7]
	v_mov_b64_e32 v[52:53], v[4:5]
	v_mov_b64_e32 v[50:51], v[2:3]
	v_mov_b64_e32 v[48:49], v[0:1]
	v_mov_b64_e32 v[44:45], v[12:13]
	v_mov_b64_e32 v[42:43], v[10:11]
	v_mov_b64_e32 v[40:41], v[8:9]
	v_mov_b64_e32 v[38:39], v[6:7]
	v_mov_b64_e32 v[36:37], v[4:5]
	v_mov_b64_e32 v[34:35], v[2:3]
	v_mov_b64_e32 v[32:33], v[0:1]
	v_mov_b64_e32 v[28:29], v[12:13]
	v_mov_b64_e32 v[26:27], v[10:11]
	v_mov_b64_e32 v[24:25], v[8:9]
	v_mov_b64_e32 v[22:23], v[6:7]
	v_mov_b64_e32 v[20:21], v[4:5]
	v_mov_b64_e32 v[18:19], v[2:3]
	v_mov_b64_e32 v[16:17], v[0:1]
	v_mov_b32_e32 v94, 0
	v_mov_b32_e32 v95, v219
	v_mov_b32_e32 v96, v219
	v_mov_b32_e32 v97, v219
	v_mov_b32_e32 v98, v219
	v_mov_b32_e32 v99, v219
	v_mov_b32_e32 v100, v219
	v_mov_b32_e32 v101, v219
	v_mov_b32_e32 v102, v219
	v_mov_b32_e32 v103, v219
	v_mov_b32_e32 v104, v219
	v_mov_b32_e32 v105, v219
	v_mov_b32_e32 v106, v219
	v_mov_b32_e32 v107, v219
	v_mov_b32_e32 v108, v219
	v_mov_b32_e32 v109, v219
	v_mov_b32_e32 v65, v64
	v_mov_b32_e32 v66, v64
	v_mov_b32_e32 v67, v64
	v_mov_b32_e32 v68, v64
	v_mov_b32_e32 v69, v64
	v_mov_b32_e32 v70, v64
	v_mov_b32_e32 v71, v64
	v_mov_b32_e32 v72, v64
	v_mov_b32_e32 v73, v64
	v_mov_b32_e32 v74, v64
	v_mov_b32_e32 v75, v64
	v_mov_b32_e32 v76, v64
	v_mov_b32_e32 v77, v64
	v_mov_b32_e32 v78, v64
	v_mov_b32_e32 v79, v64
	.p2align 6

; #define PG8_STAGE(bufoff, gbase, voff) do { _Pragma("unroll") for (int _i = 0; _i < 2; ++_i) \
;         __builtin_amdgcn_global_load_lds((const unsigned*)((const char*)(gbase) + (voff)[_i]), (PG8_LAS unsigned*)(lds + (bufoff) + ldsw + _i * 8192), 16, 0, 0); } while (0)
; #define PG8_LDA(dst, b, h) do { _Pragma("unroll") for (int m = 0; m < 4; ++m) _Pragma("unroll") for (int k = 0; k < 2; ++k) dst[m][k] = *(const PG8_LAS bf16x8*)(lds + PG8_SA(b, h) + aoff + m * 2048 + k * 1024); } while (0)
; #define PG8_LDB(dst, b, h) do { _Pragma("unroll") for (int n = 0; n < 2; ++n) _Pragma("unroll") for (int k = 0; k < 2; ++k) dst[n][k] = *(const PG8_LAS bf16x8*)(lds + PG8_SB(b, h) + boff + n * 2048 + k * 1024); } while (0)
; template <class Epi, class Sched, bool ALIGN_EPI = false, bool SP2 = false>
; __device__ __forceinline__ void gemm_phase(PG8_LAS unsigned char* lds, const Gemm g, const Sched& S, const Epi& E, const int tid_in) {
;     ...
;         const bool has_next = S.next(ui + 1, nxt);
;         const char* nA = has_next ? (const char*)g.A + (size_t)nxt.pm * tstepA : cA; const char* nB = has_next ? (const char*)g.Bt + (size_t)nxt.pn * tstepB : cB;
;         for (int t = 0; t < nt; t += 2) {
;             const bool last = (t == nt - 2);
;             const char* a1 = cA + (size_t)(t + 1) * kstep;
;             const char* a2 = last ? nA : cA + (size_t)(t + 2) * kstep; const char* b2 = last ? nB : cB + (size_t)(t + 2) * kstep;
;             const char* a3 = a2 + kstep; const char* b3 = b2 + kstep;
;             if (last && has_next) S.a_ready(nxt);
;             if constexpr (SP2) {
;             PG8_LDB(B0, 0, 0); PG8_LDB(B1, 0, 1); PG8_SCHED; PG8_LDA(At, 0, 0); PG8_STAGE(PG8_SA(1, 1), a1 + hstepA, voffA);
;             PG8_WAIT_V(8); PG8_WAIT_L(0); PG8_BAR; PG8_MMA(0, 0, At, B0); PG8_MMA(0, 1, At, B1); PG8_BAR; PG8_SCHED;
;             PG8_LDA(At, 0, 1); PG8_STAGE(PG8_SB(0, 0), b2, voffB); PG8_STAGE(PG8_SB(0, 1), b2 + hstepB, voffB); PG8_STAGE(PG8_SA(0, 0), a2, voffA);
;             PG8_WAIT_V(8); PG8_WAIT_L(0); PG8_BAR; PG8_MMA(1, 0, At, B0); PG8_MMA(1, 1, At, B1); PG8_BAR; PG8_SCHED;
;     ...
;         for (int a = 0; a < 2; ++a)
; #pragma unroll
;             for (int b = 0; b < 2; ++b)
; #pragma unroll
;                 for (int m = 0; m < 4; ++m)
; #pragma unroll
;                     for (int n = 0; n < 2; ++n) acc[a][b][m][n] = (f32x4){0.f, 0.f, 0.f, 0.f};
.LBB0_736:
	s_ashr_i32 s39, s38, 31
	s_lshl_b64 s[12:13], s[38:39], 20
	s_add_u32 s40, s10, s12
	s_addc_u32 s41, s11, s13
	s_and_b64 s[12:13], s[34:35], exec
	s_cselect_b32 s39, s41, s45
	s_cselect_b32 s61, s40, s44
	s_ashr_i32 s37, s36, 31
	s_lshl_b64 s[12:13], s[36:37], 20
	s_add_u32 s42, s18, s12
	s_addc_u32 s43, s50, s13
	s_and_b64 s[12:13], s[34:35], exec
	s_cselect_b32 s37, s43, s47
	s_cselect_b32 s62, s42, s46
	s_add_u32 s44, s44, 0x80080
	s_addc_u32 s45, s45, 0
	s_add_u32 s63, s46, 0x100
	s_addc_u32 s64, s47, 0
	s_mov_b32 s65, -2
	s_add_u32 s12, s44, 0xfff80080
	s_addc_u32 s13, s45, -1
	s_add_i32 s66, 0, 0x10000
	s_cmp_eq_u32 s65, 28
	s_cselect_b32 s49, s39, s13
	s_cselect_b32 s48, s61, s12
	s_cselect_b32 s47, s37, s64
	s_cselect_b32 s46, s62, s63
	s_add_i32 s67, 0, 0x14000
	v_add_u32_e32 v140, s66, v225
	v_add_u32_e32 v156, s67, v225
	ds_read_b128 v[128:131], v140
	ds_read_b128 v[132:135], v140 offset:1024
	ds_read_b128 v[136:139], v140 offset:2048
	ds_read_b128 v[140:143], v140 offset:3072
	ds_read_b128 v[144:147], v156
	ds_read_b128 v[148:151], v156 offset:1024
	ds_read_b128 v[152:155], v156 offset:2048
	ds_read_b128 v[156:159], v156 offset:3072
	v_lshl_add_u64 v[194:195], s[44:45], 0, v[204:205]
	s_add_i32 m0, s52, 0xc000
	ds_read_b128 v[160:163], v227
	ds_read_b128 v[164:167], v227 offset:1024
	ds_read_b128 v[168:171], v227 offset:2048
	ds_read_b128 v[172:175], v227 offset:3072
	ds_read_b128 v[176:179], v227 offset:4096
	ds_read_b128 v[180:183], v227 offset:5120
	ds_read_b128 v[184:187], v227 offset:6144
	ds_read_b128 v[188:191], v227 offset:7168
	global_load_lds_dwordx4 v[194:195], off
	v_lshl_add_u64 v[194:195], s[44:45], 0, v[206:207]
	s_add_i32 m0, s52, 0xe000
	s_nop 0
	global_load_lds_dwordx4 v[194:195], off
	s_waitcnt vmcnt(8)
	s_waitcnt lgkmcnt(0)
	s_barrier
	s_setprio 1
	s_waitcnt lgkmcnt(0)
	v_mfma_f32_16x16x32_bf16 v[124:127], v[128:131], v[160:163], 0
	v_mfma_f32_16x16x32_bf16 v[120:123], v[136:139], v[160:163], 0
	v_mfma_f32_16x16x32_bf16 v[108:111], v[128:131], v[168:171], 0
	v_mfma_f32_16x16x32_bf16 v[104:107], v[136:139], v[168:171], 0
	v_mfma_f32_16x16x32_bf16 v[96:99], v[128:131], v[176:179], 0
	v_mfma_f32_16x16x32_bf16 v[88:91], v[136:139], v[176:179], 0
	v_mfma_f32_16x16x32_bf16 v[80:83], v[128:131], v[184:187], 0
	v_mfma_f32_16x16x32_bf16 v[72:75], v[136:139], v[184:187], 0
	v_mfma_f32_16x16x32_bf16 v[124:127], v[132:135], v[164:167], v[124:127]
	v_mfma_f32_16x16x32_bf16 v[120:123], v[140:143], v[164:167], v[120:123]
	v_mfma_f32_16x16x32_bf16 v[108:111], v[132:135], v[172:175], v[108:111]
	v_mfma_f32_16x16x32_bf16 v[104:107], v[140:143], v[172:175], v[104:107]
	v_mfma_f32_16x16x32_bf16 v[96:99], v[132:135], v[180:183], v[96:99]
	v_mfma_f32_16x16x32_bf16 v[88:91], v[140:143], v[180:183], v[88:91]
	v_mfma_f32_16x16x32_bf16 v[80:83], v[132:135], v[188:191], v[80:83]
	v_mfma_f32_16x16x32_bf16 v[72:75], v[140:143], v[188:191], v[72:75]
	s_setprio 0
	s_setprio 1
	v_mfma_f32_16x16x32_bf16 v[116:119], v[144:147], v[160:163], 0
	v_mfma_f32_16x16x32_bf16 v[112:115], v[152:155], v[160:163], 0
	v_mfma_f32_16x16x32_bf16 v[100:103], v[144:147], v[168:171], 0
	v_mfma_f32_16x16x32_bf16 v[92:95], v[152:155], v[168:171], 0
	v_mfma_f32_16x16x32_bf16 v[84:87], v[144:147], v[176:179], 0
	v_mfma_f32_16x16x32_bf16 v[76:79], v[152:155], v[176:179], 0
	v_mfma_f32_16x16x32_bf16 v[68:71], v[144:147], v[184:187], 0
	v_mfma_f32_16x16x32_bf16 v[64:67], v[152:155], v[184:187], 0
	v_mfma_f32_16x16x32_bf16 v[116:119], v[148:151], v[164:167], v[116:119]
	v_mfma_f32_16x16x32_bf16 v[112:115], v[156:159], v[164:167], v[112:115]
	v_mfma_f32_16x16x32_bf16 v[100:103], v[148:151], v[172:175], v[100:103]
	v_mfma_f32_16x16x32_bf16 v[92:95], v[156:159], v[172:175], v[92:95]
	v_mfma_f32_16x16x32_bf16 v[84:87], v[148:151], v[180:183], v[84:87]
	v_mfma_f32_16x16x32_bf16 v[76:79], v[156:159], v[180:183], v[76:79]
	v_mfma_f32_16x16x32_bf16 v[68:71], v[148:151], v[188:191], v[68:71]
	v_mfma_f32_16x16x32_bf16 v[64:67], v[156:159], v[188:191], v[64:67]
	s_setprio 0
	s_barrier
	s_add_i32 s12, s66, s51
	v_lshl_add_u64 v[194:195], s[46:47], 0, v[192:193]
	s_mov_b32 m0, s12
	ds_read_b128 v[160:163], v227 offset:16384
	ds_read_b128 v[164:167], v227 offset:17408
	ds_read_b128 v[168:171], v227 offset:18432
	ds_read_b128 v[172:175], v227 offset:19456
	ds_read_b128 v[176:179], v227 offset:20480
	ds_read_b128 v[180:183], v227 offset:21504
	ds_read_b128 v[184:187], v227 offset:22528
	ds_read_b128 v[188:191], v227 offset:23552
	global_load_lds_dwordx4 v[194:195], off
	s_add_i32 m0, s12, 0x2000
	s_add_u32 s12, s46, 0x80000
	v_lshl_add_u64 v[196:197], s[46:47], 0, v[202:203]
	s_addc_u32 s13, s47, 0
	s_add_i32 s66, s67, s51
	global_load_lds_dwordx4 v[196:197], off
	v_lshl_add_u64 v[208:209], s[12:13], 0, v[192:193]
	s_mov_b32 m0, s66
	v_lshl_add_u64 v[210:211], s[48:49], 0, v[200:201]
	global_load_lds_dwordx4 v[208:209], off
	v_lshl_add_u64 v[208:209], s[12:13], 0, v[202:203]
	s_add_i32 m0, s66, 0x2000
	s_nop 0
	global_load_lds_dwordx4 v[208:209], off
	v_lshl_add_u64 v[208:209], s[48:49], 0, v[198:199]
	s_mov_b32 m0, s52
	s_nop 0
	global_load_lds_dwordx4 v[208:209], off
	s_mov_b32 m0, s53
	s_nop 0
	global_load_lds_dwordx4 v[210:211], off
	s_waitcnt vmcnt(8)
	s_waitcnt lgkmcnt(0)
	s_barrier
; #define PG8_STAGE(bufoff, gbase, voff) do { _Pragma("unroll") for (int _i = 0; _i < 2; ++_i) \
;         __builtin_amdgcn_global_load_lds((const unsigned*)((const char*)(gbase) + (voff)[_i]), (PG8_LAS unsigned*)(lds + (bufoff) + ldsw + _i * 8192), 16, 0, 0); } while (0)
; #define PG8_LDA(dst, b, h) do { _Pragma("unroll") for (int m = 0; m < 4; ++m) _Pragma("unroll") for (int k = 0; k < 2; ++k) dst[m][k] = *(const PG8_LAS bf16x8*)(lds + PG8_SA(b, h) + aoff + m * 2048 + k * 1024); } while (0)
; #define PG8_LDB(dst, b, h) do { _Pragma("unroll") for (int n = 0; n < 2; ++n) _Pragma("unroll") for (int k = 0; k < 2; ++k) dst[n][k] = *(const PG8_LAS bf16x8*)(lds + PG8_SB(b, h) + boff + n * 2048 + k * 1024); } while (0)
; #define PG8_MMA(ai, bj, At, Bt) do { __builtin_amdgcn_s_setprio(1); _Pragma("unroll") for (int m = 0; m < 4; ++m) _Pragma("unroll") for (int n = 0; n < 2; ++n) _Pragma("unroll") for (int k = 0; k < 2; ++k) \
;         acc[ai][bj][m][n] = __builtin_amdgcn_mfma_f32_16x16x32_bf16(Bt[n][k], At[m][k], acc[ai][bj][m][n], 0, 0, 0); __builtin_amdgcn_s_setprio(0); } while (0)
; #define PG8_WAIT_V(n) asm volatile("s_waitcnt vmcnt(" #n ")" ::: "memory")
; #define PG8_WAIT_L(n) asm volatile("s_waitcnt lgkmcnt(" #n ")" ::: "memory")
; #define PG8_BAR __builtin_amdgcn_s_barrier()
; #define PG8_SCHED __builtin_amdgcn_sched_barrier(0)
; template <class Epi, class Sched, bool ALIGN_EPI = false, bool SP2 = false>
; __device__ __forceinline__ void gemm_phase(PG8_LAS unsigned char* lds, const Gemm g, const Sched& S, const Epi& E, const int tid_in) {
;     ...
;             PG8_WAIT_V(8); PG8_WAIT_L(0); PG8_BAR; PG8_MMA(1, 0, At, B0); PG8_MMA(1, 1, At, B1); PG8_BAR; PG8_SCHED;
;             PG8_LDB(B0, 1, 0); PG8_LDB(B1, 1, 1); PG8_SCHED; PG8_LDA(At, 1, 0); PG8_STAGE(PG8_SA(0, 1), a2 + hstepA, voffA);
;             PG8_WAIT_V(8); PG8_WAIT_L(0); PG8_BAR; PG8_MMA(0, 0, At, B0); PG8_MMA(0, 1, At, B1); PG8_BAR; PG8_SCHED;
	s_setprio 1
	s_waitcnt lgkmcnt(0)
	v_mfma_f32_16x16x32_bf16 v[60:63], v[128:131], v[160:163], 0
	v_mfma_f32_16x16x32_bf16 v[56:59], v[136:139], v[160:163], 0
	v_mfma_f32_16x16x32_bf16 v[48:51], v[128:131], v[168:171], 0
	v_mfma_f32_16x16x32_bf16 v[40:43], v[136:139], v[168:171], 0
	v_mfma_f32_16x16x32_bf16 v[32:35], v[128:131], v[176:179], 0
	v_mfma_f32_16x16x32_bf16 v[24:27], v[136:139], v[176:179], 0
	v_mfma_f32_16x16x32_bf16 v[16:19], v[128:131], v[184:187], 0
	v_mfma_f32_16x16x32_bf16 v[8:11], v[136:139], v[184:187], 0
	v_mfma_f32_16x16x32_bf16 v[60:63], v[132:135], v[164:167], v[60:63]
	v_mfma_f32_16x16x32_bf16 v[56:59], v[140:143], v[164:167], v[56:59]
	v_mfma_f32_16x16x32_bf16 v[48:51], v[132:135], v[172:175], v[48:51]
	v_mfma_f32_16x16x32_bf16 v[40:43], v[140:143], v[172:175], v[40:43]
	v_mfma_f32_16x16x32_bf16 v[32:35], v[132:135], v[180:183], v[32:35]
	v_mfma_f32_16x16x32_bf16 v[24:27], v[140:143], v[180:183], v[24:27]
	v_mfma_f32_16x16x32_bf16 v[16:19], v[132:135], v[188:191], v[16:19]
	v_mfma_f32_16x16x32_bf16 v[8:11], v[140:143], v[188:191], v[8:11]
	s_setprio 0
	s_setprio 1
	v_mfma_f32_16x16x32_bf16 v[52:55], v[144:147], v[160:163], 0
	v_mfma_f32_16x16x32_bf16 v[44:47], v[152:155], v[160:163], 0
	v_mfma_f32_16x16x32_bf16 v[36:39], v[144:147], v[168:171], 0
	v_mfma_f32_16x16x32_bf16 v[28:31], v[152:155], v[168:171], 0
	v_mfma_f32_16x16x32_bf16 v[20:23], v[144:147], v[176:179], 0
	v_mfma_f32_16x16x32_bf16 v[12:15], v[152:155], v[176:179], 0
	v_mfma_f32_16x16x32_bf16 v[4:7], v[144:147], v[184:187], 0
	v_mfma_f32_16x16x32_bf16 v[0:3], v[152:155], v[184:187], 0
	v_mfma_f32_16x16x32_bf16 v[52:55], v[148:151], v[164:167], v[52:55]
	v_mfma_f32_16x16x32_bf16 v[44:47], v[156:159], v[164:167], v[44:47]
	v_mfma_f32_16x16x32_bf16 v[36:39], v[148:151], v[172:175], v[36:39]
	v_mfma_f32_16x16x32_bf16 v[28:31], v[156:159], v[172:175], v[28:31]
	v_mfma_f32_16x16x32_bf16 v[20:23], v[148:151], v[180:183], v[20:23]
	v_mfma_f32_16x16x32_bf16 v[12:15], v[156:159], v[180:183], v[12:15]
	v_mfma_f32_16x16x32_bf16 v[4:7], v[148:151], v[188:191], v[4:7]
	v_mfma_f32_16x16x32_bf16 v[0:3], v[156:159], v[188:191], v[0:3]
	s_setprio 0
	s_barrier
	s_add_i32 s66, 0, 0x18000
	s_add_i32 s67, 0, 0x1c000
	v_add_u32_e32 v140, s66, v225
	v_add_u32_e32 v156, s67, v225
	ds_read_b128 v[128:131], v140
	ds_read_b128 v[132:135], v140 offset:1024
	ds_read_b128 v[136:139], v140 offset:2048
	ds_read_b128 v[140:143], v140 offset:3072
	ds_read_b128 v[144:147], v156
	ds_read_b128 v[148:151], v156 offset:1024
	ds_read_b128 v[152:155], v156 offset:2048
	ds_read_b128 v[156:159], v156 offset:3072
	s_add_u32 s12, s48, 0x80000
	s_addc_u32 s13, s49, 0
	s_mov_b32 m0, s54
	v_lshl_add_u64 v[212:213], s[12:13], 0, v[198:199]
	ds_read_b128 v[160:163], v227 offset:32768
	ds_read_b128 v[164:167], v227 offset:33792
	ds_read_b128 v[168:171], v227 offset:34816
	ds_read_b128 v[172:175], v227 offset:35840
	ds_read_b128 v[176:179], v227 offset:36864
	ds_read_b128 v[180:183], v227 offset:37888
	ds_read_b128 v[184:187], v227 offset:38912
	ds_read_b128 v[188:191], v227 offset:39936
	global_load_lds_dwordx4 v[212:213], off
	v_lshl_add_u64 v[212:213], s[12:13], 0, v[200:201]
	s_mov_b32 m0, s55
	s_nop 0
	global_load_lds_dwordx4 v[212:213], off
	s_waitcnt vmcnt(8)
	s_waitcnt lgkmcnt(0)
	s_barrier
	s_setprio 1
	s_waitcnt lgkmcnt(0)
	v_mfma_f32_16x16x32_bf16 v[124:127], v[128:131], v[160:163], v[124:127]
	v_mfma_f32_16x16x32_bf16 v[120:123], v[136:139], v[160:163], v[120:123]
	v_mfma_f32_16x16x32_bf16 v[108:111], v[128:131], v[168:171], v[108:111]
	v_mfma_f32_16x16x32_bf16 v[104:107], v[136:139], v[168:171], v[104:107]
	v_mfma_f32_16x16x32_bf16 v[96:99], v[128:131], v[176:179], v[96:99]
	v_mfma_f32_16x16x32_bf16 v[88:91], v[136:139], v[176:179], v[88:91]
	v_mfma_f32_16x16x32_bf16 v[80:83], v[128:131], v[184:187], v[80:83]
	v_mfma_f32_16x16x32_bf16 v[72:75], v[136:139], v[184:187], v[72:75]
	v_mfma_f32_16x16x32_bf16 v[124:127], v[132:135], v[164:167], v[124:127]
	v_mfma_f32_16x16x32_bf16 v[120:123], v[140:143], v[164:167], v[120:123]
	v_mfma_f32_16x16x32_bf16 v[108:111], v[132:135], v[172:175], v[108:111]
	v_mfma_f32_16x16x32_bf16 v[104:107], v[140:143], v[172:175], v[104:107]
	v_mfma_f32_16x16x32_bf16 v[96:99], v[132:135], v[180:183], v[96:99]
	v_mfma_f32_16x16x32_bf16 v[88:91], v[140:143], v[180:183], v[88:91]
	v_mfma_f32_16x16x32_bf16 v[80:83], v[132:135], v[188:191], v[80:83]
	v_mfma_f32_16x16x32_bf16 v[72:75], v[140:143], v[188:191], v[72:75]
	s_setprio 0
	s_setprio 1
	v_mfma_f32_16x16x32_bf16 v[116:119], v[144:147], v[160:163], v[116:119]
	v_mfma_f32_16x16x32_bf16 v[112:115], v[152:155], v[160:163], v[112:115]
	v_mfma_f32_16x16x32_bf16 v[100:103], v[144:147], v[168:171], v[100:103]
	v_mfma_f32_16x16x32_bf16 v[92:95], v[152:155], v[168:171], v[92:95]
	v_mfma_f32_16x16x32_bf16 v[84:87], v[144:147], v[176:179], v[84:87]
	v_mfma_f32_16x16x32_bf16 v[76:79], v[152:155], v[176:179], v[76:79]
	v_mfma_f32_16x16x32_bf16 v[68:71], v[144:147], v[184:187], v[68:71]
	v_mfma_f32_16x16x32_bf16 v[64:67], v[152:155], v[184:187], v[64:67]
	v_mfma_f32_16x16x32_bf16 v[116:119], v[148:151], v[164:167], v[116:119]
	v_mfma_f32_16x16x32_bf16 v[112:115], v[156:159], v[164:167], v[112:115]
	v_mfma_f32_16x16x32_bf16 v[100:103], v[148:151], v[172:175], v[100:103]
	v_mfma_f32_16x16x32_bf16 v[92:95], v[156:159], v[172:175], v[92:95]
	v_mfma_f32_16x16x32_bf16 v[84:87], v[148:151], v[180:183], v[84:87]
	v_mfma_f32_16x16x32_bf16 v[76:79], v[156:159], v[180:183], v[76:79]
	v_mfma_f32_16x16x32_bf16 v[68:71], v[148:151], v[188:191], v[68:71]
	v_mfma_f32_16x16x32_bf16 v[64:67], v[156:159], v[188:191], v[64:67]
	s_setprio 0
	s_barrier
; #define PG8_STAGE(bufoff, gbase, voff) do { _Pragma("unroll") for (int _i = 0; _i < 2; ++_i) \
;         __builtin_amdgcn_global_load_lds((const unsigned*)((const char*)(gbase) + (voff)[_i]), (PG8_LAS unsigned*)(lds + (bufoff) + ldsw + _i * 8192), 16, 0, 0); } while (0)
; #define PG8_LDA(dst, b, h) do { _Pragma("unroll") for (int m = 0; m < 4; ++m) _Pragma("unroll") for (int k = 0; k < 2; ++k) dst[m][k] = *(const PG8_LAS bf16x8*)(lds + PG8_SA(b, h) + aoff + m * 2048 + k * 1024); } while (0)
; #define PG8_LDB(dst, b, h) do { _Pragma("unroll") for (int n = 0; n < 2; ++n) _Pragma("unroll") for (int k = 0; k < 2; ++k) dst[n][k] = *(const PG8_LAS bf16x8*)(lds + PG8_SB(b, h) + boff + n * 2048 + k * 1024); } while (0)
; #define PG8_MMA(ai, bj, At, Bt) do { __builtin_amdgcn_s_setprio(1); _Pragma("unroll") for (int m = 0; m < 4; ++m) _Pragma("unroll") for (int n = 0; n < 2; ++n) _Pragma("unroll") for (int k = 0; k < 2; ++k) \
;         acc[ai][bj][m][n] = __builtin_amdgcn_mfma_f32_16x16x32_bf16(Bt[n][k], At[m][k], acc[ai][bj][m][n], 0, 0, 0); __builtin_amdgcn_s_setprio(0); } while (0)
; #define PG8_BAR __builtin_amdgcn_s_barrier()
; template <class Epi, class Sched, bool ALIGN_EPI = false, bool SP2 = false>
; __device__ __forceinline__ void gemm_phase(PG8_LAS unsigned char* lds, const Gemm g, const Sched& S, const Epi& E, const int tid_in) {
;     ...
;             PG8_LDB(B0, 0, 0); PG8_LDB(B1, 0, 1); PG8_SCHED; PG8_LDA(At, 0, 0); PG8_STAGE(PG8_SA(1, 1), a1 + hstepA, voffA);
;             PG8_WAIT_V(8); PG8_WAIT_L(0); PG8_BAR; PG8_MMA(0, 0, At, B0); PG8_MMA(0, 1, At, B1); PG8_BAR; PG8_SCHED;
;             PG8_LDA(At, 0, 1); PG8_STAGE(PG8_SB(0, 0), b2, voffB); PG8_STAGE(PG8_SB(0, 1), b2 + hstepB, voffB); PG8_STAGE(PG8_SA(0, 0), a2, voffA);
;             PG8_WAIT_V(8); PG8_WAIT_L(0); PG8_BAR; PG8_MMA(1, 0, At, B0); PG8_MMA(1, 1, At, B1); PG8_BAR; PG8_SCHED;
;             PG8_LDB(B0, 1, 0); PG8_LDB(B1, 1, 1); PG8_SCHED; PG8_LDA(At, 1, 0); PG8_STAGE(PG8_SA(0, 1), a2 + hstepA, voffA);
;             PG8_WAIT_V(8); PG8_WAIT_L(0); PG8_BAR; PG8_MMA(0, 0, At, B0); PG8_MMA(0, 1, At, B1); PG8_BAR; PG8_SCHED;
;             PG8_LDA(At, 1, 1); PG8_STAGE(PG8_SB(1, 0), b3, voffB); PG8_STAGE(PG8_SB(1, 1), b3 + hstepB, voffB); PG8_STAGE(PG8_SA(1, 0), a3, voffA);
;             PG8_WAIT_V(8); PG8_WAIT_L(0); PG8_BAR; PG8_MMA(1, 0, At, B0); PG8_MMA(1, 1, At, B1); PG8_BAR; PG8_SCHED;
	s_add_i32 s12, s66, s51
	v_lshl_add_u64 v[194:195], v[194:195], 0, s[26:27]
	s_mov_b32 m0, s12
	ds_read_b128 v[160:163], v227 offset:49152
	ds_read_b128 v[164:167], v227 offset:50176
	ds_read_b128 v[168:171], v227 offset:51200
	ds_read_b128 v[172:175], v227 offset:52224
	ds_read_b128 v[176:179], v227 offset:53248
	ds_read_b128 v[180:183], v227 offset:54272
	ds_read_b128 v[184:187], v227 offset:55296
	ds_read_b128 v[188:191], v227 offset:56320
	global_load_lds_dwordx4 v[194:195], off
	s_add_i32 m0, s12, 0x2000
	s_add_u32 s12, s46, 0x80080
	v_lshl_add_u64 v[194:195], v[196:197], 0, s[26:27]
	s_addc_u32 s13, s47, 0
	s_add_i32 s46, s67, s51
	global_load_lds_dwordx4 v[194:195], off
	v_lshl_add_u64 v[194:195], s[12:13], 0, v[192:193]
	s_mov_b32 m0, s46
	s_nop 0
	global_load_lds_dwordx4 v[194:195], off
	v_lshl_add_u64 v[194:195], s[12:13], 0, v[202:203]
	s_add_i32 m0, s46, 0x2000
	s_nop 0
	global_load_lds_dwordx4 v[194:195], off
	v_lshl_add_u64 v[194:195], v[208:209], 0, s[26:27]
	s_mov_b32 m0, s56
	s_nop 0
	global_load_lds_dwordx4 v[194:195], off
	v_lshl_add_u64 v[194:195], v[210:211], 0, s[26:27]
	s_mov_b32 m0, s57
	s_nop 0
	global_load_lds_dwordx4 v[194:195], off
	s_waitcnt vmcnt(8)
	s_waitcnt lgkmcnt(0)
	s_barrier
	s_setprio 1
	s_waitcnt lgkmcnt(0)
	v_mfma_f32_16x16x32_bf16 v[60:63], v[128:131], v[160:163], v[60:63]
	v_mfma_f32_16x16x32_bf16 v[56:59], v[136:139], v[160:163], v[56:59]
	v_mfma_f32_16x16x32_bf16 v[48:51], v[128:131], v[168:171], v[48:51]
	v_mfma_f32_16x16x32_bf16 v[40:43], v[136:139], v[168:171], v[40:43]
	v_mfma_f32_16x16x32_bf16 v[32:35], v[128:131], v[176:179], v[32:35]
	v_mfma_f32_16x16x32_bf16 v[24:27], v[136:139], v[176:179], v[24:27]
	v_mfma_f32_16x16x32_bf16 v[16:19], v[128:131], v[184:187], v[16:19]
	v_mfma_f32_16x16x32_bf16 v[8:11], v[136:139], v[184:187], v[8:11]
	v_mfma_f32_16x16x32_bf16 v[60:63], v[132:135], v[164:167], v[60:63]
	v_mfma_f32_16x16x32_bf16 v[56:59], v[140:143], v[164:167], v[56:59]
	v_mfma_f32_16x16x32_bf16 v[48:51], v[132:135], v[172:175], v[48:51]
	v_mfma_f32_16x16x32_bf16 v[40:43], v[140:143], v[172:175], v[40:43]
	v_mfma_f32_16x16x32_bf16 v[32:35], v[132:135], v[180:183], v[32:35]
	v_mfma_f32_16x16x32_bf16 v[24:27], v[140:143], v[180:183], v[24:27]
	v_mfma_f32_16x16x32_bf16 v[16:19], v[132:135], v[188:191], v[16:19]
	v_mfma_f32_16x16x32_bf16 v[8:11], v[140:143], v[188:191], v[8:11]
	s_setprio 0
	s_setprio 1
	v_mfma_f32_16x16x32_bf16 v[52:55], v[144:147], v[160:163], v[52:55]
	v_mfma_f32_16x16x32_bf16 v[44:47], v[152:155], v[160:163], v[44:47]
	v_mfma_f32_16x16x32_bf16 v[36:39], v[144:147], v[168:171], v[36:39]
	v_mfma_f32_16x16x32_bf16 v[28:31], v[152:155], v[168:171], v[28:31]
	v_mfma_f32_16x16x32_bf16 v[20:23], v[144:147], v[176:179], v[20:23]
	v_mfma_f32_16x16x32_bf16 v[12:15], v[152:155], v[176:179], v[12:15]
	v_mfma_f32_16x16x32_bf16 v[4:7], v[144:147], v[184:187], v[4:7]
	v_mfma_f32_16x16x32_bf16 v[0:3], v[152:155], v[184:187], v[0:3]
	v_mfma_f32_16x16x32_bf16 v[52:55], v[148:151], v[164:167], v[52:55]
	v_mfma_f32_16x16x32_bf16 v[44:47], v[156:159], v[164:167], v[44:47]
	v_mfma_f32_16x16x32_bf16 v[36:39], v[148:151], v[172:175], v[36:39]
	v_mfma_f32_16x16x32_bf16 v[28:31], v[156:159], v[172:175], v[28:31]
	v_mfma_f32_16x16x32_bf16 v[20:23], v[148:151], v[180:183], v[20:23]
	v_mfma_f32_16x16x32_bf16 v[12:15], v[156:159], v[180:183], v[12:15]
	v_mfma_f32_16x16x32_bf16 v[4:7], v[148:151], v[188:191], v[4:7]
	v_mfma_f32_16x16x32_bf16 v[0:3], v[156:159], v[188:191], v[0:3]
	s_setprio 0
	s_barrier
	s_add_i32 s65, s65, 2
	s_add_u32 s44, s44, 0x100
	s_addc_u32 s45, s45, 0
	s_add_u32 s63, s63, 0x100
	s_addc_u32 s64, s64, 0
	s_cmp_gt_u32 s65, 29
	.p2align 6
.LBB0_737:
	s_add_u32 s12, s44, 0xfff80080
	s_addc_u32 s13, s45, -1
	s_add_i32 s66, 0, 0x10000
	s_cmp_eq_u32 s65, 28
	s_cselect_b32 s49, s39, s13
	s_cselect_b32 s48, s61, s12
	s_cselect_b32 s47, s37, s64
	s_cselect_b32 s46, s62, s63
	s_add_i32 s67, 0, 0x14000
	v_add_u32_e32 v140, s66, v225
	v_add_u32_e32 v156, s67, v225
	ds_read_b128 v[128:131], v140
	ds_read_b128 v[132:135], v140 offset:1024
	ds_read_b128 v[136:139], v140 offset:2048
	ds_read_b128 v[140:143], v140 offset:3072
	ds_read_b128 v[144:147], v156
	ds_read_b128 v[148:151], v156 offset:1024
	ds_read_b128 v[152:155], v156 offset:2048
	ds_read_b128 v[156:159], v156 offset:3072
	v_lshl_add_u64 v[194:195], s[44:45], 0, v[204:205]
	s_add_i32 m0, s52, 0xc000
	ds_read_b128 v[160:163], v227
	ds_read_b128 v[164:167], v227 offset:1024
	ds_read_b128 v[168:171], v227 offset:2048
	ds_read_b128 v[172:175], v227 offset:3072
	ds_read_b128 v[176:179], v227 offset:4096
	ds_read_b128 v[180:183], v227 offset:5120
	ds_read_b128 v[184:187], v227 offset:6144
	ds_read_b128 v[188:191], v227 offset:7168
	global_load_lds_dwordx4 v[194:195], off
	v_lshl_add_u64 v[194:195], s[44:45], 0, v[206:207]
	s_add_i32 m0, s52, 0xe000
	s_nop 0
	global_load_lds_dwordx4 v[194:195], off
	s_waitcnt vmcnt(8)
	s_waitcnt lgkmcnt(0)
	s_barrier
; #define PG8_STAGE(bufoff, gbase, voff) do { _Pragma("unroll") for (int _i = 0; _i < 2; ++_i) \
;         __builtin_amdgcn_global_load_lds((const unsigned*)((const char*)(gbase) + (voff)[_i]), (PG8_LAS unsigned*)(lds + (bufoff) + ldsw + _i * 8192), 16, 0, 0); } while (0)
; #define PG8_LDA(dst, b, h) do { _Pragma("unroll") for (int m = 0; m < 4; ++m) _Pragma("unroll") for (int k = 0; k < 2; ++k) dst[m][k] = *(const PG8_LAS bf16x8*)(lds + PG8_SA(b, h) + aoff + m * 2048 + k * 1024); } while (0)
; #define PG8_LDB(dst, b, h) do { _Pragma("unroll") for (int n = 0; n < 2; ++n) _Pragma("unroll") for (int k = 0; k < 2; ++k) dst[n][k] = *(const PG8_LAS bf16x8*)(lds + PG8_SB(b, h) + boff + n * 2048 + k * 1024); } while (0)
; #define PG8_MMA(ai, bj, At, Bt) do { __builtin_amdgcn_s_setprio(1); _Pragma("unroll") for (int m = 0; m < 4; ++m) _Pragma("unroll") for (int n = 0; n < 2; ++n) _Pragma("unroll") for (int k = 0; k < 2; ++k) \
;         acc[ai][bj][m][n] = __builtin_amdgcn_mfma_f32_16x16x32_bf16(Bt[n][k], At[m][k], acc[ai][bj][m][n], 0, 0, 0); __builtin_amdgcn_s_setprio(0); } while (0)
; #define PG8_WAIT_V(n) asm volatile("s_waitcnt vmcnt(" #n ")" ::: "memory")
; #define PG8_WAIT_L(n) asm volatile("s_waitcnt lgkmcnt(" #n ")" ::: "memory")
; #define PG8_BAR __builtin_amdgcn_s_barrier()
; #define PG8_SCHED __builtin_amdgcn_sched_barrier(0)
; template <class Epi, class Sched, bool ALIGN_EPI = false, bool SP2 = false>
; __device__ __forceinline__ void gemm_phase(PG8_LAS unsigned char* lds, const Gemm g, const Sched& S, const Epi& E, const int tid_in) {
;     ...
;             PG8_LDB(B0, 0, 0); PG8_LDB(B1, 0, 1); PG8_SCHED; PG8_LDA(At, 0, 0); PG8_STAGE(PG8_SA(1, 1), a1 + hstepA, voffA);
;             PG8_WAIT_V(8); PG8_WAIT_L(0); PG8_BAR; PG8_MMA(0, 0, At, B0); PG8_MMA(0, 1, At, B1); PG8_BAR; PG8_SCHED;
;             PG8_LDA(At, 0, 1); PG8_STAGE(PG8_SB(0, 0), b2, voffB); PG8_STAGE(PG8_SB(0, 1), b2 + hstepB, voffB); PG8_STAGE(PG8_SA(0, 0), a2, voffA);
;             PG8_WAIT_V(8); PG8_WAIT_L(0); PG8_BAR; PG8_MMA(1, 0, At, B0); PG8_MMA(1, 1, At, B1); PG8_BAR; PG8_SCHED;
	s_setprio 1
	s_waitcnt lgkmcnt(0)
	v_mfma_f32_16x16x32_bf16 v[124:127], v[128:131], v[160:163], v[124:127]
	v_mfma_f32_16x16x32_bf16 v[120:123], v[136:139], v[160:163], v[120:123]
	v_mfma_f32_16x16x32_bf16 v[108:111], v[128:131], v[168:171], v[108:111]
	v_mfma_f32_16x16x32_bf16 v[104:107], v[136:139], v[168:171], v[104:107]
	v_mfma_f32_16x16x32_bf16 v[96:99], v[128:131], v[176:179], v[96:99]
	v_mfma_f32_16x16x32_bf16 v[88:91], v[136:139], v[176:179], v[88:91]
	v_mfma_f32_16x16x32_bf16 v[80:83], v[128:131], v[184:187], v[80:83]
	v_mfma_f32_16x16x32_bf16 v[72:75], v[136:139], v[184:187], v[72:75]
	v_mfma_f32_16x16x32_bf16 v[124:127], v[132:135], v[164:167], v[124:127]
	v_mfma_f32_16x16x32_bf16 v[120:123], v[140:143], v[164:167], v[120:123]
	v_mfma_f32_16x16x32_bf16 v[108:111], v[132:135], v[172:175], v[108:111]
	v_mfma_f32_16x16x32_bf16 v[104:107], v[140:143], v[172:175], v[104:107]
	v_mfma_f32_16x16x32_bf16 v[96:99], v[132:135], v[180:183], v[96:99]
	v_mfma_f32_16x16x32_bf16 v[88:91], v[140:143], v[180:183], v[88:91]
	v_mfma_f32_16x16x32_bf16 v[80:83], v[132:135], v[188:191], v[80:83]
	v_mfma_f32_16x16x32_bf16 v[72:75], v[140:143], v[188:191], v[72:75]
	v_mfma_f32_16x16x32_bf16 v[116:119], v[144:147], v[160:163], v[116:119]
	v_mfma_f32_16x16x32_bf16 v[112:115], v[152:155], v[160:163], v[112:115]
	v_mfma_f32_16x16x32_bf16 v[100:103], v[144:147], v[168:171], v[100:103]
	v_mfma_f32_16x16x32_bf16 v[92:95], v[152:155], v[168:171], v[92:95]
	v_mfma_f32_16x16x32_bf16 v[84:87], v[144:147], v[176:179], v[84:87]
	v_mfma_f32_16x16x32_bf16 v[76:79], v[152:155], v[176:179], v[76:79]
	v_mfma_f32_16x16x32_bf16 v[68:71], v[144:147], v[184:187], v[68:71]
	v_mfma_f32_16x16x32_bf16 v[64:67], v[152:155], v[184:187], v[64:67]
	v_mfma_f32_16x16x32_bf16 v[116:119], v[148:151], v[164:167], v[116:119]
	v_mfma_f32_16x16x32_bf16 v[112:115], v[156:159], v[164:167], v[112:115]
	v_mfma_f32_16x16x32_bf16 v[100:103], v[148:151], v[172:175], v[100:103]
	v_mfma_f32_16x16x32_bf16 v[92:95], v[156:159], v[172:175], v[92:95]
	v_mfma_f32_16x16x32_bf16 v[84:87], v[148:151], v[180:183], v[84:87]
	v_mfma_f32_16x16x32_bf16 v[76:79], v[156:159], v[180:183], v[76:79]
	v_mfma_f32_16x16x32_bf16 v[68:71], v[148:151], v[188:191], v[68:71]
	v_mfma_f32_16x16x32_bf16 v[64:67], v[156:159], v[188:191], v[64:67]
	s_setprio 0
	s_barrier
	s_add_i32 s12, s66, s51
	v_lshl_add_u64 v[194:195], s[46:47], 0, v[192:193]
	s_mov_b32 m0, s12
	ds_read_b128 v[160:163], v227 offset:16384
	ds_read_b128 v[164:167], v227 offset:17408
	ds_read_b128 v[168:171], v227 offset:18432
	ds_read_b128 v[172:175], v227 offset:19456
	ds_read_b128 v[176:179], v227 offset:20480
	ds_read_b128 v[180:183], v227 offset:21504
	ds_read_b128 v[184:187], v227 offset:22528
	ds_read_b128 v[188:191], v227 offset:23552
	global_load_lds_dwordx4 v[194:195], off
	s_add_i32 m0, s12, 0x2000
	s_add_u32 s12, s46, 0x80000
	v_lshl_add_u64 v[196:197], s[46:47], 0, v[202:203]
	s_addc_u32 s13, s47, 0
	s_add_i32 s66, s67, s51
	global_load_lds_dwordx4 v[196:197], off
	v_lshl_add_u64 v[208:209], s[12:13], 0, v[192:193]
	s_mov_b32 m0, s66
	v_lshl_add_u64 v[210:211], s[48:49], 0, v[200:201]
	global_load_lds_dwordx4 v[208:209], off
	v_lshl_add_u64 v[208:209], s[12:13], 0, v[202:203]
	s_add_i32 m0, s66, 0x2000
	s_nop 0
	global_load_lds_dwordx4 v[208:209], off
	v_lshl_add_u64 v[208:209], s[48:49], 0, v[198:199]
	s_mov_b32 m0, s52
	s_nop 0
	global_load_lds_dwordx4 v[208:209], off
	s_mov_b32 m0, s53
	s_nop 0
	global_load_lds_dwordx4 v[210:211], off
	s_waitcnt vmcnt(8)
	s_waitcnt lgkmcnt(0)
	s_barrier
	s_setprio 1
	s_waitcnt lgkmcnt(0)
	v_mfma_f32_16x16x32_bf16 v[60:63], v[128:131], v[160:163], v[60:63]
	v_mfma_f32_16x16x32_bf16 v[56:59], v[136:139], v[160:163], v[56:59]
	v_mfma_f32_16x16x32_bf16 v[48:51], v[128:131], v[168:171], v[48:51]
	v_mfma_f32_16x16x32_bf16 v[40:43], v[136:139], v[168:171], v[40:43]
	v_mfma_f32_16x16x32_bf16 v[32:35], v[128:131], v[176:179], v[32:35]
	v_mfma_f32_16x16x32_bf16 v[24:27], v[136:139], v[176:179], v[24:27]
	v_mfma_f32_16x16x32_bf16 v[16:19], v[128:131], v[184:187], v[16:19]
	v_mfma_f32_16x16x32_bf16 v[8:11], v[136:139], v[184:187], v[8:11]
	v_mfma_f32_16x16x32_bf16 v[60:63], v[132:135], v[164:167], v[60:63]
	v_mfma_f32_16x16x32_bf16 v[56:59], v[140:143], v[164:167], v[56:59]
	v_mfma_f32_16x16x32_bf16 v[48:51], v[132:135], v[172:175], v[48:51]
	v_mfma_f32_16x16x32_bf16 v[40:43], v[140:143], v[172:175], v[40:43]
	v_mfma_f32_16x16x32_bf16 v[32:35], v[132:135], v[180:183], v[32:35]
	v_mfma_f32_16x16x32_bf16 v[24:27], v[140:143], v[180:183], v[24:27]
	v_mfma_f32_16x16x32_bf16 v[16:19], v[132:135], v[188:191], v[16:19]
	v_mfma_f32_16x16x32_bf16 v[8:11], v[140:143], v[188:191], v[8:11]
	v_mfma_f32_16x16x32_bf16 v[52:55], v[144:147], v[160:163], v[52:55]
	v_mfma_f32_16x16x32_bf16 v[44:47], v[152:155], v[160:163], v[44:47]
	v_mfma_f32_16x16x32_bf16 v[36:39], v[144:147], v[168:171], v[36:39]
	v_mfma_f32_16x16x32_bf16 v[28:31], v[152:155], v[168:171], v[28:31]
	v_mfma_f32_16x16x32_bf16 v[20:23], v[144:147], v[176:179], v[20:23]
	v_mfma_f32_16x16x32_bf16 v[12:15], v[152:155], v[176:179], v[12:15]
	v_mfma_f32_16x16x32_bf16 v[4:7], v[144:147], v[184:187], v[4:7]
	v_mfma_f32_16x16x32_bf16 v[0:3], v[152:155], v[184:187], v[0:3]
	v_mfma_f32_16x16x32_bf16 v[52:55], v[148:151], v[164:167], v[52:55]
	v_mfma_f32_16x16x32_bf16 v[44:47], v[156:159], v[164:167], v[44:47]
	v_mfma_f32_16x16x32_bf16 v[36:39], v[148:151], v[172:175], v[36:39]
	v_mfma_f32_16x16x32_bf16 v[28:31], v[156:159], v[172:175], v[28:31]
	v_mfma_f32_16x16x32_bf16 v[20:23], v[148:151], v[180:183], v[20:23]
	v_mfma_f32_16x16x32_bf16 v[12:15], v[156:159], v[180:183], v[12:15]
	v_mfma_f32_16x16x32_bf16 v[4:7], v[148:151], v[188:191], v[4:7]
	v_mfma_f32_16x16x32_bf16 v[0:3], v[156:159], v[188:191], v[0:3]
	s_setprio 0
	s_barrier
; #define PG8_STAGE(bufoff, gbase, voff) do { _Pragma("unroll") for (int _i = 0; _i < 2; ++_i) \
;         __builtin_amdgcn_global_load_lds((const unsigned*)((const char*)(gbase) + (voff)[_i]), (PG8_LAS unsigned*)(lds + (bufoff) + ldsw + _i * 8192), 16, 0, 0); } while (0)
; #define PG8_LDA(dst, b, h) do { _Pragma("unroll") for (int m = 0; m < 4; ++m) _Pragma("unroll") for (int k = 0; k < 2; ++k) dst[m][k] = *(const PG8_LAS bf16x8*)(lds + PG8_SA(b, h) + aoff + m * 2048 + k * 1024); } while (0)
; #define PG8_LDB(dst, b, h) do { _Pragma("unroll") for (int n = 0; n < 2; ++n) _Pragma("unroll") for (int k = 0; k < 2; ++k) dst[n][k] = *(const PG8_LAS bf16x8*)(lds + PG8_SB(b, h) + boff + n * 2048 + k * 1024); } while (0)
; #define PG8_MMA(ai, bj, At, Bt) do { __builtin_amdgcn_s_setprio(1); _Pragma("unroll") for (int m = 0; m < 4; ++m) _Pragma("unroll") for (int n = 0; n < 2; ++n) _Pragma("unroll") for (int k = 0; k < 2; ++k) \
;         acc[ai][bj][m][n] = __builtin_amdgcn_mfma_f32_16x16x32_bf16(Bt[n][k], At[m][k], acc[ai][bj][m][n], 0, 0, 0); __builtin_amdgcn_s_setprio(0); } while (0)
; #define PG8_WAIT_V(n) asm volatile("s_waitcnt vmcnt(" #n ")" ::: "memory")
; #define PG8_WAIT_L(n) asm volatile("s_waitcnt lgkmcnt(" #n ")" ::: "memory")
; #define PG8_BAR __builtin_amdgcn_s_barrier()
; #define PG8_SCHED __builtin_amdgcn_sched_barrier(0)
; template <class Epi, class Sched, bool ALIGN_EPI = false, bool SP2 = false>
; __device__ __forceinline__ void gemm_phase(PG8_LAS unsigned char* lds, const Gemm g, const Sched& S, const Epi& E, const int tid_in) {
;     ...
;             PG8_LDB(B0, 1, 0); PG8_LDB(B1, 1, 1); PG8_SCHED; PG8_LDA(At, 1, 0); PG8_STAGE(PG8_SA(0, 1), a2 + hstepA, voffA);
;             PG8_WAIT_V(8); PG8_WAIT_L(0); PG8_BAR; PG8_MMA(0, 0, At, B0); PG8_MMA(0, 1, At, B1); PG8_BAR; PG8_SCHED;
	s_add_i32 s66, 0, 0x18000
	s_add_i32 s67, 0, 0x1c000
	v_add_u32_e32 v140, s66, v225
	v_add_u32_e32 v156, s67, v225
	ds_read_b128 v[128:131], v140
	ds_read_b128 v[132:135], v140 offset:1024
	ds_read_b128 v[136:139], v140 offset:2048
	ds_read_b128 v[140:143], v140 offset:3072
	ds_read_b128 v[144:147], v156
	ds_read_b128 v[148:151], v156 offset:1024
	ds_read_b128 v[152:155], v156 offset:2048
	ds_read_b128 v[156:159], v156 offset:3072
	s_add_u32 s12, s48, 0x80000
	s_addc_u32 s13, s49, 0
	s_mov_b32 m0, s54
	v_lshl_add_u64 v[212:213], s[12:13], 0, v[198:199]
	ds_read_b128 v[160:163], v227 offset:32768
	ds_read_b128 v[164:167], v227 offset:33792
	ds_read_b128 v[168:171], v227 offset:34816
	ds_read_b128 v[172:175], v227 offset:35840
	ds_read_b128 v[176:179], v227 offset:36864
	ds_read_b128 v[180:183], v227 offset:37888
	ds_read_b128 v[184:187], v227 offset:38912
	ds_read_b128 v[188:191], v227 offset:39936
	global_load_lds_dwordx4 v[212:213], off
	v_lshl_add_u64 v[212:213], s[12:13], 0, v[200:201]
	s_mov_b32 m0, s55
	s_nop 0
	global_load_lds_dwordx4 v[212:213], off
	s_waitcnt vmcnt(8)
	s_waitcnt lgkmcnt(0)
	s_barrier
	s_setprio 1
	s_waitcnt lgkmcnt(0)
	v_mfma_f32_16x16x32_bf16 v[124:127], v[128:131], v[160:163], v[124:127]
	v_mfma_f32_16x16x32_bf16 v[120:123], v[136:139], v[160:163], v[120:123]
	v_mfma_f32_16x16x32_bf16 v[108:111], v[128:131], v[168:171], v[108:111]
	v_mfma_f32_16x16x32_bf16 v[104:107], v[136:139], v[168:171], v[104:107]
	v_mfma_f32_16x16x32_bf16 v[96:99], v[128:131], v[176:179], v[96:99]
	v_mfma_f32_16x16x32_bf16 v[88:91], v[136:139], v[176:179], v[88:91]
	v_mfma_f32_16x16x32_bf16 v[80:83], v[128:131], v[184:187], v[80:83]
	v_mfma_f32_16x16x32_bf16 v[72:75], v[136:139], v[184:187], v[72:75]
	v_mfma_f32_16x16x32_bf16 v[124:127], v[132:135], v[164:167], v[124:127]
	v_mfma_f32_16x16x32_bf16 v[120:123], v[140:143], v[164:167], v[120:123]
	v_mfma_f32_16x16x32_bf16 v[108:111], v[132:135], v[172:175], v[108:111]
	v_mfma_f32_16x16x32_bf16 v[104:107], v[140:143], v[172:175], v[104:107]
	v_mfma_f32_16x16x32_bf16 v[96:99], v[132:135], v[180:183], v[96:99]
	v_mfma_f32_16x16x32_bf16 v[88:91], v[140:143], v[180:183], v[88:91]
	v_mfma_f32_16x16x32_bf16 v[80:83], v[132:135], v[188:191], v[80:83]
	v_mfma_f32_16x16x32_bf16 v[72:75], v[140:143], v[188:191], v[72:75]
	v_mfma_f32_16x16x32_bf16 v[116:119], v[144:147], v[160:163], v[116:119]
	v_mfma_f32_16x16x32_bf16 v[112:115], v[152:155], v[160:163], v[112:115]
	v_mfma_f32_16x16x32_bf16 v[100:103], v[144:147], v[168:171], v[100:103]
	v_mfma_f32_16x16x32_bf16 v[92:95], v[152:155], v[168:171], v[92:95]
	v_mfma_f32_16x16x32_bf16 v[84:87], v[144:147], v[176:179], v[84:87]
	v_mfma_f32_16x16x32_bf16 v[76:79], v[152:155], v[176:179], v[76:79]
	v_mfma_f32_16x16x32_bf16 v[68:71], v[144:147], v[184:187], v[68:71]
	v_mfma_f32_16x16x32_bf16 v[64:67], v[152:155], v[184:187], v[64:67]
	v_mfma_f32_16x16x32_bf16 v[116:119], v[148:151], v[164:167], v[116:119]
	v_mfma_f32_16x16x32_bf16 v[112:115], v[156:159], v[164:167], v[112:115]
	v_mfma_f32_16x16x32_bf16 v[100:103], v[148:151], v[172:175], v[100:103]
	v_mfma_f32_16x16x32_bf16 v[92:95], v[156:159], v[172:175], v[92:95]
	v_mfma_f32_16x16x32_bf16 v[84:87], v[148:151], v[180:183], v[84:87]
	v_mfma_f32_16x16x32_bf16 v[76:79], v[156:159], v[180:183], v[76:79]
	v_mfma_f32_16x16x32_bf16 v[68:71], v[148:151], v[188:191], v[68:71]
	v_mfma_f32_16x16x32_bf16 v[64:67], v[156:159], v[188:191], v[64:67]
	s_setprio 0
	s_barrier
; #define PG8_STAGE(bufoff, gbase, voff) do { _Pragma("unroll") for (int _i = 0; _i < 2; ++_i) \
;         __builtin_amdgcn_global_load_lds((const unsigned*)((const char*)(gbase) + (voff)[_i]), (PG8_LAS unsigned*)(lds + (bufoff) + ldsw + _i * 8192), 16, 0, 0); } while (0)
; #define PG8_LDA(dst, b, h) do { _Pragma("unroll") for (int m = 0; m < 4; ++m) _Pragma("unroll") for (int k = 0; k < 2; ++k) dst[m][k] = *(const PG8_LAS bf16x8*)(lds + PG8_SA(b, h) + aoff + m * 2048 + k * 1024); } while (0)
; #define PG8_MMA(ai, bj, At, Bt) do { __builtin_amdgcn_s_setprio(1); _Pragma("unroll") for (int m = 0; m < 4; ++m) _Pragma("unroll") for (int n = 0; n < 2; ++n) _Pragma("unroll") for (int k = 0; k < 2; ++k) \
;         acc[ai][bj][m][n] = __builtin_amdgcn_mfma_f32_16x16x32_bf16(Bt[n][k], At[m][k], acc[ai][bj][m][n], 0, 0, 0); __builtin_amdgcn_s_setprio(0); } while (0)
; #define PG8_WAIT_V(n) asm volatile("s_waitcnt vmcnt(" #n ")" ::: "memory")
; #define PG8_WAIT_L(n) asm volatile("s_waitcnt lgkmcnt(" #n ")" ::: "memory")
; #define PG8_BAR __builtin_amdgcn_s_barrier()
; #define PG8_SCHED __builtin_amdgcn_sched_barrier(0)
; template <class Epi, class Sched, bool ALIGN_EPI = false, bool SP2 = false>
; __device__ __forceinline__ void gemm_phase(PG8_LAS unsigned char* lds, const Gemm g, const Sched& S, const Epi& E, const int tid_in) {
;     ...
;             PG8_LDA(At, 1, 1); PG8_STAGE(PG8_SB(1, 0), b3, voffB); PG8_STAGE(PG8_SB(1, 1), b3 + hstepB, voffB); PG8_STAGE(PG8_SA(1, 0), a3, voffA);
;             PG8_WAIT_V(8); PG8_WAIT_L(0); PG8_BAR; PG8_MMA(1, 0, At, B0); PG8_MMA(1, 1, At, B1); PG8_BAR; PG8_SCHED;
;     ...
;         if constexpr (ALIGN_EPI) { if (wr == 0) PG8_BAR; }
	s_add_i32 s12, s66, s51
	v_lshl_add_u64 v[194:195], v[194:195], 0, s[26:27]
	s_mov_b32 m0, s12
	ds_read_b128 v[160:163], v227 offset:49152
	ds_read_b128 v[164:167], v227 offset:50176
	ds_read_b128 v[168:171], v227 offset:51200
	ds_read_b128 v[172:175], v227 offset:52224
	ds_read_b128 v[176:179], v227 offset:53248
	ds_read_b128 v[180:183], v227 offset:54272
	ds_read_b128 v[184:187], v227 offset:55296
	ds_read_b128 v[188:191], v227 offset:56320
	global_load_lds_dwordx4 v[194:195], off
	s_add_i32 m0, s12, 0x2000
	s_add_u32 s12, s46, 0x80080
	v_lshl_add_u64 v[194:195], v[196:197], 0, s[26:27]
	s_addc_u32 s13, s47, 0
	s_add_i32 s46, s67, s51
	global_load_lds_dwordx4 v[194:195], off
	v_lshl_add_u64 v[194:195], s[12:13], 0, v[192:193]
	s_mov_b32 m0, s46
	s_nop 0
	global_load_lds_dwordx4 v[194:195], off
	v_lshl_add_u64 v[194:195], s[12:13], 0, v[202:203]
	s_add_i32 m0, s46, 0x2000
	s_nop 0
	global_load_lds_dwordx4 v[194:195], off
	v_lshl_add_u64 v[194:195], v[208:209], 0, s[26:27]
	s_mov_b32 m0, s56
	s_nop 0
	global_load_lds_dwordx4 v[194:195], off
	v_lshl_add_u64 v[194:195], v[210:211], 0, s[26:27]
	s_mov_b32 m0, s57
	s_nop 0
	global_load_lds_dwordx4 v[194:195], off
	s_waitcnt vmcnt(8)
	s_waitcnt lgkmcnt(0)
	s_barrier
	s_setprio 1
	s_waitcnt lgkmcnt(0)
	v_mfma_f32_16x16x32_bf16 v[60:63], v[128:131], v[160:163], v[60:63]
	v_mfma_f32_16x16x32_bf16 v[56:59], v[136:139], v[160:163], v[56:59]
	v_mfma_f32_16x16x32_bf16 v[48:51], v[128:131], v[168:171], v[48:51]
	v_mfma_f32_16x16x32_bf16 v[40:43], v[136:139], v[168:171], v[40:43]
	v_mfma_f32_16x16x32_bf16 v[32:35], v[128:131], v[176:179], v[32:35]
	v_mfma_f32_16x16x32_bf16 v[24:27], v[136:139], v[176:179], v[24:27]
	v_mfma_f32_16x16x32_bf16 v[16:19], v[128:131], v[184:187], v[16:19]
	v_mfma_f32_16x16x32_bf16 v[8:11], v[136:139], v[184:187], v[8:11]
	v_mfma_f32_16x16x32_bf16 v[60:63], v[132:135], v[164:167], v[60:63]
	v_mfma_f32_16x16x32_bf16 v[56:59], v[140:143], v[164:167], v[56:59]
	v_mfma_f32_16x16x32_bf16 v[48:51], v[132:135], v[172:175], v[48:51]
	v_mfma_f32_16x16x32_bf16 v[40:43], v[140:143], v[172:175], v[40:43]
	v_mfma_f32_16x16x32_bf16 v[32:35], v[132:135], v[180:183], v[32:35]
	v_mfma_f32_16x16x32_bf16 v[24:27], v[140:143], v[180:183], v[24:27]
	v_mfma_f32_16x16x32_bf16 v[16:19], v[132:135], v[188:191], v[16:19]
	v_mfma_f32_16x16x32_bf16 v[8:11], v[140:143], v[188:191], v[8:11]
	v_mfma_f32_16x16x32_bf16 v[52:55], v[144:147], v[160:163], v[52:55]
	v_mfma_f32_16x16x32_bf16 v[44:47], v[152:155], v[160:163], v[44:47]
	v_mfma_f32_16x16x32_bf16 v[36:39], v[144:147], v[168:171], v[36:39]
	v_mfma_f32_16x16x32_bf16 v[28:31], v[152:155], v[168:171], v[28:31]
	v_mfma_f32_16x16x32_bf16 v[20:23], v[144:147], v[176:179], v[20:23]
	v_mfma_f32_16x16x32_bf16 v[12:15], v[152:155], v[176:179], v[12:15]
	v_mfma_f32_16x16x32_bf16 v[4:7], v[144:147], v[184:187], v[4:7]
	v_mfma_f32_16x16x32_bf16 v[0:3], v[152:155], v[184:187], v[0:3]
	v_mfma_f32_16x16x32_bf16 v[52:55], v[148:151], v[164:167], v[52:55]
	v_mfma_f32_16x16x32_bf16 v[44:47], v[156:159], v[164:167], v[44:47]
	v_mfma_f32_16x16x32_bf16 v[36:39], v[148:151], v[172:175], v[36:39]
	v_mfma_f32_16x16x32_bf16 v[28:31], v[156:159], v[172:175], v[28:31]
	v_mfma_f32_16x16x32_bf16 v[20:23], v[148:151], v[180:183], v[20:23]
	v_mfma_f32_16x16x32_bf16 v[12:15], v[156:159], v[180:183], v[12:15]
	v_mfma_f32_16x16x32_bf16 v[4:7], v[148:151], v[188:191], v[4:7]
	v_mfma_f32_16x16x32_bf16 v[0:3], v[156:159], v[188:191], v[0:3]
	s_setprio 0
	s_barrier
	s_add_i32 s65, s65, 2
	s_add_u32 s44, s44, 0x100
	s_addc_u32 s45, s45, 0
	s_add_u32 s63, s63, 0x100
	s_addc_u32 s64, s64, 0
	s_cmp_gt_u32 s65, 29
	s_cbranch_scc0 .LBB0_737
	s_and_b64 vcc, exec, s[30:31]
	s_cbranch_vccz .LBB0_740
	s_barrier

; #define PG8_STAGE(bufoff, gbase, voff) do { _Pragma("unroll") for (int _i = 0; _i < 2; ++_i) \
;         __builtin_amdgcn_global_load_lds((const unsigned*)((const char*)(gbase) + (voff)[_i]), (PG8_LAS unsigned*)(lds + (bufoff) + ldsw + _i * 8192), 16, 0, 0); } while (0)
; #define PG8_LDA(dst, b, h) do { _Pragma("unroll") for (int m = 0; m < 4; ++m) _Pragma("unroll") for (int k = 0; k < 2; ++k) dst[m][k] = *(const PG8_LAS bf16x8*)(lds + PG8_SA(b, h) + aoff + m * 2048 + k * 1024); } while (0)
; #define PG8_LDB(dst, b, h) do { _Pragma("unroll") for (int n = 0; n < 2; ++n) _Pragma("unroll") for (int k = 0; k < 2; ++k) dst[n][k] = *(const PG8_LAS bf16x8*)(lds + PG8_SB(b, h) + boff + n * 2048 + k * 1024); } while (0)
; #define PG8_MMA(ai, bj, At, Bt) do { __builtin_amdgcn_s_setprio(1); _Pragma("unroll") for (int m = 0; m < 4; ++m) _Pragma("unroll") for (int n = 0; n < 2; ++n) _Pragma("unroll") for (int k = 0; k < 2; ++k) \
;         acc[ai][bj][m][n] = __builtin_amdgcn_mfma_f32_16x16x32_bf16(Bt[n][k], At[m][k], acc[ai][bj][m][n], 0, 0, 0); __builtin_amdgcn_s_setprio(0); } while (0)
; #define PG8_WAIT_V(n) asm volatile("s_waitcnt vmcnt(" #n ")" ::: "memory")
; #define PG8_WAIT_L(n) asm volatile("s_waitcnt lgkmcnt(" #n ")" ::: "memory")
; #define PG8_BAR __builtin_amdgcn_s_barrier()
; template <class Epi, class Sched, bool ALIGN_EPI = false, bool SP2 = false>
; __device__ __forceinline__ void gemm_phase(PG8_LAS unsigned char* lds, const Gemm g, const Sched& S, const Epi& E, const int tid_in) {
;     ...
;         const char* nA = has_next ? (const char*)g.A + (size_t)nxt.pm * tstepA : cA; const char* nB = has_next ? (const char*)g.Bt + (size_t)nxt.pn * tstepB : cB;
;         for (int t = 0; t < nt; t += 2) {
;             const bool last = (t == nt - 2);
;             const char* a1 = cA + (size_t)(t + 1) * kstep;
;             const char* a2 = last ? nA : cA + (size_t)(t + 2) * kstep; const char* b2 = last ? nB : cB + (size_t)(t + 2) * kstep;
;             const char* a3 = a2 + kstep; const char* b3 = b2 + kstep;
;             if (last && has_next) S.a_ready(nxt);
;             if constexpr (SP2) {
;             PG8_LDB(B0, 0, 0); PG8_LDB(B1, 0, 1); PG8_SCHED; PG8_LDA(At, 0, 0); PG8_STAGE(PG8_SA(1, 1), a1 + hstepA, voffA);
;             PG8_WAIT_V(8); PG8_WAIT_L(0); PG8_BAR; PG8_MMA(0, 0, At, B0); PG8_MMA(0, 1, At, B1); PG8_BAR; PG8_SCHED;
.LBB0_814:
	s_ashr_i32 s47, s46, 31
	s_lshl_b64 s[12:13], s[46:47], 20
	s_add_u32 s48, s60, s12
	s_addc_u32 s49, s61, s13
	s_and_b64 s[12:13], s[34:35], exec
	s_cselect_b32 s23, s49, s53
	s_cselect_b32 s31, s48, s52
	s_ashr_i32 s45, s44, 31
	s_lshl_b64 s[12:13], s[44:45], 20
	s_add_u32 s50, s62, s12
	s_addc_u32 s51, s63, s13
	s_and_b64 s[12:13], s[34:35], exec
	s_cselect_b32 s45, s51, s55
	s_cselect_b32 s47, s50, s54
	s_add_u32 s52, s52, 0x80080
	s_addc_u32 s53, s53, 0
	s_add_u32 s76, s54, 0x100
	s_addc_u32 s77, s55, 0
	s_mov_b32 s78, -2
	s_add_u32 s12, s52, 0xfff80080
	s_addc_u32 s13, s53, -1
	s_add_i32 s79, 0, 0x10000
	s_cmp_eq_u32 s78, 28
	s_cselect_b32 s57, s23, s13
	s_cselect_b32 s56, s31, s12
	s_cselect_b32 s55, s45, s77
	s_cselect_b32 s54, s47, s76
	s_add_i32 s80, 0, 0x14000
	v_add_u32_e32 v140, s79, v174
	v_add_u32_e32 v161, s80, v174
	ds_read_b128 v[128:131], v140
	ds_read_b128 v[132:135], v140 offset:1024
	ds_read_b128 v[136:139], v140 offset:2048
	ds_read_b128 v[140:143], v140 offset:3072
	ds_read_b128 v[162:165], v161
	ds_read_b128 v[166:169], v161 offset:1024
	ds_read_b128 v[178:181], v161 offset:2048
	ds_read_b128 v[182:185], v161 offset:3072
	v_lshl_add_u64 v[170:171], s[52:53], 0, v[156:157]
	s_add_i32 m0, s65, 0xc000
	ds_read_b128 v[186:189], v176
	ds_read_b128 v[198:201], v176 offset:1024
	ds_read_b128 v[202:205], v176 offset:2048
	ds_read_b128 v[206:209], v176 offset:3072
	ds_read_b128 v[210:213], v176 offset:4096
	ds_read_b128 v[214:217], v176 offset:5120
	ds_read_b128 v[218:221], v176 offset:6144
	ds_read_b128 v[222:225], v176 offset:7168
	global_load_lds_dwordx4 v[170:171], off
	v_lshl_add_u64 v[170:171], s[52:53], 0, v[158:159]
	s_add_i32 m0, s65, 0xe000
	s_nop 0
	global_load_lds_dwordx4 v[170:171], off
	s_waitcnt vmcnt(8)
	s_waitcnt lgkmcnt(0)
	s_barrier
	s_setprio 1
	s_waitcnt lgkmcnt(0)
	v_mfma_f32_16x16x32_bf16 v[124:127], v[128:131], v[186:189], 0
	v_mfma_f32_16x16x32_bf16 v[120:123], v[136:139], v[186:189], 0
	v_mfma_f32_16x16x32_bf16 v[116:119], v[128:131], v[202:205], 0
	v_mfma_f32_16x16x32_bf16 v[112:115], v[136:139], v[202:205], 0
	v_mfma_f32_16x16x32_bf16 v[108:111], v[128:131], v[210:213], 0
	v_mfma_f32_16x16x32_bf16 v[100:103], v[136:139], v[210:213], 0
	v_mfma_f32_16x16x32_bf16 v[92:95], v[128:131], v[218:221], 0
	v_mfma_f32_16x16x32_bf16 v[80:83], v[136:139], v[218:221], 0
	v_mfma_f32_16x16x32_bf16 v[124:127], v[132:135], v[198:201], v[124:127]
	v_mfma_f32_16x16x32_bf16 v[120:123], v[140:143], v[198:201], v[120:123]
	v_mfma_f32_16x16x32_bf16 v[116:119], v[132:135], v[206:209], v[116:119]
	v_mfma_f32_16x16x32_bf16 v[112:115], v[140:143], v[206:209], v[112:115]
	v_mfma_f32_16x16x32_bf16 v[108:111], v[132:135], v[214:217], v[108:111]
	v_mfma_f32_16x16x32_bf16 v[100:103], v[140:143], v[214:217], v[100:103]
	v_mfma_f32_16x16x32_bf16 v[92:95], v[132:135], v[222:225], v[92:95]
	v_mfma_f32_16x16x32_bf16 v[80:83], v[140:143], v[222:225], v[80:83]
	s_setprio 0
	s_setprio 1
	v_mfma_f32_16x16x32_bf16 v[104:107], v[162:165], v[186:189], 0
	v_mfma_f32_16x16x32_bf16 v[96:99], v[178:181], v[186:189], 0
	v_mfma_f32_16x16x32_bf16 v[88:91], v[162:165], v[202:205], 0
	v_mfma_f32_16x16x32_bf16 v[84:87], v[178:181], v[202:205], 0
	v_mfma_f32_16x16x32_bf16 v[76:79], v[162:165], v[210:213], 0
	v_mfma_f32_16x16x32_bf16 v[72:75], v[178:181], v[210:213], 0
	v_mfma_f32_16x16x32_bf16 v[68:71], v[162:165], v[218:221], 0
	v_mfma_f32_16x16x32_bf16 v[64:67], v[178:181], v[218:221], 0
	v_mfma_f32_16x16x32_bf16 v[104:107], v[166:169], v[198:201], v[104:107]
	v_mfma_f32_16x16x32_bf16 v[96:99], v[182:185], v[198:201], v[96:99]
	v_mfma_f32_16x16x32_bf16 v[88:91], v[166:169], v[206:209], v[88:91]
	v_mfma_f32_16x16x32_bf16 v[84:87], v[182:185], v[206:209], v[84:87]
	v_mfma_f32_16x16x32_bf16 v[76:79], v[166:169], v[214:217], v[76:79]
	v_mfma_f32_16x16x32_bf16 v[72:75], v[182:185], v[214:217], v[72:75]
	v_mfma_f32_16x16x32_bf16 v[68:71], v[166:169], v[222:225], v[68:71]
	v_mfma_f32_16x16x32_bf16 v[64:67], v[182:185], v[222:225], v[64:67]
	s_setprio 0
	s_barrier
	s_add_i32 s12, s79, s64
	v_lshl_add_u64 v[170:171], s[54:55], 0, v[146:147]
	s_mov_b32 m0, s12
	ds_read_b128 v[186:189], v176 offset:16384
	ds_read_b128 v[198:201], v176 offset:17408
	ds_read_b128 v[202:205], v176 offset:18432
	ds_read_b128 v[206:209], v176 offset:19456
	ds_read_b128 v[210:213], v176 offset:20480
	ds_read_b128 v[214:217], v176 offset:21504
	ds_read_b128 v[218:221], v176 offset:22528
	ds_read_b128 v[222:225], v176 offset:23552
	global_load_lds_dwordx4 v[170:171], off
	s_add_i32 m0, s12, 0x2000
	s_add_u32 s12, s54, 0x80000
	v_lshl_add_u64 v[190:191], s[54:55], 0, v[150:151]
	s_addc_u32 s13, s55, 0
	s_add_i32 s79, s80, s64
	global_load_lds_dwordx4 v[190:191], off
	v_lshl_add_u64 v[194:195], s[12:13], 0, v[146:147]
	s_mov_b32 m0, s79
	v_lshl_add_u64 v[196:197], s[56:57], 0, v[148:149]
	global_load_lds_dwordx4 v[194:195], off
	v_lshl_add_u64 v[194:195], s[12:13], 0, v[150:151]
	s_add_i32 m0, s79, 0x2000
	s_nop 0
	global_load_lds_dwordx4 v[194:195], off
	v_lshl_add_u64 v[194:195], s[56:57], 0, v[144:145]
	s_mov_b32 m0, s65
	s_nop 0
	global_load_lds_dwordx4 v[194:195], off
	s_mov_b32 m0, s66
	s_nop 0
	global_load_lds_dwordx4 v[196:197], off
	s_waitcnt vmcnt(8)
	s_waitcnt lgkmcnt(0)
	s_barrier
; #define PG8_STAGE(bufoff, gbase, voff) do { _Pragma("unroll") for (int _i = 0; _i < 2; ++_i) \
;         __builtin_amdgcn_global_load_lds((const unsigned*)((const char*)(gbase) + (voff)[_i]), (PG8_LAS unsigned*)(lds + (bufoff) + ldsw + _i * 8192), 16, 0, 0); } while (0)
; #define PG8_LDA(dst, b, h) do { _Pragma("unroll") for (int m = 0; m < 4; ++m) _Pragma("unroll") for (int k = 0; k < 2; ++k) dst[m][k] = *(const PG8_LAS bf16x8*)(lds + PG8_SA(b, h) + aoff + m * 2048 + k * 1024); } while (0)
; #define PG8_LDB(dst, b, h) do { _Pragma("unroll") for (int n = 0; n < 2; ++n) _Pragma("unroll") for (int k = 0; k < 2; ++k) dst[n][k] = *(const PG8_LAS bf16x8*)(lds + PG8_SB(b, h) + boff + n * 2048 + k * 1024); } while (0)
; #define PG8_MMA(ai, bj, At, Bt) do { __builtin_amdgcn_s_setprio(1); _Pragma("unroll") for (int m = 0; m < 4; ++m) _Pragma("unroll") for (int n = 0; n < 2; ++n) _Pragma("unroll") for (int k = 0; k < 2; ++k) \
;         acc[ai][bj][m][n] = __builtin_amdgcn_mfma_f32_16x16x32_bf16(Bt[n][k], At[m][k], acc[ai][bj][m][n], 0, 0, 0); __builtin_amdgcn_s_setprio(0); } while (0)
; #define PG8_WAIT_V(n) asm volatile("s_waitcnt vmcnt(" #n ")" ::: "memory")
; #define PG8_WAIT_L(n) asm volatile("s_waitcnt lgkmcnt(" #n ")" ::: "memory")
; #define PG8_BAR __builtin_amdgcn_s_barrier()
; #define PG8_SCHED __builtin_amdgcn_sched_barrier(0)
; template <class Epi, class Sched, bool ALIGN_EPI = false, bool SP2 = false>
; __device__ __forceinline__ void gemm_phase(PG8_LAS unsigned char* lds, const Gemm g, const Sched& S, const Epi& E, const int tid_in) {
;     ...
;             PG8_WAIT_V(8); PG8_WAIT_L(0); PG8_BAR; PG8_MMA(0, 0, At, B0); PG8_MMA(0, 1, At, B1); PG8_BAR; PG8_SCHED;
;             PG8_LDA(At, 0, 1); PG8_STAGE(PG8_SB(0, 0), b2, voffB); PG8_STAGE(PG8_SB(0, 1), b2 + hstepB, voffB); PG8_STAGE(PG8_SA(0, 0), a2, voffA);
;             PG8_WAIT_V(8); PG8_WAIT_L(0); PG8_BAR; PG8_MMA(1, 0, At, B0); PG8_MMA(1, 1, At, B1); PG8_BAR; PG8_SCHED;
;             PG8_LDB(B0, 1, 0); PG8_LDB(B1, 1, 1); PG8_SCHED; PG8_LDA(At, 1, 0); PG8_STAGE(PG8_SA(0, 1), a2 + hstepA, voffA);
;             PG8_WAIT_V(8); PG8_WAIT_L(0); PG8_BAR; PG8_MMA(0, 0, At, B0); PG8_MMA(0, 1, At, B1); PG8_BAR; PG8_SCHED;
	s_setprio 1
	s_waitcnt lgkmcnt(0)
	v_mfma_f32_16x16x32_bf16 v[60:63], v[128:131], v[186:189], 0
	v_mfma_f32_16x16x32_bf16 v[56:59], v[136:139], v[186:189], 0
	v_mfma_f32_16x16x32_bf16 v[48:51], v[128:131], v[202:205], 0
	v_mfma_f32_16x16x32_bf16 v[40:43], v[136:139], v[202:205], 0
	v_mfma_f32_16x16x32_bf16 v[32:35], v[128:131], v[210:213], 0
	v_mfma_f32_16x16x32_bf16 v[24:27], v[136:139], v[210:213], 0
	v_mfma_f32_16x16x32_bf16 v[16:19], v[128:131], v[218:221], 0
	v_mfma_f32_16x16x32_bf16 v[8:11], v[136:139], v[218:221], 0
	v_mfma_f32_16x16x32_bf16 v[60:63], v[132:135], v[198:201], v[60:63]
	v_mfma_f32_16x16x32_bf16 v[56:59], v[140:143], v[198:201], v[56:59]
	v_mfma_f32_16x16x32_bf16 v[48:51], v[132:135], v[206:209], v[48:51]
	v_mfma_f32_16x16x32_bf16 v[40:43], v[140:143], v[206:209], v[40:43]
	v_mfma_f32_16x16x32_bf16 v[32:35], v[132:135], v[214:217], v[32:35]
	v_mfma_f32_16x16x32_bf16 v[24:27], v[140:143], v[214:217], v[24:27]
	v_mfma_f32_16x16x32_bf16 v[16:19], v[132:135], v[222:225], v[16:19]
	v_mfma_f32_16x16x32_bf16 v[8:11], v[140:143], v[222:225], v[8:11]
	s_setprio 0
	s_setprio 1
	v_mfma_f32_16x16x32_bf16 v[52:55], v[162:165], v[186:189], 0
	v_mfma_f32_16x16x32_bf16 v[44:47], v[178:181], v[186:189], 0
	v_mfma_f32_16x16x32_bf16 v[36:39], v[162:165], v[202:205], 0
	v_mfma_f32_16x16x32_bf16 v[28:31], v[178:181], v[202:205], 0
	v_mfma_f32_16x16x32_bf16 v[20:23], v[162:165], v[210:213], 0
	v_mfma_f32_16x16x32_bf16 v[12:15], v[178:181], v[210:213], 0
	v_mfma_f32_16x16x32_bf16 v[4:7], v[162:165], v[218:221], 0
	v_mfma_f32_16x16x32_bf16 v[0:3], v[178:181], v[218:221], 0
	v_mfma_f32_16x16x32_bf16 v[52:55], v[166:169], v[198:201], v[52:55]
	v_mfma_f32_16x16x32_bf16 v[44:47], v[182:185], v[198:201], v[44:47]
	v_mfma_f32_16x16x32_bf16 v[36:39], v[166:169], v[206:209], v[36:39]
	v_mfma_f32_16x16x32_bf16 v[28:31], v[182:185], v[206:209], v[28:31]
	v_mfma_f32_16x16x32_bf16 v[20:23], v[166:169], v[214:217], v[20:23]
	v_mfma_f32_16x16x32_bf16 v[12:15], v[182:185], v[214:217], v[12:15]
	v_mfma_f32_16x16x32_bf16 v[4:7], v[166:169], v[222:225], v[4:7]
	v_mfma_f32_16x16x32_bf16 v[0:3], v[182:185], v[222:225], v[0:3]
	s_setprio 0
	s_barrier
	s_add_i32 s79, 0, 0x18000
	s_add_i32 s80, 0, 0x1c000
	v_add_u32_e32 v140, s79, v174
	v_add_u32_e32 v161, s80, v174
	ds_read_b128 v[128:131], v140
	ds_read_b128 v[132:135], v140 offset:1024
	ds_read_b128 v[136:139], v140 offset:2048
	ds_read_b128 v[140:143], v140 offset:3072
	ds_read_b128 v[162:165], v161
	ds_read_b128 v[166:169], v161 offset:1024
	ds_read_b128 v[178:181], v161 offset:2048
	ds_read_b128 v[182:185], v161 offset:3072
	s_add_u32 s12, s56, 0x80000
	s_addc_u32 s13, s57, 0
	s_mov_b32 m0, s67
	v_lshl_add_u64 v[226:227], s[12:13], 0, v[144:145]
	ds_read_b128 v[186:189], v176 offset:32768
	ds_read_b128 v[198:201], v176 offset:33792
	ds_read_b128 v[202:205], v176 offset:34816
	ds_read_b128 v[206:209], v176 offset:35840
	ds_read_b128 v[210:213], v176 offset:36864
	ds_read_b128 v[214:217], v176 offset:37888
	ds_read_b128 v[218:221], v176 offset:38912
	ds_read_b128 v[222:225], v176 offset:39936
	global_load_lds_dwordx4 v[226:227], off
	v_lshl_add_u64 v[226:227], s[12:13], 0, v[148:149]
	s_mov_b32 m0, s68
	s_nop 0
	global_load_lds_dwordx4 v[226:227], off
	s_waitcnt vmcnt(8)
	s_waitcnt lgkmcnt(0)
	s_barrier
	s_setprio 1
	s_waitcnt lgkmcnt(0)
	v_mfma_f32_16x16x32_bf16 v[124:127], v[128:131], v[186:189], v[124:127]
	v_mfma_f32_16x16x32_bf16 v[120:123], v[136:139], v[186:189], v[120:123]
	v_mfma_f32_16x16x32_bf16 v[116:119], v[128:131], v[202:205], v[116:119]
	v_mfma_f32_16x16x32_bf16 v[112:115], v[136:139], v[202:205], v[112:115]
	v_mfma_f32_16x16x32_bf16 v[108:111], v[128:131], v[210:213], v[108:111]
	v_mfma_f32_16x16x32_bf16 v[100:103], v[136:139], v[210:213], v[100:103]
	v_mfma_f32_16x16x32_bf16 v[92:95], v[128:131], v[218:221], v[92:95]
	v_mfma_f32_16x16x32_bf16 v[80:83], v[136:139], v[218:221], v[80:83]
	v_mfma_f32_16x16x32_bf16 v[124:127], v[132:135], v[198:201], v[124:127]
	v_mfma_f32_16x16x32_bf16 v[120:123], v[140:143], v[198:201], v[120:123]
	v_mfma_f32_16x16x32_bf16 v[116:119], v[132:135], v[206:209], v[116:119]
	v_mfma_f32_16x16x32_bf16 v[112:115], v[140:143], v[206:209], v[112:115]
	v_mfma_f32_16x16x32_bf16 v[108:111], v[132:135], v[214:217], v[108:111]
	v_mfma_f32_16x16x32_bf16 v[100:103], v[140:143], v[214:217], v[100:103]
	v_mfma_f32_16x16x32_bf16 v[92:95], v[132:135], v[222:225], v[92:95]
	v_mfma_f32_16x16x32_bf16 v[80:83], v[140:143], v[222:225], v[80:83]
	s_setprio 0
	s_setprio 1
	v_mfma_f32_16x16x32_bf16 v[104:107], v[162:165], v[186:189], v[104:107]
	v_mfma_f32_16x16x32_bf16 v[96:99], v[178:181], v[186:189], v[96:99]
	v_mfma_f32_16x16x32_bf16 v[88:91], v[162:165], v[202:205], v[88:91]
	v_mfma_f32_16x16x32_bf16 v[84:87], v[178:181], v[202:205], v[84:87]
	v_mfma_f32_16x16x32_bf16 v[76:79], v[162:165], v[210:213], v[76:79]
	v_mfma_f32_16x16x32_bf16 v[72:75], v[178:181], v[210:213], v[72:75]
	v_mfma_f32_16x16x32_bf16 v[68:71], v[162:165], v[218:221], v[68:71]
	v_mfma_f32_16x16x32_bf16 v[64:67], v[178:181], v[218:221], v[64:67]
	v_mfma_f32_16x16x32_bf16 v[104:107], v[166:169], v[198:201], v[104:107]
	v_mfma_f32_16x16x32_bf16 v[96:99], v[182:185], v[198:201], v[96:99]
	v_mfma_f32_16x16x32_bf16 v[88:91], v[166:169], v[206:209], v[88:91]
	v_mfma_f32_16x16x32_bf16 v[84:87], v[182:185], v[206:209], v[84:87]
	v_mfma_f32_16x16x32_bf16 v[76:79], v[166:169], v[214:217], v[76:79]
	v_mfma_f32_16x16x32_bf16 v[72:75], v[182:185], v[214:217], v[72:75]
	v_mfma_f32_16x16x32_bf16 v[68:71], v[166:169], v[222:225], v[68:71]
	v_mfma_f32_16x16x32_bf16 v[64:67], v[182:185], v[222:225], v[64:67]
	s_setprio 0
	s_barrier
; #define PG8_STAGE(bufoff, gbase, voff) do { _Pragma("unroll") for (int _i = 0; _i < 2; ++_i) \
;         __builtin_amdgcn_global_load_lds((const unsigned*)((const char*)(gbase) + (voff)[_i]), (PG8_LAS unsigned*)(lds + (bufoff) + ldsw + _i * 8192), 16, 0, 0); } while (0)
; #define PG8_LDA(dst, b, h) do { _Pragma("unroll") for (int m = 0; m < 4; ++m) _Pragma("unroll") for (int k = 0; k < 2; ++k) dst[m][k] = *(const PG8_LAS bf16x8*)(lds + PG8_SA(b, h) + aoff + m * 2048 + k * 1024); } while (0)
; #define PG8_LDB(dst, b, h) do { _Pragma("unroll") for (int n = 0; n < 2; ++n) _Pragma("unroll") for (int k = 0; k < 2; ++k) dst[n][k] = *(const PG8_LAS bf16x8*)(lds + PG8_SB(b, h) + boff + n * 2048 + k * 1024); } while (0)
; #define PG8_MMA(ai, bj, At, Bt) do { __builtin_amdgcn_s_setprio(1); _Pragma("unroll") for (int m = 0; m < 4; ++m) _Pragma("unroll") for (int n = 0; n < 2; ++n) _Pragma("unroll") for (int k = 0; k < 2; ++k) \
;         acc[ai][bj][m][n] = __builtin_amdgcn_mfma_f32_16x16x32_bf16(Bt[n][k], At[m][k], acc[ai][bj][m][n], 0, 0, 0); __builtin_amdgcn_s_setprio(0); } while (0)
; #define PG8_BAR __builtin_amdgcn_s_barrier()
; template <class Epi, class Sched, bool ALIGN_EPI = false, bool SP2 = false>
; __device__ __forceinline__ void gemm_phase(PG8_LAS unsigned char* lds, const Gemm g, const Sched& S, const Epi& E, const int tid_in) {
;     ...
;             PG8_LDB(B0, 0, 0); PG8_LDB(B1, 0, 1); PG8_SCHED; PG8_LDA(At, 0, 0); PG8_STAGE(PG8_SA(1, 1), a1 + hstepA, voffA);
;             PG8_WAIT_V(8); PG8_WAIT_L(0); PG8_BAR; PG8_MMA(0, 0, At, B0); PG8_MMA(0, 1, At, B1); PG8_BAR; PG8_SCHED;
;             PG8_LDA(At, 0, 1); PG8_STAGE(PG8_SB(0, 0), b2, voffB); PG8_STAGE(PG8_SB(0, 1), b2 + hstepB, voffB); PG8_STAGE(PG8_SA(0, 0), a2, voffA);
;             PG8_WAIT_V(8); PG8_WAIT_L(0); PG8_BAR; PG8_MMA(1, 0, At, B0); PG8_MMA(1, 1, At, B1); PG8_BAR; PG8_SCHED;
;             PG8_LDB(B0, 1, 0); PG8_LDB(B1, 1, 1); PG8_SCHED; PG8_LDA(At, 1, 0); PG8_STAGE(PG8_SA(0, 1), a2 + hstepA, voffA);
;             PG8_WAIT_V(8); PG8_WAIT_L(0); PG8_BAR; PG8_MMA(0, 0, At, B0); PG8_MMA(0, 1, At, B1); PG8_BAR; PG8_SCHED;
;             PG8_LDA(At, 1, 1); PG8_STAGE(PG8_SB(1, 0), b3, voffB); PG8_STAGE(PG8_SB(1, 1), b3 + hstepB, voffB); PG8_STAGE(PG8_SA(1, 0), a3, voffA);
;             PG8_WAIT_V(8); PG8_WAIT_L(0); PG8_BAR; PG8_MMA(1, 0, At, B0); PG8_MMA(1, 1, At, B1); PG8_BAR; PG8_SCHED;
	s_add_i32 s12, s79, s64
	v_lshl_add_u64 v[170:171], v[170:171], 0, s[26:27]
	s_mov_b32 m0, s12
	ds_read_b128 v[186:189], v176 offset:49152
	ds_read_b128 v[198:201], v176 offset:50176
	ds_read_b128 v[202:205], v176 offset:51200
	ds_read_b128 v[206:209], v176 offset:52224
	ds_read_b128 v[210:213], v176 offset:53248
	ds_read_b128 v[214:217], v176 offset:54272
	ds_read_b128 v[218:221], v176 offset:55296
	ds_read_b128 v[222:225], v176 offset:56320
	global_load_lds_dwordx4 v[170:171], off
	s_add_i32 m0, s12, 0x2000
	s_add_u32 s12, s54, 0x80080
	v_lshl_add_u64 v[170:171], v[190:191], 0, s[26:27]
	s_addc_u32 s13, s55, 0
	s_add_i32 s54, s80, s64
	global_load_lds_dwordx4 v[170:171], off
	v_lshl_add_u64 v[170:171], s[12:13], 0, v[146:147]
	s_mov_b32 m0, s54
	s_nop 0
	global_load_lds_dwordx4 v[170:171], off
	v_lshl_add_u64 v[170:171], s[12:13], 0, v[150:151]
	s_add_i32 m0, s54, 0x2000
	s_nop 0
	global_load_lds_dwordx4 v[170:171], off
	v_lshl_add_u64 v[170:171], v[194:195], 0, s[26:27]
	s_mov_b32 m0, s73
	s_nop 0
	global_load_lds_dwordx4 v[170:171], off
	v_lshl_add_u64 v[170:171], v[196:197], 0, s[26:27]
	s_mov_b32 m0, s74
	s_nop 0
	global_load_lds_dwordx4 v[170:171], off
	s_waitcnt vmcnt(8)
	s_waitcnt lgkmcnt(0)
	s_barrier
	s_setprio 1
	s_waitcnt lgkmcnt(0)
	v_mfma_f32_16x16x32_bf16 v[60:63], v[128:131], v[186:189], v[60:63]
	v_mfma_f32_16x16x32_bf16 v[56:59], v[136:139], v[186:189], v[56:59]
	v_mfma_f32_16x16x32_bf16 v[48:51], v[128:131], v[202:205], v[48:51]
	v_mfma_f32_16x16x32_bf16 v[40:43], v[136:139], v[202:205], v[40:43]
	v_mfma_f32_16x16x32_bf16 v[32:35], v[128:131], v[210:213], v[32:35]
	v_mfma_f32_16x16x32_bf16 v[24:27], v[136:139], v[210:213], v[24:27]
	v_mfma_f32_16x16x32_bf16 v[16:19], v[128:131], v[218:221], v[16:19]
	v_mfma_f32_16x16x32_bf16 v[8:11], v[136:139], v[218:221], v[8:11]
	v_mfma_f32_16x16x32_bf16 v[60:63], v[132:135], v[198:201], v[60:63]
	v_mfma_f32_16x16x32_bf16 v[56:59], v[140:143], v[198:201], v[56:59]
	v_mfma_f32_16x16x32_bf16 v[48:51], v[132:135], v[206:209], v[48:51]
	v_mfma_f32_16x16x32_bf16 v[40:43], v[140:143], v[206:209], v[40:43]
	v_mfma_f32_16x16x32_bf16 v[32:35], v[132:135], v[214:217], v[32:35]
	v_mfma_f32_16x16x32_bf16 v[24:27], v[140:143], v[214:217], v[24:27]
	v_mfma_f32_16x16x32_bf16 v[16:19], v[132:135], v[222:225], v[16:19]
	v_mfma_f32_16x16x32_bf16 v[8:11], v[140:143], v[222:225], v[8:11]
	s_setprio 0
	s_setprio 1
	v_mfma_f32_16x16x32_bf16 v[52:55], v[162:165], v[186:189], v[52:55]
	v_mfma_f32_16x16x32_bf16 v[44:47], v[178:181], v[186:189], v[44:47]
	v_mfma_f32_16x16x32_bf16 v[36:39], v[162:165], v[202:205], v[36:39]
	v_mfma_f32_16x16x32_bf16 v[28:31], v[178:181], v[202:205], v[28:31]
	v_mfma_f32_16x16x32_bf16 v[20:23], v[162:165], v[210:213], v[20:23]
	v_mfma_f32_16x16x32_bf16 v[12:15], v[178:181], v[210:213], v[12:15]
	v_mfma_f32_16x16x32_bf16 v[4:7], v[162:165], v[218:221], v[4:7]
	v_mfma_f32_16x16x32_bf16 v[0:3], v[178:181], v[218:221], v[0:3]
	v_mfma_f32_16x16x32_bf16 v[52:55], v[166:169], v[198:201], v[52:55]
	v_mfma_f32_16x16x32_bf16 v[44:47], v[182:185], v[198:201], v[44:47]
	v_mfma_f32_16x16x32_bf16 v[36:39], v[166:169], v[206:209], v[36:39]
	v_mfma_f32_16x16x32_bf16 v[28:31], v[182:185], v[206:209], v[28:31]
	v_mfma_f32_16x16x32_bf16 v[20:23], v[166:169], v[214:217], v[20:23]
	v_mfma_f32_16x16x32_bf16 v[12:15], v[182:185], v[214:217], v[12:15]
	v_mfma_f32_16x16x32_bf16 v[4:7], v[166:169], v[222:225], v[4:7]
	v_mfma_f32_16x16x32_bf16 v[0:3], v[182:185], v[222:225], v[0:3]
	s_setprio 0
	s_barrier
	s_add_i32 s78, s78, 2
	s_add_u32 s52, s52, 0x100
	s_addc_u32 s53, s53, 0
	s_add_u32 s76, s76, 0x100
	s_addc_u32 s77, s77, 0
	s_cmp_gt_u32 s78, 29
	.p2align 6
.LBB0_815:
	s_add_u32 s12, s52, 0xfff80080
	s_addc_u32 s13, s53, -1
	s_add_i32 s79, 0, 0x10000
	s_cmp_eq_u32 s78, 28
	s_cselect_b32 s57, s23, s13
	s_cselect_b32 s56, s31, s12
	s_cselect_b32 s55, s45, s77
	s_cselect_b32 s54, s47, s76
	s_add_i32 s80, 0, 0x14000
	v_add_u32_e32 v140, s79, v174
	v_add_u32_e32 v161, s80, v174
	ds_read_b128 v[128:131], v140
	ds_read_b128 v[132:135], v140 offset:1024
	ds_read_b128 v[136:139], v140 offset:2048
	ds_read_b128 v[140:143], v140 offset:3072
	ds_read_b128 v[162:165], v161
	ds_read_b128 v[166:169], v161 offset:1024
	ds_read_b128 v[178:181], v161 offset:2048
	ds_read_b128 v[182:185], v161 offset:3072
	v_lshl_add_u64 v[170:171], s[52:53], 0, v[156:157]
	s_add_i32 m0, s65, 0xc000
	ds_read_b128 v[186:189], v176
	ds_read_b128 v[198:201], v176 offset:1024
	ds_read_b128 v[202:205], v176 offset:2048
	ds_read_b128 v[206:209], v176 offset:3072
	ds_read_b128 v[210:213], v176 offset:4096
	ds_read_b128 v[214:217], v176 offset:5120
	ds_read_b128 v[218:221], v176 offset:6144
	ds_read_b128 v[222:225], v176 offset:7168
	global_load_lds_dwordx4 v[170:171], off
	v_lshl_add_u64 v[170:171], s[52:53], 0, v[158:159]
	s_add_i32 m0, s65, 0xe000
	s_nop 0
	global_load_lds_dwordx4 v[170:171], off
	s_waitcnt vmcnt(8)
	s_waitcnt lgkmcnt(0)
	s_barrier
; #define PG8_STAGE(bufoff, gbase, voff) do { _Pragma("unroll") for (int _i = 0; _i < 2; ++_i) \
;         __builtin_amdgcn_global_load_lds((const unsigned*)((const char*)(gbase) + (voff)[_i]), (PG8_LAS unsigned*)(lds + (bufoff) + ldsw + _i * 8192), 16, 0, 0); } while (0)
; #define PG8_LDA(dst, b, h) do { _Pragma("unroll") for (int m = 0; m < 4; ++m) _Pragma("unroll") for (int k = 0; k < 2; ++k) dst[m][k] = *(const PG8_LAS bf16x8*)(lds + PG8_SA(b, h) + aoff + m * 2048 + k * 1024); } while (0)
; #define PG8_LDB(dst, b, h) do { _Pragma("unroll") for (int n = 0; n < 2; ++n) _Pragma("unroll") for (int k = 0; k < 2; ++k) dst[n][k] = *(const PG8_LAS bf16x8*)(lds + PG8_SB(b, h) + boff + n * 2048 + k * 1024); } while (0)
; #define PG8_MMA(ai, bj, At, Bt) do { __builtin_amdgcn_s_setprio(1); _Pragma("unroll") for (int m = 0; m < 4; ++m) _Pragma("unroll") for (int n = 0; n < 2; ++n) _Pragma("unroll") for (int k = 0; k < 2; ++k) \
;         acc[ai][bj][m][n] = __builtin_amdgcn_mfma_f32_16x16x32_bf16(Bt[n][k], At[m][k], acc[ai][bj][m][n], 0, 0, 0); __builtin_amdgcn_s_setprio(0); } while (0)
; #define PG8_WAIT_V(n) asm volatile("s_waitcnt vmcnt(" #n ")" ::: "memory")
; #define PG8_WAIT_L(n) asm volatile("s_waitcnt lgkmcnt(" #n ")" ::: "memory")
; #define PG8_BAR __builtin_amdgcn_s_barrier()
; #define PG8_SCHED __builtin_amdgcn_sched_barrier(0)
; template <class Epi, class Sched, bool ALIGN_EPI = false, bool SP2 = false>
; __device__ __forceinline__ void gemm_phase(PG8_LAS unsigned char* lds, const Gemm g, const Sched& S, const Epi& E, const int tid_in) {
;     ...
;             PG8_LDB(B0, 0, 0); PG8_LDB(B1, 0, 1); PG8_SCHED; PG8_LDA(At, 0, 0); PG8_STAGE(PG8_SA(1, 1), a1 + hstepA, voffA);
;             PG8_WAIT_V(8); PG8_WAIT_L(0); PG8_BAR; PG8_MMA(0, 0, At, B0); PG8_MMA(0, 1, At, B1); PG8_BAR; PG8_SCHED;
;             PG8_LDA(At, 0, 1); PG8_STAGE(PG8_SB(0, 0), b2, voffB); PG8_STAGE(PG8_SB(0, 1), b2 + hstepB, voffB); PG8_STAGE(PG8_SA(0, 0), a2, voffA);
;             PG8_WAIT_V(8); PG8_WAIT_L(0); PG8_BAR; PG8_MMA(1, 0, At, B0); PG8_MMA(1, 1, At, B1); PG8_BAR; PG8_SCHED;
	s_setprio 1
	s_waitcnt lgkmcnt(0)
	v_mfma_f32_16x16x32_bf16 v[124:127], v[128:131], v[186:189], v[124:127]
	v_mfma_f32_16x16x32_bf16 v[120:123], v[136:139], v[186:189], v[120:123]
	v_mfma_f32_16x16x32_bf16 v[116:119], v[128:131], v[202:205], v[116:119]
	v_mfma_f32_16x16x32_bf16 v[112:115], v[136:139], v[202:205], v[112:115]
	v_mfma_f32_16x16x32_bf16 v[108:111], v[128:131], v[210:213], v[108:111]
	v_mfma_f32_16x16x32_bf16 v[100:103], v[136:139], v[210:213], v[100:103]
	v_mfma_f32_16x16x32_bf16 v[92:95], v[128:131], v[218:221], v[92:95]
	v_mfma_f32_16x16x32_bf16 v[80:83], v[136:139], v[218:221], v[80:83]
	v_mfma_f32_16x16x32_bf16 v[124:127], v[132:135], v[198:201], v[124:127]
	v_mfma_f32_16x16x32_bf16 v[120:123], v[140:143], v[198:201], v[120:123]
	v_mfma_f32_16x16x32_bf16 v[116:119], v[132:135], v[206:209], v[116:119]
	v_mfma_f32_16x16x32_bf16 v[112:115], v[140:143], v[206:209], v[112:115]
	v_mfma_f32_16x16x32_bf16 v[108:111], v[132:135], v[214:217], v[108:111]
	v_mfma_f32_16x16x32_bf16 v[100:103], v[140:143], v[214:217], v[100:103]
	v_mfma_f32_16x16x32_bf16 v[92:95], v[132:135], v[222:225], v[92:95]
	v_mfma_f32_16x16x32_bf16 v[80:83], v[140:143], v[222:225], v[80:83]
	v_mfma_f32_16x16x32_bf16 v[104:107], v[162:165], v[186:189], v[104:107]
	v_mfma_f32_16x16x32_bf16 v[96:99], v[178:181], v[186:189], v[96:99]
	v_mfma_f32_16x16x32_bf16 v[88:91], v[162:165], v[202:205], v[88:91]
	v_mfma_f32_16x16x32_bf16 v[84:87], v[178:181], v[202:205], v[84:87]
	v_mfma_f32_16x16x32_bf16 v[76:79], v[162:165], v[210:213], v[76:79]
	v_mfma_f32_16x16x32_bf16 v[72:75], v[178:181], v[210:213], v[72:75]
	v_mfma_f32_16x16x32_bf16 v[68:71], v[162:165], v[218:221], v[68:71]
	v_mfma_f32_16x16x32_bf16 v[64:67], v[178:181], v[218:221], v[64:67]
	v_mfma_f32_16x16x32_bf16 v[104:107], v[166:169], v[198:201], v[104:107]
	v_mfma_f32_16x16x32_bf16 v[96:99], v[182:185], v[198:201], v[96:99]
	v_mfma_f32_16x16x32_bf16 v[88:91], v[166:169], v[206:209], v[88:91]
	v_mfma_f32_16x16x32_bf16 v[84:87], v[182:185], v[206:209], v[84:87]
	v_mfma_f32_16x16x32_bf16 v[76:79], v[166:169], v[214:217], v[76:79]
	v_mfma_f32_16x16x32_bf16 v[72:75], v[182:185], v[214:217], v[72:75]
	v_mfma_f32_16x16x32_bf16 v[68:71], v[166:169], v[222:225], v[68:71]
	v_mfma_f32_16x16x32_bf16 v[64:67], v[182:185], v[222:225], v[64:67]
	s_setprio 0
	s_barrier
	s_add_i32 s12, s79, s64
	v_lshl_add_u64 v[170:171], s[54:55], 0, v[146:147]
	s_mov_b32 m0, s12
	ds_read_b128 v[186:189], v176 offset:16384
	ds_read_b128 v[198:201], v176 offset:17408
	ds_read_b128 v[202:205], v176 offset:18432
	ds_read_b128 v[206:209], v176 offset:19456
	ds_read_b128 v[210:213], v176 offset:20480
	ds_read_b128 v[214:217], v176 offset:21504
	ds_read_b128 v[218:221], v176 offset:22528
	ds_read_b128 v[222:225], v176 offset:23552
	global_load_lds_dwordx4 v[170:171], off
	s_add_i32 m0, s12, 0x2000
	s_add_u32 s12, s54, 0x80000
	v_lshl_add_u64 v[190:191], s[54:55], 0, v[150:151]
	s_addc_u32 s13, s55, 0
	s_add_i32 s79, s80, s64
	global_load_lds_dwordx4 v[190:191], off
	v_lshl_add_u64 v[194:195], s[12:13], 0, v[146:147]
	s_mov_b32 m0, s79
	v_lshl_add_u64 v[196:197], s[56:57], 0, v[148:149]
	global_load_lds_dwordx4 v[194:195], off
	v_lshl_add_u64 v[194:195], s[12:13], 0, v[150:151]
	s_add_i32 m0, s79, 0x2000
	s_nop 0
	global_load_lds_dwordx4 v[194:195], off
	v_lshl_add_u64 v[194:195], s[56:57], 0, v[144:145]
	s_mov_b32 m0, s65
	s_nop 0
	global_load_lds_dwordx4 v[194:195], off
	s_mov_b32 m0, s66
	s_nop 0
	global_load_lds_dwordx4 v[196:197], off
	s_waitcnt vmcnt(8)
	s_waitcnt lgkmcnt(0)
	s_barrier
	s_setprio 1
	s_waitcnt lgkmcnt(0)
	v_mfma_f32_16x16x32_bf16 v[60:63], v[128:131], v[186:189], v[60:63]
	v_mfma_f32_16x16x32_bf16 v[56:59], v[136:139], v[186:189], v[56:59]
	v_mfma_f32_16x16x32_bf16 v[48:51], v[128:131], v[202:205], v[48:51]
	v_mfma_f32_16x16x32_bf16 v[40:43], v[136:139], v[202:205], v[40:43]
	v_mfma_f32_16x16x32_bf16 v[32:35], v[128:131], v[210:213], v[32:35]
	v_mfma_f32_16x16x32_bf16 v[24:27], v[136:139], v[210:213], v[24:27]
	v_mfma_f32_16x16x32_bf16 v[16:19], v[128:131], v[218:221], v[16:19]
	v_mfma_f32_16x16x32_bf16 v[8:11], v[136:139], v[218:221], v[8:11]
	v_mfma_f32_16x16x32_bf16 v[60:63], v[132:135], v[198:201], v[60:63]
	v_mfma_f32_16x16x32_bf16 v[56:59], v[140:143], v[198:201], v[56:59]
	v_mfma_f32_16x16x32_bf16 v[48:51], v[132:135], v[206:209], v[48:51]
	v_mfma_f32_16x16x32_bf16 v[40:43], v[140:143], v[206:209], v[40:43]
	v_mfma_f32_16x16x32_bf16 v[32:35], v[132:135], v[214:217], v[32:35]
	v_mfma_f32_16x16x32_bf16 v[24:27], v[140:143], v[214:217], v[24:27]
	v_mfma_f32_16x16x32_bf16 v[16:19], v[132:135], v[222:225], v[16:19]
	v_mfma_f32_16x16x32_bf16 v[8:11], v[140:143], v[222:225], v[8:11]
	v_mfma_f32_16x16x32_bf16 v[52:55], v[162:165], v[186:189], v[52:55]
	v_mfma_f32_16x16x32_bf16 v[44:47], v[178:181], v[186:189], v[44:47]
	v_mfma_f32_16x16x32_bf16 v[36:39], v[162:165], v[202:205], v[36:39]
	v_mfma_f32_16x16x32_bf16 v[28:31], v[178:181], v[202:205], v[28:31]
	v_mfma_f32_16x16x32_bf16 v[20:23], v[162:165], v[210:213], v[20:23]
	v_mfma_f32_16x16x32_bf16 v[12:15], v[178:181], v[210:213], v[12:15]
	v_mfma_f32_16x16x32_bf16 v[4:7], v[162:165], v[218:221], v[4:7]
	v_mfma_f32_16x16x32_bf16 v[0:3], v[178:181], v[218:221], v[0:3]
	v_mfma_f32_16x16x32_bf16 v[52:55], v[166:169], v[198:201], v[52:55]
	v_mfma_f32_16x16x32_bf16 v[44:47], v[182:185], v[198:201], v[44:47]
	v_mfma_f32_16x16x32_bf16 v[36:39], v[166:169], v[206:209], v[36:39]
	v_mfma_f32_16x16x32_bf16 v[28:31], v[182:185], v[206:209], v[28:31]
	v_mfma_f32_16x16x32_bf16 v[20:23], v[166:169], v[214:217], v[20:23]
	v_mfma_f32_16x16x32_bf16 v[12:15], v[182:185], v[214:217], v[12:15]
	v_mfma_f32_16x16x32_bf16 v[4:7], v[166:169], v[222:225], v[4:7]
	v_mfma_f32_16x16x32_bf16 v[0:3], v[182:185], v[222:225], v[0:3]
	s_setprio 0
	s_barrier
; #define PG8_STAGE(bufoff, gbase, voff) do { _Pragma("unroll") for (int _i = 0; _i < 2; ++_i) \
;         __builtin_amdgcn_global_load_lds((const unsigned*)((const char*)(gbase) + (voff)[_i]), (PG8_LAS unsigned*)(lds + (bufoff) + ldsw + _i * 8192), 16, 0, 0); } while (0)
; #define PG8_LDA(dst, b, h) do { _Pragma("unroll") for (int m = 0; m < 4; ++m) _Pragma("unroll") for (int k = 0; k < 2; ++k) dst[m][k] = *(const PG8_LAS bf16x8*)(lds + PG8_SA(b, h) + aoff + m * 2048 + k * 1024); } while (0)
; #define PG8_LDB(dst, b, h) do { _Pragma("unroll") for (int n = 0; n < 2; ++n) _Pragma("unroll") for (int k = 0; k < 2; ++k) dst[n][k] = *(const PG8_LAS bf16x8*)(lds + PG8_SB(b, h) + boff + n * 2048 + k * 1024); } while (0)
; #define PG8_MMA(ai, bj, At, Bt) do { __builtin_amdgcn_s_setprio(1); _Pragma("unroll") for (int m = 0; m < 4; ++m) _Pragma("unroll") for (int n = 0; n < 2; ++n) _Pragma("unroll") for (int k = 0; k < 2; ++k) \
;         acc[ai][bj][m][n] = __builtin_amdgcn_mfma_f32_16x16x32_bf16(Bt[n][k], At[m][k], acc[ai][bj][m][n], 0, 0, 0); __builtin_amdgcn_s_setprio(0); } while (0)
; #define PG8_WAIT_V(n) asm volatile("s_waitcnt vmcnt(" #n ")" ::: "memory")
; #define PG8_WAIT_L(n) asm volatile("s_waitcnt lgkmcnt(" #n ")" ::: "memory")
; #define PG8_BAR __builtin_amdgcn_s_barrier()
; #define PG8_SCHED __builtin_amdgcn_sched_barrier(0)
; template <class Epi, class Sched, bool ALIGN_EPI = false, bool SP2 = false>
; __device__ __forceinline__ void gemm_phase(PG8_LAS unsigned char* lds, const Gemm g, const Sched& S, const Epi& E, const int tid_in) {
;     ...
;             PG8_LDB(B0, 1, 0); PG8_LDB(B1, 1, 1); PG8_SCHED; PG8_LDA(At, 1, 0); PG8_STAGE(PG8_SA(0, 1), a2 + hstepA, voffA);
;             PG8_WAIT_V(8); PG8_WAIT_L(0); PG8_BAR; PG8_MMA(0, 0, At, B0); PG8_MMA(0, 1, At, B1); PG8_BAR; PG8_SCHED;
	s_add_i32 s79, 0, 0x18000
	s_add_i32 s80, 0, 0x1c000
	v_add_u32_e32 v140, s79, v174
	v_add_u32_e32 v161, s80, v174
	ds_read_b128 v[128:131], v140
	ds_read_b128 v[132:135], v140 offset:1024
	ds_read_b128 v[136:139], v140 offset:2048
	ds_read_b128 v[140:143], v140 offset:3072
	ds_read_b128 v[162:165], v161
	ds_read_b128 v[166:169], v161 offset:1024
	ds_read_b128 v[178:181], v161 offset:2048
	ds_read_b128 v[182:185], v161 offset:3072
	s_add_u32 s12, s56, 0x80000
	s_addc_u32 s13, s57, 0
	s_mov_b32 m0, s67
	v_lshl_add_u64 v[226:227], s[12:13], 0, v[144:145]
	ds_read_b128 v[186:189], v176 offset:32768
	ds_read_b128 v[198:201], v176 offset:33792
	ds_read_b128 v[202:205], v176 offset:34816
	ds_read_b128 v[206:209], v176 offset:35840
	ds_read_b128 v[210:213], v176 offset:36864
	ds_read_b128 v[214:217], v176 offset:37888
	ds_read_b128 v[218:221], v176 offset:38912
	ds_read_b128 v[222:225], v176 offset:39936
	global_load_lds_dwordx4 v[226:227], off
	v_lshl_add_u64 v[226:227], s[12:13], 0, v[148:149]
	s_mov_b32 m0, s68
	s_nop 0
	global_load_lds_dwordx4 v[226:227], off
	s_waitcnt vmcnt(8)
	s_waitcnt lgkmcnt(0)
	s_barrier
	s_setprio 1
	s_waitcnt lgkmcnt(0)
	v_mfma_f32_16x16x32_bf16 v[124:127], v[128:131], v[186:189], v[124:127]
	v_mfma_f32_16x16x32_bf16 v[120:123], v[136:139], v[186:189], v[120:123]
	v_mfma_f32_16x16x32_bf16 v[116:119], v[128:131], v[202:205], v[116:119]
	v_mfma_f32_16x16x32_bf16 v[112:115], v[136:139], v[202:205], v[112:115]
	v_mfma_f32_16x16x32_bf16 v[108:111], v[128:131], v[210:213], v[108:111]
	v_mfma_f32_16x16x32_bf16 v[100:103], v[136:139], v[210:213], v[100:103]
	v_mfma_f32_16x16x32_bf16 v[92:95], v[128:131], v[218:221], v[92:95]
	v_mfma_f32_16x16x32_bf16 v[80:83], v[136:139], v[218:221], v[80:83]
	v_mfma_f32_16x16x32_bf16 v[124:127], v[132:135], v[198:201], v[124:127]
	v_mfma_f32_16x16x32_bf16 v[120:123], v[140:143], v[198:201], v[120:123]
	v_mfma_f32_16x16x32_bf16 v[116:119], v[132:135], v[206:209], v[116:119]
	v_mfma_f32_16x16x32_bf16 v[112:115], v[140:143], v[206:209], v[112:115]
	v_mfma_f32_16x16x32_bf16 v[108:111], v[132:135], v[214:217], v[108:111]
	v_mfma_f32_16x16x32_bf16 v[100:103], v[140:143], v[214:217], v[100:103]
	v_mfma_f32_16x16x32_bf16 v[92:95], v[132:135], v[222:225], v[92:95]
	v_mfma_f32_16x16x32_bf16 v[80:83], v[140:143], v[222:225], v[80:83]
	v_mfma_f32_16x16x32_bf16 v[104:107], v[162:165], v[186:189], v[104:107]
	v_mfma_f32_16x16x32_bf16 v[96:99], v[178:181], v[186:189], v[96:99]
	v_mfma_f32_16x16x32_bf16 v[88:91], v[162:165], v[202:205], v[88:91]
	v_mfma_f32_16x16x32_bf16 v[84:87], v[178:181], v[202:205], v[84:87]
	v_mfma_f32_16x16x32_bf16 v[76:79], v[162:165], v[210:213], v[76:79]
	v_mfma_f32_16x16x32_bf16 v[72:75], v[178:181], v[210:213], v[72:75]
	v_mfma_f32_16x16x32_bf16 v[68:71], v[162:165], v[218:221], v[68:71]
	v_mfma_f32_16x16x32_bf16 v[64:67], v[178:181], v[218:221], v[64:67]
	v_mfma_f32_16x16x32_bf16 v[104:107], v[166:169], v[198:201], v[104:107]
	v_mfma_f32_16x16x32_bf16 v[96:99], v[182:185], v[198:201], v[96:99]
	v_mfma_f32_16x16x32_bf16 v[88:91], v[166:169], v[206:209], v[88:91]
	v_mfma_f32_16x16x32_bf16 v[84:87], v[182:185], v[206:209], v[84:87]
	v_mfma_f32_16x16x32_bf16 v[76:79], v[166:169], v[214:217], v[76:79]
	v_mfma_f32_16x16x32_bf16 v[72:75], v[182:185], v[214:217], v[72:75]
	v_mfma_f32_16x16x32_bf16 v[68:71], v[166:169], v[222:225], v[68:71]
	v_mfma_f32_16x16x32_bf16 v[64:67], v[182:185], v[222:225], v[64:67]
	s_setprio 0
	s_barrier
; #define PG8_STAGE(bufoff, gbase, voff) do { _Pragma("unroll") for (int _i = 0; _i < 2; ++_i) \
;         __builtin_amdgcn_global_load_lds((const unsigned*)((const char*)(gbase) + (voff)[_i]), (PG8_LAS unsigned*)(lds + (bufoff) + ldsw + _i * 8192), 16, 0, 0); } while (0)
; #define PG8_LDA(dst, b, h) do { _Pragma("unroll") for (int m = 0; m < 4; ++m) _Pragma("unroll") for (int k = 0; k < 2; ++k) dst[m][k] = *(const PG8_LAS bf16x8*)(lds + PG8_SA(b, h) + aoff + m * 2048 + k * 1024); } while (0)
; #define PG8_MMA(ai, bj, At, Bt) do { __builtin_amdgcn_s_setprio(1); _Pragma("unroll") for (int m = 0; m < 4; ++m) _Pragma("unroll") for (int n = 0; n < 2; ++n) _Pragma("unroll") for (int k = 0; k < 2; ++k) \
;         acc[ai][bj][m][n] = __builtin_amdgcn_mfma_f32_16x16x32_bf16(Bt[n][k], At[m][k], acc[ai][bj][m][n], 0, 0, 0); __builtin_amdgcn_s_setprio(0); } while (0)
; #define PG8_WAIT_V(n) asm volatile("s_waitcnt vmcnt(" #n ")" ::: "memory")
; #define PG8_WAIT_L(n) asm volatile("s_waitcnt lgkmcnt(" #n ")" ::: "memory")
; #define PG8_BAR __builtin_amdgcn_s_barrier()
; #define PG8_SCHED __builtin_amdgcn_sched_barrier(0)
; template <class Epi, class Sched, bool ALIGN_EPI = false, bool SP2 = false>
; __device__ __forceinline__ void gemm_phase(PG8_LAS unsigned char* lds, const Gemm g, const Sched& S, const Epi& E, const int tid_in) {
;     ...
;             PG8_LDA(At, 1, 1); PG8_STAGE(PG8_SB(1, 0), b3, voffB); PG8_STAGE(PG8_SB(1, 1), b3 + hstepB, voffB); PG8_STAGE(PG8_SA(1, 0), a3, voffA);
;             PG8_WAIT_V(8); PG8_WAIT_L(0); PG8_BAR; PG8_MMA(1, 0, At, B0); PG8_MMA(1, 1, At, B1); PG8_BAR; PG8_SCHED;
;     ...
;         if constexpr (ALIGN_EPI) { if (wr == 0) PG8_BAR; }
	s_add_i32 s12, s79, s64
	v_lshl_add_u64 v[170:171], v[170:171], 0, s[26:27]
	s_mov_b32 m0, s12
	ds_read_b128 v[186:189], v176 offset:49152
	ds_read_b128 v[198:201], v176 offset:50176
	ds_read_b128 v[202:205], v176 offset:51200
	ds_read_b128 v[206:209], v176 offset:52224
	ds_read_b128 v[210:213], v176 offset:53248
	ds_read_b128 v[214:217], v176 offset:54272
	ds_read_b128 v[218:221], v176 offset:55296
	ds_read_b128 v[222:225], v176 offset:56320
	global_load_lds_dwordx4 v[170:171], off
	s_add_i32 m0, s12, 0x2000
	s_add_u32 s12, s54, 0x80080
	v_lshl_add_u64 v[170:171], v[190:191], 0, s[26:27]
	s_addc_u32 s13, s55, 0
	s_add_i32 s54, s80, s64
	global_load_lds_dwordx4 v[170:171], off
	v_lshl_add_u64 v[170:171], s[12:13], 0, v[146:147]
	s_mov_b32 m0, s54
	s_nop 0
	global_load_lds_dwordx4 v[170:171], off
	v_lshl_add_u64 v[170:171], s[12:13], 0, v[150:151]
	s_add_i32 m0, s54, 0x2000
	s_nop 0
	global_load_lds_dwordx4 v[170:171], off
	v_lshl_add_u64 v[170:171], v[194:195], 0, s[26:27]
	s_mov_b32 m0, s73
	s_nop 0
	global_load_lds_dwordx4 v[170:171], off
	v_lshl_add_u64 v[170:171], v[196:197], 0, s[26:27]
	s_mov_b32 m0, s74
	s_nop 0
	global_load_lds_dwordx4 v[170:171], off
	s_waitcnt vmcnt(8)
	s_waitcnt lgkmcnt(0)
	s_barrier
	s_setprio 1
	s_waitcnt lgkmcnt(0)
	v_mfma_f32_16x16x32_bf16 v[60:63], v[128:131], v[186:189], v[60:63]
	v_mfma_f32_16x16x32_bf16 v[56:59], v[136:139], v[186:189], v[56:59]
	v_mfma_f32_16x16x32_bf16 v[48:51], v[128:131], v[202:205], v[48:51]
	v_mfma_f32_16x16x32_bf16 v[40:43], v[136:139], v[202:205], v[40:43]
	v_mfma_f32_16x16x32_bf16 v[32:35], v[128:131], v[210:213], v[32:35]
	v_mfma_f32_16x16x32_bf16 v[24:27], v[136:139], v[210:213], v[24:27]
	v_mfma_f32_16x16x32_bf16 v[16:19], v[128:131], v[218:221], v[16:19]
	v_mfma_f32_16x16x32_bf16 v[8:11], v[136:139], v[218:221], v[8:11]
	v_mfma_f32_16x16x32_bf16 v[60:63], v[132:135], v[198:201], v[60:63]
	v_mfma_f32_16x16x32_bf16 v[56:59], v[140:143], v[198:201], v[56:59]
	v_mfma_f32_16x16x32_bf16 v[48:51], v[132:135], v[206:209], v[48:51]
	v_mfma_f32_16x16x32_bf16 v[40:43], v[140:143], v[206:209], v[40:43]
	v_mfma_f32_16x16x32_bf16 v[32:35], v[132:135], v[214:217], v[32:35]
	v_mfma_f32_16x16x32_bf16 v[24:27], v[140:143], v[214:217], v[24:27]
	v_mfma_f32_16x16x32_bf16 v[16:19], v[132:135], v[222:225], v[16:19]
	v_mfma_f32_16x16x32_bf16 v[8:11], v[140:143], v[222:225], v[8:11]
	v_mfma_f32_16x16x32_bf16 v[52:55], v[162:165], v[186:189], v[52:55]
	v_mfma_f32_16x16x32_bf16 v[44:47], v[178:181], v[186:189], v[44:47]
	v_mfma_f32_16x16x32_bf16 v[36:39], v[162:165], v[202:205], v[36:39]
	v_mfma_f32_16x16x32_bf16 v[28:31], v[178:181], v[202:205], v[28:31]
	v_mfma_f32_16x16x32_bf16 v[20:23], v[162:165], v[210:213], v[20:23]
	v_mfma_f32_16x16x32_bf16 v[12:15], v[178:181], v[210:213], v[12:15]
	v_mfma_f32_16x16x32_bf16 v[4:7], v[162:165], v[218:221], v[4:7]
	v_mfma_f32_16x16x32_bf16 v[0:3], v[178:181], v[218:221], v[0:3]
	v_mfma_f32_16x16x32_bf16 v[52:55], v[166:169], v[198:201], v[52:55]
	v_mfma_f32_16x16x32_bf16 v[44:47], v[182:185], v[198:201], v[44:47]
	v_mfma_f32_16x16x32_bf16 v[36:39], v[166:169], v[206:209], v[36:39]
	v_mfma_f32_16x16x32_bf16 v[28:31], v[182:185], v[206:209], v[28:31]
	v_mfma_f32_16x16x32_bf16 v[20:23], v[166:169], v[214:217], v[20:23]
	v_mfma_f32_16x16x32_bf16 v[12:15], v[182:185], v[214:217], v[12:15]
	v_mfma_f32_16x16x32_bf16 v[4:7], v[166:169], v[222:225], v[4:7]
	v_mfma_f32_16x16x32_bf16 v[0:3], v[182:185], v[222:225], v[0:3]
	s_setprio 0
	s_barrier
	s_add_i32 s78, s78, 2
	s_add_u32 s52, s52, 0x100
	s_addc_u32 s53, s53, 0
	s_add_u32 s76, s76, 0x100
	s_addc_u32 s77, s77, 0
	s_cmp_gt_u32 s78, 29
	s_cbranch_scc0 .LBB0_815
	s_and_b64 vcc, exec, s[42:43]
	s_cbranch_vccz .LBB0_818
	s_barrier

; __device__ __forceinline__ void scan_phase(const Frame& F, const bf16_t* Q, const bf16_t* K, const bf16_t* V, const bf16_t* PB, bf16_t* OF, bf16_t* OB, int half) {
;     ...
;                 {
;                     bf16x8 Rf[2];
; #pragma unroll
;                     for (int ks = 0; ks < 2; ++ks) { const f32x4 r0v = Rt[4 * p + 2 * ks], r1v = Rt[4 * p + 2 * ks + 1];
;                         const u32x4 wvv = {cvt_pk_bf16(r0v[0], r0v[1]), cvt_pk_bf16(r0v[2], r0v[3]), cvt_pk_bf16(r1v[0], r1v[1]), cvt_pk_bf16(r1v[2], r1v[3])};
;                         Rf[ks] = __builtin_bit_cast(bf16x8, wvv); }
;                     u32x4 qf[2][2];
;     ...
;                     SCAN_QREAD(0, 0);
; #pragma unroll
;                     for (int it = 0; it < 8; ++it) { if (it < 7) SCAN_QREAD((it + 1) & 1, it + 1);
; #pragma unroll
;                         for (int ks = 0; ks < 2; ++ks) Ot[it] = __builtin_amdgcn_mfma_f32_16x16x32_bf16(Rf[ks], __builtin_bit_cast(bf16x8, qf[it & 1][ks]), Ot[it], 0, 0, 0); }
;     ...
;                     __builtin_amdgcn_sched_group_barrier(0x100, 4, 0);
;                     __builtin_amdgcn_sched_group_barrier(0x100, 4, 0); __builtin_amdgcn_sched_group_barrier(0x8, 2, 0);
;                     __builtin_amdgcn_sched_group_barrier(0x100, 4, 0); __builtin_amdgcn_sched_group_barrier(0x8, 2, 0);
;                     __builtin_amdgcn_sched_group_barrier(0x100, 4, 0); __builtin_amdgcn_sched_group_barrier(0x8, 2, 0);
;                     __builtin_amdgcn_sched_group_barrier(0x100, 4, 0); __builtin_amdgcn_sched_group_barrier(0x8, 2, 0);
;                     __builtin_amdgcn_sched_group_barrier(0x100, 4, 0); __builtin_amdgcn_sched_group_barrier(0x8, 2, 0);
;                     __builtin_amdgcn_sched_group_barrier(0x100, 4, 0); __builtin_amdgcn_sched_group_barrier(0x8, 2, 0);
;                     __builtin_amdgcn_sched_group_barrier(0x100, 4, 0); __builtin_amdgcn_sched_group_barrier(0x8, 2, 0);
;                     __builtin_amdgcn_sched_group_barrier(0x8, 2, 0);
;                 }
;                 __builtin_amdgcn_sched_barrier(0);
;                 { s16x4 kl[2][4], kh[2][4];
;     ...
;                 SCAN_KREAD(0, 0);
; #pragma unroll
;                 for (int mt = 0; mt < 4; ++mt) { if (mt < 3) SCAN_KREAD((mt + 1) & 1, mt + 1);
;                     f32x4 acc = Rt[4 * p + mt] * c1;
; #pragma unroll
.LBB0_977:
	v_sub_u32_e32 v128, 0x80, v192
	v_cvt_f32_i32_e32 v238, v128
	v_cvt_pk_bf16_f32 v136, v48, v49
	v_cvt_pk_bf16_f32 v137, v50, v51
	v_cvt_pk_bf16_f32 v138, v52, v53
	v_cvt_pk_bf16_f32 v139, v54, v55
	v_cvt_pk_bf16_f32 v140, v56, v57
	v_cvt_pk_bf16_f32 v141, v58, v59
	v_cvt_pk_bf16_f32 v142, v60, v61
	v_cvt_pk_bf16_f32 v143, v62, v63
	ds_read_b64 v[128:129], v223 offset:16384
	ds_read_b64 v[130:131], v224 offset:16384
	ds_read_b64 v[132:133], v225 offset:16384
	ds_read_b64 v[134:135], v226 offset:16384
	ds_read_b64 v[156:157], v223 offset:18432
	ds_read_b64 v[158:159], v224 offset:18432
	ds_read_b64 v[194:195], v225 offset:18432
	ds_read_b64 v[196:197], v226 offset:18432
	s_waitcnt lgkmcnt(6)
	v_mfma_f32_16x16x32_bf16 v[96:99], v[136:139], v[128:131], v[96:99]
	s_waitcnt lgkmcnt(4)
	v_mfma_f32_16x16x32_bf16 v[128:131], v[140:143], v[132:135], v[96:99]
	s_nop 5
	ds_read_b64 v[96:97], v223 offset:20480
	ds_read_b64 v[98:99], v224 offset:20480
	ds_read_b64 v[234:235], v225 offset:20480
	ds_read_b64 v[236:237], v226 offset:20480
	s_waitcnt lgkmcnt(6)
	v_mfma_f32_16x16x32_bf16 v[100:103], v[136:139], v[156:159], v[100:103]
	s_waitcnt lgkmcnt(4)
	v_mfma_f32_16x16x32_bf16 v[132:135], v[140:143], v[194:197], v[100:103]
	s_nop 5
	ds_read_b64 v[100:101], v223 offset:22528
	ds_read_b64 v[102:103], v224 offset:22528
	ds_read_b64 v[156:157], v225 offset:22528
	ds_read_b64 v[158:159], v226 offset:22528
	s_waitcnt lgkmcnt(6)
	v_mfma_f32_16x16x32_bf16 v[96:99], v[136:139], v[96:99], v[104:107]
	s_waitcnt lgkmcnt(4)
	v_mfma_f32_16x16x32_bf16 v[104:107], v[140:143], v[234:237], v[96:99]
	s_nop 5
	ds_read_b64 v[96:97], v223 offset:24576
	ds_read_b64 v[98:99], v224 offset:24576
	ds_read_b64 v[194:195], v225 offset:24576
	ds_read_b64 v[196:197], v226 offset:24576
	s_waitcnt lgkmcnt(6)
	v_mfma_f32_16x16x32_bf16 v[100:103], v[136:139], v[100:103], v[108:111]
	s_waitcnt lgkmcnt(4)
	v_mfma_f32_16x16x32_bf16 v[108:111], v[140:143], v[156:159], v[100:103]
	s_nop 5
	ds_read_b64 v[100:101], v223 offset:26624
	ds_read_b64 v[102:103], v224 offset:26624
	ds_read_b64 v[156:157], v225 offset:26624
	ds_read_b64 v[158:159], v226 offset:26624
	s_waitcnt lgkmcnt(6)
	v_mfma_f32_16x16x32_bf16 v[96:99], v[136:139], v[96:99], v[112:115]
	s_waitcnt lgkmcnt(4)
	v_mfma_f32_16x16x32_bf16 v[112:115], v[140:143], v[194:197], v[96:99]
	s_nop 5
	ds_read_b64 v[96:97], v223 offset:28672
	ds_read_b64 v[98:99], v224 offset:28672
	ds_read_b64 v[194:195], v225 offset:28672
	ds_read_b64 v[196:197], v226 offset:28672
	s_waitcnt lgkmcnt(6)
	v_mfma_f32_16x16x32_bf16 v[100:103], v[136:139], v[100:103], v[116:119]
	s_waitcnt lgkmcnt(4)
	v_mfma_f32_16x16x32_bf16 v[100:103], v[140:143], v[156:159], v[100:103]
	s_nop 0
	ds_read_b64 v[116:117], v223 offset:30720
	ds_read_b64 v[118:119], v224 offset:30720
	ds_read_b64 v[156:157], v225 offset:30720
	ds_read_b64 v[158:159], v226 offset:30720
	s_waitcnt lgkmcnt(6)
	v_mfma_f32_16x16x32_bf16 v[96:99], v[136:139], v[96:99], v[120:123]
	s_waitcnt lgkmcnt(4)
	v_mfma_f32_16x16x32_bf16 v[96:99], v[140:143], v[194:197], v[96:99]
	s_waitcnt lgkmcnt(2)
	v_mfma_f32_16x16x32_bf16 v[116:119], v[136:139], v[116:119], v[124:127]
	s_waitcnt lgkmcnt(0)
	v_mfma_f32_16x16x32_bf16 v[116:119], v[140:143], v[156:159], v[116:119]
	ds_read_b64_tr_b16 v[120:121], v227 offset:49152
	ds_read_b64_tr_b16 v[122:123], v228 offset:49664
	ds_read_b64_tr_b16 v[124:125], v227 offset:53248
	ds_read_b64_tr_b16 v[126:127], v228 offset:53760
	ds_read_b64_tr_b16 v[136:137], v227 offset:57344
	ds_read_b64_tr_b16 v[138:139], v228 offset:57856
	v_pk_mul_f32 v[50:51], v[144:145], v[50:51]
	v_pk_mul_f32 v[48:49], v[146:147], v[48:49]
	ds_read_b64_tr_b16 v[140:141], v227 offset:61440
	ds_read_b64_tr_b16 v[142:143], v228 offset:61952
	ds_read_b64_tr_b16 v[156:157], v229 offset:49152
	ds_read_b64_tr_b16 v[158:159], v230 offset:49664
	ds_read_b64_tr_b16 v[194:195], v229 offset:53248
	ds_read_b64_tr_b16 v[196:197], v230 offset:53760
	ds_read_b64_tr_b16 v[224:225], v229 offset:57344
	ds_read_b64_tr_b16 v[226:227], v230 offset:57856
	ds_read_b64_tr_b16 v[234:235], v229 offset:61440
	ds_read_b64_tr_b16 v[236:237], v230 offset:61952
	s_waitcnt lgkmcnt(14)
	v_mfma_f32_16x16x32_bf16 v[48:51], v[120:123], v[72:75], v[48:51]
	v_mul_f32_e64 v54, v144, v54
	v_mul_f32_e64 v55, v145, v55
	v_pk_mul_f32 v[52:53], v[146:147], v[52:53]
	v_pk_mul_f32 v[58:59], v[144:145], v[58:59]
	s_waitcnt lgkmcnt(12)
	v_mfma_f32_16x16x32_bf16 v[48:51], v[124:127], v[80:83], v[48:51]
	v_mul_f32_e64 v56, v146, v56
	v_mul_f32_e64 v57, v147, v57
	v_pk_mul_f32 v[62:63], v[144:145], v[62:63]
	v_pk_mul_f32 v[60:61], v[146:147], v[60:61]
	s_waitcnt lgkmcnt(10)
	v_mfma_f32_16x16x32_bf16 v[48:51], v[136:139], v[88:91], v[48:51]
	s_add_u32 s12, s23, s40
	v_lshl_add_u32 v192, v192, 12, v213
	s_addc_u32 s13, s92, s41
	s_waitcnt lgkmcnt(8)
; #define GAS __attribute__((address_space(1)))
; __device__ __forceinline__ unsigned cvt_pk_bf16(float lo, float hi) { unsigned r; asm volatile("v_cvt_pk_bf16_f32 %0, %1, %2" : "=v"(r) : "v"(lo), "v"(hi)); return r; }
; __device__ __forceinline__ bf16x8 pack8(s16x4 lo, s16x4 hi) { return (bf16x8){lo[0], lo[1], lo[2], lo[3], hi[0], hi[1], hi[2], hi[3]}; }
; #define SCAN_BAR() asm volatile("s_waitcnt lgkmcnt(0)\n\ts_barrier" ::: "memory")
; __device__ __forceinline__ void scan_phase(const Frame& F, const bf16_t* Q, const bf16_t* K, const bf16_t* V, const bf16_t* PB, bf16_t* OF, bf16_t* OB, int half) {
;     ...
;                 { s16x4 kl[2][4], kh[2][4];
;     ...
;                 SCAN_KREAD(0, 0);
; #pragma unroll
;                 for (int mt = 0; mt < 4; ++mt) { if (mt < 3) SCAN_KREAD((mt + 1) & 1, mt + 1);
;                     f32x4 acc = Rt[4 * p + mt] * c1;
; #pragma unroll
;                     for (int ks = 0; ks < 4; ++ks) acc = __builtin_amdgcn_mfma_f32_16x16x32_bf16(pack8(kl[mt & 1][ks], kh[mt & 1][ks]), Vf[ks], acc, 0, 0, 0);
;                     Rt[4 * p + mt] = acc; }
;     ...
;                 __builtin_amdgcn_sched_group_barrier(0x100, 8, 0);
;                 __builtin_amdgcn_sched_group_barrier(0x100, 8, 0); __builtin_amdgcn_sched_group_barrier(0x8, 4, 0);
;                 __builtin_amdgcn_sched_group_barrier(0x100, 8, 0); __builtin_amdgcn_sched_group_barrier(0x8, 4, 0);
;                 __builtin_amdgcn_sched_group_barrier(0x100, 8, 0); __builtin_amdgcn_sched_group_barrier(0x8, 4, 0);
;                 __builtin_amdgcn_sched_group_barrier(0x8, 4, 0);
;                 }
;                 if (p == 3) {
;                     bf16_t* ob_ = O + r0 * 4096 + head * 512 + vq * 128; const unsigned lo_ = (unsigned)(l15_l * 4096 + 16 * wv + 4 * quad);
;                     float fi = __builtin_amdgcn_exp2f(lg2 * (float)(dir ? 128 - l15_l : l15_l + 1));
; #pragma unroll
;                     for (int it = 0; it < 8; ++it) {
;                         *(GAS u32x2*)(ob_ + (size_t)(16 * it) * 4096 + lo_) = (u32x2){cvt_pk_bf16(Ot[it][0] * fi, Ot[it][1] * fi), cvt_pk_bf16(Ot[it][2] * fi, Ot[it][3] * fi)}; fi *= gm16; }
;                 }
;                 SCAN_BAR();
	v_mfma_f32_16x16x32_bf16 v[48:51], v[140:143], v[92:95], v[48:51]
	ds_read_b64_tr_b16 v[120:121], v231 offset:49152
	ds_read_b64_tr_b16 v[122:123], v232 offset:49664
	ds_read_b64_tr_b16 v[124:125], v231 offset:53248
	ds_read_b64_tr_b16 v[126:127], v232 offset:53760
	ds_read_b64_tr_b16 v[136:137], v231 offset:57344
	ds_read_b64_tr_b16 v[138:139], v232 offset:57856
	ds_read_b64_tr_b16 v[140:141], v231 offset:61440
	ds_read_b64_tr_b16 v[142:143], v232 offset:61952
	s_waitcnt lgkmcnt(14)
	v_mfma_f32_16x16x32_bf16 v[52:55], v[156:159], v[72:75], v[52:55]
	s_add_u32 s40, s40, 0xfff00000
	s_addc_u32 s41, s41, -1
	s_add_i32 s59, s59, 1
	s_waitcnt lgkmcnt(12)
	v_mfma_f32_16x16x32_bf16 v[52:55], v[194:197], v[80:83], v[52:55]
	s_add_i32 s38, s38, -1
	s_waitcnt lgkmcnt(10)
	v_mfma_f32_16x16x32_bf16 v[52:55], v[224:227], v[88:91], v[52:55]
	s_waitcnt lgkmcnt(8)
	v_mfma_f32_16x16x32_bf16 v[52:55], v[234:237], v[92:95], v[52:55]
	ds_read_b64_tr_b16 v[156:157], v233 offset:49152
	ds_read_b64_tr_b16 v[158:159], v241 offset:49664
	ds_read_b64_tr_b16 v[194:195], v233 offset:53248
	ds_read_b64_tr_b16 v[196:197], v241 offset:53760
	ds_read_b64_tr_b16 v[224:225], v233 offset:57344
	ds_read_b64_tr_b16 v[226:227], v241 offset:57856
	ds_read_b64_tr_b16 v[228:229], v233 offset:61440
	ds_read_b64_tr_b16 v[230:231], v241 offset:61952
	s_waitcnt lgkmcnt(14)
	v_mfma_f32_16x16x32_bf16 v[56:59], v[120:123], v[72:75], v[56:59]
	s_waitcnt lgkmcnt(12)
	v_mfma_f32_16x16x32_bf16 v[56:59], v[124:127], v[80:83], v[56:59]
	s_waitcnt lgkmcnt(10)
	v_mfma_f32_16x16x32_bf16 v[56:59], v[136:139], v[88:91], v[56:59]
	s_waitcnt lgkmcnt(8)
	v_mfma_f32_16x16x32_bf16 v[56:59], v[140:143], v[92:95], v[56:59]
	s_waitcnt lgkmcnt(6)
	v_mfma_f32_16x16x32_bf16 v[60:63], v[156:159], v[72:75], v[60:63]
	v_mul_f32_e32 v72, s54, v238
	s_waitcnt lgkmcnt(4)
	v_mfma_f32_16x16x32_bf16 v[60:63], v[194:197], v[80:83], v[60:63]
	v_exp_f32_e32 v82, v72
	v_lshl_add_u64 v[72:73], v[192:193], 1, s[12:13]
	s_mov_b32 s12, 0x180000
	s_waitcnt lgkmcnt(2)
	v_mfma_f32_16x16x32_bf16 v[60:63], v[224:227], v[88:91], v[60:63]
	v_mul_f32_e32 v74, v82, v128
	v_mul_f32_e32 v75, v82, v129
	v_cvt_pk_bf16_f32 v74, v74, v75
	v_mul_f32_e32 v75, v82, v130
	v_mul_f32_e32 v80, v82, v131
	v_cvt_pk_bf16_f32 v75, v75, v80
	v_add_co_u32_e32 v80, vcc, s6, v72
	v_mul_f32_e32 v82, s87, v82
	s_nop 0
	v_addc_co_u32_e32 v81, vcc, 0, v73, vcc
	global_store_dwordx2 v[80:81], v[74:75], off
	v_mul_f32_e32 v74, v82, v132
	v_mul_f32_e32 v75, v82, v133
	v_cvt_pk_bf16_f32 v74, v74, v75
	v_mul_f32_e32 v75, v82, v134
	v_mul_f32_e32 v80, v82, v135
	v_cvt_pk_bf16_f32 v75, v75, v80
	v_add_co_u32_e32 v80, vcc, s7, v72
	v_mul_f32_e32 v82, s87, v82
	s_nop 0
	v_addc_co_u32_e32 v81, vcc, 0, v73, vcc
	global_store_dwordx2 v[80:81], v[74:75], off
	v_mul_f32_e32 v74, v82, v104
	v_mul_f32_e32 v75, v82, v105
	v_cvt_pk_bf16_f32 v74, v74, v75
	v_mul_f32_e32 v75, v82, v106
	v_mul_f32_e32 v80, v82, v107
	v_cvt_pk_bf16_f32 v75, v75, v80
	v_add_co_u32_e32 v80, vcc, s4, v72
	v_mul_f32_e32 v82, s87, v82
	s_nop 0
	v_addc_co_u32_e32 v81, vcc, 0, v73, vcc
	global_store_dwordx2 v[80:81], v[74:75], off
	v_mul_f32_e32 v74, v82, v108
	v_mul_f32_e32 v75, v82, v109
	v_cvt_pk_bf16_f32 v74, v74, v75
	v_mul_f32_e32 v75, v82, v110
	v_mul_f32_e32 v80, v82, v111
	v_cvt_pk_bf16_f32 v75, v75, v80
	v_add_co_u32_e32 v80, vcc, s5, v72
	v_mul_f32_e32 v82, s87, v82
	s_nop 0
	v_addc_co_u32_e32 v81, vcc, 0, v73, vcc
	global_store_dwordx2 v[80:81], v[74:75], off
	v_mul_f32_e32 v74, v82, v112
	v_mul_f32_e32 v75, v82, v113
	v_cvt_pk_bf16_f32 v74, v74, v75
	v_mul_f32_e32 v75, v82, v114
	v_mul_f32_e32 v80, v82, v115
	v_cvt_pk_bf16_f32 v75, v75, v80
	v_add_co_u32_e32 v80, vcc, s12, v72
	v_mul_f32_e32 v82, s87, v82
	s_nop 0
	v_addc_co_u32_e32 v81, vcc, 0, v73, vcc
	global_store_dwordx2 v[80:81], v[74:75], off
	v_mul_f32_e32 v74, v82, v100
	v_mul_f32_e32 v75, v82, v101
	v_cvt_pk_bf16_f32 v74, v74, v75
	v_mul_f32_e32 v75, v82, v102
	v_mul_f32_e32 v80, v82, v103
	s_mov_b32 s12, 0x1a0000
	v_cvt_pk_bf16_f32 v75, v75, v80
	v_add_co_u32_e32 v80, vcc, s12, v72
	v_mul_f32_e32 v82, s87, v82
	s_nop 0
	v_addc_co_u32_e32 v81, vcc, 0, v73, vcc
	global_store_dwordx2 v[80:81], v[74:75], off
	v_mul_f32_e32 v74, v82, v96
	v_mul_f32_e32 v75, v82, v97
	v_cvt_pk_bf16_f32 v74, v74, v75
	v_mul_f32_e32 v75, v82, v98
	v_mul_f32_e32 v80, v82, v99
	s_mov_b32 s12, 0x1c0000
	v_cvt_pk_bf16_f32 v75, v75, v80
	v_add_co_u32_e32 v80, vcc, s12, v72
	s_mov_b32 s12, 0x1e0000
	s_nop 0
	v_addc_co_u32_e32 v81, vcc, 0, v73, vcc
	global_store_dwordx2 v[80:81], v[74:75], off
	v_mul_f32_e32 v75, s87, v82
	v_mul_f32_e32 v74, v75, v116
	v_mul_f32_e32 v80, v75, v117
	v_add_co_u32_e32 v72, vcc, s12, v72
	v_cvt_pk_bf16_f32 v74, v74, v80
	v_mul_f32_e32 v80, v75, v118
	v_mul_f32_e32 v75, v75, v119
	v_addc_co_u32_e32 v73, vcc, 0, v73, vcc
	s_waitcnt lgkmcnt(0)
	v_mfma_f32_16x16x32_bf16 v[60:63], v[228:231], v[92:95], v[60:63]
	v_cvt_pk_bf16_f32 v75, v80, v75
	global_store_dwordx2 v[72:73], v[74:75], off
	s_add_i32 s12, s48, s40
	s_add_u32 s42, s42, 0xfff80000
	s_waitcnt lgkmcnt(0)
	s_barrier
	s_addc_u32 s43, s43, -1
	s_cmp_eq_u32 s12, 0xffe00000
	s_cbranch_scc1 .LBB0_984
	.p2align 6

; __device__ __forceinline__ void scan_phase(const Frame& F, const bf16_t* Q, const bf16_t* K, const bf16_t* V, const bf16_t* PB, bf16_t* OF, bf16_t* OB, int half) {
;     ...
;                 {
;                     bf16x8 Rf[2];
; #pragma unroll
;                     for (int ks = 0; ks < 2; ++ks) { const f32x4 r0v = Rt[4 * p + 2 * ks], r1v = Rt[4 * p + 2 * ks + 1];
;                         const u32x4 wvv = {cvt_pk_bf16(r0v[0], r0v[1]), cvt_pk_bf16(r0v[2], r0v[3]), cvt_pk_bf16(r1v[0], r1v[1]), cvt_pk_bf16(r1v[2], r1v[3])};
;                         Rf[ks] = __builtin_bit_cast(bf16x8, wvv); }
;                     u32x4 qf[2][2];
;     ...
;                     SCAN_QREAD(0, 0);
; #pragma unroll
;                     for (int it = 0; it < 8; ++it) { if (it < 7) SCAN_QREAD((it + 1) & 1, it + 1);
; #pragma unroll
;                         for (int ks = 0; ks < 2; ++ks) Ot[it] = __builtin_amdgcn_mfma_f32_16x16x32_bf16(Rf[ks], __builtin_bit_cast(bf16x8, qf[it & 1][ks]), Ot[it], 0, 0, 0); }
;     ...
;                     __builtin_amdgcn_sched_group_barrier(0x100, 4, 0);
;                     __builtin_amdgcn_sched_group_barrier(0x100, 4, 0); __builtin_amdgcn_sched_group_barrier(0x8, 2, 0);
;                     __builtin_amdgcn_sched_group_barrier(0x100, 4, 0); __builtin_amdgcn_sched_group_barrier(0x8, 2, 0);
;                     __builtin_amdgcn_sched_group_barrier(0x100, 4, 0); __builtin_amdgcn_sched_group_barrier(0x8, 2, 0);
;                     __builtin_amdgcn_sched_group_barrier(0x100, 4, 0); __builtin_amdgcn_sched_group_barrier(0x8, 2, 0);
;                     __builtin_amdgcn_sched_group_barrier(0x100, 4, 0); __builtin_amdgcn_sched_group_barrier(0x8, 2, 0);
;                     __builtin_amdgcn_sched_group_barrier(0x100, 4, 0); __builtin_amdgcn_sched_group_barrier(0x8, 2, 0);
;                     __builtin_amdgcn_sched_group_barrier(0x100, 4, 0); __builtin_amdgcn_sched_group_barrier(0x8, 2, 0);
;                     __builtin_amdgcn_sched_group_barrier(0x8, 2, 0);
;                 }
;                 __builtin_amdgcn_sched_barrier(0);
;                 { s16x4 kl[2][4], kh[2][4];
;     ...
;                 SCAN_KREAD(0, 0);
; #pragma unroll
;                 for (int mt = 0; mt < 4; ++mt) { if (mt < 3) SCAN_KREAD((mt + 1) & 1, mt + 1);
;                     f32x4 acc = Rt[4 * p + mt] * c1;
; #pragma unroll
.LBB0_987:
	v_add_u32_e32 v128, 1, v192
	v_cvt_f32_i32_e32 v229, v128
	v_cvt_pk_bf16_f32 v140, v48, v49
	v_cvt_pk_bf16_f32 v141, v50, v51
	v_cvt_pk_bf16_f32 v142, v52, v53
	v_cvt_pk_bf16_f32 v143, v54, v55
	v_cvt_pk_bf16_f32 v150, v56, v57
	v_cvt_pk_bf16_f32 v151, v58, v59
	v_cvt_pk_bf16_f32 v152, v60, v61
	v_cvt_pk_bf16_f32 v153, v62, v63
	ds_read_b64 v[128:129], v217 offset:16384
	ds_read_b64 v[130:131], v218 offset:16384
	ds_read_b64 v[132:133], v219 offset:16384
	ds_read_b64 v[134:135], v220 offset:16384
	ds_read_b64 v[136:137], v217 offset:18432
	ds_read_b64 v[138:139], v218 offset:18432
	ds_read_b64 v[194:195], v219 offset:18432
	ds_read_b64 v[196:197], v220 offset:18432
	s_waitcnt lgkmcnt(6)
	v_mfma_f32_16x16x32_bf16 v[96:99], v[140:143], v[128:131], v[96:99]
	s_waitcnt lgkmcnt(4)
	v_mfma_f32_16x16x32_bf16 v[132:135], v[150:153], v[132:135], v[96:99]
	s_nop 5
	ds_read_b64 v[96:97], v217 offset:20480
	ds_read_b64 v[98:99], v218 offset:20480
	ds_read_b64 v[128:129], v219 offset:20480
	ds_read_b64 v[130:131], v220 offset:20480
	s_waitcnt lgkmcnt(6)
	v_mfma_f32_16x16x32_bf16 v[100:103], v[140:143], v[136:139], v[100:103]
	s_waitcnt lgkmcnt(4)
	v_mfma_f32_16x16x32_bf16 v[136:139], v[150:153], v[194:197], v[100:103]
	s_nop 5
	ds_read_b64 v[100:101], v217 offset:22528
	ds_read_b64 v[102:103], v218 offset:22528
	ds_read_b64 v[194:195], v219 offset:22528
	ds_read_b64 v[196:197], v220 offset:22528
	s_waitcnt lgkmcnt(6)
	v_mfma_f32_16x16x32_bf16 v[96:99], v[140:143], v[96:99], v[104:107]
	s_waitcnt lgkmcnt(4)
	v_mfma_f32_16x16x32_bf16 v[128:131], v[150:153], v[128:131], v[96:99]
	s_nop 5
	ds_read_b64 v[96:97], v217 offset:24576
	ds_read_b64 v[98:99], v218 offset:24576
	ds_read_b64 v[104:105], v219 offset:24576
	ds_read_b64 v[106:107], v220 offset:24576
	s_waitcnt lgkmcnt(6)
	v_mfma_f32_16x16x32_bf16 v[100:103], v[140:143], v[100:103], v[108:111]
	s_waitcnt lgkmcnt(4)
	v_mfma_f32_16x16x32_bf16 v[108:111], v[150:153], v[194:197], v[100:103]
	s_nop 5
	ds_read_b64 v[100:101], v217 offset:26624
	ds_read_b64 v[102:103], v218 offset:26624
	ds_read_b64 v[194:195], v219 offset:26624
	ds_read_b64 v[196:197], v220 offset:26624
	s_waitcnt lgkmcnt(6)
	v_mfma_f32_16x16x32_bf16 v[96:99], v[140:143], v[96:99], v[112:115]
	s_waitcnt lgkmcnt(4)
	v_mfma_f32_16x16x32_bf16 v[104:107], v[150:153], v[104:107], v[96:99]
	s_nop 5
	ds_read_b64 v[96:97], v217 offset:28672
	ds_read_b64 v[98:99], v218 offset:28672
	ds_read_b64 v[112:113], v219 offset:28672
	ds_read_b64 v[114:115], v220 offset:28672
	s_waitcnt lgkmcnt(6)
	v_mfma_f32_16x16x32_bf16 v[100:103], v[140:143], v[100:103], v[116:119]
	s_waitcnt lgkmcnt(4)
	v_mfma_f32_16x16x32_bf16 v[100:103], v[150:153], v[194:197], v[100:103]
	s_nop 0
	ds_read_b64 v[116:117], v217 offset:30720
	ds_read_b64 v[118:119], v218 offset:30720
	ds_read_b64 v[194:195], v219 offset:30720
	ds_read_b64 v[196:197], v220 offset:30720
	s_waitcnt lgkmcnt(6)
	v_mfma_f32_16x16x32_bf16 v[96:99], v[140:143], v[96:99], v[120:123]
	s_waitcnt lgkmcnt(4)
	v_mfma_f32_16x16x32_bf16 v[96:99], v[150:153], v[112:115], v[96:99]
	s_waitcnt lgkmcnt(2)
	v_mfma_f32_16x16x32_bf16 v[112:115], v[140:143], v[116:119], v[124:127]
	s_waitcnt lgkmcnt(0)
	v_mfma_f32_16x16x32_bf16 v[112:115], v[150:153], v[194:197], v[112:115]
	ds_read_b64_tr_b16 v[116:117], v221 offset:49152
	ds_read_b64_tr_b16 v[118:119], v222 offset:49664
	ds_read_b64_tr_b16 v[120:121], v221 offset:53248
	ds_read_b64_tr_b16 v[122:123], v222 offset:53760
	ds_read_b64_tr_b16 v[124:125], v221 offset:57344
	ds_read_b64_tr_b16 v[126:127], v222 offset:57856
	v_pk_mul_f32 v[50:51], v[144:145], v[50:51]
	v_pk_mul_f32 v[48:49], v[146:147], v[48:49]
	ds_read_b64_tr_b16 v[140:141], v221 offset:61440
	ds_read_b64_tr_b16 v[142:143], v222 offset:61952
	ds_read_b64_tr_b16 v[150:151], v223 offset:49152
	ds_read_b64_tr_b16 v[152:153], v224 offset:49664
	ds_read_b64_tr_b16 v[194:195], v223 offset:53248
	ds_read_b64_tr_b16 v[196:197], v224 offset:53760
	ds_read_b64_tr_b16 v[218:219], v223 offset:57344
	ds_read_b64_tr_b16 v[220:221], v224 offset:57856
	ds_read_b64_tr_b16 v[230:231], v223 offset:61440
	ds_read_b64_tr_b16 v[232:233], v224 offset:61952
	s_waitcnt lgkmcnt(14)
	v_mfma_f32_16x16x32_bf16 v[48:51], v[116:119], v[72:75], v[48:51]
	v_mul_f32_e64 v54, v144, v54
	v_mul_f32_e64 v55, v145, v55
	v_pk_mul_f32 v[52:53], v[146:147], v[52:53]
	v_pk_mul_f32 v[58:59], v[144:145], v[58:59]
	s_waitcnt lgkmcnt(12)
	v_mfma_f32_16x16x32_bf16 v[48:51], v[120:123], v[80:83], v[48:51]
	v_mul_f32_e64 v56, v146, v56
	v_mul_f32_e64 v57, v147, v57
	v_pk_mul_f32 v[62:63], v[144:145], v[62:63]
	v_pk_mul_f32 v[60:61], v[146:147], v[60:61]
	s_waitcnt lgkmcnt(10)
	v_mfma_f32_16x16x32_bf16 v[48:51], v[124:127], v[88:91], v[48:51]
	s_add_u32 s12, s62, s41
	v_lshl_add_u32 v192, v192, 12, v213
	s_addc_u32 s13, s63, s42
	s_waitcnt lgkmcnt(8)
; #define GAS __attribute__((address_space(1)))
; __device__ __forceinline__ unsigned cvt_pk_bf16(float lo, float hi) { unsigned r; asm volatile("v_cvt_pk_bf16_f32 %0, %1, %2" : "=v"(r) : "v"(lo), "v"(hi)); return r; }
; __device__ __forceinline__ bf16x8 pack8(s16x4 lo, s16x4 hi) { return (bf16x8){lo[0], lo[1], lo[2], lo[3], hi[0], hi[1], hi[2], hi[3]}; }
; #define SCAN_BAR() asm volatile("s_waitcnt lgkmcnt(0)\n\ts_barrier" ::: "memory")
; __device__ __forceinline__ void scan_phase(const Frame& F, const bf16_t* Q, const bf16_t* K, const bf16_t* V, const bf16_t* PB, bf16_t* OF, bf16_t* OB, int half) {
;     ...
;                 { s16x4 kl[2][4], kh[2][4];
;     ...
;                 SCAN_KREAD(0, 0);
; #pragma unroll
;                 for (int mt = 0; mt < 4; ++mt) { if (mt < 3) SCAN_KREAD((mt + 1) & 1, mt + 1);
;                     f32x4 acc = Rt[4 * p + mt] * c1;
; #pragma unroll
;                     for (int ks = 0; ks < 4; ++ks) acc = __builtin_amdgcn_mfma_f32_16x16x32_bf16(pack8(kl[mt & 1][ks], kh[mt & 1][ks]), Vf[ks], acc, 0, 0, 0);
;                     Rt[4 * p + mt] = acc; }
;     ...
;                 __builtin_amdgcn_sched_group_barrier(0x100, 8, 0);
;                 __builtin_amdgcn_sched_group_barrier(0x100, 8, 0); __builtin_amdgcn_sched_group_barrier(0x8, 4, 0);
;                 __builtin_amdgcn_sched_group_barrier(0x100, 8, 0); __builtin_amdgcn_sched_group_barrier(0x8, 4, 0);
;                 __builtin_amdgcn_sched_group_barrier(0x100, 8, 0); __builtin_amdgcn_sched_group_barrier(0x8, 4, 0);
;                 __builtin_amdgcn_sched_group_barrier(0x8, 4, 0);
;                 }
;                 if (p == 3) {
;                     bf16_t* ob_ = O + r0 * 4096 + head * 512 + vq * 128; const unsigned lo_ = (unsigned)(l15_l * 4096 + 16 * wv + 4 * quad);
;                     float fi = __builtin_amdgcn_exp2f(lg2 * (float)(dir ? 128 - l15_l : l15_l + 1));
; #pragma unroll
;                     for (int it = 0; it < 8; ++it) {
;                         *(GAS u32x2*)(ob_ + (size_t)(16 * it) * 4096 + lo_) = (u32x2){cvt_pk_bf16(Ot[it][0] * fi, Ot[it][1] * fi), cvt_pk_bf16(Ot[it][2] * fi, Ot[it][3] * fi)}; fi *= gm16; }
;                 }
;                 SCAN_BAR();
	v_mfma_f32_16x16x32_bf16 v[48:51], v[140:143], v[92:95], v[48:51]
	ds_read_b64_tr_b16 v[116:117], v225 offset:49152
	ds_read_b64_tr_b16 v[118:119], v226 offset:49664
	ds_read_b64_tr_b16 v[120:121], v225 offset:53248
	ds_read_b64_tr_b16 v[122:123], v226 offset:53760
	ds_read_b64_tr_b16 v[124:125], v225 offset:57344
	ds_read_b64_tr_b16 v[126:127], v226 offset:57856
	ds_read_b64_tr_b16 v[140:141], v225 offset:61440
	ds_read_b64_tr_b16 v[142:143], v226 offset:61952
	s_waitcnt lgkmcnt(14)
	v_mfma_f32_16x16x32_bf16 v[52:55], v[150:153], v[72:75], v[52:55]
	s_add_u32 s30, s30, 0x100000
	s_addc_u32 s31, s31, 0
	s_add_u32 s41, s41, 0x100000
	s_waitcnt lgkmcnt(12)
	v_mfma_f32_16x16x32_bf16 v[52:55], v[194:197], v[80:83], v[52:55]
	s_addc_u32 s42, s42, 0
	v_lshl_add_u64 v[148:149], v[148:149], 0, s[24:25]
	s_cmp_eq_u32 s73, s43
	s_waitcnt lgkmcnt(10)
	v_mfma_f32_16x16x32_bf16 v[52:55], v[218:221], v[88:91], v[52:55]
	s_mov_b32 s44, s43
	s_waitcnt lgkmcnt(8)
	v_mfma_f32_16x16x32_bf16 v[52:55], v[230:233], v[92:95], v[52:55]
	ds_read_b64_tr_b16 v[150:151], v227 offset:49152
	ds_read_b64_tr_b16 v[152:153], v228 offset:49664
	ds_read_b64_tr_b16 v[194:195], v227 offset:53248
	ds_read_b64_tr_b16 v[196:197], v228 offset:53760
	ds_read_b64_tr_b16 v[218:219], v227 offset:57344
	ds_read_b64_tr_b16 v[220:221], v228 offset:57856
	ds_read_b64_tr_b16 v[222:223], v227 offset:61440
	ds_read_b64_tr_b16 v[224:225], v228 offset:61952
	s_waitcnt lgkmcnt(14)
	v_mfma_f32_16x16x32_bf16 v[56:59], v[116:119], v[72:75], v[56:59]
	s_waitcnt lgkmcnt(12)
	v_mfma_f32_16x16x32_bf16 v[56:59], v[120:123], v[80:83], v[56:59]
	s_waitcnt lgkmcnt(10)
	v_mfma_f32_16x16x32_bf16 v[56:59], v[124:127], v[88:91], v[56:59]
	s_waitcnt lgkmcnt(8)
	v_mfma_f32_16x16x32_bf16 v[56:59], v[140:143], v[92:95], v[56:59]
	s_waitcnt lgkmcnt(6)
	v_mfma_f32_16x16x32_bf16 v[60:63], v[150:153], v[72:75], v[60:63]
	v_mul_f32_e32 v72, s54, v229
	s_waitcnt lgkmcnt(4)
	v_mfma_f32_16x16x32_bf16 v[60:63], v[194:197], v[80:83], v[60:63]
	v_exp_f32_e32 v82, v72
	v_lshl_add_u64 v[72:73], v[192:193], 1, s[12:13]
	s_mov_b32 s12, 0x3a120000
	s_waitcnt lgkmcnt(2)
	v_mfma_f32_16x16x32_bf16 v[60:63], v[218:221], v[88:91], v[60:63]
	v_mul_f32_e32 v74, v82, v132
	v_mul_f32_e32 v75, v82, v133
	v_cvt_pk_bf16_f32 v74, v74, v75
	v_mul_f32_e32 v75, v82, v134
	v_mul_f32_e32 v80, v82, v135
	v_cvt_pk_bf16_f32 v75, v75, v80
	v_add_co_u32_e32 v80, vcc, s97, v72
	v_mul_f32_e32 v82, s37, v82
	s_nop 0
	v_addc_co_u32_e32 v81, vcc, 0, v73, vcc
	global_store_dwordx2 v[80:81], v[74:75], off
	v_mul_f32_e32 v74, v82, v136
	v_mul_f32_e32 v75, v82, v137
	v_cvt_pk_bf16_f32 v74, v74, v75
	v_mul_f32_e32 v75, v82, v138
	v_mul_f32_e32 v80, v82, v139
	v_cvt_pk_bf16_f32 v75, v75, v80
	v_add_co_u32_e32 v80, vcc, s12, v72
	v_mul_f32_e32 v82, s37, v82
	s_nop 0
	v_addc_co_u32_e32 v81, vcc, 0, v73, vcc
	global_store_dwordx2 v[80:81], v[74:75], off
	v_mul_f32_e32 v74, v82, v128
	v_mul_f32_e32 v75, v82, v129
	v_cvt_pk_bf16_f32 v74, v74, v75
	v_mul_f32_e32 v75, v82, v130
	v_mul_f32_e32 v80, v82, v131
	s_mov_b32 s12, 0x3a140000
	v_cvt_pk_bf16_f32 v75, v75, v80
	v_add_co_u32_e32 v80, vcc, s12, v72
	v_mul_f32_e32 v82, s37, v82
	s_nop 0
	v_addc_co_u32_e32 v81, vcc, 0, v73, vcc
	global_store_dwordx2 v[80:81], v[74:75], off
	v_mul_f32_e32 v74, v82, v108
	v_mul_f32_e32 v75, v82, v109
	v_cvt_pk_bf16_f32 v74, v74, v75
	v_mul_f32_e32 v75, v82, v110
	v_mul_f32_e32 v80, v82, v111
	s_mov_b32 s12, 0x3a160000
	v_cvt_pk_bf16_f32 v75, v75, v80
	v_add_co_u32_e32 v80, vcc, s12, v72
	v_mul_f32_e32 v82, s37, v82
	s_nop 0
	v_addc_co_u32_e32 v81, vcc, 0, v73, vcc
	global_store_dwordx2 v[80:81], v[74:75], off
	v_mul_f32_e32 v74, v82, v104
	v_mul_f32_e32 v75, v82, v105
	v_cvt_pk_bf16_f32 v74, v74, v75
	v_mul_f32_e32 v75, v82, v106
	v_mul_f32_e32 v80, v82, v107
	s_mov_b32 s12, 0x3a180000
	v_cvt_pk_bf16_f32 v75, v75, v80
	v_add_co_u32_e32 v80, vcc, s12, v72
	v_mul_f32_e32 v82, s37, v82
	s_nop 0
	v_addc_co_u32_e32 v81, vcc, 0, v73, vcc
	global_store_dwordx2 v[80:81], v[74:75], off
	v_mul_f32_e32 v74, v82, v100
	v_mul_f32_e32 v75, v82, v101
	v_cvt_pk_bf16_f32 v74, v74, v75
	v_mul_f32_e32 v75, v82, v102
	v_mul_f32_e32 v80, v82, v103
	s_mov_b32 s12, 0x3a1a0000
	v_cvt_pk_bf16_f32 v75, v75, v80
	v_add_co_u32_e32 v80, vcc, s12, v72
	v_mul_f32_e32 v82, s37, v82
	s_nop 0
	v_addc_co_u32_e32 v81, vcc, 0, v73, vcc
	global_store_dwordx2 v[80:81], v[74:75], off
	v_mul_f32_e32 v74, v82, v96
	v_mul_f32_e32 v75, v82, v97
	v_cvt_pk_bf16_f32 v74, v74, v75
	v_mul_f32_e32 v75, v82, v98
	v_mul_f32_e32 v80, v82, v99
	s_mov_b32 s12, 0x3a1c0000
	v_cvt_pk_bf16_f32 v75, v75, v80
	v_add_co_u32_e32 v80, vcc, s12, v72
	s_mov_b32 s12, 0x3a1e0000
	s_nop 0
	v_addc_co_u32_e32 v81, vcc, 0, v73, vcc
	global_store_dwordx2 v[80:81], v[74:75], off
	v_mul_f32_e32 v75, s37, v82
	v_mul_f32_e32 v74, v75, v112
	v_mul_f32_e32 v80, v75, v113
	v_add_co_u32_e32 v72, vcc, s12, v72
	v_cvt_pk_bf16_f32 v74, v74, v80
	v_mul_f32_e32 v80, v75, v114
	v_mul_f32_e32 v75, v75, v115
	v_addc_co_u32_e32 v73, vcc, 0, v73, vcc
	s_waitcnt lgkmcnt(0)
	v_mfma_f32_16x16x32_bf16 v[60:63], v[222:225], v[92:95], v[60:63]
	v_cvt_pk_bf16_f32 v75, v80, v75
	global_store_dwordx2 v[72:73], v[74:75], off
	s_waitcnt lgkmcnt(0)
	s_barrier
	s_cbranch_scc1 .LBB0_974
	.p2align 6

; #define PG8_STAGE(bufoff, gbase, voff) do { _Pragma("unroll") for (int _i = 0; _i < 2; ++_i) \
;         __builtin_amdgcn_global_load_lds((const unsigned*)((const char*)(gbase) + (voff)[_i]), (PG8_LAS unsigned*)(lds + (bufoff) + ldsw + _i * 8192), 16, 0, 0); } while (0)
; #define PG8_LDA(dst, b, h) do { _Pragma("unroll") for (int m = 0; m < 4; ++m) _Pragma("unroll") for (int k = 0; k < 2; ++k) dst[m][k] = *(const PG8_LAS bf16x8*)(lds + PG8_SA(b, h) + aoff + m * 2048 + k * 1024); } while (0)
; #define PG8_LDB(dst, b, h) do { _Pragma("unroll") for (int n = 0; n < 2; ++n) _Pragma("unroll") for (int k = 0; k < 2; ++k) dst[n][k] = *(const PG8_LAS bf16x8*)(lds + PG8_SB(b, h) + boff + n * 2048 + k * 1024); } while (0)
; #define PG8_MMA(ai, bj, At, Bt) do { __builtin_amdgcn_s_setprio(1); _Pragma("unroll") for (int m = 0; m < 4; ++m) _Pragma("unroll") for (int n = 0; n < 2; ++n) _Pragma("unroll") for (int k = 0; k < 2; ++k) \
;         acc[ai][bj][m][n] = __builtin_amdgcn_mfma_f32_16x16x32_bf16(Bt[n][k], At[m][k], acc[ai][bj][m][n], 0, 0, 0); __builtin_amdgcn_s_setprio(0); } while (0)
; #define PG8_WAIT_V(n) asm volatile("s_waitcnt vmcnt(" #n ")" ::: "memory")
; #define PG8_WAIT_L(n) asm volatile("s_waitcnt lgkmcnt(" #n ")" ::: "memory")
; #define PG8_BAR __builtin_amdgcn_s_barrier()
; template <class Epi, class Sched, bool ALIGN_EPI = false, bool SP2 = false>
; __device__ __forceinline__ void gemm_phase(PG8_LAS unsigned char* lds, const Gemm g, const Sched& S, const Epi& E, const int tid_in) {
;     ...
;         const char* nA = has_next ? (const char*)g.A + (size_t)nxt.pm * tstepA : cA; const char* nB = has_next ? (const char*)g.Bt + (size_t)nxt.pn * tstepB : cB;
;         for (int t = 0; t < nt; t += 2) {
;             const bool last = (t == nt - 2);
;             const char* a1 = cA + (size_t)(t + 1) * kstep;
;             const char* a2 = last ? nA : cA + (size_t)(t + 2) * kstep; const char* b2 = last ? nB : cB + (size_t)(t + 2) * kstep;
;             const char* a3 = a2 + kstep; const char* b3 = b2 + kstep;
;             if (last && has_next) S.a_ready(nxt);
;             if constexpr (SP2) {
;             PG8_LDB(B0, 0, 0); PG8_LDB(B1, 0, 1); PG8_SCHED; PG8_LDA(At, 0, 0); PG8_STAGE(PG8_SA(1, 1), a1 + hstepA, voffA);
;             PG8_WAIT_V(8); PG8_WAIT_L(0); PG8_BAR; PG8_MMA(0, 0, At, B0); PG8_MMA(0, 1, At, B1); PG8_BAR; PG8_SCHED;
.LBB0_1059:
	s_ashr_i32 s47, s46, 31
	s_lshl_b64 s[12:13], s[46:47], 20
	s_add_u32 s48, s62, s12
	s_addc_u32 s49, s63, s13
	s_and_b64 s[12:13], s[34:35], exec
	s_cselect_b32 s37, s49, s55
	s_cselect_b32 s47, s48, s54
	s_ashr_i32 s45, s44, 31
	s_lshl_b64 s[12:13], s[44:45], 20
	s_add_u32 s50, s64, s12
	s_addc_u32 s51, s65, s13
	s_and_b64 s[12:13], s[34:35], exec
	s_cselect_b32 s45, s51, s57
	s_cselect_b32 s72, s50, s56
	s_add_u32 s54, s54, 0x80080
	s_addc_u32 s55, s55, 0
	s_add_u32 s73, s56, 0x100
	s_addc_u32 s74, s57, 0
	s_mov_b32 s75, -2
	s_add_u32 s12, s54, 0xfff80080
	s_addc_u32 s13, s55, -1
	s_add_i32 s76, 0, 0x10000
	s_cmp_eq_u32 s75, 28
	s_cselect_b32 s59, s37, s13
	s_cselect_b32 s58, s47, s12
	v_add_u32_e32 v138, s76, v141
	s_cselect_b32 s57, s45, s74
	s_cselect_b32 s56, s72, s73
	s_add_i32 s77, 0, 0x14000
	ds_read_b128 v[146:149], v138
	ds_read_b128 v[150:153], v138 offset:1024
	ds_read_b128 v[154:157], v138 offset:2048
	ds_read_b128 v[158:161], v138 offset:3072
	v_add_u32_e32 v138, s77, v141
	ds_read_b128 v[162:165], v138
	ds_read_b128 v[166:169], v138 offset:1024
	ds_read_b128 v[170:173], v138 offset:2048
	ds_read_b128 v[174:177], v138 offset:3072
	v_lshl_add_u64 v[190:191], s[54:55], 0, v[134:135]
	s_add_i32 m0, s53, 0xc000
	ds_read_b128 v[178:181], v145
	ds_read_b128 v[182:185], v145 offset:1024
	ds_read_b128 v[186:189], v145 offset:2048
	ds_read_b128 v[194:197], v145 offset:3072
	ds_read_b128 v[198:201], v145 offset:4096
	ds_read_b128 v[202:205], v145 offset:5120
	ds_read_b128 v[206:209], v145 offset:6144
	ds_read_b128 v[210:213], v145 offset:7168
	global_load_lds_dwordx4 v[190:191], off
	v_lshl_add_u64 v[190:191], s[54:55], 0, v[136:137]
	s_add_i32 m0, s53, 0xe000
	s_nop 0
	global_load_lds_dwordx4 v[190:191], off
	s_waitcnt vmcnt(8)
	s_waitcnt lgkmcnt(0)
	s_barrier
	s_setprio 1
	s_waitcnt lgkmcnt(0)
	v_mfma_f32_16x16x32_bf16 v[124:127], v[146:149], v[178:181], 0
	v_mfma_f32_16x16x32_bf16 v[120:123], v[154:157], v[178:181], 0
	v_mfma_f32_16x16x32_bf16 v[112:115], v[146:149], v[186:189], 0
	v_mfma_f32_16x16x32_bf16 v[104:107], v[154:157], v[186:189], 0
	v_mfma_f32_16x16x32_bf16 v[96:99], v[146:149], v[198:201], 0
	v_mfma_f32_16x16x32_bf16 v[88:91], v[154:157], v[198:201], 0
	v_mfma_f32_16x16x32_bf16 v[80:83], v[146:149], v[206:209], 0
	v_mfma_f32_16x16x32_bf16 v[72:75], v[154:157], v[206:209], 0
	v_mfma_f32_16x16x32_bf16 v[124:127], v[150:153], v[182:185], v[124:127]
	v_mfma_f32_16x16x32_bf16 v[120:123], v[158:161], v[182:185], v[120:123]
	v_mfma_f32_16x16x32_bf16 v[112:115], v[150:153], v[194:197], v[112:115]
	v_mfma_f32_16x16x32_bf16 v[104:107], v[158:161], v[194:197], v[104:107]
	v_mfma_f32_16x16x32_bf16 v[96:99], v[150:153], v[202:205], v[96:99]
	v_mfma_f32_16x16x32_bf16 v[88:91], v[158:161], v[202:205], v[88:91]
	v_mfma_f32_16x16x32_bf16 v[80:83], v[150:153], v[210:213], v[80:83]
	v_mfma_f32_16x16x32_bf16 v[72:75], v[158:161], v[210:213], v[72:75]
	s_setprio 0
	s_setprio 1
	v_mfma_f32_16x16x32_bf16 v[116:119], v[162:165], v[178:181], 0
	v_mfma_f32_16x16x32_bf16 v[108:111], v[170:173], v[178:181], 0
	v_mfma_f32_16x16x32_bf16 v[100:103], v[162:165], v[186:189], 0
	v_mfma_f32_16x16x32_bf16 v[92:95], v[170:173], v[186:189], 0
	v_mfma_f32_16x16x32_bf16 v[84:87], v[162:165], v[198:201], 0
	v_mfma_f32_16x16x32_bf16 v[76:79], v[170:173], v[198:201], 0
	v_mfma_f32_16x16x32_bf16 v[68:71], v[162:165], v[206:209], 0
	v_mfma_f32_16x16x32_bf16 v[64:67], v[170:173], v[206:209], 0
	v_mfma_f32_16x16x32_bf16 v[116:119], v[166:169], v[182:185], v[116:119]
	v_mfma_f32_16x16x32_bf16 v[108:111], v[174:177], v[182:185], v[108:111]
	v_mfma_f32_16x16x32_bf16 v[100:103], v[166:169], v[194:197], v[100:103]
	v_mfma_f32_16x16x32_bf16 v[92:95], v[174:177], v[194:197], v[92:95]
	v_mfma_f32_16x16x32_bf16 v[84:87], v[166:169], v[202:205], v[84:87]
	v_mfma_f32_16x16x32_bf16 v[76:79], v[174:177], v[202:205], v[76:79]
	v_mfma_f32_16x16x32_bf16 v[68:71], v[166:169], v[210:213], v[68:71]
	v_mfma_f32_16x16x32_bf16 v[64:67], v[174:177], v[210:213], v[64:67]
	s_setprio 0
	s_barrier
	s_add_i32 s12, s76, s66
	v_lshl_add_u64 v[190:191], s[56:57], 0, v[192:193]
	s_mov_b32 m0, s12
	ds_read_b128 v[178:181], v145 offset:16384
	ds_read_b128 v[182:185], v145 offset:17408
	ds_read_b128 v[186:189], v145 offset:18432
	ds_read_b128 v[194:197], v145 offset:19456
	ds_read_b128 v[198:201], v145 offset:20480
	ds_read_b128 v[202:205], v145 offset:21504
	ds_read_b128 v[206:209], v145 offset:22528
	ds_read_b128 v[210:213], v145 offset:23552
	global_load_lds_dwordx4 v[190:191], off
	s_add_i32 m0, s12, 0x2000
	s_add_u32 s12, s56, 0x80000
	v_lshl_add_u64 v[214:215], s[56:57], 0, v[132:133]
	s_addc_u32 s13, s57, 0
	s_add_i32 s76, s77, s66
	global_load_lds_dwordx4 v[214:215], off
	v_lshl_add_u64 v[216:217], s[12:13], 0, v[192:193]
	s_mov_b32 m0, s76
	v_lshl_add_u64 v[218:219], s[58:59], 0, v[130:131]
	global_load_lds_dwordx4 v[216:217], off
	v_lshl_add_u64 v[216:217], s[12:13], 0, v[132:133]
	s_add_i32 m0, s76, 0x2000
	s_nop 0
	global_load_lds_dwordx4 v[216:217], off
	v_lshl_add_u64 v[216:217], s[58:59], 0, v[128:129]
	s_mov_b32 m0, s53
	s_nop 0
	global_load_lds_dwordx4 v[216:217], off
	s_mov_b32 m0, s67
	s_nop 0
	global_load_lds_dwordx4 v[218:219], off
	s_waitcnt vmcnt(8)
	s_waitcnt lgkmcnt(0)
	s_barrier
; #define PG8_STAGE(bufoff, gbase, voff) do { _Pragma("unroll") for (int _i = 0; _i < 2; ++_i) \
;         __builtin_amdgcn_global_load_lds((const unsigned*)((const char*)(gbase) + (voff)[_i]), (PG8_LAS unsigned*)(lds + (bufoff) + ldsw + _i * 8192), 16, 0, 0); } while (0)
; #define PG8_LDA(dst, b, h) do { _Pragma("unroll") for (int m = 0; m < 4; ++m) _Pragma("unroll") for (int k = 0; k < 2; ++k) dst[m][k] = *(const PG8_LAS bf16x8*)(lds + PG8_SA(b, h) + aoff + m * 2048 + k * 1024); } while (0)
; #define PG8_LDB(dst, b, h) do { _Pragma("unroll") for (int n = 0; n < 2; ++n) _Pragma("unroll") for (int k = 0; k < 2; ++k) dst[n][k] = *(const PG8_LAS bf16x8*)(lds + PG8_SB(b, h) + boff + n * 2048 + k * 1024); } while (0)
; #define PG8_MMA(ai, bj, At, Bt) do { __builtin_amdgcn_s_setprio(1); _Pragma("unroll") for (int m = 0; m < 4; ++m) _Pragma("unroll") for (int n = 0; n < 2; ++n) _Pragma("unroll") for (int k = 0; k < 2; ++k) \
;         acc[ai][bj][m][n] = __builtin_amdgcn_mfma_f32_16x16x32_bf16(Bt[n][k], At[m][k], acc[ai][bj][m][n], 0, 0, 0); __builtin_amdgcn_s_setprio(0); } while (0)
; #define PG8_WAIT_V(n) asm volatile("s_waitcnt vmcnt(" #n ")" ::: "memory")
; #define PG8_WAIT_L(n) asm volatile("s_waitcnt lgkmcnt(" #n ")" ::: "memory")
; #define PG8_BAR __builtin_amdgcn_s_barrier()
; #define PG8_SCHED __builtin_amdgcn_sched_barrier(0)
; template <class Epi, class Sched, bool ALIGN_EPI = false, bool SP2 = false>
; __device__ __forceinline__ void gemm_phase(PG8_LAS unsigned char* lds, const Gemm g, const Sched& S, const Epi& E, const int tid_in) {
;     ...
;             PG8_WAIT_V(8); PG8_WAIT_L(0); PG8_BAR; PG8_MMA(0, 0, At, B0); PG8_MMA(0, 1, At, B1); PG8_BAR; PG8_SCHED;
;             PG8_LDA(At, 0, 1); PG8_STAGE(PG8_SB(0, 0), b2, voffB); PG8_STAGE(PG8_SB(0, 1), b2 + hstepB, voffB); PG8_STAGE(PG8_SA(0, 0), a2, voffA);
;             PG8_WAIT_V(8); PG8_WAIT_L(0); PG8_BAR; PG8_MMA(1, 0, At, B0); PG8_MMA(1, 1, At, B1); PG8_BAR; PG8_SCHED;
;             PG8_LDB(B0, 1, 0); PG8_LDB(B1, 1, 1); PG8_SCHED; PG8_LDA(At, 1, 0); PG8_STAGE(PG8_SA(0, 1), a2 + hstepA, voffA);
;             PG8_WAIT_V(8); PG8_WAIT_L(0); PG8_BAR; PG8_MMA(0, 0, At, B0); PG8_MMA(0, 1, At, B1); PG8_BAR; PG8_SCHED;
	s_setprio 1
	s_waitcnt lgkmcnt(0)
	v_mfma_f32_16x16x32_bf16 v[60:63], v[146:149], v[178:181], 0
	v_mfma_f32_16x16x32_bf16 v[56:59], v[154:157], v[178:181], 0
	v_mfma_f32_16x16x32_bf16 v[48:51], v[146:149], v[186:189], 0
	v_mfma_f32_16x16x32_bf16 v[40:43], v[154:157], v[186:189], 0
	v_mfma_f32_16x16x32_bf16 v[32:35], v[146:149], v[198:201], 0
	v_mfma_f32_16x16x32_bf16 v[24:27], v[154:157], v[198:201], 0
	v_mfma_f32_16x16x32_bf16 v[16:19], v[146:149], v[206:209], 0
	v_mfma_f32_16x16x32_bf16 v[8:11], v[154:157], v[206:209], 0
	v_mfma_f32_16x16x32_bf16 v[60:63], v[150:153], v[182:185], v[60:63]
	v_mfma_f32_16x16x32_bf16 v[56:59], v[158:161], v[182:185], v[56:59]
	v_mfma_f32_16x16x32_bf16 v[48:51], v[150:153], v[194:197], v[48:51]
	v_mfma_f32_16x16x32_bf16 v[40:43], v[158:161], v[194:197], v[40:43]
	v_mfma_f32_16x16x32_bf16 v[32:35], v[150:153], v[202:205], v[32:35]
	v_mfma_f32_16x16x32_bf16 v[24:27], v[158:161], v[202:205], v[24:27]
	v_mfma_f32_16x16x32_bf16 v[16:19], v[150:153], v[210:213], v[16:19]
	v_mfma_f32_16x16x32_bf16 v[8:11], v[158:161], v[210:213], v[8:11]
	s_setprio 0
	s_setprio 1
	v_mfma_f32_16x16x32_bf16 v[52:55], v[162:165], v[178:181], 0
	v_mfma_f32_16x16x32_bf16 v[44:47], v[170:173], v[178:181], 0
	v_mfma_f32_16x16x32_bf16 v[36:39], v[162:165], v[186:189], 0
	v_mfma_f32_16x16x32_bf16 v[28:31], v[170:173], v[186:189], 0
	v_mfma_f32_16x16x32_bf16 v[20:23], v[162:165], v[198:201], 0
	v_mfma_f32_16x16x32_bf16 v[12:15], v[170:173], v[198:201], 0
	v_mfma_f32_16x16x32_bf16 v[4:7], v[162:165], v[206:209], 0
	v_mfma_f32_16x16x32_bf16 v[0:3], v[170:173], v[206:209], 0
	v_mfma_f32_16x16x32_bf16 v[52:55], v[166:169], v[182:185], v[52:55]
	v_mfma_f32_16x16x32_bf16 v[44:47], v[174:177], v[182:185], v[44:47]
	v_mfma_f32_16x16x32_bf16 v[36:39], v[166:169], v[194:197], v[36:39]
	v_mfma_f32_16x16x32_bf16 v[28:31], v[174:177], v[194:197], v[28:31]
	v_mfma_f32_16x16x32_bf16 v[20:23], v[166:169], v[202:205], v[20:23]
	v_mfma_f32_16x16x32_bf16 v[12:15], v[174:177], v[202:205], v[12:15]
	v_mfma_f32_16x16x32_bf16 v[4:7], v[166:169], v[210:213], v[4:7]
	v_mfma_f32_16x16x32_bf16 v[0:3], v[174:177], v[210:213], v[0:3]
	s_setprio 0
	s_barrier
	s_add_i32 s76, 0, 0x18000
	v_add_u32_e32 v138, s76, v141
	s_add_i32 s77, 0, 0x1c000
	ds_read_b128 v[146:149], v138
	ds_read_b128 v[150:153], v138 offset:1024
	ds_read_b128 v[154:157], v138 offset:2048
	ds_read_b128 v[158:161], v138 offset:3072
	v_add_u32_e32 v138, s77, v141
	ds_read_b128 v[162:165], v138
	ds_read_b128 v[166:169], v138 offset:1024
	ds_read_b128 v[170:173], v138 offset:2048
	ds_read_b128 v[174:177], v138 offset:3072
	s_add_u32 s12, s58, 0x80000
	s_addc_u32 s13, s59, 0
	s_mov_b32 m0, s68
	v_lshl_add_u64 v[220:221], s[12:13], 0, v[128:129]
	ds_read_b128 v[178:181], v145 offset:32768
	ds_read_b128 v[182:185], v145 offset:33792
	ds_read_b128 v[186:189], v145 offset:34816
	ds_read_b128 v[194:197], v145 offset:35840
	ds_read_b128 v[198:201], v145 offset:36864
	ds_read_b128 v[202:205], v145 offset:37888
	ds_read_b128 v[206:209], v145 offset:38912
	ds_read_b128 v[210:213], v145 offset:39936
	global_load_lds_dwordx4 v[220:221], off
	v_lshl_add_u64 v[220:221], s[12:13], 0, v[130:131]
	s_mov_b32 m0, s69
	s_nop 0
	global_load_lds_dwordx4 v[220:221], off
	s_waitcnt vmcnt(8)
	s_waitcnt lgkmcnt(0)
	s_barrier
	s_setprio 1
	s_waitcnt lgkmcnt(0)
	v_mfma_f32_16x16x32_bf16 v[124:127], v[146:149], v[178:181], v[124:127]
	v_mfma_f32_16x16x32_bf16 v[120:123], v[154:157], v[178:181], v[120:123]
	v_mfma_f32_16x16x32_bf16 v[112:115], v[146:149], v[186:189], v[112:115]
	v_mfma_f32_16x16x32_bf16 v[104:107], v[154:157], v[186:189], v[104:107]
	v_mfma_f32_16x16x32_bf16 v[96:99], v[146:149], v[198:201], v[96:99]
	v_mfma_f32_16x16x32_bf16 v[88:91], v[154:157], v[198:201], v[88:91]
	v_mfma_f32_16x16x32_bf16 v[80:83], v[146:149], v[206:209], v[80:83]
	v_mfma_f32_16x16x32_bf16 v[72:75], v[154:157], v[206:209], v[72:75]
	v_mfma_f32_16x16x32_bf16 v[124:127], v[150:153], v[182:185], v[124:127]
	v_mfma_f32_16x16x32_bf16 v[120:123], v[158:161], v[182:185], v[120:123]
	v_mfma_f32_16x16x32_bf16 v[112:115], v[150:153], v[194:197], v[112:115]
	v_mfma_f32_16x16x32_bf16 v[104:107], v[158:161], v[194:197], v[104:107]
	v_mfma_f32_16x16x32_bf16 v[96:99], v[150:153], v[202:205], v[96:99]
	v_mfma_f32_16x16x32_bf16 v[88:91], v[158:161], v[202:205], v[88:91]
	v_mfma_f32_16x16x32_bf16 v[80:83], v[150:153], v[210:213], v[80:83]
	v_mfma_f32_16x16x32_bf16 v[72:75], v[158:161], v[210:213], v[72:75]
	s_setprio 0
	s_setprio 1
	v_mfma_f32_16x16x32_bf16 v[116:119], v[162:165], v[178:181], v[116:119]
	v_mfma_f32_16x16x32_bf16 v[108:111], v[170:173], v[178:181], v[108:111]
	v_mfma_f32_16x16x32_bf16 v[100:103], v[162:165], v[186:189], v[100:103]
	v_mfma_f32_16x16x32_bf16 v[92:95], v[170:173], v[186:189], v[92:95]
	v_mfma_f32_16x16x32_bf16 v[84:87], v[162:165], v[198:201], v[84:87]
	v_mfma_f32_16x16x32_bf16 v[76:79], v[170:173], v[198:201], v[76:79]
	v_mfma_f32_16x16x32_bf16 v[68:71], v[162:165], v[206:209], v[68:71]
	v_mfma_f32_16x16x32_bf16 v[64:67], v[170:173], v[206:209], v[64:67]
	v_mfma_f32_16x16x32_bf16 v[116:119], v[166:169], v[182:185], v[116:119]
	v_mfma_f32_16x16x32_bf16 v[108:111], v[174:177], v[182:185], v[108:111]
	v_mfma_f32_16x16x32_bf16 v[100:103], v[166:169], v[194:197], v[100:103]
	v_mfma_f32_16x16x32_bf16 v[92:95], v[174:177], v[194:197], v[92:95]
	v_mfma_f32_16x16x32_bf16 v[84:87], v[166:169], v[202:205], v[84:87]
	v_mfma_f32_16x16x32_bf16 v[76:79], v[174:177], v[202:205], v[76:79]
	v_mfma_f32_16x16x32_bf16 v[68:71], v[166:169], v[210:213], v[68:71]
	v_mfma_f32_16x16x32_bf16 v[64:67], v[174:177], v[210:213], v[64:67]
	s_setprio 0
	s_barrier
; #define PG8_STAGE(bufoff, gbase, voff) do { _Pragma("unroll") for (int _i = 0; _i < 2; ++_i) \
;         __builtin_amdgcn_global_load_lds((const unsigned*)((const char*)(gbase) + (voff)[_i]), (PG8_LAS unsigned*)(lds + (bufoff) + ldsw + _i * 8192), 16, 0, 0); } while (0)
; #define PG8_LDA(dst, b, h) do { _Pragma("unroll") for (int m = 0; m < 4; ++m) _Pragma("unroll") for (int k = 0; k < 2; ++k) dst[m][k] = *(const PG8_LAS bf16x8*)(lds + PG8_SA(b, h) + aoff + m * 2048 + k * 1024); } while (0)
; #define PG8_LDB(dst, b, h) do { _Pragma("unroll") for (int n = 0; n < 2; ++n) _Pragma("unroll") for (int k = 0; k < 2; ++k) dst[n][k] = *(const PG8_LAS bf16x8*)(lds + PG8_SB(b, h) + boff + n * 2048 + k * 1024); } while (0)
; #define PG8_MMA(ai, bj, At, Bt) do { __builtin_amdgcn_s_setprio(1); _Pragma("unroll") for (int m = 0; m < 4; ++m) _Pragma("unroll") for (int n = 0; n < 2; ++n) _Pragma("unroll") for (int k = 0; k < 2; ++k) \
;         acc[ai][bj][m][n] = __builtin_amdgcn_mfma_f32_16x16x32_bf16(Bt[n][k], At[m][k], acc[ai][bj][m][n], 0, 0, 0); __builtin_amdgcn_s_setprio(0); } while (0)
; #define PG8_BAR __builtin_amdgcn_s_barrier()
; template <class Epi, class Sched, bool ALIGN_EPI = false, bool SP2 = false>
; __device__ __forceinline__ void gemm_phase(PG8_LAS unsigned char* lds, const Gemm g, const Sched& S, const Epi& E, const int tid_in) {
;     ...
;             PG8_LDB(B0, 0, 0); PG8_LDB(B1, 0, 1); PG8_SCHED; PG8_LDA(At, 0, 0); PG8_STAGE(PG8_SA(1, 1), a1 + hstepA, voffA);
;             PG8_WAIT_V(8); PG8_WAIT_L(0); PG8_BAR; PG8_MMA(0, 0, At, B0); PG8_MMA(0, 1, At, B1); PG8_BAR; PG8_SCHED;
;             PG8_LDA(At, 0, 1); PG8_STAGE(PG8_SB(0, 0), b2, voffB); PG8_STAGE(PG8_SB(0, 1), b2 + hstepB, voffB); PG8_STAGE(PG8_SA(0, 0), a2, voffA);
;             PG8_WAIT_V(8); PG8_WAIT_L(0); PG8_BAR; PG8_MMA(1, 0, At, B0); PG8_MMA(1, 1, At, B1); PG8_BAR; PG8_SCHED;
;             PG8_LDB(B0, 1, 0); PG8_LDB(B1, 1, 1); PG8_SCHED; PG8_LDA(At, 1, 0); PG8_STAGE(PG8_SA(0, 1), a2 + hstepA, voffA);
;             PG8_WAIT_V(8); PG8_WAIT_L(0); PG8_BAR; PG8_MMA(0, 0, At, B0); PG8_MMA(0, 1, At, B1); PG8_BAR; PG8_SCHED;
;             PG8_LDA(At, 1, 1); PG8_STAGE(PG8_SB(1, 0), b3, voffB); PG8_STAGE(PG8_SB(1, 1), b3 + hstepB, voffB); PG8_STAGE(PG8_SA(1, 0), a3, voffA);
;             PG8_WAIT_V(8); PG8_WAIT_L(0); PG8_BAR; PG8_MMA(1, 0, At, B0); PG8_MMA(1, 1, At, B1); PG8_BAR; PG8_SCHED;
	s_add_i32 s12, s76, s66
	v_lshl_add_u64 v[190:191], v[190:191], 0, s[26:27]
	s_mov_b32 m0, s12
	ds_read_b128 v[178:181], v145 offset:49152
	ds_read_b128 v[182:185], v145 offset:50176
	ds_read_b128 v[186:189], v145 offset:51200
	ds_read_b128 v[194:197], v145 offset:52224
	ds_read_b128 v[198:201], v145 offset:53248
	ds_read_b128 v[202:205], v145 offset:54272
	ds_read_b128 v[206:209], v145 offset:55296
	ds_read_b128 v[210:213], v145 offset:56320
	global_load_lds_dwordx4 v[190:191], off
	s_add_i32 m0, s12, 0x2000
	s_add_u32 s12, s56, 0x80080
	v_lshl_add_u64 v[190:191], v[214:215], 0, s[26:27]
	s_addc_u32 s13, s57, 0
	s_add_i32 s56, s77, s66
	global_load_lds_dwordx4 v[190:191], off
	v_lshl_add_u64 v[190:191], s[12:13], 0, v[192:193]
	s_mov_b32 m0, s56
	s_nop 0
	global_load_lds_dwordx4 v[190:191], off
	v_lshl_add_u64 v[190:191], s[12:13], 0, v[132:133]
	s_add_i32 m0, s56, 0x2000
	s_nop 0
	global_load_lds_dwordx4 v[190:191], off
	v_lshl_add_u64 v[190:191], v[216:217], 0, s[26:27]
	s_mov_b32 m0, s11
	s_nop 0
	global_load_lds_dwordx4 v[190:191], off
	v_lshl_add_u64 v[190:191], v[218:219], 0, s[26:27]
	s_mov_b32 m0, s70
	s_nop 0
	global_load_lds_dwordx4 v[190:191], off
	s_waitcnt vmcnt(8)
	s_waitcnt lgkmcnt(0)
	s_barrier
	s_setprio 1
	s_waitcnt lgkmcnt(0)
	v_mfma_f32_16x16x32_bf16 v[60:63], v[146:149], v[178:181], v[60:63]
	v_mfma_f32_16x16x32_bf16 v[56:59], v[154:157], v[178:181], v[56:59]
	v_mfma_f32_16x16x32_bf16 v[48:51], v[146:149], v[186:189], v[48:51]
	v_mfma_f32_16x16x32_bf16 v[40:43], v[154:157], v[186:189], v[40:43]
	v_mfma_f32_16x16x32_bf16 v[32:35], v[146:149], v[198:201], v[32:35]
	v_mfma_f32_16x16x32_bf16 v[24:27], v[154:157], v[198:201], v[24:27]
	v_mfma_f32_16x16x32_bf16 v[16:19], v[146:149], v[206:209], v[16:19]
	v_mfma_f32_16x16x32_bf16 v[8:11], v[154:157], v[206:209], v[8:11]
	v_mfma_f32_16x16x32_bf16 v[60:63], v[150:153], v[182:185], v[60:63]
	v_mfma_f32_16x16x32_bf16 v[56:59], v[158:161], v[182:185], v[56:59]
	v_mfma_f32_16x16x32_bf16 v[48:51], v[150:153], v[194:197], v[48:51]
	v_mfma_f32_16x16x32_bf16 v[40:43], v[158:161], v[194:197], v[40:43]
	v_mfma_f32_16x16x32_bf16 v[32:35], v[150:153], v[202:205], v[32:35]
	v_mfma_f32_16x16x32_bf16 v[24:27], v[158:161], v[202:205], v[24:27]
	v_mfma_f32_16x16x32_bf16 v[16:19], v[150:153], v[210:213], v[16:19]
	v_mfma_f32_16x16x32_bf16 v[8:11], v[158:161], v[210:213], v[8:11]
	s_setprio 0
	s_setprio 1
	v_mfma_f32_16x16x32_bf16 v[52:55], v[162:165], v[178:181], v[52:55]
	v_mfma_f32_16x16x32_bf16 v[44:47], v[170:173], v[178:181], v[44:47]
	v_mfma_f32_16x16x32_bf16 v[36:39], v[162:165], v[186:189], v[36:39]
	v_mfma_f32_16x16x32_bf16 v[28:31], v[170:173], v[186:189], v[28:31]
	v_mfma_f32_16x16x32_bf16 v[20:23], v[162:165], v[198:201], v[20:23]
	v_mfma_f32_16x16x32_bf16 v[12:15], v[170:173], v[198:201], v[12:15]
	v_mfma_f32_16x16x32_bf16 v[4:7], v[162:165], v[206:209], v[4:7]
	v_mfma_f32_16x16x32_bf16 v[0:3], v[170:173], v[206:209], v[0:3]
	v_mfma_f32_16x16x32_bf16 v[52:55], v[166:169], v[182:185], v[52:55]
	v_mfma_f32_16x16x32_bf16 v[44:47], v[174:177], v[182:185], v[44:47]
	v_mfma_f32_16x16x32_bf16 v[36:39], v[166:169], v[194:197], v[36:39]
	v_mfma_f32_16x16x32_bf16 v[28:31], v[174:177], v[194:197], v[28:31]
	v_mfma_f32_16x16x32_bf16 v[20:23], v[166:169], v[202:205], v[20:23]
	v_mfma_f32_16x16x32_bf16 v[12:15], v[174:177], v[202:205], v[12:15]
	v_mfma_f32_16x16x32_bf16 v[4:7], v[166:169], v[210:213], v[4:7]
	v_mfma_f32_16x16x32_bf16 v[0:3], v[174:177], v[210:213], v[0:3]
	s_setprio 0
	s_barrier
	s_add_i32 s75, s75, 2
	s_add_u32 s54, s54, 0x100
	s_addc_u32 s55, s55, 0
	s_add_u32 s73, s73, 0x100
	s_addc_u32 s74, s74, 0
	s_cmp_gt_u32 s75, 29
	.p2align 6
.LBB0_1060:
	s_add_u32 s12, s54, 0xfff80080
	s_addc_u32 s13, s55, -1
	s_add_i32 s76, 0, 0x10000
	s_cmp_eq_u32 s75, 28
	s_cselect_b32 s59, s37, s13
	s_cselect_b32 s58, s47, s12
	v_add_u32_e32 v138, s76, v141
	s_cselect_b32 s57, s45, s74
	s_cselect_b32 s56, s72, s73
	s_add_i32 s77, 0, 0x14000
	ds_read_b128 v[146:149], v138
	ds_read_b128 v[150:153], v138 offset:1024
	ds_read_b128 v[154:157], v138 offset:2048
	ds_read_b128 v[158:161], v138 offset:3072
	v_add_u32_e32 v138, s77, v141
	ds_read_b128 v[162:165], v138
	ds_read_b128 v[166:169], v138 offset:1024
	ds_read_b128 v[170:173], v138 offset:2048
	ds_read_b128 v[174:177], v138 offset:3072
	v_lshl_add_u64 v[190:191], s[54:55], 0, v[134:135]
	s_add_i32 m0, s53, 0xc000
	ds_read_b128 v[178:181], v145
	ds_read_b128 v[182:185], v145 offset:1024
	ds_read_b128 v[186:189], v145 offset:2048
	ds_read_b128 v[194:197], v145 offset:3072
	ds_read_b128 v[198:201], v145 offset:4096
	ds_read_b128 v[202:205], v145 offset:5120
	ds_read_b128 v[206:209], v145 offset:6144
	ds_read_b128 v[210:213], v145 offset:7168
	global_load_lds_dwordx4 v[190:191], off
	v_lshl_add_u64 v[190:191], s[54:55], 0, v[136:137]
	s_add_i32 m0, s53, 0xe000
	s_nop 0
	global_load_lds_dwordx4 v[190:191], off
	s_waitcnt vmcnt(8)
	s_waitcnt lgkmcnt(0)
	s_barrier
; #define PG8_STAGE(bufoff, gbase, voff) do { _Pragma("unroll") for (int _i = 0; _i < 2; ++_i) \
;         __builtin_amdgcn_global_load_lds((const unsigned*)((const char*)(gbase) + (voff)[_i]), (PG8_LAS unsigned*)(lds + (bufoff) + ldsw + _i * 8192), 16, 0, 0); } while (0)
; #define PG8_LDA(dst, b, h) do { _Pragma("unroll") for (int m = 0; m < 4; ++m) _Pragma("unroll") for (int k = 0; k < 2; ++k) dst[m][k] = *(const PG8_LAS bf16x8*)(lds + PG8_SA(b, h) + aoff + m * 2048 + k * 1024); } while (0)
; #define PG8_LDB(dst, b, h) do { _Pragma("unroll") for (int n = 0; n < 2; ++n) _Pragma("unroll") for (int k = 0; k < 2; ++k) dst[n][k] = *(const PG8_LAS bf16x8*)(lds + PG8_SB(b, h) + boff + n * 2048 + k * 1024); } while (0)
; #define PG8_MMA(ai, bj, At, Bt) do { __builtin_amdgcn_s_setprio(1); _Pragma("unroll") for (int m = 0; m < 4; ++m) _Pragma("unroll") for (int n = 0; n < 2; ++n) _Pragma("unroll") for (int k = 0; k < 2; ++k) \
;         acc[ai][bj][m][n] = __builtin_amdgcn_mfma_f32_16x16x32_bf16(Bt[n][k], At[m][k], acc[ai][bj][m][n], 0, 0, 0); __builtin_amdgcn_s_setprio(0); } while (0)
; #define PG8_WAIT_V(n) asm volatile("s_waitcnt vmcnt(" #n ")" ::: "memory")
; #define PG8_WAIT_L(n) asm volatile("s_waitcnt lgkmcnt(" #n ")" ::: "memory")
; #define PG8_BAR __builtin_amdgcn_s_barrier()
; #define PG8_SCHED __builtin_amdgcn_sched_barrier(0)
; template <class Epi, class Sched, bool ALIGN_EPI = false, bool SP2 = false>
; __device__ __forceinline__ void gemm_phase(PG8_LAS unsigned char* lds, const Gemm g, const Sched& S, const Epi& E, const int tid_in) {
;     ...
;             PG8_LDB(B0, 0, 0); PG8_LDB(B1, 0, 1); PG8_SCHED; PG8_LDA(At, 0, 0); PG8_STAGE(PG8_SA(1, 1), a1 + hstepA, voffA);
;             PG8_WAIT_V(8); PG8_WAIT_L(0); PG8_BAR; PG8_MMA(0, 0, At, B0); PG8_MMA(0, 1, At, B1); PG8_BAR; PG8_SCHED;
;             PG8_LDA(At, 0, 1); PG8_STAGE(PG8_SB(0, 0), b2, voffB); PG8_STAGE(PG8_SB(0, 1), b2 + hstepB, voffB); PG8_STAGE(PG8_SA(0, 0), a2, voffA);
;             PG8_WAIT_V(8); PG8_WAIT_L(0); PG8_BAR; PG8_MMA(1, 0, At, B0); PG8_MMA(1, 1, At, B1); PG8_BAR; PG8_SCHED;
	s_setprio 1
	s_waitcnt lgkmcnt(0)
	v_mfma_f32_16x16x32_bf16 v[124:127], v[146:149], v[178:181], v[124:127]
	v_mfma_f32_16x16x32_bf16 v[120:123], v[154:157], v[178:181], v[120:123]
	v_mfma_f32_16x16x32_bf16 v[112:115], v[146:149], v[186:189], v[112:115]
	v_mfma_f32_16x16x32_bf16 v[104:107], v[154:157], v[186:189], v[104:107]
	v_mfma_f32_16x16x32_bf16 v[96:99], v[146:149], v[198:201], v[96:99]
	v_mfma_f32_16x16x32_bf16 v[88:91], v[154:157], v[198:201], v[88:91]
	v_mfma_f32_16x16x32_bf16 v[80:83], v[146:149], v[206:209], v[80:83]
	v_mfma_f32_16x16x32_bf16 v[72:75], v[154:157], v[206:209], v[72:75]
	v_mfma_f32_16x16x32_bf16 v[124:127], v[150:153], v[182:185], v[124:127]
	v_mfma_f32_16x16x32_bf16 v[120:123], v[158:161], v[182:185], v[120:123]
	v_mfma_f32_16x16x32_bf16 v[112:115], v[150:153], v[194:197], v[112:115]
	v_mfma_f32_16x16x32_bf16 v[104:107], v[158:161], v[194:197], v[104:107]
	v_mfma_f32_16x16x32_bf16 v[96:99], v[150:153], v[202:205], v[96:99]
	v_mfma_f32_16x16x32_bf16 v[88:91], v[158:161], v[202:205], v[88:91]
	v_mfma_f32_16x16x32_bf16 v[80:83], v[150:153], v[210:213], v[80:83]
	v_mfma_f32_16x16x32_bf16 v[72:75], v[158:161], v[210:213], v[72:75]
	v_mfma_f32_16x16x32_bf16 v[116:119], v[162:165], v[178:181], v[116:119]
	v_mfma_f32_16x16x32_bf16 v[108:111], v[170:173], v[178:181], v[108:111]
	v_mfma_f32_16x16x32_bf16 v[100:103], v[162:165], v[186:189], v[100:103]
	v_mfma_f32_16x16x32_bf16 v[92:95], v[170:173], v[186:189], v[92:95]
	v_mfma_f32_16x16x32_bf16 v[84:87], v[162:165], v[198:201], v[84:87]
	v_mfma_f32_16x16x32_bf16 v[76:79], v[170:173], v[198:201], v[76:79]
	v_mfma_f32_16x16x32_bf16 v[68:71], v[162:165], v[206:209], v[68:71]
	v_mfma_f32_16x16x32_bf16 v[64:67], v[170:173], v[206:209], v[64:67]
	v_mfma_f32_16x16x32_bf16 v[116:119], v[166:169], v[182:185], v[116:119]
	v_mfma_f32_16x16x32_bf16 v[108:111], v[174:177], v[182:185], v[108:111]
	v_mfma_f32_16x16x32_bf16 v[100:103], v[166:169], v[194:197], v[100:103]
	v_mfma_f32_16x16x32_bf16 v[92:95], v[174:177], v[194:197], v[92:95]
	v_mfma_f32_16x16x32_bf16 v[84:87], v[166:169], v[202:205], v[84:87]
	v_mfma_f32_16x16x32_bf16 v[76:79], v[174:177], v[202:205], v[76:79]
	v_mfma_f32_16x16x32_bf16 v[68:71], v[166:169], v[210:213], v[68:71]
	v_mfma_f32_16x16x32_bf16 v[64:67], v[174:177], v[210:213], v[64:67]
	s_setprio 0
	s_barrier
	s_add_i32 s12, s76, s66
	v_lshl_add_u64 v[190:191], s[56:57], 0, v[192:193]
	s_mov_b32 m0, s12
	ds_read_b128 v[178:181], v145 offset:16384
	ds_read_b128 v[182:185], v145 offset:17408
	ds_read_b128 v[186:189], v145 offset:18432
	ds_read_b128 v[194:197], v145 offset:19456
	ds_read_b128 v[198:201], v145 offset:20480
	ds_read_b128 v[202:205], v145 offset:21504
	ds_read_b128 v[206:209], v145 offset:22528
	ds_read_b128 v[210:213], v145 offset:23552
	global_load_lds_dwordx4 v[190:191], off
	s_add_i32 m0, s12, 0x2000
	s_add_u32 s12, s56, 0x80000
	v_lshl_add_u64 v[214:215], s[56:57], 0, v[132:133]
	s_addc_u32 s13, s57, 0
	s_add_i32 s76, s77, s66
	global_load_lds_dwordx4 v[214:215], off
	v_lshl_add_u64 v[216:217], s[12:13], 0, v[192:193]
	s_mov_b32 m0, s76
	v_lshl_add_u64 v[218:219], s[58:59], 0, v[130:131]
	global_load_lds_dwordx4 v[216:217], off
	v_lshl_add_u64 v[216:217], s[12:13], 0, v[132:133]
	s_add_i32 m0, s76, 0x2000
	s_nop 0
	global_load_lds_dwordx4 v[216:217], off
	v_lshl_add_u64 v[216:217], s[58:59], 0, v[128:129]
	s_mov_b32 m0, s53
	s_nop 0
	global_load_lds_dwordx4 v[216:217], off
	s_mov_b32 m0, s67
	s_nop 0
	global_load_lds_dwordx4 v[218:219], off
	s_waitcnt vmcnt(8)
	s_waitcnt lgkmcnt(0)
	s_barrier
	s_setprio 1
	s_waitcnt lgkmcnt(0)
	v_mfma_f32_16x16x32_bf16 v[60:63], v[146:149], v[178:181], v[60:63]
	v_mfma_f32_16x16x32_bf16 v[56:59], v[154:157], v[178:181], v[56:59]
	v_mfma_f32_16x16x32_bf16 v[48:51], v[146:149], v[186:189], v[48:51]
	v_mfma_f32_16x16x32_bf16 v[40:43], v[154:157], v[186:189], v[40:43]
	v_mfma_f32_16x16x32_bf16 v[32:35], v[146:149], v[198:201], v[32:35]
	v_mfma_f32_16x16x32_bf16 v[24:27], v[154:157], v[198:201], v[24:27]
	v_mfma_f32_16x16x32_bf16 v[16:19], v[146:149], v[206:209], v[16:19]
	v_mfma_f32_16x16x32_bf16 v[8:11], v[154:157], v[206:209], v[8:11]
	v_mfma_f32_16x16x32_bf16 v[60:63], v[150:153], v[182:185], v[60:63]
	v_mfma_f32_16x16x32_bf16 v[56:59], v[158:161], v[182:185], v[56:59]
	v_mfma_f32_16x16x32_bf16 v[48:51], v[150:153], v[194:197], v[48:51]
	v_mfma_f32_16x16x32_bf16 v[40:43], v[158:161], v[194:197], v[40:43]
	v_mfma_f32_16x16x32_bf16 v[32:35], v[150:153], v[202:205], v[32:35]
	v_mfma_f32_16x16x32_bf16 v[24:27], v[158:161], v[202:205], v[24:27]
	v_mfma_f32_16x16x32_bf16 v[16:19], v[150:153], v[210:213], v[16:19]
	v_mfma_f32_16x16x32_bf16 v[8:11], v[158:161], v[210:213], v[8:11]
	v_mfma_f32_16x16x32_bf16 v[52:55], v[162:165], v[178:181], v[52:55]
	v_mfma_f32_16x16x32_bf16 v[44:47], v[170:173], v[178:181], v[44:47]
	v_mfma_f32_16x16x32_bf16 v[36:39], v[162:165], v[186:189], v[36:39]
	v_mfma_f32_16x16x32_bf16 v[28:31], v[170:173], v[186:189], v[28:31]
	v_mfma_f32_16x16x32_bf16 v[20:23], v[162:165], v[198:201], v[20:23]
	v_mfma_f32_16x16x32_bf16 v[12:15], v[170:173], v[198:201], v[12:15]
	v_mfma_f32_16x16x32_bf16 v[4:7], v[162:165], v[206:209], v[4:7]
	v_mfma_f32_16x16x32_bf16 v[0:3], v[170:173], v[206:209], v[0:3]
	v_mfma_f32_16x16x32_bf16 v[52:55], v[166:169], v[182:185], v[52:55]
	v_mfma_f32_16x16x32_bf16 v[44:47], v[174:177], v[182:185], v[44:47]
	v_mfma_f32_16x16x32_bf16 v[36:39], v[166:169], v[194:197], v[36:39]
	v_mfma_f32_16x16x32_bf16 v[28:31], v[174:177], v[194:197], v[28:31]
	v_mfma_f32_16x16x32_bf16 v[20:23], v[166:169], v[202:205], v[20:23]
	v_mfma_f32_16x16x32_bf16 v[12:15], v[174:177], v[202:205], v[12:15]
	v_mfma_f32_16x16x32_bf16 v[4:7], v[166:169], v[210:213], v[4:7]
	v_mfma_f32_16x16x32_bf16 v[0:3], v[174:177], v[210:213], v[0:3]
	s_setprio 0
	s_barrier
; #define PG8_STAGE(bufoff, gbase, voff) do { _Pragma("unroll") for (int _i = 0; _i < 2; ++_i) \
;         __builtin_amdgcn_global_load_lds((const unsigned*)((const char*)(gbase) + (voff)[_i]), (PG8_LAS unsigned*)(lds + (bufoff) + ldsw + _i * 8192), 16, 0, 0); } while (0)
; #define PG8_LDA(dst, b, h) do { _Pragma("unroll") for (int m = 0; m < 4; ++m) _Pragma("unroll") for (int k = 0; k < 2; ++k) dst[m][k] = *(const PG8_LAS bf16x8*)(lds + PG8_SA(b, h) + aoff + m * 2048 + k * 1024); } while (0)
; #define PG8_LDB(dst, b, h) do { _Pragma("unroll") for (int n = 0; n < 2; ++n) _Pragma("unroll") for (int k = 0; k < 2; ++k) dst[n][k] = *(const PG8_LAS bf16x8*)(lds + PG8_SB(b, h) + boff + n * 2048 + k * 1024); } while (0)
; #define PG8_MMA(ai, bj, At, Bt) do { __builtin_amdgcn_s_setprio(1); _Pragma("unroll") for (int m = 0; m < 4; ++m) _Pragma("unroll") for (int n = 0; n < 2; ++n) _Pragma("unroll") for (int k = 0; k < 2; ++k) \
;         acc[ai][bj][m][n] = __builtin_amdgcn_mfma_f32_16x16x32_bf16(Bt[n][k], At[m][k], acc[ai][bj][m][n], 0, 0, 0); __builtin_amdgcn_s_setprio(0); } while (0)
; #define PG8_WAIT_V(n) asm volatile("s_waitcnt vmcnt(" #n ")" ::: "memory")
; #define PG8_WAIT_L(n) asm volatile("s_waitcnt lgkmcnt(" #n ")" ::: "memory")
; #define PG8_BAR __builtin_amdgcn_s_barrier()
; #define PG8_SCHED __builtin_amdgcn_sched_barrier(0)
; template <class Epi, class Sched, bool ALIGN_EPI = false, bool SP2 = false>
; __device__ __forceinline__ void gemm_phase(PG8_LAS unsigned char* lds, const Gemm g, const Sched& S, const Epi& E, const int tid_in) {
;     ...
;             PG8_LDB(B0, 1, 0); PG8_LDB(B1, 1, 1); PG8_SCHED; PG8_LDA(At, 1, 0); PG8_STAGE(PG8_SA(0, 1), a2 + hstepA, voffA);
;             PG8_WAIT_V(8); PG8_WAIT_L(0); PG8_BAR; PG8_MMA(0, 0, At, B0); PG8_MMA(0, 1, At, B1); PG8_BAR; PG8_SCHED;
	s_add_i32 s76, 0, 0x18000
	v_add_u32_e32 v138, s76, v141
	s_add_i32 s77, 0, 0x1c000
	ds_read_b128 v[146:149], v138
	ds_read_b128 v[150:153], v138 offset:1024
	ds_read_b128 v[154:157], v138 offset:2048
	ds_read_b128 v[158:161], v138 offset:3072
	v_add_u32_e32 v138, s77, v141
	ds_read_b128 v[162:165], v138
	ds_read_b128 v[166:169], v138 offset:1024
	ds_read_b128 v[170:173], v138 offset:2048
	ds_read_b128 v[174:177], v138 offset:3072
	s_add_u32 s12, s58, 0x80000
	s_addc_u32 s13, s59, 0
	s_mov_b32 m0, s68
	v_lshl_add_u64 v[220:221], s[12:13], 0, v[128:129]
	ds_read_b128 v[178:181], v145 offset:32768
	ds_read_b128 v[182:185], v145 offset:33792
	ds_read_b128 v[186:189], v145 offset:34816
	ds_read_b128 v[194:197], v145 offset:35840
	ds_read_b128 v[198:201], v145 offset:36864
	ds_read_b128 v[202:205], v145 offset:37888
	ds_read_b128 v[206:209], v145 offset:38912
	ds_read_b128 v[210:213], v145 offset:39936
	global_load_lds_dwordx4 v[220:221], off
	v_lshl_add_u64 v[220:221], s[12:13], 0, v[130:131]
	s_mov_b32 m0, s69
	s_nop 0
	global_load_lds_dwordx4 v[220:221], off
	s_waitcnt vmcnt(8)
	s_waitcnt lgkmcnt(0)
	s_barrier
	s_setprio 1
	s_waitcnt lgkmcnt(0)
	v_mfma_f32_16x16x32_bf16 v[124:127], v[146:149], v[178:181], v[124:127]
	v_mfma_f32_16x16x32_bf16 v[120:123], v[154:157], v[178:181], v[120:123]
	v_mfma_f32_16x16x32_bf16 v[112:115], v[146:149], v[186:189], v[112:115]
	v_mfma_f32_16x16x32_bf16 v[104:107], v[154:157], v[186:189], v[104:107]
	v_mfma_f32_16x16x32_bf16 v[96:99], v[146:149], v[198:201], v[96:99]
	v_mfma_f32_16x16x32_bf16 v[88:91], v[154:157], v[198:201], v[88:91]
	v_mfma_f32_16x16x32_bf16 v[80:83], v[146:149], v[206:209], v[80:83]
	v_mfma_f32_16x16x32_bf16 v[72:75], v[154:157], v[206:209], v[72:75]
	v_mfma_f32_16x16x32_bf16 v[124:127], v[150:153], v[182:185], v[124:127]
	v_mfma_f32_16x16x32_bf16 v[120:123], v[158:161], v[182:185], v[120:123]
	v_mfma_f32_16x16x32_bf16 v[112:115], v[150:153], v[194:197], v[112:115]
	v_mfma_f32_16x16x32_bf16 v[104:107], v[158:161], v[194:197], v[104:107]
	v_mfma_f32_16x16x32_bf16 v[96:99], v[150:153], v[202:205], v[96:99]
	v_mfma_f32_16x16x32_bf16 v[88:91], v[158:161], v[202:205], v[88:91]
	v_mfma_f32_16x16x32_bf16 v[80:83], v[150:153], v[210:213], v[80:83]
	v_mfma_f32_16x16x32_bf16 v[72:75], v[158:161], v[210:213], v[72:75]
	v_mfma_f32_16x16x32_bf16 v[116:119], v[162:165], v[178:181], v[116:119]
	v_mfma_f32_16x16x32_bf16 v[108:111], v[170:173], v[178:181], v[108:111]
	v_mfma_f32_16x16x32_bf16 v[100:103], v[162:165], v[186:189], v[100:103]
	v_mfma_f32_16x16x32_bf16 v[92:95], v[170:173], v[186:189], v[92:95]
	v_mfma_f32_16x16x32_bf16 v[84:87], v[162:165], v[198:201], v[84:87]
	v_mfma_f32_16x16x32_bf16 v[76:79], v[170:173], v[198:201], v[76:79]
	v_mfma_f32_16x16x32_bf16 v[68:71], v[162:165], v[206:209], v[68:71]
	v_mfma_f32_16x16x32_bf16 v[64:67], v[170:173], v[206:209], v[64:67]
	v_mfma_f32_16x16x32_bf16 v[116:119], v[166:169], v[182:185], v[116:119]
	v_mfma_f32_16x16x32_bf16 v[108:111], v[174:177], v[182:185], v[108:111]
	v_mfma_f32_16x16x32_bf16 v[100:103], v[166:169], v[194:197], v[100:103]
	v_mfma_f32_16x16x32_bf16 v[92:95], v[174:177], v[194:197], v[92:95]
	v_mfma_f32_16x16x32_bf16 v[84:87], v[166:169], v[202:205], v[84:87]
	v_mfma_f32_16x16x32_bf16 v[76:79], v[174:177], v[202:205], v[76:79]
	v_mfma_f32_16x16x32_bf16 v[68:71], v[166:169], v[210:213], v[68:71]
	v_mfma_f32_16x16x32_bf16 v[64:67], v[174:177], v[210:213], v[64:67]
	s_setprio 0
	s_barrier
; #define PG8_STAGE(bufoff, gbase, voff) do { _Pragma("unroll") for (int _i = 0; _i < 2; ++_i) \
;         __builtin_amdgcn_global_load_lds((const unsigned*)((const char*)(gbase) + (voff)[_i]), (PG8_LAS unsigned*)(lds + (bufoff) + ldsw + _i * 8192), 16, 0, 0); } while (0)
; #define PG8_LDA(dst, b, h) do { _Pragma("unroll") for (int m = 0; m < 4; ++m) _Pragma("unroll") for (int k = 0; k < 2; ++k) dst[m][k] = *(const PG8_LAS bf16x8*)(lds + PG8_SA(b, h) + aoff + m * 2048 + k * 1024); } while (0)
; #define PG8_MMA(ai, bj, At, Bt) do { __builtin_amdgcn_s_setprio(1); _Pragma("unroll") for (int m = 0; m < 4; ++m) _Pragma("unroll") for (int n = 0; n < 2; ++n) _Pragma("unroll") for (int k = 0; k < 2; ++k) \
;         acc[ai][bj][m][n] = __builtin_amdgcn_mfma_f32_16x16x32_bf16(Bt[n][k], At[m][k], acc[ai][bj][m][n], 0, 0, 0); __builtin_amdgcn_s_setprio(0); } while (0)
; #define PG8_WAIT_V(n) asm volatile("s_waitcnt vmcnt(" #n ")" ::: "memory")
; #define PG8_WAIT_L(n) asm volatile("s_waitcnt lgkmcnt(" #n ")" ::: "memory")
; #define PG8_BAR __builtin_amdgcn_s_barrier()
; #define PG8_SCHED __builtin_amdgcn_sched_barrier(0)
; template <class Epi, class Sched, bool ALIGN_EPI = false, bool SP2 = false>
; __device__ __forceinline__ void gemm_phase(PG8_LAS unsigned char* lds, const Gemm g, const Sched& S, const Epi& E, const int tid_in) {
;     ...
;             PG8_LDA(At, 1, 1); PG8_STAGE(PG8_SB(1, 0), b3, voffB); PG8_STAGE(PG8_SB(1, 1), b3 + hstepB, voffB); PG8_STAGE(PG8_SA(1, 0), a3, voffA);
;             PG8_WAIT_V(8); PG8_WAIT_L(0); PG8_BAR; PG8_MMA(1, 0, At, B0); PG8_MMA(1, 1, At, B1); PG8_BAR; PG8_SCHED;
;     ...
;         if constexpr (ALIGN_EPI) { if (wr == 0) PG8_BAR; }
	s_add_i32 s12, s76, s66
	v_lshl_add_u64 v[190:191], v[190:191], 0, s[26:27]
	s_mov_b32 m0, s12
	ds_read_b128 v[178:181], v145 offset:49152
	ds_read_b128 v[182:185], v145 offset:50176
	ds_read_b128 v[186:189], v145 offset:51200
	ds_read_b128 v[194:197], v145 offset:52224
	ds_read_b128 v[198:201], v145 offset:53248
	ds_read_b128 v[202:205], v145 offset:54272
	ds_read_b128 v[206:209], v145 offset:55296
	ds_read_b128 v[210:213], v145 offset:56320
	global_load_lds_dwordx4 v[190:191], off
	s_add_i32 m0, s12, 0x2000
	s_add_u32 s12, s56, 0x80080
	v_lshl_add_u64 v[190:191], v[214:215], 0, s[26:27]
	s_addc_u32 s13, s57, 0
	s_add_i32 s56, s77, s66
	global_load_lds_dwordx4 v[190:191], off
	v_lshl_add_u64 v[190:191], s[12:13], 0, v[192:193]
	s_mov_b32 m0, s56
	s_nop 0
	global_load_lds_dwordx4 v[190:191], off
	v_lshl_add_u64 v[190:191], s[12:13], 0, v[132:133]
	s_add_i32 m0, s56, 0x2000
	s_nop 0
	global_load_lds_dwordx4 v[190:191], off
	v_lshl_add_u64 v[190:191], v[216:217], 0, s[26:27]
	s_mov_b32 m0, s11
	s_nop 0
	global_load_lds_dwordx4 v[190:191], off
	v_lshl_add_u64 v[190:191], v[218:219], 0, s[26:27]
	s_mov_b32 m0, s70
	s_nop 0
	global_load_lds_dwordx4 v[190:191], off
	s_waitcnt vmcnt(8)
	s_waitcnt lgkmcnt(0)
	s_barrier
	s_setprio 1
	s_waitcnt lgkmcnt(0)
	v_mfma_f32_16x16x32_bf16 v[60:63], v[146:149], v[178:181], v[60:63]
	v_mfma_f32_16x16x32_bf16 v[56:59], v[154:157], v[178:181], v[56:59]
	v_mfma_f32_16x16x32_bf16 v[48:51], v[146:149], v[186:189], v[48:51]
	v_mfma_f32_16x16x32_bf16 v[40:43], v[154:157], v[186:189], v[40:43]
	v_mfma_f32_16x16x32_bf16 v[32:35], v[146:149], v[198:201], v[32:35]
	v_mfma_f32_16x16x32_bf16 v[24:27], v[154:157], v[198:201], v[24:27]
	v_mfma_f32_16x16x32_bf16 v[16:19], v[146:149], v[206:209], v[16:19]
	v_mfma_f32_16x16x32_bf16 v[8:11], v[154:157], v[206:209], v[8:11]
	v_mfma_f32_16x16x32_bf16 v[60:63], v[150:153], v[182:185], v[60:63]
	v_mfma_f32_16x16x32_bf16 v[56:59], v[158:161], v[182:185], v[56:59]
	v_mfma_f32_16x16x32_bf16 v[48:51], v[150:153], v[194:197], v[48:51]
	v_mfma_f32_16x16x32_bf16 v[40:43], v[158:161], v[194:197], v[40:43]
	v_mfma_f32_16x16x32_bf16 v[32:35], v[150:153], v[202:205], v[32:35]
	v_mfma_f32_16x16x32_bf16 v[24:27], v[158:161], v[202:205], v[24:27]
	v_mfma_f32_16x16x32_bf16 v[16:19], v[150:153], v[210:213], v[16:19]
	v_mfma_f32_16x16x32_bf16 v[8:11], v[158:161], v[210:213], v[8:11]
	v_mfma_f32_16x16x32_bf16 v[52:55], v[162:165], v[178:181], v[52:55]
	v_mfma_f32_16x16x32_bf16 v[44:47], v[170:173], v[178:181], v[44:47]
	v_mfma_f32_16x16x32_bf16 v[36:39], v[162:165], v[186:189], v[36:39]
	v_mfma_f32_16x16x32_bf16 v[28:31], v[170:173], v[186:189], v[28:31]
	v_mfma_f32_16x16x32_bf16 v[20:23], v[162:165], v[198:201], v[20:23]
	v_mfma_f32_16x16x32_bf16 v[12:15], v[170:173], v[198:201], v[12:15]
	v_mfma_f32_16x16x32_bf16 v[4:7], v[162:165], v[206:209], v[4:7]
	v_mfma_f32_16x16x32_bf16 v[0:3], v[170:173], v[206:209], v[0:3]
	v_mfma_f32_16x16x32_bf16 v[52:55], v[166:169], v[182:185], v[52:55]
	v_mfma_f32_16x16x32_bf16 v[44:47], v[174:177], v[182:185], v[44:47]
	v_mfma_f32_16x16x32_bf16 v[36:39], v[166:169], v[194:197], v[36:39]
	v_mfma_f32_16x16x32_bf16 v[28:31], v[174:177], v[194:197], v[28:31]
	v_mfma_f32_16x16x32_bf16 v[20:23], v[166:169], v[202:205], v[20:23]
	v_mfma_f32_16x16x32_bf16 v[12:15], v[174:177], v[202:205], v[12:15]
	v_mfma_f32_16x16x32_bf16 v[4:7], v[166:169], v[210:213], v[4:7]
	v_mfma_f32_16x16x32_bf16 v[0:3], v[174:177], v[210:213], v[0:3]
	s_setprio 0
	s_barrier
	s_add_i32 s75, s75, 2
	s_add_u32 s54, s54, 0x100
	s_addc_u32 s55, s55, 0
	s_add_u32 s73, s73, 0x100
	s_addc_u32 s74, s74, 0
	s_cmp_gt_u32 s75, 29
	s_cbranch_scc0 .LBB0_1060
	s_and_b64 vcc, exec, s[42:43]
	s_cbranch_vccz .LBB0_1063
	s_barrier

; #define PG8_STAGE(bufoff, gbase, voff) do { _Pragma("unroll") for (int _i = 0; _i < 2; ++_i) \
;         __builtin_amdgcn_global_load_lds((const unsigned*)((const char*)(gbase) + (voff)[_i]), (PG8_LAS unsigned*)(lds + (bufoff) + ldsw + _i * 8192), 16, 0, 0); } while (0)
; #define PG8_LDA(dst, b, h) do { _Pragma("unroll") for (int m = 0; m < 4; ++m) _Pragma("unroll") for (int k = 0; k < 2; ++k) dst[m][k] = *(const PG8_LAS bf16x8*)(lds + PG8_SA(b, h) + aoff + m * 2048 + k * 1024); } while (0)
; #define PG8_LDB(dst, b, h) do { _Pragma("unroll") for (int n = 0; n < 2; ++n) _Pragma("unroll") for (int k = 0; k < 2; ++k) dst[n][k] = *(const PG8_LAS bf16x8*)(lds + PG8_SB(b, h) + boff + n * 2048 + k * 1024); } while (0)
; #define PG8_MMA(ai, bj, At, Bt) do { __builtin_amdgcn_s_setprio(1); _Pragma("unroll") for (int m = 0; m < 4; ++m) _Pragma("unroll") for (int n = 0; n < 2; ++n) _Pragma("unroll") for (int k = 0; k < 2; ++k) \
;         acc[ai][bj][m][n] = __builtin_amdgcn_mfma_f32_16x16x32_bf16(Bt[n][k], At[m][k], acc[ai][bj][m][n], 0, 0, 0); __builtin_amdgcn_s_setprio(0); } while (0)
; #define PG8_WAIT_V(n) asm volatile("s_waitcnt vmcnt(" #n ")" ::: "memory")
; #define PG8_WAIT_L(n) asm volatile("s_waitcnt lgkmcnt(" #n ")" ::: "memory")
; #define PG8_BAR __builtin_amdgcn_s_barrier()
; template <class Epi, class Sched, bool ALIGN_EPI = false, bool SP2 = false>
; __device__ __forceinline__ void gemm_phase(PG8_LAS unsigned char* lds, const Gemm g, const Sched& S, const Epi& E, const int tid_in) {
;     ...
;         const char* nA = has_next ? (const char*)g.A + (size_t)nxt.pm * tstepA : cA; const char* nB = has_next ? (const char*)g.Bt + (size_t)nxt.pn * tstepB : cB;
;         for (int t = 0; t < nt; t += 2) {
;             const bool last = (t == nt - 2);
;             const char* a1 = cA + (size_t)(t + 1) * kstep;
;             const char* a2 = last ? nA : cA + (size_t)(t + 2) * kstep; const char* b2 = last ? nB : cB + (size_t)(t + 2) * kstep;
;             const char* a3 = a2 + kstep; const char* b3 = b2 + kstep;
;             if (last && has_next) S.a_ready(nxt);
;             if constexpr (SP2) {
;             PG8_LDB(B0, 0, 0); PG8_LDB(B1, 0, 1); PG8_SCHED; PG8_LDA(At, 0, 0); PG8_STAGE(PG8_SA(1, 1), a1 + hstepA, voffA);
;             PG8_WAIT_V(8); PG8_WAIT_L(0); PG8_BAR; PG8_MMA(0, 0, At, B0); PG8_MMA(0, 1, At, B1); PG8_BAR; PG8_SCHED;
.LBB0_1220:
	s_ashr_i32 s41, s40, 31
	s_lshl_b64 s[12:13], s[40:41], 21
	s_add_u32 s42, s15, s12
	s_addc_u32 s43, s54, s13
	s_and_b64 s[12:13], s[34:35], exec
	s_cselect_b32 s41, s43, s49
	s_cselect_b32 s66, s42, s48
	s_ashr_i32 s39, s38, 31
	s_lshl_b64 s[12:13], s[38:39], 21
	s_add_u32 s44, s55, s12
	s_addc_u32 s45, s56, s13
	s_and_b64 s[12:13], s[34:35], exec
	s_cselect_b32 s39, s45, s51
	s_cselect_b32 s67, s44, s50
	s_add_u32 s48, s48, 0x100080
	s_addc_u32 s49, s49, 0
	s_add_u32 s68, s50, 0x100
	s_addc_u32 s69, s51, 0
	s_mov_b32 s70, -2
	s_add_u32 s12, s48, 0xfff00080
	s_addc_u32 s13, s49, -1
	s_add_i32 s71, 0, 0x10000
	s_cmp_eq_u32 s70, 60
	s_cselect_b32 s53, s41, s13
	s_cselect_b32 s52, s66, s12
	s_cselect_b32 s51, s39, s69
	s_cselect_b32 s50, s67, s68
	s_add_i32 s72, 0, 0x14000
	v_add_u32_e32 v140, s71, v224
	v_add_u32_e32 v156, s72, v224
	ds_read_b128 v[128:131], v140
	ds_read_b128 v[132:135], v140 offset:1024
	ds_read_b128 v[136:139], v140 offset:2048
	ds_read_b128 v[140:143], v140 offset:3072
	ds_read_b128 v[144:147], v156
	ds_read_b128 v[148:151], v156 offset:1024
	ds_read_b128 v[152:155], v156 offset:2048
	ds_read_b128 v[156:159], v156 offset:3072
	v_lshl_add_u64 v[204:205], s[48:49], 0, v[190:191]
	s_add_i32 m0, s59, 0xc000
	ds_read_b128 v[160:163], v226
	ds_read_b128 v[164:167], v226 offset:1024
	ds_read_b128 v[168:171], v226 offset:2048
	ds_read_b128 v[172:175], v226 offset:3072
	ds_read_b128 v[176:179], v226 offset:4096
	ds_read_b128 v[180:183], v226 offset:5120
	ds_read_b128 v[194:197], v226 offset:6144
	ds_read_b128 v[200:203], v226 offset:7168
	global_load_lds_dwordx4 v[204:205], off
	v_lshl_add_u64 v[204:205], s[48:49], 0, v[198:199]
	s_add_i32 m0, s59, 0xe000
	s_nop 0
	global_load_lds_dwordx4 v[204:205], off
	s_waitcnt vmcnt(8)
	s_waitcnt lgkmcnt(0)
	s_barrier
	s_setprio 1
	s_waitcnt lgkmcnt(0)
	v_mfma_f32_16x16x32_bf16 v[124:127], v[128:131], v[160:163], 0
	v_mfma_f32_16x16x32_bf16 v[120:123], v[136:139], v[160:163], 0
	v_mfma_f32_16x16x32_bf16 v[108:111], v[128:131], v[168:171], 0
	v_mfma_f32_16x16x32_bf16 v[104:107], v[136:139], v[168:171], 0
	v_mfma_f32_16x16x32_bf16 v[96:99], v[128:131], v[176:179], 0
	v_mfma_f32_16x16x32_bf16 v[88:91], v[136:139], v[176:179], 0
	v_mfma_f32_16x16x32_bf16 v[80:83], v[128:131], v[194:197], 0
	v_mfma_f32_16x16x32_bf16 v[72:75], v[136:139], v[194:197], 0
	v_mfma_f32_16x16x32_bf16 v[124:127], v[132:135], v[164:167], v[124:127]
	v_mfma_f32_16x16x32_bf16 v[120:123], v[140:143], v[164:167], v[120:123]
	v_mfma_f32_16x16x32_bf16 v[108:111], v[132:135], v[172:175], v[108:111]
	v_mfma_f32_16x16x32_bf16 v[104:107], v[140:143], v[172:175], v[104:107]
	v_mfma_f32_16x16x32_bf16 v[96:99], v[132:135], v[180:183], v[96:99]
	v_mfma_f32_16x16x32_bf16 v[88:91], v[140:143], v[180:183], v[88:91]
	v_mfma_f32_16x16x32_bf16 v[80:83], v[132:135], v[200:203], v[80:83]
	v_mfma_f32_16x16x32_bf16 v[72:75], v[140:143], v[200:203], v[72:75]
	s_setprio 0
	s_setprio 1
	v_mfma_f32_16x16x32_bf16 v[116:119], v[144:147], v[160:163], 0
	v_mfma_f32_16x16x32_bf16 v[112:115], v[152:155], v[160:163], 0
	v_mfma_f32_16x16x32_bf16 v[100:103], v[144:147], v[168:171], 0
	v_mfma_f32_16x16x32_bf16 v[92:95], v[152:155], v[168:171], 0
	v_mfma_f32_16x16x32_bf16 v[84:87], v[144:147], v[176:179], 0
	v_mfma_f32_16x16x32_bf16 v[76:79], v[152:155], v[176:179], 0
	v_mfma_f32_16x16x32_bf16 v[68:71], v[144:147], v[194:197], 0
	v_mfma_f32_16x16x32_bf16 v[64:67], v[152:155], v[194:197], 0
	v_mfma_f32_16x16x32_bf16 v[116:119], v[148:151], v[164:167], v[116:119]
	v_mfma_f32_16x16x32_bf16 v[112:115], v[156:159], v[164:167], v[112:115]
	v_mfma_f32_16x16x32_bf16 v[100:103], v[148:151], v[172:175], v[100:103]
	v_mfma_f32_16x16x32_bf16 v[92:95], v[156:159], v[172:175], v[92:95]
	v_mfma_f32_16x16x32_bf16 v[84:87], v[148:151], v[180:183], v[84:87]
	v_mfma_f32_16x16x32_bf16 v[76:79], v[156:159], v[180:183], v[76:79]
	v_mfma_f32_16x16x32_bf16 v[68:71], v[148:151], v[200:203], v[68:71]
	v_mfma_f32_16x16x32_bf16 v[64:67], v[156:159], v[200:203], v[64:67]
	s_setprio 0
	s_barrier
	s_add_i32 s12, s71, s58
	v_lshl_add_u64 v[204:205], s[50:51], 0, v[192:193]
	s_mov_b32 m0, s12
	ds_read_b128 v[160:163], v226 offset:16384
	ds_read_b128 v[164:167], v226 offset:17408
	ds_read_b128 v[168:171], v226 offset:18432
	ds_read_b128 v[172:175], v226 offset:19456
	ds_read_b128 v[176:179], v226 offset:20480
	ds_read_b128 v[180:183], v226 offset:21504
	ds_read_b128 v[194:197], v226 offset:22528
	ds_read_b128 v[200:203], v226 offset:23552
	global_load_lds_dwordx4 v[204:205], off
	s_add_i32 m0, s12, 0x2000
	s_add_u32 s12, s50, 0x100000
	v_lshl_add_u64 v[206:207], s[50:51], 0, v[188:189]
	s_addc_u32 s13, s51, 0
	s_add_i32 s71, s72, s58
	global_load_lds_dwordx4 v[206:207], off
	v_lshl_add_u64 v[208:209], s[12:13], 0, v[192:193]
	s_mov_b32 m0, s71
	v_lshl_add_u64 v[210:211], s[52:53], 0, v[186:187]
	global_load_lds_dwordx4 v[208:209], off
	v_lshl_add_u64 v[208:209], s[12:13], 0, v[188:189]
	s_add_i32 m0, s71, 0x2000
	s_nop 0
	global_load_lds_dwordx4 v[208:209], off
	v_lshl_add_u64 v[208:209], s[52:53], 0, v[184:185]
	s_mov_b32 m0, s59
	s_nop 0
	global_load_lds_dwordx4 v[208:209], off
	s_mov_b32 m0, s60
	s_nop 0
	global_load_lds_dwordx4 v[210:211], off
	s_waitcnt vmcnt(8)
	s_waitcnt lgkmcnt(0)
	s_barrier
; #define PG8_STAGE(bufoff, gbase, voff) do { _Pragma("unroll") for (int _i = 0; _i < 2; ++_i) \
;         __builtin_amdgcn_global_load_lds((const unsigned*)((const char*)(gbase) + (voff)[_i]), (PG8_LAS unsigned*)(lds + (bufoff) + ldsw + _i * 8192), 16, 0, 0); } while (0)
; #define PG8_LDA(dst, b, h) do { _Pragma("unroll") for (int m = 0; m < 4; ++m) _Pragma("unroll") for (int k = 0; k < 2; ++k) dst[m][k] = *(const PG8_LAS bf16x8*)(lds + PG8_SA(b, h) + aoff + m * 2048 + k * 1024); } while (0)
; #define PG8_LDB(dst, b, h) do { _Pragma("unroll") for (int n = 0; n < 2; ++n) _Pragma("unroll") for (int k = 0; k < 2; ++k) dst[n][k] = *(const PG8_LAS bf16x8*)(lds + PG8_SB(b, h) + boff + n * 2048 + k * 1024); } while (0)
; #define PG8_MMA(ai, bj, At, Bt) do { __builtin_amdgcn_s_setprio(1); _Pragma("unroll") for (int m = 0; m < 4; ++m) _Pragma("unroll") for (int n = 0; n < 2; ++n) _Pragma("unroll") for (int k = 0; k < 2; ++k) \
;         acc[ai][bj][m][n] = __builtin_amdgcn_mfma_f32_16x16x32_bf16(Bt[n][k], At[m][k], acc[ai][bj][m][n], 0, 0, 0); __builtin_amdgcn_s_setprio(0); } while (0)
; #define PG8_WAIT_V(n) asm volatile("s_waitcnt vmcnt(" #n ")" ::: "memory")
; #define PG8_WAIT_L(n) asm volatile("s_waitcnt lgkmcnt(" #n ")" ::: "memory")
; #define PG8_BAR __builtin_amdgcn_s_barrier()
; #define PG8_SCHED __builtin_amdgcn_sched_barrier(0)
; template <class Epi, class Sched, bool ALIGN_EPI = false, bool SP2 = false>
; __device__ __forceinline__ void gemm_phase(PG8_LAS unsigned char* lds, const Gemm g, const Sched& S, const Epi& E, const int tid_in) {
;     ...
;             PG8_WAIT_V(8); PG8_WAIT_L(0); PG8_BAR; PG8_MMA(0, 0, At, B0); PG8_MMA(0, 1, At, B1); PG8_BAR; PG8_SCHED;
;             PG8_LDA(At, 0, 1); PG8_STAGE(PG8_SB(0, 0), b2, voffB); PG8_STAGE(PG8_SB(0, 1), b2 + hstepB, voffB); PG8_STAGE(PG8_SA(0, 0), a2, voffA);
;             PG8_WAIT_V(8); PG8_WAIT_L(0); PG8_BAR; PG8_MMA(1, 0, At, B0); PG8_MMA(1, 1, At, B1); PG8_BAR; PG8_SCHED;
;             PG8_LDB(B0, 1, 0); PG8_LDB(B1, 1, 1); PG8_SCHED; PG8_LDA(At, 1, 0); PG8_STAGE(PG8_SA(0, 1), a2 + hstepA, voffA);
;             PG8_WAIT_V(8); PG8_WAIT_L(0); PG8_BAR; PG8_MMA(0, 0, At, B0); PG8_MMA(0, 1, At, B1); PG8_BAR; PG8_SCHED;
	s_setprio 1
	s_waitcnt lgkmcnt(0)
	v_mfma_f32_16x16x32_bf16 v[60:63], v[128:131], v[160:163], 0
	v_mfma_f32_16x16x32_bf16 v[56:59], v[136:139], v[160:163], 0
	v_mfma_f32_16x16x32_bf16 v[48:51], v[128:131], v[168:171], 0
	v_mfma_f32_16x16x32_bf16 v[40:43], v[136:139], v[168:171], 0
	v_mfma_f32_16x16x32_bf16 v[32:35], v[128:131], v[176:179], 0
	v_mfma_f32_16x16x32_bf16 v[24:27], v[136:139], v[176:179], 0
	v_mfma_f32_16x16x32_bf16 v[16:19], v[128:131], v[194:197], 0
	v_mfma_f32_16x16x32_bf16 v[8:11], v[136:139], v[194:197], 0
	v_mfma_f32_16x16x32_bf16 v[60:63], v[132:135], v[164:167], v[60:63]
	v_mfma_f32_16x16x32_bf16 v[56:59], v[140:143], v[164:167], v[56:59]
	v_mfma_f32_16x16x32_bf16 v[48:51], v[132:135], v[172:175], v[48:51]
	v_mfma_f32_16x16x32_bf16 v[40:43], v[140:143], v[172:175], v[40:43]
	v_mfma_f32_16x16x32_bf16 v[32:35], v[132:135], v[180:183], v[32:35]
	v_mfma_f32_16x16x32_bf16 v[24:27], v[140:143], v[180:183], v[24:27]
	v_mfma_f32_16x16x32_bf16 v[16:19], v[132:135], v[200:203], v[16:19]
	v_mfma_f32_16x16x32_bf16 v[8:11], v[140:143], v[200:203], v[8:11]
	s_setprio 0
	s_setprio 1
	v_mfma_f32_16x16x32_bf16 v[52:55], v[144:147], v[160:163], 0
	v_mfma_f32_16x16x32_bf16 v[44:47], v[152:155], v[160:163], 0
	v_mfma_f32_16x16x32_bf16 v[36:39], v[144:147], v[168:171], 0
	v_mfma_f32_16x16x32_bf16 v[28:31], v[152:155], v[168:171], 0
	v_mfma_f32_16x16x32_bf16 v[20:23], v[144:147], v[176:179], 0
	v_mfma_f32_16x16x32_bf16 v[12:15], v[152:155], v[176:179], 0
	v_mfma_f32_16x16x32_bf16 v[4:7], v[144:147], v[194:197], 0
	v_mfma_f32_16x16x32_bf16 v[0:3], v[152:155], v[194:197], 0
	v_mfma_f32_16x16x32_bf16 v[52:55], v[148:151], v[164:167], v[52:55]
	v_mfma_f32_16x16x32_bf16 v[44:47], v[156:159], v[164:167], v[44:47]
	v_mfma_f32_16x16x32_bf16 v[36:39], v[148:151], v[172:175], v[36:39]
	v_mfma_f32_16x16x32_bf16 v[28:31], v[156:159], v[172:175], v[28:31]
	v_mfma_f32_16x16x32_bf16 v[20:23], v[148:151], v[180:183], v[20:23]
	v_mfma_f32_16x16x32_bf16 v[12:15], v[156:159], v[180:183], v[12:15]
	v_mfma_f32_16x16x32_bf16 v[4:7], v[148:151], v[200:203], v[4:7]
	v_mfma_f32_16x16x32_bf16 v[0:3], v[156:159], v[200:203], v[0:3]
	s_setprio 0
	s_barrier
	s_add_i32 s71, 0, 0x18000
	s_add_i32 s72, 0, 0x1c000
	v_add_u32_e32 v140, s71, v224
	v_add_u32_e32 v156, s72, v224
	ds_read_b128 v[128:131], v140
	ds_read_b128 v[132:135], v140 offset:1024
	ds_read_b128 v[136:139], v140 offset:2048
	ds_read_b128 v[140:143], v140 offset:3072
	ds_read_b128 v[144:147], v156
	ds_read_b128 v[148:151], v156 offset:1024
	ds_read_b128 v[152:155], v156 offset:2048
	ds_read_b128 v[156:159], v156 offset:3072
	s_add_u32 s12, s52, 0x100000
	s_addc_u32 s13, s53, 0
	s_mov_b32 m0, s61
	v_lshl_add_u64 v[212:213], s[12:13], 0, v[184:185]
	ds_read_b128 v[160:163], v226 offset:32768
	ds_read_b128 v[164:167], v226 offset:33792
	ds_read_b128 v[168:171], v226 offset:34816
	ds_read_b128 v[172:175], v226 offset:35840
	ds_read_b128 v[176:179], v226 offset:36864
	ds_read_b128 v[180:183], v226 offset:37888
	ds_read_b128 v[194:197], v226 offset:38912
	ds_read_b128 v[200:203], v226 offset:39936
	global_load_lds_dwordx4 v[212:213], off
	v_lshl_add_u64 v[212:213], s[12:13], 0, v[186:187]
	s_mov_b32 m0, s62
	s_nop 0
	global_load_lds_dwordx4 v[212:213], off
	s_waitcnt vmcnt(8)
	s_waitcnt lgkmcnt(0)
	s_barrier
	s_setprio 1
	s_waitcnt lgkmcnt(0)
	v_mfma_f32_16x16x32_bf16 v[124:127], v[128:131], v[160:163], v[124:127]
	v_mfma_f32_16x16x32_bf16 v[120:123], v[136:139], v[160:163], v[120:123]
	v_mfma_f32_16x16x32_bf16 v[108:111], v[128:131], v[168:171], v[108:111]
	v_mfma_f32_16x16x32_bf16 v[104:107], v[136:139], v[168:171], v[104:107]
	v_mfma_f32_16x16x32_bf16 v[96:99], v[128:131], v[176:179], v[96:99]
	v_mfma_f32_16x16x32_bf16 v[88:91], v[136:139], v[176:179], v[88:91]
	v_mfma_f32_16x16x32_bf16 v[80:83], v[128:131], v[194:197], v[80:83]
	v_mfma_f32_16x16x32_bf16 v[72:75], v[136:139], v[194:197], v[72:75]
	v_mfma_f32_16x16x32_bf16 v[124:127], v[132:135], v[164:167], v[124:127]
	v_mfma_f32_16x16x32_bf16 v[120:123], v[140:143], v[164:167], v[120:123]
	v_mfma_f32_16x16x32_bf16 v[108:111], v[132:135], v[172:175], v[108:111]
	v_mfma_f32_16x16x32_bf16 v[104:107], v[140:143], v[172:175], v[104:107]
	v_mfma_f32_16x16x32_bf16 v[96:99], v[132:135], v[180:183], v[96:99]
	v_mfma_f32_16x16x32_bf16 v[88:91], v[140:143], v[180:183], v[88:91]
	v_mfma_f32_16x16x32_bf16 v[80:83], v[132:135], v[200:203], v[80:83]
	v_mfma_f32_16x16x32_bf16 v[72:75], v[140:143], v[200:203], v[72:75]
	s_setprio 0
	s_setprio 1
	v_mfma_f32_16x16x32_bf16 v[116:119], v[144:147], v[160:163], v[116:119]
	v_mfma_f32_16x16x32_bf16 v[112:115], v[152:155], v[160:163], v[112:115]
	v_mfma_f32_16x16x32_bf16 v[100:103], v[144:147], v[168:171], v[100:103]
	v_mfma_f32_16x16x32_bf16 v[92:95], v[152:155], v[168:171], v[92:95]
	v_mfma_f32_16x16x32_bf16 v[84:87], v[144:147], v[176:179], v[84:87]
	v_mfma_f32_16x16x32_bf16 v[76:79], v[152:155], v[176:179], v[76:79]
	v_mfma_f32_16x16x32_bf16 v[68:71], v[144:147], v[194:197], v[68:71]
	v_mfma_f32_16x16x32_bf16 v[64:67], v[152:155], v[194:197], v[64:67]
	v_mfma_f32_16x16x32_bf16 v[116:119], v[148:151], v[164:167], v[116:119]
	v_mfma_f32_16x16x32_bf16 v[112:115], v[156:159], v[164:167], v[112:115]
	v_mfma_f32_16x16x32_bf16 v[100:103], v[148:151], v[172:175], v[100:103]
	v_mfma_f32_16x16x32_bf16 v[92:95], v[156:159], v[172:175], v[92:95]
	v_mfma_f32_16x16x32_bf16 v[84:87], v[148:151], v[180:183], v[84:87]
	v_mfma_f32_16x16x32_bf16 v[76:79], v[156:159], v[180:183], v[76:79]
	v_mfma_f32_16x16x32_bf16 v[68:71], v[148:151], v[200:203], v[68:71]
	v_mfma_f32_16x16x32_bf16 v[64:67], v[156:159], v[200:203], v[64:67]
	s_setprio 0
	s_barrier
; #define PG8_STAGE(bufoff, gbase, voff) do { _Pragma("unroll") for (int _i = 0; _i < 2; ++_i) \
;         __builtin_amdgcn_global_load_lds((const unsigned*)((const char*)(gbase) + (voff)[_i]), (PG8_LAS unsigned*)(lds + (bufoff) + ldsw + _i * 8192), 16, 0, 0); } while (0)
; #define PG8_LDA(dst, b, h) do { _Pragma("unroll") for (int m = 0; m < 4; ++m) _Pragma("unroll") for (int k = 0; k < 2; ++k) dst[m][k] = *(const PG8_LAS bf16x8*)(lds + PG8_SA(b, h) + aoff + m * 2048 + k * 1024); } while (0)
; #define PG8_LDB(dst, b, h) do { _Pragma("unroll") for (int n = 0; n < 2; ++n) _Pragma("unroll") for (int k = 0; k < 2; ++k) dst[n][k] = *(const PG8_LAS bf16x8*)(lds + PG8_SB(b, h) + boff + n * 2048 + k * 1024); } while (0)
; #define PG8_MMA(ai, bj, At, Bt) do { __builtin_amdgcn_s_setprio(1); _Pragma("unroll") for (int m = 0; m < 4; ++m) _Pragma("unroll") for (int n = 0; n < 2; ++n) _Pragma("unroll") for (int k = 0; k < 2; ++k) \
;         acc[ai][bj][m][n] = __builtin_amdgcn_mfma_f32_16x16x32_bf16(Bt[n][k], At[m][k], acc[ai][bj][m][n], 0, 0, 0); __builtin_amdgcn_s_setprio(0); } while (0)
; #define PG8_BAR __builtin_amdgcn_s_barrier()
; template <class Epi, class Sched, bool ALIGN_EPI = false, bool SP2 = false>
; __device__ __forceinline__ void gemm_phase(PG8_LAS unsigned char* lds, const Gemm g, const Sched& S, const Epi& E, const int tid_in) {
;     ...
;             PG8_LDB(B0, 0, 0); PG8_LDB(B1, 0, 1); PG8_SCHED; PG8_LDA(At, 0, 0); PG8_STAGE(PG8_SA(1, 1), a1 + hstepA, voffA);
;             PG8_WAIT_V(8); PG8_WAIT_L(0); PG8_BAR; PG8_MMA(0, 0, At, B0); PG8_MMA(0, 1, At, B1); PG8_BAR; PG8_SCHED;
;             PG8_LDA(At, 0, 1); PG8_STAGE(PG8_SB(0, 0), b2, voffB); PG8_STAGE(PG8_SB(0, 1), b2 + hstepB, voffB); PG8_STAGE(PG8_SA(0, 0), a2, voffA);
;             PG8_WAIT_V(8); PG8_WAIT_L(0); PG8_BAR; PG8_MMA(1, 0, At, B0); PG8_MMA(1, 1, At, B1); PG8_BAR; PG8_SCHED;
;             PG8_LDB(B0, 1, 0); PG8_LDB(B1, 1, 1); PG8_SCHED; PG8_LDA(At, 1, 0); PG8_STAGE(PG8_SA(0, 1), a2 + hstepA, voffA);
;             PG8_WAIT_V(8); PG8_WAIT_L(0); PG8_BAR; PG8_MMA(0, 0, At, B0); PG8_MMA(0, 1, At, B1); PG8_BAR; PG8_SCHED;
;             PG8_LDA(At, 1, 1); PG8_STAGE(PG8_SB(1, 0), b3, voffB); PG8_STAGE(PG8_SB(1, 1), b3 + hstepB, voffB); PG8_STAGE(PG8_SA(1, 0), a3, voffA);
;             PG8_WAIT_V(8); PG8_WAIT_L(0); PG8_BAR; PG8_MMA(1, 0, At, B0); PG8_MMA(1, 1, At, B1); PG8_BAR; PG8_SCHED;
	s_add_i32 s12, s71, s58
	v_lshl_add_u64 v[204:205], v[204:205], 0, s[26:27]
	s_mov_b32 m0, s12
	ds_read_b128 v[160:163], v226 offset:49152
	ds_read_b128 v[164:167], v226 offset:50176
	ds_read_b128 v[168:171], v226 offset:51200
	ds_read_b128 v[172:175], v226 offset:52224
	ds_read_b128 v[176:179], v226 offset:53248
	ds_read_b128 v[180:183], v226 offset:54272
	ds_read_b128 v[194:197], v226 offset:55296
	ds_read_b128 v[200:203], v226 offset:56320
	global_load_lds_dwordx4 v[204:205], off
	s_add_i32 m0, s12, 0x2000
	s_add_u32 s12, s50, 0x100080
	v_lshl_add_u64 v[204:205], v[206:207], 0, s[26:27]
	s_addc_u32 s13, s51, 0
	s_add_i32 s50, s72, s58
	global_load_lds_dwordx4 v[204:205], off
	v_lshl_add_u64 v[204:205], s[12:13], 0, v[192:193]
	s_mov_b32 m0, s50
	s_nop 0
	global_load_lds_dwordx4 v[204:205], off
	v_lshl_add_u64 v[204:205], s[12:13], 0, v[188:189]
	s_add_i32 m0, s50, 0x2000
	s_nop 0
	global_load_lds_dwordx4 v[204:205], off
	v_lshl_add_u64 v[204:205], v[208:209], 0, s[26:27]
	s_mov_b32 m0, s64
	s_nop 0
	global_load_lds_dwordx4 v[204:205], off
	v_lshl_add_u64 v[204:205], v[210:211], 0, s[26:27]
	s_mov_b32 m0, s65
	s_nop 0
	global_load_lds_dwordx4 v[204:205], off
	s_waitcnt vmcnt(8)
	s_waitcnt lgkmcnt(0)
	s_barrier
	s_setprio 1
	s_waitcnt lgkmcnt(0)
	v_mfma_f32_16x16x32_bf16 v[60:63], v[128:131], v[160:163], v[60:63]
	v_mfma_f32_16x16x32_bf16 v[56:59], v[136:139], v[160:163], v[56:59]
	v_mfma_f32_16x16x32_bf16 v[48:51], v[128:131], v[168:171], v[48:51]
	v_mfma_f32_16x16x32_bf16 v[40:43], v[136:139], v[168:171], v[40:43]
	v_mfma_f32_16x16x32_bf16 v[32:35], v[128:131], v[176:179], v[32:35]
	v_mfma_f32_16x16x32_bf16 v[24:27], v[136:139], v[176:179], v[24:27]
	v_mfma_f32_16x16x32_bf16 v[16:19], v[128:131], v[194:197], v[16:19]
	v_mfma_f32_16x16x32_bf16 v[8:11], v[136:139], v[194:197], v[8:11]
	v_mfma_f32_16x16x32_bf16 v[60:63], v[132:135], v[164:167], v[60:63]
	v_mfma_f32_16x16x32_bf16 v[56:59], v[140:143], v[164:167], v[56:59]
	v_mfma_f32_16x16x32_bf16 v[48:51], v[132:135], v[172:175], v[48:51]
	v_mfma_f32_16x16x32_bf16 v[40:43], v[140:143], v[172:175], v[40:43]
	v_mfma_f32_16x16x32_bf16 v[32:35], v[132:135], v[180:183], v[32:35]
	v_mfma_f32_16x16x32_bf16 v[24:27], v[140:143], v[180:183], v[24:27]
	v_mfma_f32_16x16x32_bf16 v[16:19], v[132:135], v[200:203], v[16:19]
	v_mfma_f32_16x16x32_bf16 v[8:11], v[140:143], v[200:203], v[8:11]
	s_setprio 0
	s_setprio 1
	v_mfma_f32_16x16x32_bf16 v[52:55], v[144:147], v[160:163], v[52:55]
	v_mfma_f32_16x16x32_bf16 v[44:47], v[152:155], v[160:163], v[44:47]
	v_mfma_f32_16x16x32_bf16 v[36:39], v[144:147], v[168:171], v[36:39]
	v_mfma_f32_16x16x32_bf16 v[28:31], v[152:155], v[168:171], v[28:31]
	v_mfma_f32_16x16x32_bf16 v[20:23], v[144:147], v[176:179], v[20:23]
	v_mfma_f32_16x16x32_bf16 v[12:15], v[152:155], v[176:179], v[12:15]
	v_mfma_f32_16x16x32_bf16 v[4:7], v[144:147], v[194:197], v[4:7]
	v_mfma_f32_16x16x32_bf16 v[0:3], v[152:155], v[194:197], v[0:3]
	v_mfma_f32_16x16x32_bf16 v[52:55], v[148:151], v[164:167], v[52:55]
	v_mfma_f32_16x16x32_bf16 v[44:47], v[156:159], v[164:167], v[44:47]
	v_mfma_f32_16x16x32_bf16 v[36:39], v[148:151], v[172:175], v[36:39]
	v_mfma_f32_16x16x32_bf16 v[28:31], v[156:159], v[172:175], v[28:31]
	v_mfma_f32_16x16x32_bf16 v[20:23], v[148:151], v[180:183], v[20:23]
	v_mfma_f32_16x16x32_bf16 v[12:15], v[156:159], v[180:183], v[12:15]
	v_mfma_f32_16x16x32_bf16 v[4:7], v[148:151], v[200:203], v[4:7]
	v_mfma_f32_16x16x32_bf16 v[0:3], v[156:159], v[200:203], v[0:3]
	s_setprio 0
	s_barrier
	s_add_i32 s70, s70, 2
	s_add_u32 s48, s48, 0x100
	s_addc_u32 s49, s49, 0
	s_add_u32 s68, s68, 0x100
	s_addc_u32 s69, s69, 0
	s_cmp_gt_u32 s70, 61
	.p2align 6
.LBB0_1221:
	s_add_u32 s12, s48, 0xfff00080
	s_addc_u32 s13, s49, -1
	s_add_i32 s71, 0, 0x10000
	s_cmp_eq_u32 s70, 60
	s_cselect_b32 s53, s41, s13
	s_cselect_b32 s52, s66, s12
	s_cselect_b32 s51, s39, s69
	s_cselect_b32 s50, s67, s68
	s_add_i32 s72, 0, 0x14000
	v_add_u32_e32 v140, s71, v224
	v_add_u32_e32 v156, s72, v224
	ds_read_b128 v[128:131], v140
	ds_read_b128 v[132:135], v140 offset:1024
	ds_read_b128 v[136:139], v140 offset:2048
	ds_read_b128 v[140:143], v140 offset:3072
	ds_read_b128 v[144:147], v156
	ds_read_b128 v[148:151], v156 offset:1024
	ds_read_b128 v[152:155], v156 offset:2048
	ds_read_b128 v[156:159], v156 offset:3072
	v_lshl_add_u64 v[204:205], s[48:49], 0, v[190:191]
	s_add_i32 m0, s59, 0xc000
	ds_read_b128 v[160:163], v226
	ds_read_b128 v[164:167], v226 offset:1024
	ds_read_b128 v[168:171], v226 offset:2048
	ds_read_b128 v[172:175], v226 offset:3072
	ds_read_b128 v[176:179], v226 offset:4096
	ds_read_b128 v[180:183], v226 offset:5120
	ds_read_b128 v[194:197], v226 offset:6144
	ds_read_b128 v[200:203], v226 offset:7168
	global_load_lds_dwordx4 v[204:205], off
	v_lshl_add_u64 v[204:205], s[48:49], 0, v[198:199]
	s_add_i32 m0, s59, 0xe000
	s_nop 0
	global_load_lds_dwordx4 v[204:205], off
	s_waitcnt vmcnt(8)
	s_waitcnt lgkmcnt(0)
	s_barrier
; #define PG8_STAGE(bufoff, gbase, voff) do { _Pragma("unroll") for (int _i = 0; _i < 2; ++_i) \
;         __builtin_amdgcn_global_load_lds((const unsigned*)((const char*)(gbase) + (voff)[_i]), (PG8_LAS unsigned*)(lds + (bufoff) + ldsw + _i * 8192), 16, 0, 0); } while (0)
; #define PG8_LDA(dst, b, h) do { _Pragma("unroll") for (int m = 0; m < 4; ++m) _Pragma("unroll") for (int k = 0; k < 2; ++k) dst[m][k] = *(const PG8_LAS bf16x8*)(lds + PG8_SA(b, h) + aoff + m * 2048 + k * 1024); } while (0)
; #define PG8_MMA(ai, bj, At, Bt) do { __builtin_amdgcn_s_setprio(1); _Pragma("unroll") for (int m = 0; m < 4; ++m) _Pragma("unroll") for (int n = 0; n < 2; ++n) _Pragma("unroll") for (int k = 0; k < 2; ++k) \
;         acc[ai][bj][m][n] = __builtin_amdgcn_mfma_f32_16x16x32_bf16(Bt[n][k], At[m][k], acc[ai][bj][m][n], 0, 0, 0); __builtin_amdgcn_s_setprio(0); } while (0)
; #define PG8_WAIT_V(n) asm volatile("s_waitcnt vmcnt(" #n ")" ::: "memory")
; #define PG8_WAIT_L(n) asm volatile("s_waitcnt lgkmcnt(" #n ")" ::: "memory")
; #define PG8_BAR __builtin_amdgcn_s_barrier()
; #define PG8_SCHED __builtin_amdgcn_sched_barrier(0)
; template <class Epi, class Sched, bool ALIGN_EPI = false, bool SP2 = false>
; __device__ __forceinline__ void gemm_phase(PG8_LAS unsigned char* lds, const Gemm g, const Sched& S, const Epi& E, const int tid_in) {
;     ...
;             PG8_WAIT_V(8); PG8_WAIT_L(0); PG8_BAR; PG8_MMA(0, 0, At, B0); PG8_MMA(0, 1, At, B1); PG8_BAR; PG8_SCHED;
;             PG8_LDA(At, 0, 1); PG8_STAGE(PG8_SB(0, 0), b2, voffB); PG8_STAGE(PG8_SB(0, 1), b2 + hstepB, voffB); PG8_STAGE(PG8_SA(0, 0), a2, voffA);
;             PG8_WAIT_V(8); PG8_WAIT_L(0); PG8_BAR; PG8_MMA(1, 0, At, B0); PG8_MMA(1, 1, At, B1); PG8_BAR; PG8_SCHED;
	s_setprio 1
	s_waitcnt lgkmcnt(0)
	v_mfma_f32_16x16x32_bf16 v[124:127], v[128:131], v[160:163], v[124:127]
	v_mfma_f32_16x16x32_bf16 v[120:123], v[136:139], v[160:163], v[120:123]
	v_mfma_f32_16x16x32_bf16 v[108:111], v[128:131], v[168:171], v[108:111]
	v_mfma_f32_16x16x32_bf16 v[104:107], v[136:139], v[168:171], v[104:107]
	v_mfma_f32_16x16x32_bf16 v[96:99], v[128:131], v[176:179], v[96:99]
	v_mfma_f32_16x16x32_bf16 v[88:91], v[136:139], v[176:179], v[88:91]
	v_mfma_f32_16x16x32_bf16 v[80:83], v[128:131], v[194:197], v[80:83]
	v_mfma_f32_16x16x32_bf16 v[72:75], v[136:139], v[194:197], v[72:75]
	v_mfma_f32_16x16x32_bf16 v[124:127], v[132:135], v[164:167], v[124:127]
	v_mfma_f32_16x16x32_bf16 v[120:123], v[140:143], v[164:167], v[120:123]
	v_mfma_f32_16x16x32_bf16 v[108:111], v[132:135], v[172:175], v[108:111]
	v_mfma_f32_16x16x32_bf16 v[104:107], v[140:143], v[172:175], v[104:107]
	v_mfma_f32_16x16x32_bf16 v[96:99], v[132:135], v[180:183], v[96:99]
	v_mfma_f32_16x16x32_bf16 v[88:91], v[140:143], v[180:183], v[88:91]
	v_mfma_f32_16x16x32_bf16 v[80:83], v[132:135], v[200:203], v[80:83]
	v_mfma_f32_16x16x32_bf16 v[72:75], v[140:143], v[200:203], v[72:75]
	v_mfma_f32_16x16x32_bf16 v[116:119], v[144:147], v[160:163], v[116:119]
	v_mfma_f32_16x16x32_bf16 v[112:115], v[152:155], v[160:163], v[112:115]
	v_mfma_f32_16x16x32_bf16 v[100:103], v[144:147], v[168:171], v[100:103]
	v_mfma_f32_16x16x32_bf16 v[92:95], v[152:155], v[168:171], v[92:95]
	v_mfma_f32_16x16x32_bf16 v[84:87], v[144:147], v[176:179], v[84:87]
	v_mfma_f32_16x16x32_bf16 v[76:79], v[152:155], v[176:179], v[76:79]
	v_mfma_f32_16x16x32_bf16 v[68:71], v[144:147], v[194:197], v[68:71]
	v_mfma_f32_16x16x32_bf16 v[64:67], v[152:155], v[194:197], v[64:67]
	v_mfma_f32_16x16x32_bf16 v[116:119], v[148:151], v[164:167], v[116:119]
	v_mfma_f32_16x16x32_bf16 v[112:115], v[156:159], v[164:167], v[112:115]
	v_mfma_f32_16x16x32_bf16 v[100:103], v[148:151], v[172:175], v[100:103]
	v_mfma_f32_16x16x32_bf16 v[92:95], v[156:159], v[172:175], v[92:95]
	v_mfma_f32_16x16x32_bf16 v[84:87], v[148:151], v[180:183], v[84:87]
	v_mfma_f32_16x16x32_bf16 v[76:79], v[156:159], v[180:183], v[76:79]
	v_mfma_f32_16x16x32_bf16 v[68:71], v[148:151], v[200:203], v[68:71]
	v_mfma_f32_16x16x32_bf16 v[64:67], v[156:159], v[200:203], v[64:67]
	s_setprio 0
	s_barrier
	s_add_i32 s12, s71, s58
	v_lshl_add_u64 v[204:205], s[50:51], 0, v[192:193]
	s_mov_b32 m0, s12
	ds_read_b128 v[160:163], v226 offset:16384
	ds_read_b128 v[164:167], v226 offset:17408
	ds_read_b128 v[168:171], v226 offset:18432
	ds_read_b128 v[172:175], v226 offset:19456
	ds_read_b128 v[176:179], v226 offset:20480
	ds_read_b128 v[180:183], v226 offset:21504
	ds_read_b128 v[194:197], v226 offset:22528
	ds_read_b128 v[200:203], v226 offset:23552
	global_load_lds_dwordx4 v[204:205], off
	s_add_i32 m0, s12, 0x2000
	s_add_u32 s12, s50, 0x100000
	v_lshl_add_u64 v[206:207], s[50:51], 0, v[188:189]
	s_addc_u32 s13, s51, 0
	s_add_i32 s71, s72, s58
	global_load_lds_dwordx4 v[206:207], off
	v_lshl_add_u64 v[208:209], s[12:13], 0, v[192:193]
	s_mov_b32 m0, s71
	v_lshl_add_u64 v[210:211], s[52:53], 0, v[186:187]
	global_load_lds_dwordx4 v[208:209], off
	v_lshl_add_u64 v[208:209], s[12:13], 0, v[188:189]
	s_add_i32 m0, s71, 0x2000
	s_nop 0
	global_load_lds_dwordx4 v[208:209], off
	v_lshl_add_u64 v[208:209], s[52:53], 0, v[184:185]
	s_mov_b32 m0, s59
	s_nop 0
	global_load_lds_dwordx4 v[208:209], off
	s_mov_b32 m0, s60
	s_nop 0
	global_load_lds_dwordx4 v[210:211], off
	s_waitcnt vmcnt(8)
	s_waitcnt lgkmcnt(0)
	s_barrier
	s_setprio 1
	s_waitcnt lgkmcnt(0)
	v_mfma_f32_16x16x32_bf16 v[60:63], v[128:131], v[160:163], v[60:63]
	v_mfma_f32_16x16x32_bf16 v[56:59], v[136:139], v[160:163], v[56:59]
	v_mfma_f32_16x16x32_bf16 v[48:51], v[128:131], v[168:171], v[48:51]
	v_mfma_f32_16x16x32_bf16 v[40:43], v[136:139], v[168:171], v[40:43]
	v_mfma_f32_16x16x32_bf16 v[32:35], v[128:131], v[176:179], v[32:35]
	v_mfma_f32_16x16x32_bf16 v[24:27], v[136:139], v[176:179], v[24:27]
	v_mfma_f32_16x16x32_bf16 v[16:19], v[128:131], v[194:197], v[16:19]
	v_mfma_f32_16x16x32_bf16 v[8:11], v[136:139], v[194:197], v[8:11]
	v_mfma_f32_16x16x32_bf16 v[60:63], v[132:135], v[164:167], v[60:63]
	v_mfma_f32_16x16x32_bf16 v[56:59], v[140:143], v[164:167], v[56:59]
	v_mfma_f32_16x16x32_bf16 v[48:51], v[132:135], v[172:175], v[48:51]
	v_mfma_f32_16x16x32_bf16 v[40:43], v[140:143], v[172:175], v[40:43]
	v_mfma_f32_16x16x32_bf16 v[32:35], v[132:135], v[180:183], v[32:35]
	v_mfma_f32_16x16x32_bf16 v[24:27], v[140:143], v[180:183], v[24:27]
	v_mfma_f32_16x16x32_bf16 v[16:19], v[132:135], v[200:203], v[16:19]
	v_mfma_f32_16x16x32_bf16 v[8:11], v[140:143], v[200:203], v[8:11]
	v_mfma_f32_16x16x32_bf16 v[52:55], v[144:147], v[160:163], v[52:55]
	v_mfma_f32_16x16x32_bf16 v[44:47], v[152:155], v[160:163], v[44:47]
	v_mfma_f32_16x16x32_bf16 v[36:39], v[144:147], v[168:171], v[36:39]
	v_mfma_f32_16x16x32_bf16 v[28:31], v[152:155], v[168:171], v[28:31]
	v_mfma_f32_16x16x32_bf16 v[20:23], v[144:147], v[176:179], v[20:23]
	v_mfma_f32_16x16x32_bf16 v[12:15], v[152:155], v[176:179], v[12:15]
	v_mfma_f32_16x16x32_bf16 v[4:7], v[144:147], v[194:197], v[4:7]
	v_mfma_f32_16x16x32_bf16 v[0:3], v[152:155], v[194:197], v[0:3]
	v_mfma_f32_16x16x32_bf16 v[52:55], v[148:151], v[164:167], v[52:55]
	v_mfma_f32_16x16x32_bf16 v[44:47], v[156:159], v[164:167], v[44:47]
	v_mfma_f32_16x16x32_bf16 v[36:39], v[148:151], v[172:175], v[36:39]
	v_mfma_f32_16x16x32_bf16 v[28:31], v[156:159], v[172:175], v[28:31]
	v_mfma_f32_16x16x32_bf16 v[20:23], v[148:151], v[180:183], v[20:23]
	v_mfma_f32_16x16x32_bf16 v[12:15], v[156:159], v[180:183], v[12:15]
	v_mfma_f32_16x16x32_bf16 v[4:7], v[148:151], v[200:203], v[4:7]
	v_mfma_f32_16x16x32_bf16 v[0:3], v[156:159], v[200:203], v[0:3]
	s_setprio 0
	s_barrier
; #define PG8_STAGE(bufoff, gbase, voff) do { _Pragma("unroll") for (int _i = 0; _i < 2; ++_i) \
;         __builtin_amdgcn_global_load_lds((const unsigned*)((const char*)(gbase) + (voff)[_i]), (PG8_LAS unsigned*)(lds + (bufoff) + ldsw + _i * 8192), 16, 0, 0); } while (0)
; #define PG8_LDA(dst, b, h) do { _Pragma("unroll") for (int m = 0; m < 4; ++m) _Pragma("unroll") for (int k = 0; k < 2; ++k) dst[m][k] = *(const PG8_LAS bf16x8*)(lds + PG8_SA(b, h) + aoff + m * 2048 + k * 1024); } while (0)
; #define PG8_LDB(dst, b, h) do { _Pragma("unroll") for (int n = 0; n < 2; ++n) _Pragma("unroll") for (int k = 0; k < 2; ++k) dst[n][k] = *(const PG8_LAS bf16x8*)(lds + PG8_SB(b, h) + boff + n * 2048 + k * 1024); } while (0)
; #define PG8_MMA(ai, bj, At, Bt) do { __builtin_amdgcn_s_setprio(1); _Pragma("unroll") for (int m = 0; m < 4; ++m) _Pragma("unroll") for (int n = 0; n < 2; ++n) _Pragma("unroll") for (int k = 0; k < 2; ++k) \
;         acc[ai][bj][m][n] = __builtin_amdgcn_mfma_f32_16x16x32_bf16(Bt[n][k], At[m][k], acc[ai][bj][m][n], 0, 0, 0); __builtin_amdgcn_s_setprio(0); } while (0)
; #define PG8_WAIT_V(n) asm volatile("s_waitcnt vmcnt(" #n ")" ::: "memory")
; #define PG8_WAIT_L(n) asm volatile("s_waitcnt lgkmcnt(" #n ")" ::: "memory")
; #define PG8_BAR __builtin_amdgcn_s_barrier()
; #define PG8_SCHED __builtin_amdgcn_sched_barrier(0)
; template <class Epi, class Sched, bool ALIGN_EPI = false, bool SP2 = false>
; __device__ __forceinline__ void gemm_phase(PG8_LAS unsigned char* lds, const Gemm g, const Sched& S, const Epi& E, const int tid_in) {
;     ...
;             PG8_LDB(B0, 1, 0); PG8_LDB(B1, 1, 1); PG8_SCHED; PG8_LDA(At, 1, 0); PG8_STAGE(PG8_SA(0, 1), a2 + hstepA, voffA);
;             PG8_WAIT_V(8); PG8_WAIT_L(0); PG8_BAR; PG8_MMA(0, 0, At, B0); PG8_MMA(0, 1, At, B1); PG8_BAR; PG8_SCHED;
	s_add_i32 s71, 0, 0x18000
	s_add_i32 s72, 0, 0x1c000
	v_add_u32_e32 v140, s71, v224
	v_add_u32_e32 v156, s72, v224
	ds_read_b128 v[128:131], v140
	ds_read_b128 v[132:135], v140 offset:1024
	ds_read_b128 v[136:139], v140 offset:2048
	ds_read_b128 v[140:143], v140 offset:3072
	ds_read_b128 v[144:147], v156
	ds_read_b128 v[148:151], v156 offset:1024
	ds_read_b128 v[152:155], v156 offset:2048
	ds_read_b128 v[156:159], v156 offset:3072
	s_add_u32 s12, s52, 0x100000
	s_addc_u32 s13, s53, 0
	s_mov_b32 m0, s61
	v_lshl_add_u64 v[212:213], s[12:13], 0, v[184:185]
	ds_read_b128 v[160:163], v226 offset:32768
	ds_read_b128 v[164:167], v226 offset:33792
	ds_read_b128 v[168:171], v226 offset:34816
	ds_read_b128 v[172:175], v226 offset:35840
	ds_read_b128 v[176:179], v226 offset:36864
	ds_read_b128 v[180:183], v226 offset:37888
	ds_read_b128 v[194:197], v226 offset:38912
	ds_read_b128 v[200:203], v226 offset:39936
	global_load_lds_dwordx4 v[212:213], off
	v_lshl_add_u64 v[212:213], s[12:13], 0, v[186:187]
	s_mov_b32 m0, s62
	s_nop 0
	global_load_lds_dwordx4 v[212:213], off
	s_waitcnt vmcnt(8)
	s_waitcnt lgkmcnt(0)
	s_barrier
	s_setprio 1
	s_waitcnt lgkmcnt(0)
	v_mfma_f32_16x16x32_bf16 v[124:127], v[128:131], v[160:163], v[124:127]
	v_mfma_f32_16x16x32_bf16 v[120:123], v[136:139], v[160:163], v[120:123]
	v_mfma_f32_16x16x32_bf16 v[108:111], v[128:131], v[168:171], v[108:111]
	v_mfma_f32_16x16x32_bf16 v[104:107], v[136:139], v[168:171], v[104:107]
	v_mfma_f32_16x16x32_bf16 v[96:99], v[128:131], v[176:179], v[96:99]
	v_mfma_f32_16x16x32_bf16 v[88:91], v[136:139], v[176:179], v[88:91]
	v_mfma_f32_16x16x32_bf16 v[80:83], v[128:131], v[194:197], v[80:83]
	v_mfma_f32_16x16x32_bf16 v[72:75], v[136:139], v[194:197], v[72:75]
	v_mfma_f32_16x16x32_bf16 v[124:127], v[132:135], v[164:167], v[124:127]
	v_mfma_f32_16x16x32_bf16 v[120:123], v[140:143], v[164:167], v[120:123]
	v_mfma_f32_16x16x32_bf16 v[108:111], v[132:135], v[172:175], v[108:111]
	v_mfma_f32_16x16x32_bf16 v[104:107], v[140:143], v[172:175], v[104:107]
	v_mfma_f32_16x16x32_bf16 v[96:99], v[132:135], v[180:183], v[96:99]
	v_mfma_f32_16x16x32_bf16 v[88:91], v[140:143], v[180:183], v[88:91]
	v_mfma_f32_16x16x32_bf16 v[80:83], v[132:135], v[200:203], v[80:83]
	v_mfma_f32_16x16x32_bf16 v[72:75], v[140:143], v[200:203], v[72:75]
	v_mfma_f32_16x16x32_bf16 v[116:119], v[144:147], v[160:163], v[116:119]
	v_mfma_f32_16x16x32_bf16 v[112:115], v[152:155], v[160:163], v[112:115]
	v_mfma_f32_16x16x32_bf16 v[100:103], v[144:147], v[168:171], v[100:103]
	v_mfma_f32_16x16x32_bf16 v[92:95], v[152:155], v[168:171], v[92:95]
	v_mfma_f32_16x16x32_bf16 v[84:87], v[144:147], v[176:179], v[84:87]
	v_mfma_f32_16x16x32_bf16 v[76:79], v[152:155], v[176:179], v[76:79]
	v_mfma_f32_16x16x32_bf16 v[68:71], v[144:147], v[194:197], v[68:71]
	v_mfma_f32_16x16x32_bf16 v[64:67], v[152:155], v[194:197], v[64:67]
	v_mfma_f32_16x16x32_bf16 v[116:119], v[148:151], v[164:167], v[116:119]
	v_mfma_f32_16x16x32_bf16 v[112:115], v[156:159], v[164:167], v[112:115]
	v_mfma_f32_16x16x32_bf16 v[100:103], v[148:151], v[172:175], v[100:103]
	v_mfma_f32_16x16x32_bf16 v[92:95], v[156:159], v[172:175], v[92:95]
	v_mfma_f32_16x16x32_bf16 v[84:87], v[148:151], v[180:183], v[84:87]
	v_mfma_f32_16x16x32_bf16 v[76:79], v[156:159], v[180:183], v[76:79]
	v_mfma_f32_16x16x32_bf16 v[68:71], v[148:151], v[200:203], v[68:71]
	v_mfma_f32_16x16x32_bf16 v[64:67], v[156:159], v[200:203], v[64:67]
	s_setprio 0
	s_barrier
; #define PG8_STAGE(bufoff, gbase, voff) do { _Pragma("unroll") for (int _i = 0; _i < 2; ++_i) \
;         __builtin_amdgcn_global_load_lds((const unsigned*)((const char*)(gbase) + (voff)[_i]), (PG8_LAS unsigned*)(lds + (bufoff) + ldsw + _i * 8192), 16, 0, 0); } while (0)
; #define PG8_LDA(dst, b, h) do { _Pragma("unroll") for (int m = 0; m < 4; ++m) _Pragma("unroll") for (int k = 0; k < 2; ++k) dst[m][k] = *(const PG8_LAS bf16x8*)(lds + PG8_SA(b, h) + aoff + m * 2048 + k * 1024); } while (0)
; #define PG8_MMA(ai, bj, At, Bt) do { __builtin_amdgcn_s_setprio(1); _Pragma("unroll") for (int m = 0; m < 4; ++m) _Pragma("unroll") for (int n = 0; n < 2; ++n) _Pragma("unroll") for (int k = 0; k < 2; ++k) \
;         acc[ai][bj][m][n] = __builtin_amdgcn_mfma_f32_16x16x32_bf16(Bt[n][k], At[m][k], acc[ai][bj][m][n], 0, 0, 0); __builtin_amdgcn_s_setprio(0); } while (0)
; #define PG8_WAIT_V(n) asm volatile("s_waitcnt vmcnt(" #n ")" ::: "memory")
; #define PG8_WAIT_L(n) asm volatile("s_waitcnt lgkmcnt(" #n ")" ::: "memory")
; #define PG8_BAR __builtin_amdgcn_s_barrier()
; #define PG8_SCHED __builtin_amdgcn_sched_barrier(0)
; template <class Epi, class Sched, bool ALIGN_EPI = false, bool SP2 = false>
; __device__ __forceinline__ void gemm_phase(PG8_LAS unsigned char* lds, const Gemm g, const Sched& S, const Epi& E, const int tid_in) {
;     ...
;         for (int t = 0; t < nt; t += 2) {
;             const bool last = (t == nt - 2);
;             const char* a1 = cA + (size_t)(t + 1) * kstep;
;             const char* a2 = last ? nA : cA + (size_t)(t + 2) * kstep; const char* b2 = last ? nB : cB + (size_t)(t + 2) * kstep;
;             const char* a3 = a2 + kstep; const char* b3 = b2 + kstep;
;             if (last && has_next) S.a_ready(nxt);
;     ...
;             PG8_LDA(At, 1, 1); PG8_STAGE(PG8_SB(1, 0), b3, voffB); PG8_STAGE(PG8_SB(1, 1), b3 + hstepB, voffB); PG8_STAGE(PG8_SA(1, 0), a3, voffA);
;             PG8_WAIT_V(8); PG8_WAIT_L(0); PG8_BAR; PG8_MMA(1, 0, At, B0); PG8_MMA(1, 1, At, B1); PG8_BAR; PG8_SCHED;
	s_add_i32 s12, s71, s58
	v_lshl_add_u64 v[204:205], v[204:205], 0, s[26:27]
	s_mov_b32 m0, s12
	ds_read_b128 v[160:163], v226 offset:49152
	ds_read_b128 v[164:167], v226 offset:50176
	ds_read_b128 v[168:171], v226 offset:51200
	ds_read_b128 v[172:175], v226 offset:52224
	ds_read_b128 v[176:179], v226 offset:53248
	ds_read_b128 v[180:183], v226 offset:54272
	ds_read_b128 v[194:197], v226 offset:55296
	ds_read_b128 v[200:203], v226 offset:56320
	global_load_lds_dwordx4 v[204:205], off
	s_add_i32 m0, s12, 0x2000
	s_add_u32 s12, s50, 0x100080
	v_lshl_add_u64 v[204:205], v[206:207], 0, s[26:27]
	s_addc_u32 s13, s51, 0
	s_add_i32 s50, s72, s58
	global_load_lds_dwordx4 v[204:205], off
	v_lshl_add_u64 v[204:205], s[12:13], 0, v[192:193]
	s_mov_b32 m0, s50
	s_nop 0
	global_load_lds_dwordx4 v[204:205], off
	v_lshl_add_u64 v[204:205], s[12:13], 0, v[188:189]
	s_add_i32 m0, s50, 0x2000
	s_nop 0
	global_load_lds_dwordx4 v[204:205], off
	v_lshl_add_u64 v[204:205], v[208:209], 0, s[26:27]
	s_mov_b32 m0, s64
	s_nop 0
	global_load_lds_dwordx4 v[204:205], off
	v_lshl_add_u64 v[204:205], v[210:211], 0, s[26:27]
	s_mov_b32 m0, s65
	s_nop 0
	global_load_lds_dwordx4 v[204:205], off
	s_waitcnt vmcnt(8)
	s_waitcnt lgkmcnt(0)
	s_barrier
	s_setprio 1
	s_waitcnt lgkmcnt(0)
	v_mfma_f32_16x16x32_bf16 v[60:63], v[128:131], v[160:163], v[60:63]
	v_mfma_f32_16x16x32_bf16 v[56:59], v[136:139], v[160:163], v[56:59]
	v_mfma_f32_16x16x32_bf16 v[48:51], v[128:131], v[168:171], v[48:51]
	v_mfma_f32_16x16x32_bf16 v[40:43], v[136:139], v[168:171], v[40:43]
	v_mfma_f32_16x16x32_bf16 v[32:35], v[128:131], v[176:179], v[32:35]
	v_mfma_f32_16x16x32_bf16 v[24:27], v[136:139], v[176:179], v[24:27]
	v_mfma_f32_16x16x32_bf16 v[16:19], v[128:131], v[194:197], v[16:19]
	v_mfma_f32_16x16x32_bf16 v[8:11], v[136:139], v[194:197], v[8:11]
	v_mfma_f32_16x16x32_bf16 v[60:63], v[132:135], v[164:167], v[60:63]
	v_mfma_f32_16x16x32_bf16 v[56:59], v[140:143], v[164:167], v[56:59]
	v_mfma_f32_16x16x32_bf16 v[48:51], v[132:135], v[172:175], v[48:51]
	v_mfma_f32_16x16x32_bf16 v[40:43], v[140:143], v[172:175], v[40:43]
	v_mfma_f32_16x16x32_bf16 v[32:35], v[132:135], v[180:183], v[32:35]
	v_mfma_f32_16x16x32_bf16 v[24:27], v[140:143], v[180:183], v[24:27]
	v_mfma_f32_16x16x32_bf16 v[16:19], v[132:135], v[200:203], v[16:19]
	v_mfma_f32_16x16x32_bf16 v[8:11], v[140:143], v[200:203], v[8:11]
	v_mfma_f32_16x16x32_bf16 v[52:55], v[144:147], v[160:163], v[52:55]
	v_mfma_f32_16x16x32_bf16 v[44:47], v[152:155], v[160:163], v[44:47]
	v_mfma_f32_16x16x32_bf16 v[36:39], v[144:147], v[168:171], v[36:39]
	v_mfma_f32_16x16x32_bf16 v[28:31], v[152:155], v[168:171], v[28:31]
	v_mfma_f32_16x16x32_bf16 v[20:23], v[144:147], v[176:179], v[20:23]
	v_mfma_f32_16x16x32_bf16 v[12:15], v[152:155], v[176:179], v[12:15]
	v_mfma_f32_16x16x32_bf16 v[4:7], v[144:147], v[194:197], v[4:7]
	v_mfma_f32_16x16x32_bf16 v[0:3], v[152:155], v[194:197], v[0:3]
	v_mfma_f32_16x16x32_bf16 v[52:55], v[148:151], v[164:167], v[52:55]
	v_mfma_f32_16x16x32_bf16 v[44:47], v[156:159], v[164:167], v[44:47]
	v_mfma_f32_16x16x32_bf16 v[36:39], v[148:151], v[172:175], v[36:39]
	v_mfma_f32_16x16x32_bf16 v[28:31], v[156:159], v[172:175], v[28:31]
	v_mfma_f32_16x16x32_bf16 v[20:23], v[148:151], v[180:183], v[20:23]
	v_mfma_f32_16x16x32_bf16 v[12:15], v[156:159], v[180:183], v[12:15]
	v_mfma_f32_16x16x32_bf16 v[4:7], v[148:151], v[200:203], v[4:7]
	v_mfma_f32_16x16x32_bf16 v[0:3], v[156:159], v[200:203], v[0:3]
	s_setprio 0
	s_barrier
	s_add_i32 s70, s70, 2
	s_add_u32 s48, s48, 0x100
	s_addc_u32 s49, s49, 0
	s_add_u32 s68, s68, 0x100
	s_addc_u32 s69, s69, 0
	s_cmp_gt_u32 s70, 61
	s_cbranch_scc0 .LBB0_1221
	s_and_b64 vcc, exec, s[36:37]
	s_cbranch_vccz .LBB0_1224
	s_barrier

; #define PG8_STAGE(bufoff, gbase, voff) do { _Pragma("unroll") for (int _i = 0; _i < 2; ++_i) \
;         __builtin_amdgcn_global_load_lds((const unsigned*)((const char*)(gbase) + (voff)[_i]), (PG8_LAS unsigned*)(lds + (bufoff) + ldsw + _i * 8192), 16, 0, 0); } while (0)
; #define PG8_LDA(dst, b, h) do { _Pragma("unroll") for (int m = 0; m < 4; ++m) _Pragma("unroll") for (int k = 0; k < 2; ++k) dst[m][k] = *(const PG8_LAS bf16x8*)(lds + PG8_SA(b, h) + aoff + m * 2048 + k * 1024); } while (0)
; #define PG8_LDB(dst, b, h) do { _Pragma("unroll") for (int n = 0; n < 2; ++n) _Pragma("unroll") for (int k = 0; k < 2; ++k) dst[n][k] = *(const PG8_LAS bf16x8*)(lds + PG8_SB(b, h) + boff + n * 2048 + k * 1024); } while (0)
; #define PG8_MMA(ai, bj, At, Bt) do { __builtin_amdgcn_s_setprio(1); _Pragma("unroll") for (int m = 0; m < 4; ++m) _Pragma("unroll") for (int n = 0; n < 2; ++n) _Pragma("unroll") for (int k = 0; k < 2; ++k) \
;         acc[ai][bj][m][n] = __builtin_amdgcn_mfma_f32_16x16x32_bf16(Bt[n][k], At[m][k], acc[ai][bj][m][n], 0, 0, 0); __builtin_amdgcn_s_setprio(0); } while (0)
; template <class Epi, class Sched, bool ALIGN_EPI = false, bool SP2 = false>
; __device__ __forceinline__ void gemm_phase(PG8_LAS unsigned char* lds, const Gemm g, const Sched& S, const Epi& E, const int tid_in) {
;     ...
;         const bool has_next = S.next(ui + 1, nxt);
;         const char* nA = has_next ? (const char*)g.A + (size_t)nxt.pm * tstepA : cA; const char* nB = has_next ? (const char*)g.Bt + (size_t)nxt.pn * tstepB : cB;
;         for (int t = 0; t < nt; t += 2) {
;             const bool last = (t == nt - 2);
;             const char* a1 = cA + (size_t)(t + 1) * kstep;
;             const char* a2 = last ? nA : cA + (size_t)(t + 2) * kstep; const char* b2 = last ? nB : cB + (size_t)(t + 2) * kstep;
;             const char* a3 = a2 + kstep; const char* b3 = b2 + kstep;
;             if (last && has_next) S.a_ready(nxt);
;             if constexpr (SP2) {
;             PG8_LDB(B0, 0, 0); PG8_LDB(B1, 0, 1); PG8_SCHED; PG8_LDA(At, 0, 0); PG8_STAGE(PG8_SA(1, 1), a1 + hstepA, voffA);
;             PG8_WAIT_V(8); PG8_WAIT_L(0); PG8_BAR; PG8_MMA(0, 0, At, B0); PG8_MMA(0, 1, At, B1); PG8_BAR; PG8_SCHED;
;             PG8_LDA(At, 0, 1); PG8_STAGE(PG8_SB(0, 0), b2, voffB); PG8_STAGE(PG8_SB(0, 1), b2 + hstepB, voffB); PG8_STAGE(PG8_SA(0, 0), a2, voffA);
.LBB0_1358:
	s_ashr_i32 s39, s38, 31
	s_lshl_b64 s[12:13], s[38:39], 20
	s_add_u32 s40, s10, s12
	s_addc_u32 s41, s11, s13
	s_and_b64 s[12:13], s[34:35], exec
	s_cselect_b32 s39, s41, s45
	s_cselect_b32 s61, s40, s44
	s_ashr_i32 s37, s36, 31
	s_lshl_b64 s[12:13], s[36:37], 20
	s_add_u32 s42, s15, s12
	s_addc_u32 s43, s18, s13
	s_and_b64 s[12:13], s[34:35], exec
	s_cselect_b32 s37, s43, s47
	s_cselect_b32 s62, s42, s46
	s_add_u32 s44, s44, 0x80080
	s_addc_u32 s45, s45, 0
	s_add_u32 s63, s46, 0x100
	s_addc_u32 s64, s47, 0
	s_mov_b32 s65, -2
	s_add_u32 s12, s44, 0xfff80080
	s_addc_u32 s13, s45, -1
	s_add_i32 s66, 0, 0x10000
	s_cmp_eq_u32 s65, 28
	s_cselect_b32 s49, s39, s13
	s_cselect_b32 s48, s61, s12
	v_add_u32_e32 v138, s66, v141
	s_cselect_b32 s47, s37, s64
	s_cselect_b32 s46, s62, s63
	s_add_i32 s67, 0, 0x14000
	ds_read_b128 v[144:147], v138
	ds_read_b128 v[148:151], v138 offset:1024
	ds_read_b128 v[152:155], v138 offset:2048
	ds_read_b128 v[156:159], v138 offset:3072
	v_add_u32_e32 v138, s67, v141
	ds_read_b128 v[160:163], v138
	ds_read_b128 v[164:167], v138 offset:1024
	ds_read_b128 v[168:171], v138 offset:2048
	ds_read_b128 v[172:175], v138 offset:3072
	v_lshl_add_u64 v[138:139], s[44:45], 0, v[134:135]
	s_add_i32 m0, s51, 0xc000
	ds_read_b128 v[176:179], v143
	ds_read_b128 v[180:183], v143 offset:1024
	ds_read_b128 v[184:187], v143 offset:2048
	ds_read_b128 v[188:191], v143 offset:3072
	ds_read_b128 v[194:197], v143 offset:4096
	ds_read_b128 v[198:201], v143 offset:5120
	ds_read_b128 v[202:205], v143 offset:6144
	ds_read_b128 v[206:209], v143 offset:7168
	global_load_lds_dwordx4 v[138:139], off
	v_lshl_add_u64 v[138:139], s[44:45], 0, v[136:137]
	s_add_i32 m0, s51, 0xe000
	s_nop 0
	global_load_lds_dwordx4 v[138:139], off
	s_waitcnt vmcnt(8)
	s_waitcnt lgkmcnt(0)
	s_barrier
	s_setprio 1
	s_waitcnt lgkmcnt(0)
	v_mfma_f32_16x16x32_bf16 v[124:127], v[144:147], v[176:179], 0
	v_mfma_f32_16x16x32_bf16 v[120:123], v[152:155], v[176:179], 0
	v_mfma_f32_16x16x32_bf16 v[108:111], v[144:147], v[184:187], 0
	v_mfma_f32_16x16x32_bf16 v[104:107], v[152:155], v[184:187], 0
	v_mfma_f32_16x16x32_bf16 v[92:95], v[144:147], v[194:197], 0
	v_mfma_f32_16x16x32_bf16 v[88:91], v[152:155], v[194:197], 0
	v_mfma_f32_16x16x32_bf16 v[76:79], v[144:147], v[202:205], 0
	v_mfma_f32_16x16x32_bf16 v[72:75], v[152:155], v[202:205], 0
	v_mfma_f32_16x16x32_bf16 v[124:127], v[148:151], v[180:183], v[124:127]
	v_mfma_f32_16x16x32_bf16 v[120:123], v[156:159], v[180:183], v[120:123]
	v_mfma_f32_16x16x32_bf16 v[108:111], v[148:151], v[188:191], v[108:111]
	v_mfma_f32_16x16x32_bf16 v[104:107], v[156:159], v[188:191], v[104:107]
	v_mfma_f32_16x16x32_bf16 v[92:95], v[148:151], v[198:201], v[92:95]
	v_mfma_f32_16x16x32_bf16 v[88:91], v[156:159], v[198:201], v[88:91]
	v_mfma_f32_16x16x32_bf16 v[76:79], v[148:151], v[206:209], v[76:79]
	v_mfma_f32_16x16x32_bf16 v[72:75], v[156:159], v[206:209], v[72:75]
	s_setprio 0
	s_setprio 1
	v_mfma_f32_16x16x32_bf16 v[116:119], v[160:163], v[176:179], 0
	v_mfma_f32_16x16x32_bf16 v[112:115], v[168:171], v[176:179], 0
	v_mfma_f32_16x16x32_bf16 v[100:103], v[160:163], v[184:187], 0
	v_mfma_f32_16x16x32_bf16 v[96:99], v[168:171], v[184:187], 0
	v_mfma_f32_16x16x32_bf16 v[84:87], v[160:163], v[194:197], 0
	v_mfma_f32_16x16x32_bf16 v[80:83], v[168:171], v[194:197], 0
	v_mfma_f32_16x16x32_bf16 v[68:71], v[160:163], v[202:205], 0
	v_mfma_f32_16x16x32_bf16 v[64:67], v[168:171], v[202:205], 0
	v_mfma_f32_16x16x32_bf16 v[116:119], v[164:167], v[180:183], v[116:119]
	v_mfma_f32_16x16x32_bf16 v[112:115], v[172:175], v[180:183], v[112:115]
	v_mfma_f32_16x16x32_bf16 v[100:103], v[164:167], v[188:191], v[100:103]
	v_mfma_f32_16x16x32_bf16 v[96:99], v[172:175], v[188:191], v[96:99]
	v_mfma_f32_16x16x32_bf16 v[84:87], v[164:167], v[198:201], v[84:87]
	v_mfma_f32_16x16x32_bf16 v[80:83], v[172:175], v[198:201], v[80:83]
	v_mfma_f32_16x16x32_bf16 v[68:71], v[164:167], v[206:209], v[68:71]
	v_mfma_f32_16x16x32_bf16 v[64:67], v[172:175], v[206:209], v[64:67]
	s_setprio 0
	s_barrier
	s_add_i32 s12, s66, s50
	v_lshl_add_u64 v[138:139], s[46:47], 0, v[192:193]
	s_mov_b32 m0, s12
	ds_read_b128 v[176:179], v143 offset:16384
	ds_read_b128 v[180:183], v143 offset:17408
	ds_read_b128 v[184:187], v143 offset:18432
	ds_read_b128 v[188:191], v143 offset:19456
	ds_read_b128 v[194:197], v143 offset:20480
	ds_read_b128 v[198:201], v143 offset:21504
	ds_read_b128 v[202:205], v143 offset:22528
	ds_read_b128 v[206:209], v143 offset:23552
	global_load_lds_dwordx4 v[138:139], off
	s_add_i32 m0, s12, 0x2000
	s_add_u32 s12, s46, 0x80000
	v_lshl_add_u64 v[210:211], s[46:47], 0, v[128:129]
	s_addc_u32 s13, s47, 0
	s_add_i32 s66, s67, s50
	global_load_lds_dwordx4 v[210:211], off
	v_lshl_add_u64 v[212:213], s[12:13], 0, v[192:193]
	s_mov_b32 m0, s66
	v_lshl_add_u64 v[214:215], s[48:49], 0, v[130:131]
	global_load_lds_dwordx4 v[212:213], off
	v_lshl_add_u64 v[212:213], s[12:13], 0, v[128:129]
	s_add_i32 m0, s66, 0x2000
	s_nop 0
	global_load_lds_dwordx4 v[212:213], off
	v_lshl_add_u64 v[212:213], s[48:49], 0, v[132:133]
	s_mov_b32 m0, s51
	s_nop 0
	global_load_lds_dwordx4 v[212:213], off
	s_mov_b32 m0, s52
	s_nop 0
	global_load_lds_dwordx4 v[214:215], off
	s_waitcnt vmcnt(8)
	s_waitcnt lgkmcnt(0)
	s_barrier
; #define PG8_STAGE(bufoff, gbase, voff) do { _Pragma("unroll") for (int _i = 0; _i < 2; ++_i) \
;         __builtin_amdgcn_global_load_lds((const unsigned*)((const char*)(gbase) + (voff)[_i]), (PG8_LAS unsigned*)(lds + (bufoff) + ldsw + _i * 8192), 16, 0, 0); } while (0)
; #define PG8_LDA(dst, b, h) do { _Pragma("unroll") for (int m = 0; m < 4; ++m) _Pragma("unroll") for (int k = 0; k < 2; ++k) dst[m][k] = *(const PG8_LAS bf16x8*)(lds + PG8_SA(b, h) + aoff + m * 2048 + k * 1024); } while (0)
; #define PG8_LDB(dst, b, h) do { _Pragma("unroll") for (int n = 0; n < 2; ++n) _Pragma("unroll") for (int k = 0; k < 2; ++k) dst[n][k] = *(const PG8_LAS bf16x8*)(lds + PG8_SB(b, h) + boff + n * 2048 + k * 1024); } while (0)
; #define PG8_MMA(ai, bj, At, Bt) do { __builtin_amdgcn_s_setprio(1); _Pragma("unroll") for (int m = 0; m < 4; ++m) _Pragma("unroll") for (int n = 0; n < 2; ++n) _Pragma("unroll") for (int k = 0; k < 2; ++k) \
;         acc[ai][bj][m][n] = __builtin_amdgcn_mfma_f32_16x16x32_bf16(Bt[n][k], At[m][k], acc[ai][bj][m][n], 0, 0, 0); __builtin_amdgcn_s_setprio(0); } while (0)
; #define PG8_WAIT_V(n) asm volatile("s_waitcnt vmcnt(" #n ")" ::: "memory")
; #define PG8_WAIT_L(n) asm volatile("s_waitcnt lgkmcnt(" #n ")" ::: "memory")
; #define PG8_BAR __builtin_amdgcn_s_barrier()
; #define PG8_SCHED __builtin_amdgcn_sched_barrier(0)
; template <class Epi, class Sched, bool ALIGN_EPI = false, bool SP2 = false>
; __device__ __forceinline__ void gemm_phase(PG8_LAS unsigned char* lds, const Gemm g, const Sched& S, const Epi& E, const int tid_in) {
;     ...
;             PG8_WAIT_V(8); PG8_WAIT_L(0); PG8_BAR; PG8_MMA(1, 0, At, B0); PG8_MMA(1, 1, At, B1); PG8_BAR; PG8_SCHED;
;             PG8_LDB(B0, 1, 0); PG8_LDB(B1, 1, 1); PG8_SCHED; PG8_LDA(At, 1, 0); PG8_STAGE(PG8_SA(0, 1), a2 + hstepA, voffA);
;             PG8_WAIT_V(8); PG8_WAIT_L(0); PG8_BAR; PG8_MMA(0, 0, At, B0); PG8_MMA(0, 1, At, B1); PG8_BAR; PG8_SCHED;
	s_setprio 1
	s_waitcnt lgkmcnt(0)
	v_mfma_f32_16x16x32_bf16 v[60:63], v[144:147], v[176:179], 0
	v_mfma_f32_16x16x32_bf16 v[56:59], v[152:155], v[176:179], 0
	v_mfma_f32_16x16x32_bf16 v[44:47], v[144:147], v[184:187], 0
	v_mfma_f32_16x16x32_bf16 v[40:43], v[152:155], v[184:187], 0
	v_mfma_f32_16x16x32_bf16 v[28:31], v[144:147], v[194:197], 0
	v_mfma_f32_16x16x32_bf16 v[24:27], v[152:155], v[194:197], 0
	v_mfma_f32_16x16x32_bf16 v[12:15], v[144:147], v[202:205], 0
	v_mfma_f32_16x16x32_bf16 v[8:11], v[152:155], v[202:205], 0
	v_mfma_f32_16x16x32_bf16 v[60:63], v[148:151], v[180:183], v[60:63]
	v_mfma_f32_16x16x32_bf16 v[56:59], v[156:159], v[180:183], v[56:59]
	v_mfma_f32_16x16x32_bf16 v[44:47], v[148:151], v[188:191], v[44:47]
	v_mfma_f32_16x16x32_bf16 v[40:43], v[156:159], v[188:191], v[40:43]
	v_mfma_f32_16x16x32_bf16 v[28:31], v[148:151], v[198:201], v[28:31]
	v_mfma_f32_16x16x32_bf16 v[24:27], v[156:159], v[198:201], v[24:27]
	v_mfma_f32_16x16x32_bf16 v[12:15], v[148:151], v[206:209], v[12:15]
	v_mfma_f32_16x16x32_bf16 v[8:11], v[156:159], v[206:209], v[8:11]
	s_setprio 0
	s_setprio 1
	v_mfma_f32_16x16x32_bf16 v[52:55], v[160:163], v[176:179], 0
	v_mfma_f32_16x16x32_bf16 v[48:51], v[168:171], v[176:179], 0
	v_mfma_f32_16x16x32_bf16 v[36:39], v[160:163], v[184:187], 0
	v_mfma_f32_16x16x32_bf16 v[32:35], v[168:171], v[184:187], 0
	v_mfma_f32_16x16x32_bf16 v[20:23], v[160:163], v[194:197], 0
	v_mfma_f32_16x16x32_bf16 v[16:19], v[168:171], v[194:197], 0
	v_mfma_f32_16x16x32_bf16 v[4:7], v[160:163], v[202:205], 0
	v_mfma_f32_16x16x32_bf16 v[0:3], v[168:171], v[202:205], 0
	v_mfma_f32_16x16x32_bf16 v[52:55], v[164:167], v[180:183], v[52:55]
	v_mfma_f32_16x16x32_bf16 v[48:51], v[172:175], v[180:183], v[48:51]
	v_mfma_f32_16x16x32_bf16 v[36:39], v[164:167], v[188:191], v[36:39]
	v_mfma_f32_16x16x32_bf16 v[32:35], v[172:175], v[188:191], v[32:35]
	v_mfma_f32_16x16x32_bf16 v[20:23], v[164:167], v[198:201], v[20:23]
	v_mfma_f32_16x16x32_bf16 v[16:19], v[172:175], v[198:201], v[16:19]
	v_mfma_f32_16x16x32_bf16 v[4:7], v[164:167], v[206:209], v[4:7]
	v_mfma_f32_16x16x32_bf16 v[0:3], v[172:175], v[206:209], v[0:3]
	s_setprio 0
	s_barrier
	s_add_i32 s66, 0, 0x18000
	s_add_i32 s67, 0, 0x1c000
	v_add_u32_e32 v156, s66, v141
	v_add_u32_e32 v172, s67, v141
	ds_read_b128 v[144:147], v156
	ds_read_b128 v[148:151], v156 offset:1024
	ds_read_b128 v[152:155], v156 offset:2048
	ds_read_b128 v[156:159], v156 offset:3072
	ds_read_b128 v[160:163], v172
	ds_read_b128 v[164:167], v172 offset:1024
	ds_read_b128 v[168:171], v172 offset:2048
	ds_read_b128 v[172:175], v172 offset:3072
	s_add_u32 s12, s48, 0x80000
	s_addc_u32 s13, s49, 0
	s_mov_b32 m0, s53
	v_lshl_add_u64 v[216:217], s[12:13], 0, v[132:133]
	ds_read_b128 v[176:179], v143 offset:32768
	ds_read_b128 v[180:183], v143 offset:33792
	ds_read_b128 v[184:187], v143 offset:34816
	ds_read_b128 v[188:191], v143 offset:35840
	ds_read_b128 v[194:197], v143 offset:36864
	ds_read_b128 v[198:201], v143 offset:37888
	ds_read_b128 v[202:205], v143 offset:38912
	ds_read_b128 v[206:209], v143 offset:39936
	global_load_lds_dwordx4 v[216:217], off
	v_lshl_add_u64 v[216:217], s[12:13], 0, v[130:131]
	s_mov_b32 m0, s54
	s_nop 0
	global_load_lds_dwordx4 v[216:217], off
	s_waitcnt vmcnt(8)
	s_waitcnt lgkmcnt(0)
	s_barrier
	s_setprio 1
	s_waitcnt lgkmcnt(0)
	v_mfma_f32_16x16x32_bf16 v[124:127], v[144:147], v[176:179], v[124:127]
	v_mfma_f32_16x16x32_bf16 v[120:123], v[152:155], v[176:179], v[120:123]
	v_mfma_f32_16x16x32_bf16 v[108:111], v[144:147], v[184:187], v[108:111]
	v_mfma_f32_16x16x32_bf16 v[104:107], v[152:155], v[184:187], v[104:107]
	v_mfma_f32_16x16x32_bf16 v[92:95], v[144:147], v[194:197], v[92:95]
	v_mfma_f32_16x16x32_bf16 v[88:91], v[152:155], v[194:197], v[88:91]
	v_mfma_f32_16x16x32_bf16 v[76:79], v[144:147], v[202:205], v[76:79]
	v_mfma_f32_16x16x32_bf16 v[72:75], v[152:155], v[202:205], v[72:75]
	v_mfma_f32_16x16x32_bf16 v[124:127], v[148:151], v[180:183], v[124:127]
	v_mfma_f32_16x16x32_bf16 v[120:123], v[156:159], v[180:183], v[120:123]
	v_mfma_f32_16x16x32_bf16 v[108:111], v[148:151], v[188:191], v[108:111]
	v_mfma_f32_16x16x32_bf16 v[104:107], v[156:159], v[188:191], v[104:107]
	v_mfma_f32_16x16x32_bf16 v[92:95], v[148:151], v[198:201], v[92:95]
	v_mfma_f32_16x16x32_bf16 v[88:91], v[156:159], v[198:201], v[88:91]
	v_mfma_f32_16x16x32_bf16 v[76:79], v[148:151], v[206:209], v[76:79]
	v_mfma_f32_16x16x32_bf16 v[72:75], v[156:159], v[206:209], v[72:75]
	s_setprio 0
	s_setprio 1
	v_mfma_f32_16x16x32_bf16 v[116:119], v[160:163], v[176:179], v[116:119]
	v_mfma_f32_16x16x32_bf16 v[112:115], v[168:171], v[176:179], v[112:115]
	v_mfma_f32_16x16x32_bf16 v[100:103], v[160:163], v[184:187], v[100:103]
	v_mfma_f32_16x16x32_bf16 v[96:99], v[168:171], v[184:187], v[96:99]
	v_mfma_f32_16x16x32_bf16 v[84:87], v[160:163], v[194:197], v[84:87]
	v_mfma_f32_16x16x32_bf16 v[80:83], v[168:171], v[194:197], v[80:83]
	v_mfma_f32_16x16x32_bf16 v[68:71], v[160:163], v[202:205], v[68:71]
	v_mfma_f32_16x16x32_bf16 v[64:67], v[168:171], v[202:205], v[64:67]
	v_mfma_f32_16x16x32_bf16 v[116:119], v[164:167], v[180:183], v[116:119]
	v_mfma_f32_16x16x32_bf16 v[112:115], v[172:175], v[180:183], v[112:115]
	v_mfma_f32_16x16x32_bf16 v[100:103], v[164:167], v[188:191], v[100:103]
	v_mfma_f32_16x16x32_bf16 v[96:99], v[172:175], v[188:191], v[96:99]
	v_mfma_f32_16x16x32_bf16 v[84:87], v[164:167], v[198:201], v[84:87]
	v_mfma_f32_16x16x32_bf16 v[80:83], v[172:175], v[198:201], v[80:83]
	v_mfma_f32_16x16x32_bf16 v[68:71], v[164:167], v[206:209], v[68:71]
	v_mfma_f32_16x16x32_bf16 v[64:67], v[172:175], v[206:209], v[64:67]
	s_setprio 0
	s_barrier
; #define PG8_STAGE(bufoff, gbase, voff) do { _Pragma("unroll") for (int _i = 0; _i < 2; ++_i) \
;         __builtin_amdgcn_global_load_lds((const unsigned*)((const char*)(gbase) + (voff)[_i]), (PG8_LAS unsigned*)(lds + (bufoff) + ldsw + _i * 8192), 16, 0, 0); } while (0)
; #define PG8_LDA(dst, b, h) do { _Pragma("unroll") for (int m = 0; m < 4; ++m) _Pragma("unroll") for (int k = 0; k < 2; ++k) dst[m][k] = *(const PG8_LAS bf16x8*)(lds + PG8_SA(b, h) + aoff + m * 2048 + k * 1024); } while (0)
; #define PG8_LDB(dst, b, h) do { _Pragma("unroll") for (int n = 0; n < 2; ++n) _Pragma("unroll") for (int k = 0; k < 2; ++k) dst[n][k] = *(const PG8_LAS bf16x8*)(lds + PG8_SB(b, h) + boff + n * 2048 + k * 1024); } while (0)
; #define PG8_MMA(ai, bj, At, Bt) do { __builtin_amdgcn_s_setprio(1); _Pragma("unroll") for (int m = 0; m < 4; ++m) _Pragma("unroll") for (int n = 0; n < 2; ++n) _Pragma("unroll") for (int k = 0; k < 2; ++k) \
;         acc[ai][bj][m][n] = __builtin_amdgcn_mfma_f32_16x16x32_bf16(Bt[n][k], At[m][k], acc[ai][bj][m][n], 0, 0, 0); __builtin_amdgcn_s_setprio(0); } while (0)
; #define PG8_WAIT_V(n) asm volatile("s_waitcnt vmcnt(" #n ")" ::: "memory")
; #define PG8_WAIT_L(n) asm volatile("s_waitcnt lgkmcnt(" #n ")" ::: "memory")
; #define PG8_BAR __builtin_amdgcn_s_barrier()
; template <class Epi, class Sched, bool ALIGN_EPI = false, bool SP2 = false>
; __device__ __forceinline__ void gemm_phase(PG8_LAS unsigned char* lds, const Gemm g, const Sched& S, const Epi& E, const int tid_in) {
;     ...
;         for (int t = 0; t < nt; t += 2) {
;             const bool last = (t == nt - 2);
;             const char* a1 = cA + (size_t)(t + 1) * kstep;
;             const char* a2 = last ? nA : cA + (size_t)(t + 2) * kstep; const char* b2 = last ? nB : cB + (size_t)(t + 2) * kstep;
;             const char* a3 = a2 + kstep; const char* b3 = b2 + kstep;
;             if (last && has_next) S.a_ready(nxt);
;             if constexpr (SP2) {
;             PG8_LDB(B0, 0, 0); PG8_LDB(B1, 0, 1); PG8_SCHED; PG8_LDA(At, 0, 0); PG8_STAGE(PG8_SA(1, 1), a1 + hstepA, voffA);
;     ...
;             PG8_LDA(At, 1, 1); PG8_STAGE(PG8_SB(1, 0), b3, voffB); PG8_STAGE(PG8_SB(1, 1), b3 + hstepB, voffB); PG8_STAGE(PG8_SA(1, 0), a3, voffA);
;             PG8_WAIT_V(8); PG8_WAIT_L(0); PG8_BAR; PG8_MMA(1, 0, At, B0); PG8_MMA(1, 1, At, B1); PG8_BAR; PG8_SCHED;
	s_add_i32 s12, s66, s50
	v_lshl_add_u64 v[138:139], v[138:139], 0, s[26:27]
	s_mov_b32 m0, s12
	ds_read_b128 v[176:179], v143 offset:49152
	ds_read_b128 v[180:183], v143 offset:50176
	ds_read_b128 v[184:187], v143 offset:51200
	ds_read_b128 v[188:191], v143 offset:52224
	ds_read_b128 v[194:197], v143 offset:53248
	ds_read_b128 v[198:201], v143 offset:54272
	ds_read_b128 v[202:205], v143 offset:55296
	ds_read_b128 v[206:209], v143 offset:56320
	global_load_lds_dwordx4 v[138:139], off
	s_add_i32 m0, s12, 0x2000
	s_add_u32 s12, s46, 0x80080
	v_lshl_add_u64 v[138:139], v[210:211], 0, s[26:27]
	s_addc_u32 s13, s47, 0
	s_add_i32 s46, s67, s50
	global_load_lds_dwordx4 v[138:139], off
	v_lshl_add_u64 v[138:139], s[12:13], 0, v[192:193]
	s_mov_b32 m0, s46
	s_nop 0
	global_load_lds_dwordx4 v[138:139], off
	v_lshl_add_u64 v[138:139], s[12:13], 0, v[128:129]
	s_add_i32 m0, s46, 0x2000
	s_nop 0
	global_load_lds_dwordx4 v[138:139], off
	v_lshl_add_u64 v[138:139], v[212:213], 0, s[26:27]
	s_mov_b32 m0, s55
	s_nop 0
	global_load_lds_dwordx4 v[138:139], off
	v_lshl_add_u64 v[138:139], v[214:215], 0, s[26:27]
	s_mov_b32 m0, s56
	s_nop 0
	global_load_lds_dwordx4 v[138:139], off
	s_waitcnt vmcnt(8)
	s_waitcnt lgkmcnt(0)
	s_barrier
	s_setprio 1
	s_waitcnt lgkmcnt(0)
	v_mfma_f32_16x16x32_bf16 v[60:63], v[144:147], v[176:179], v[60:63]
	v_mfma_f32_16x16x32_bf16 v[56:59], v[152:155], v[176:179], v[56:59]
	v_mfma_f32_16x16x32_bf16 v[44:47], v[144:147], v[184:187], v[44:47]
	v_mfma_f32_16x16x32_bf16 v[40:43], v[152:155], v[184:187], v[40:43]
	v_mfma_f32_16x16x32_bf16 v[28:31], v[144:147], v[194:197], v[28:31]
	v_mfma_f32_16x16x32_bf16 v[24:27], v[152:155], v[194:197], v[24:27]
	v_mfma_f32_16x16x32_bf16 v[12:15], v[144:147], v[202:205], v[12:15]
	v_mfma_f32_16x16x32_bf16 v[8:11], v[152:155], v[202:205], v[8:11]
	v_mfma_f32_16x16x32_bf16 v[60:63], v[148:151], v[180:183], v[60:63]
	v_mfma_f32_16x16x32_bf16 v[56:59], v[156:159], v[180:183], v[56:59]
	v_mfma_f32_16x16x32_bf16 v[44:47], v[148:151], v[188:191], v[44:47]
	v_mfma_f32_16x16x32_bf16 v[40:43], v[156:159], v[188:191], v[40:43]
	v_mfma_f32_16x16x32_bf16 v[28:31], v[148:151], v[198:201], v[28:31]
	v_mfma_f32_16x16x32_bf16 v[24:27], v[156:159], v[198:201], v[24:27]
	v_mfma_f32_16x16x32_bf16 v[12:15], v[148:151], v[206:209], v[12:15]
	v_mfma_f32_16x16x32_bf16 v[8:11], v[156:159], v[206:209], v[8:11]
	s_setprio 0
	s_setprio 1
	v_mfma_f32_16x16x32_bf16 v[52:55], v[160:163], v[176:179], v[52:55]
	v_mfma_f32_16x16x32_bf16 v[48:51], v[168:171], v[176:179], v[48:51]
	v_mfma_f32_16x16x32_bf16 v[36:39], v[160:163], v[184:187], v[36:39]
	v_mfma_f32_16x16x32_bf16 v[32:35], v[168:171], v[184:187], v[32:35]
	v_mfma_f32_16x16x32_bf16 v[20:23], v[160:163], v[194:197], v[20:23]
	v_mfma_f32_16x16x32_bf16 v[16:19], v[168:171], v[194:197], v[16:19]
	v_mfma_f32_16x16x32_bf16 v[4:7], v[160:163], v[202:205], v[4:7]
	v_mfma_f32_16x16x32_bf16 v[0:3], v[168:171], v[202:205], v[0:3]
	v_mfma_f32_16x16x32_bf16 v[52:55], v[164:167], v[180:183], v[52:55]
	v_mfma_f32_16x16x32_bf16 v[48:51], v[172:175], v[180:183], v[48:51]
	v_mfma_f32_16x16x32_bf16 v[36:39], v[164:167], v[188:191], v[36:39]
	v_mfma_f32_16x16x32_bf16 v[32:35], v[172:175], v[188:191], v[32:35]
	v_mfma_f32_16x16x32_bf16 v[20:23], v[164:167], v[198:201], v[20:23]
	v_mfma_f32_16x16x32_bf16 v[16:19], v[172:175], v[198:201], v[16:19]
	v_mfma_f32_16x16x32_bf16 v[4:7], v[164:167], v[206:209], v[4:7]
	v_mfma_f32_16x16x32_bf16 v[0:3], v[172:175], v[206:209], v[0:3]
	s_setprio 0
	s_barrier
	s_add_i32 s65, s65, 2
	s_add_u32 s44, s44, 0x100
	s_addc_u32 s45, s45, 0
	s_add_u32 s63, s63, 0x100
	s_addc_u32 s64, s64, 0
	s_cmp_gt_u32 s65, 29
	.p2align 6
.LBB0_1359:
	s_add_u32 s12, s44, 0xfff80080
	s_addc_u32 s13, s45, -1
	s_add_i32 s66, 0, 0x10000
	s_cmp_eq_u32 s65, 28
	s_cselect_b32 s49, s39, s13
	s_cselect_b32 s48, s61, s12
	v_add_u32_e32 v138, s66, v141
	s_cselect_b32 s47, s37, s64
	s_cselect_b32 s46, s62, s63
	s_add_i32 s67, 0, 0x14000
	ds_read_b128 v[144:147], v138
	ds_read_b128 v[148:151], v138 offset:1024
	ds_read_b128 v[152:155], v138 offset:2048
	ds_read_b128 v[156:159], v138 offset:3072
	v_add_u32_e32 v138, s67, v141
	ds_read_b128 v[160:163], v138
	ds_read_b128 v[164:167], v138 offset:1024
	ds_read_b128 v[168:171], v138 offset:2048
	ds_read_b128 v[172:175], v138 offset:3072
	v_lshl_add_u64 v[138:139], s[44:45], 0, v[134:135]
	s_add_i32 m0, s51, 0xc000
	ds_read_b128 v[176:179], v143
	ds_read_b128 v[180:183], v143 offset:1024
	ds_read_b128 v[184:187], v143 offset:2048
	ds_read_b128 v[188:191], v143 offset:3072
	ds_read_b128 v[194:197], v143 offset:4096
	ds_read_b128 v[198:201], v143 offset:5120
	ds_read_b128 v[202:205], v143 offset:6144
	ds_read_b128 v[206:209], v143 offset:7168
	global_load_lds_dwordx4 v[138:139], off
	v_lshl_add_u64 v[138:139], s[44:45], 0, v[136:137]
	s_add_i32 m0, s51, 0xe000
	s_nop 0
	global_load_lds_dwordx4 v[138:139], off
	s_waitcnt vmcnt(8)
	s_waitcnt lgkmcnt(0)
	s_barrier
; #define PG8_STAGE(bufoff, gbase, voff) do { _Pragma("unroll") for (int _i = 0; _i < 2; ++_i) \
;         __builtin_amdgcn_global_load_lds((const unsigned*)((const char*)(gbase) + (voff)[_i]), (PG8_LAS unsigned*)(lds + (bufoff) + ldsw + _i * 8192), 16, 0, 0); } while (0)
; #define PG8_LDA(dst, b, h) do { _Pragma("unroll") for (int m = 0; m < 4; ++m) _Pragma("unroll") for (int k = 0; k < 2; ++k) dst[m][k] = *(const PG8_LAS bf16x8*)(lds + PG8_SA(b, h) + aoff + m * 2048 + k * 1024); } while (0)
; #define PG8_MMA(ai, bj, At, Bt) do { __builtin_amdgcn_s_setprio(1); _Pragma("unroll") for (int m = 0; m < 4; ++m) _Pragma("unroll") for (int n = 0; n < 2; ++n) _Pragma("unroll") for (int k = 0; k < 2; ++k) \
;         acc[ai][bj][m][n] = __builtin_amdgcn_mfma_f32_16x16x32_bf16(Bt[n][k], At[m][k], acc[ai][bj][m][n], 0, 0, 0); __builtin_amdgcn_s_setprio(0); } while (0)
; #define PG8_WAIT_V(n) asm volatile("s_waitcnt vmcnt(" #n ")" ::: "memory")
; #define PG8_WAIT_L(n) asm volatile("s_waitcnt lgkmcnt(" #n ")" ::: "memory")
; #define PG8_BAR __builtin_amdgcn_s_barrier()
; #define PG8_SCHED __builtin_amdgcn_sched_barrier(0)
; template <class Epi, class Sched, bool ALIGN_EPI = false, bool SP2 = false>
; __device__ __forceinline__ void gemm_phase(PG8_LAS unsigned char* lds, const Gemm g, const Sched& S, const Epi& E, const int tid_in) {
;     ...
;             PG8_WAIT_V(8); PG8_WAIT_L(0); PG8_BAR; PG8_MMA(0, 0, At, B0); PG8_MMA(0, 1, At, B1); PG8_BAR; PG8_SCHED;
;             PG8_LDA(At, 0, 1); PG8_STAGE(PG8_SB(0, 0), b2, voffB); PG8_STAGE(PG8_SB(0, 1), b2 + hstepB, voffB); PG8_STAGE(PG8_SA(0, 0), a2, voffA);
;             PG8_WAIT_V(8); PG8_WAIT_L(0); PG8_BAR; PG8_MMA(1, 0, At, B0); PG8_MMA(1, 1, At, B1); PG8_BAR; PG8_SCHED;
	s_setprio 1
	s_waitcnt lgkmcnt(0)
	v_mfma_f32_16x16x32_bf16 v[124:127], v[144:147], v[176:179], v[124:127]
	v_mfma_f32_16x16x32_bf16 v[120:123], v[152:155], v[176:179], v[120:123]
	v_mfma_f32_16x16x32_bf16 v[108:111], v[144:147], v[184:187], v[108:111]
	v_mfma_f32_16x16x32_bf16 v[104:107], v[152:155], v[184:187], v[104:107]
	v_mfma_f32_16x16x32_bf16 v[92:95], v[144:147], v[194:197], v[92:95]
	v_mfma_f32_16x16x32_bf16 v[88:91], v[152:155], v[194:197], v[88:91]
	v_mfma_f32_16x16x32_bf16 v[76:79], v[144:147], v[202:205], v[76:79]
	v_mfma_f32_16x16x32_bf16 v[72:75], v[152:155], v[202:205], v[72:75]
	v_mfma_f32_16x16x32_bf16 v[124:127], v[148:151], v[180:183], v[124:127]
	v_mfma_f32_16x16x32_bf16 v[120:123], v[156:159], v[180:183], v[120:123]
	v_mfma_f32_16x16x32_bf16 v[108:111], v[148:151], v[188:191], v[108:111]
	v_mfma_f32_16x16x32_bf16 v[104:107], v[156:159], v[188:191], v[104:107]
	v_mfma_f32_16x16x32_bf16 v[92:95], v[148:151], v[198:201], v[92:95]
	v_mfma_f32_16x16x32_bf16 v[88:91], v[156:159], v[198:201], v[88:91]
	v_mfma_f32_16x16x32_bf16 v[76:79], v[148:151], v[206:209], v[76:79]
	v_mfma_f32_16x16x32_bf16 v[72:75], v[156:159], v[206:209], v[72:75]
	v_mfma_f32_16x16x32_bf16 v[116:119], v[160:163], v[176:179], v[116:119]
	v_mfma_f32_16x16x32_bf16 v[112:115], v[168:171], v[176:179], v[112:115]
	v_mfma_f32_16x16x32_bf16 v[100:103], v[160:163], v[184:187], v[100:103]
	v_mfma_f32_16x16x32_bf16 v[96:99], v[168:171], v[184:187], v[96:99]
	v_mfma_f32_16x16x32_bf16 v[84:87], v[160:163], v[194:197], v[84:87]
	v_mfma_f32_16x16x32_bf16 v[80:83], v[168:171], v[194:197], v[80:83]
	v_mfma_f32_16x16x32_bf16 v[68:71], v[160:163], v[202:205], v[68:71]
	v_mfma_f32_16x16x32_bf16 v[64:67], v[168:171], v[202:205], v[64:67]
	v_mfma_f32_16x16x32_bf16 v[116:119], v[164:167], v[180:183], v[116:119]
	v_mfma_f32_16x16x32_bf16 v[112:115], v[172:175], v[180:183], v[112:115]
	v_mfma_f32_16x16x32_bf16 v[100:103], v[164:167], v[188:191], v[100:103]
	v_mfma_f32_16x16x32_bf16 v[96:99], v[172:175], v[188:191], v[96:99]
	v_mfma_f32_16x16x32_bf16 v[84:87], v[164:167], v[198:201], v[84:87]
	v_mfma_f32_16x16x32_bf16 v[80:83], v[172:175], v[198:201], v[80:83]
	v_mfma_f32_16x16x32_bf16 v[68:71], v[164:167], v[206:209], v[68:71]
	v_mfma_f32_16x16x32_bf16 v[64:67], v[172:175], v[206:209], v[64:67]
	s_setprio 0
	s_barrier
	s_add_i32 s12, s66, s50
	v_lshl_add_u64 v[138:139], s[46:47], 0, v[192:193]
	s_mov_b32 m0, s12
	ds_read_b128 v[176:179], v143 offset:16384
	ds_read_b128 v[180:183], v143 offset:17408
	ds_read_b128 v[184:187], v143 offset:18432
	ds_read_b128 v[188:191], v143 offset:19456
	ds_read_b128 v[194:197], v143 offset:20480
	ds_read_b128 v[198:201], v143 offset:21504
	ds_read_b128 v[202:205], v143 offset:22528
	ds_read_b128 v[206:209], v143 offset:23552
	global_load_lds_dwordx4 v[138:139], off
	s_add_i32 m0, s12, 0x2000
	s_add_u32 s12, s46, 0x80000
	v_lshl_add_u64 v[210:211], s[46:47], 0, v[128:129]
	s_addc_u32 s13, s47, 0
	s_add_i32 s66, s67, s50
	global_load_lds_dwordx4 v[210:211], off
	v_lshl_add_u64 v[212:213], s[12:13], 0, v[192:193]
	s_mov_b32 m0, s66
	v_lshl_add_u64 v[214:215], s[48:49], 0, v[130:131]
	global_load_lds_dwordx4 v[212:213], off
	v_lshl_add_u64 v[212:213], s[12:13], 0, v[128:129]
	s_add_i32 m0, s66, 0x2000
	s_nop 0
	global_load_lds_dwordx4 v[212:213], off
	v_lshl_add_u64 v[212:213], s[48:49], 0, v[132:133]
	s_mov_b32 m0, s51
	s_nop 0
	global_load_lds_dwordx4 v[212:213], off
	s_mov_b32 m0, s52
	s_nop 0
	global_load_lds_dwordx4 v[214:215], off
	s_waitcnt vmcnt(8)
	s_waitcnt lgkmcnt(0)
	s_barrier
	s_setprio 1
	s_waitcnt lgkmcnt(0)
	v_mfma_f32_16x16x32_bf16 v[60:63], v[144:147], v[176:179], v[60:63]
	v_mfma_f32_16x16x32_bf16 v[56:59], v[152:155], v[176:179], v[56:59]
	v_mfma_f32_16x16x32_bf16 v[44:47], v[144:147], v[184:187], v[44:47]
	v_mfma_f32_16x16x32_bf16 v[40:43], v[152:155], v[184:187], v[40:43]
	v_mfma_f32_16x16x32_bf16 v[28:31], v[144:147], v[194:197], v[28:31]
	v_mfma_f32_16x16x32_bf16 v[24:27], v[152:155], v[194:197], v[24:27]
	v_mfma_f32_16x16x32_bf16 v[12:15], v[144:147], v[202:205], v[12:15]
	v_mfma_f32_16x16x32_bf16 v[8:11], v[152:155], v[202:205], v[8:11]
	v_mfma_f32_16x16x32_bf16 v[60:63], v[148:151], v[180:183], v[60:63]
	v_mfma_f32_16x16x32_bf16 v[56:59], v[156:159], v[180:183], v[56:59]
	v_mfma_f32_16x16x32_bf16 v[44:47], v[148:151], v[188:191], v[44:47]
	v_mfma_f32_16x16x32_bf16 v[40:43], v[156:159], v[188:191], v[40:43]
	v_mfma_f32_16x16x32_bf16 v[28:31], v[148:151], v[198:201], v[28:31]
	v_mfma_f32_16x16x32_bf16 v[24:27], v[156:159], v[198:201], v[24:27]
	v_mfma_f32_16x16x32_bf16 v[12:15], v[148:151], v[206:209], v[12:15]
	v_mfma_f32_16x16x32_bf16 v[8:11], v[156:159], v[206:209], v[8:11]
	v_mfma_f32_16x16x32_bf16 v[52:55], v[160:163], v[176:179], v[52:55]
	v_mfma_f32_16x16x32_bf16 v[48:51], v[168:171], v[176:179], v[48:51]
	v_mfma_f32_16x16x32_bf16 v[36:39], v[160:163], v[184:187], v[36:39]
	v_mfma_f32_16x16x32_bf16 v[32:35], v[168:171], v[184:187], v[32:35]
	v_mfma_f32_16x16x32_bf16 v[20:23], v[160:163], v[194:197], v[20:23]
	v_mfma_f32_16x16x32_bf16 v[16:19], v[168:171], v[194:197], v[16:19]
	v_mfma_f32_16x16x32_bf16 v[4:7], v[160:163], v[202:205], v[4:7]
	v_mfma_f32_16x16x32_bf16 v[0:3], v[168:171], v[202:205], v[0:3]
	v_mfma_f32_16x16x32_bf16 v[52:55], v[164:167], v[180:183], v[52:55]
	v_mfma_f32_16x16x32_bf16 v[48:51], v[172:175], v[180:183], v[48:51]
	v_mfma_f32_16x16x32_bf16 v[36:39], v[164:167], v[188:191], v[36:39]
	v_mfma_f32_16x16x32_bf16 v[32:35], v[172:175], v[188:191], v[32:35]
	v_mfma_f32_16x16x32_bf16 v[20:23], v[164:167], v[198:201], v[20:23]
	v_mfma_f32_16x16x32_bf16 v[16:19], v[172:175], v[198:201], v[16:19]
	v_mfma_f32_16x16x32_bf16 v[4:7], v[164:167], v[206:209], v[4:7]
	v_mfma_f32_16x16x32_bf16 v[0:3], v[172:175], v[206:209], v[0:3]
	s_setprio 0
	s_barrier
; #define PG8_STAGE(bufoff, gbase, voff) do { _Pragma("unroll") for (int _i = 0; _i < 2; ++_i) \
;         __builtin_amdgcn_global_load_lds((const unsigned*)((const char*)(gbase) + (voff)[_i]), (PG8_LAS unsigned*)(lds + (bufoff) + ldsw + _i * 8192), 16, 0, 0); } while (0)
; #define PG8_LDA(dst, b, h) do { _Pragma("unroll") for (int m = 0; m < 4; ++m) _Pragma("unroll") for (int k = 0; k < 2; ++k) dst[m][k] = *(const PG8_LAS bf16x8*)(lds + PG8_SA(b, h) + aoff + m * 2048 + k * 1024); } while (0)
; #define PG8_LDB(dst, b, h) do { _Pragma("unroll") for (int n = 0; n < 2; ++n) _Pragma("unroll") for (int k = 0; k < 2; ++k) dst[n][k] = *(const PG8_LAS bf16x8*)(lds + PG8_SB(b, h) + boff + n * 2048 + k * 1024); } while (0)
; #define PG8_MMA(ai, bj, At, Bt) do { __builtin_amdgcn_s_setprio(1); _Pragma("unroll") for (int m = 0; m < 4; ++m) _Pragma("unroll") for (int n = 0; n < 2; ++n) _Pragma("unroll") for (int k = 0; k < 2; ++k) \
;         acc[ai][bj][m][n] = __builtin_amdgcn_mfma_f32_16x16x32_bf16(Bt[n][k], At[m][k], acc[ai][bj][m][n], 0, 0, 0); __builtin_amdgcn_s_setprio(0); } while (0)
; #define PG8_WAIT_V(n) asm volatile("s_waitcnt vmcnt(" #n ")" ::: "memory")
; #define PG8_WAIT_L(n) asm volatile("s_waitcnt lgkmcnt(" #n ")" ::: "memory")
; #define PG8_BAR __builtin_amdgcn_s_barrier()
; #define PG8_SCHED __builtin_amdgcn_sched_barrier(0)
; template <class Epi, class Sched, bool ALIGN_EPI = false, bool SP2 = false>
; __device__ __forceinline__ void gemm_phase(PG8_LAS unsigned char* lds, const Gemm g, const Sched& S, const Epi& E, const int tid_in) {
;     ...
;             PG8_LDB(B0, 1, 0); PG8_LDB(B1, 1, 1); PG8_SCHED; PG8_LDA(At, 1, 0); PG8_STAGE(PG8_SA(0, 1), a2 + hstepA, voffA);
;             PG8_WAIT_V(8); PG8_WAIT_L(0); PG8_BAR; PG8_MMA(0, 0, At, B0); PG8_MMA(0, 1, At, B1); PG8_BAR; PG8_SCHED;
	s_add_i32 s66, 0, 0x18000
	s_add_i32 s67, 0, 0x1c000
	v_add_u32_e32 v156, s66, v141
	v_add_u32_e32 v172, s67, v141
	ds_read_b128 v[144:147], v156
	ds_read_b128 v[148:151], v156 offset:1024
	ds_read_b128 v[152:155], v156 offset:2048
	ds_read_b128 v[156:159], v156 offset:3072
	ds_read_b128 v[160:163], v172
	ds_read_b128 v[164:167], v172 offset:1024
	ds_read_b128 v[168:171], v172 offset:2048
	ds_read_b128 v[172:175], v172 offset:3072
	s_add_u32 s12, s48, 0x80000
	s_addc_u32 s13, s49, 0
	s_mov_b32 m0, s53
	v_lshl_add_u64 v[216:217], s[12:13], 0, v[132:133]
	ds_read_b128 v[176:179], v143 offset:32768
	ds_read_b128 v[180:183], v143 offset:33792
	ds_read_b128 v[184:187], v143 offset:34816
	ds_read_b128 v[188:191], v143 offset:35840
	ds_read_b128 v[194:197], v143 offset:36864
	ds_read_b128 v[198:201], v143 offset:37888
	ds_read_b128 v[202:205], v143 offset:38912
	ds_read_b128 v[206:209], v143 offset:39936
	global_load_lds_dwordx4 v[216:217], off
	v_lshl_add_u64 v[216:217], s[12:13], 0, v[130:131]
	s_mov_b32 m0, s54
	s_nop 0
	global_load_lds_dwordx4 v[216:217], off
	s_waitcnt vmcnt(8)
	s_waitcnt lgkmcnt(0)
	s_barrier
	s_setprio 1
	s_waitcnt lgkmcnt(0)
	v_mfma_f32_16x16x32_bf16 v[124:127], v[144:147], v[176:179], v[124:127]
	v_mfma_f32_16x16x32_bf16 v[120:123], v[152:155], v[176:179], v[120:123]
	v_mfma_f32_16x16x32_bf16 v[108:111], v[144:147], v[184:187], v[108:111]
	v_mfma_f32_16x16x32_bf16 v[104:107], v[152:155], v[184:187], v[104:107]
	v_mfma_f32_16x16x32_bf16 v[92:95], v[144:147], v[194:197], v[92:95]
	v_mfma_f32_16x16x32_bf16 v[88:91], v[152:155], v[194:197], v[88:91]
	v_mfma_f32_16x16x32_bf16 v[76:79], v[144:147], v[202:205], v[76:79]
	v_mfma_f32_16x16x32_bf16 v[72:75], v[152:155], v[202:205], v[72:75]
	v_mfma_f32_16x16x32_bf16 v[124:127], v[148:151], v[180:183], v[124:127]
	v_mfma_f32_16x16x32_bf16 v[120:123], v[156:159], v[180:183], v[120:123]
	v_mfma_f32_16x16x32_bf16 v[108:111], v[148:151], v[188:191], v[108:111]
	v_mfma_f32_16x16x32_bf16 v[104:107], v[156:159], v[188:191], v[104:107]
	v_mfma_f32_16x16x32_bf16 v[92:95], v[148:151], v[198:201], v[92:95]
	v_mfma_f32_16x16x32_bf16 v[88:91], v[156:159], v[198:201], v[88:91]
	v_mfma_f32_16x16x32_bf16 v[76:79], v[148:151], v[206:209], v[76:79]
	v_mfma_f32_16x16x32_bf16 v[72:75], v[156:159], v[206:209], v[72:75]
	v_mfma_f32_16x16x32_bf16 v[116:119], v[160:163], v[176:179], v[116:119]
	v_mfma_f32_16x16x32_bf16 v[112:115], v[168:171], v[176:179], v[112:115]
	v_mfma_f32_16x16x32_bf16 v[100:103], v[160:163], v[184:187], v[100:103]
	v_mfma_f32_16x16x32_bf16 v[96:99], v[168:171], v[184:187], v[96:99]
	v_mfma_f32_16x16x32_bf16 v[84:87], v[160:163], v[194:197], v[84:87]
	v_mfma_f32_16x16x32_bf16 v[80:83], v[168:171], v[194:197], v[80:83]
	v_mfma_f32_16x16x32_bf16 v[68:71], v[160:163], v[202:205], v[68:71]
	v_mfma_f32_16x16x32_bf16 v[64:67], v[168:171], v[202:205], v[64:67]
	v_mfma_f32_16x16x32_bf16 v[116:119], v[164:167], v[180:183], v[116:119]
	v_mfma_f32_16x16x32_bf16 v[112:115], v[172:175], v[180:183], v[112:115]
	v_mfma_f32_16x16x32_bf16 v[100:103], v[164:167], v[188:191], v[100:103]
	v_mfma_f32_16x16x32_bf16 v[96:99], v[172:175], v[188:191], v[96:99]
	v_mfma_f32_16x16x32_bf16 v[84:87], v[164:167], v[198:201], v[84:87]
	v_mfma_f32_16x16x32_bf16 v[80:83], v[172:175], v[198:201], v[80:83]
	v_mfma_f32_16x16x32_bf16 v[68:71], v[164:167], v[206:209], v[68:71]
	v_mfma_f32_16x16x32_bf16 v[64:67], v[172:175], v[206:209], v[64:67]
	s_setprio 0
	s_barrier
; #define PG8_STAGE(bufoff, gbase, voff) do { _Pragma("unroll") for (int _i = 0; _i < 2; ++_i) \
;         __builtin_amdgcn_global_load_lds((const unsigned*)((const char*)(gbase) + (voff)[_i]), (PG8_LAS unsigned*)(lds + (bufoff) + ldsw + _i * 8192), 16, 0, 0); } while (0)
; #define PG8_LDA(dst, b, h) do { _Pragma("unroll") for (int m = 0; m < 4; ++m) _Pragma("unroll") for (int k = 0; k < 2; ++k) dst[m][k] = *(const PG8_LAS bf16x8*)(lds + PG8_SA(b, h) + aoff + m * 2048 + k * 1024); } while (0)
; #define PG8_MMA(ai, bj, At, Bt) do { __builtin_amdgcn_s_setprio(1); _Pragma("unroll") for (int m = 0; m < 4; ++m) _Pragma("unroll") for (int n = 0; n < 2; ++n) _Pragma("unroll") for (int k = 0; k < 2; ++k) \
;         acc[ai][bj][m][n] = __builtin_amdgcn_mfma_f32_16x16x32_bf16(Bt[n][k], At[m][k], acc[ai][bj][m][n], 0, 0, 0); __builtin_amdgcn_s_setprio(0); } while (0)
; #define PG8_WAIT_V(n) asm volatile("s_waitcnt vmcnt(" #n ")" ::: "memory")
; #define PG8_WAIT_L(n) asm volatile("s_waitcnt lgkmcnt(" #n ")" ::: "memory")
; #define PG8_BAR __builtin_amdgcn_s_barrier()
; #define PG8_SCHED __builtin_amdgcn_sched_barrier(0)
; template <class Epi, class Sched, bool ALIGN_EPI = false, bool SP2 = false>
; __device__ __forceinline__ void gemm_phase(PG8_LAS unsigned char* lds, const Gemm g, const Sched& S, const Epi& E, const int tid_in) {
;     ...
;         for (int t = 0; t < nt; t += 2) {
;             const bool last = (t == nt - 2);
;             const char* a1 = cA + (size_t)(t + 1) * kstep;
;             const char* a2 = last ? nA : cA + (size_t)(t + 2) * kstep; const char* b2 = last ? nB : cB + (size_t)(t + 2) * kstep;
;             const char* a3 = a2 + kstep; const char* b3 = b2 + kstep;
;             if (last && has_next) S.a_ready(nxt);
;     ...
;             PG8_LDA(At, 1, 1); PG8_STAGE(PG8_SB(1, 0), b3, voffB); PG8_STAGE(PG8_SB(1, 1), b3 + hstepB, voffB); PG8_STAGE(PG8_SA(1, 0), a3, voffA);
;             PG8_WAIT_V(8); PG8_WAIT_L(0); PG8_BAR; PG8_MMA(1, 0, At, B0); PG8_MMA(1, 1, At, B1); PG8_BAR; PG8_SCHED;
	s_add_i32 s12, s66, s50
	v_lshl_add_u64 v[138:139], v[138:139], 0, s[26:27]
	s_mov_b32 m0, s12
	ds_read_b128 v[176:179], v143 offset:49152
	ds_read_b128 v[180:183], v143 offset:50176
	ds_read_b128 v[184:187], v143 offset:51200
	ds_read_b128 v[188:191], v143 offset:52224
	ds_read_b128 v[194:197], v143 offset:53248
	ds_read_b128 v[198:201], v143 offset:54272
	ds_read_b128 v[202:205], v143 offset:55296
	ds_read_b128 v[206:209], v143 offset:56320
	global_load_lds_dwordx4 v[138:139], off
	s_add_i32 m0, s12, 0x2000
	s_add_u32 s12, s46, 0x80080
	v_lshl_add_u64 v[138:139], v[210:211], 0, s[26:27]
	s_addc_u32 s13, s47, 0
	s_add_i32 s46, s67, s50
	global_load_lds_dwordx4 v[138:139], off
	v_lshl_add_u64 v[138:139], s[12:13], 0, v[192:193]
	s_mov_b32 m0, s46
	s_nop 0
	global_load_lds_dwordx4 v[138:139], off
	v_lshl_add_u64 v[138:139], s[12:13], 0, v[128:129]
	s_add_i32 m0, s46, 0x2000
	s_nop 0
	global_load_lds_dwordx4 v[138:139], off
	v_lshl_add_u64 v[138:139], v[212:213], 0, s[26:27]
	s_mov_b32 m0, s55
	s_nop 0
	global_load_lds_dwordx4 v[138:139], off
	v_lshl_add_u64 v[138:139], v[214:215], 0, s[26:27]
	s_mov_b32 m0, s56
	s_nop 0
	global_load_lds_dwordx4 v[138:139], off
	s_waitcnt vmcnt(8)
	s_waitcnt lgkmcnt(0)
	s_barrier
	s_setprio 1
	s_waitcnt lgkmcnt(0)
	v_mfma_f32_16x16x32_bf16 v[60:63], v[144:147], v[176:179], v[60:63]
	v_mfma_f32_16x16x32_bf16 v[56:59], v[152:155], v[176:179], v[56:59]
	v_mfma_f32_16x16x32_bf16 v[44:47], v[144:147], v[184:187], v[44:47]
	v_mfma_f32_16x16x32_bf16 v[40:43], v[152:155], v[184:187], v[40:43]
	v_mfma_f32_16x16x32_bf16 v[28:31], v[144:147], v[194:197], v[28:31]
	v_mfma_f32_16x16x32_bf16 v[24:27], v[152:155], v[194:197], v[24:27]
	v_mfma_f32_16x16x32_bf16 v[12:15], v[144:147], v[202:205], v[12:15]
	v_mfma_f32_16x16x32_bf16 v[8:11], v[152:155], v[202:205], v[8:11]
	v_mfma_f32_16x16x32_bf16 v[60:63], v[148:151], v[180:183], v[60:63]
	v_mfma_f32_16x16x32_bf16 v[56:59], v[156:159], v[180:183], v[56:59]
	v_mfma_f32_16x16x32_bf16 v[44:47], v[148:151], v[188:191], v[44:47]
	v_mfma_f32_16x16x32_bf16 v[40:43], v[156:159], v[188:191], v[40:43]
	v_mfma_f32_16x16x32_bf16 v[28:31], v[148:151], v[198:201], v[28:31]
	v_mfma_f32_16x16x32_bf16 v[24:27], v[156:159], v[198:201], v[24:27]
	v_mfma_f32_16x16x32_bf16 v[12:15], v[148:151], v[206:209], v[12:15]
	v_mfma_f32_16x16x32_bf16 v[8:11], v[156:159], v[206:209], v[8:11]
	v_mfma_f32_16x16x32_bf16 v[52:55], v[160:163], v[176:179], v[52:55]
	v_mfma_f32_16x16x32_bf16 v[48:51], v[168:171], v[176:179], v[48:51]
	v_mfma_f32_16x16x32_bf16 v[36:39], v[160:163], v[184:187], v[36:39]
	v_mfma_f32_16x16x32_bf16 v[32:35], v[168:171], v[184:187], v[32:35]
	v_mfma_f32_16x16x32_bf16 v[20:23], v[160:163], v[194:197], v[20:23]
	v_mfma_f32_16x16x32_bf16 v[16:19], v[168:171], v[194:197], v[16:19]
	v_mfma_f32_16x16x32_bf16 v[4:7], v[160:163], v[202:205], v[4:7]
	v_mfma_f32_16x16x32_bf16 v[0:3], v[168:171], v[202:205], v[0:3]
	v_mfma_f32_16x16x32_bf16 v[52:55], v[164:167], v[180:183], v[52:55]
	v_mfma_f32_16x16x32_bf16 v[48:51], v[172:175], v[180:183], v[48:51]
	v_mfma_f32_16x16x32_bf16 v[36:39], v[164:167], v[188:191], v[36:39]
	v_mfma_f32_16x16x32_bf16 v[32:35], v[172:175], v[188:191], v[32:35]
	v_mfma_f32_16x16x32_bf16 v[20:23], v[164:167], v[198:201], v[20:23]
	v_mfma_f32_16x16x32_bf16 v[16:19], v[172:175], v[198:201], v[16:19]
	v_mfma_f32_16x16x32_bf16 v[4:7], v[164:167], v[206:209], v[4:7]
	v_mfma_f32_16x16x32_bf16 v[0:3], v[172:175], v[206:209], v[0:3]
	s_setprio 0
	s_barrier
	s_add_i32 s65, s65, 2
	s_add_u32 s44, s44, 0x100
	s_addc_u32 s45, s45, 0
	s_add_u32 s63, s63, 0x100
	s_addc_u32 s64, s64, 0
	s_cmp_gt_u32 s65, 29
	s_cbranch_scc0 .LBB0_1359
	s_and_b64 vcc, exec, s[30:31]
	s_cbranch_vccz .LBB0_1362
	s_barrier

; #define PG8_STAGE(bufoff, gbase, voff) do { _Pragma("unroll") for (int _i = 0; _i < 2; ++_i) \
;         __builtin_amdgcn_global_load_lds((const unsigned*)((const char*)(gbase) + (voff)[_i]), (PG8_LAS unsigned*)(lds + (bufoff) + ldsw + _i * 8192), 16, 0, 0); } while (0)
; #define PG8_LDA(dst, b, h) do { _Pragma("unroll") for (int m = 0; m < 4; ++m) _Pragma("unroll") for (int k = 0; k < 2; ++k) dst[m][k] = *(const PG8_LAS bf16x8*)(lds + PG8_SA(b, h) + aoff + m * 2048 + k * 1024); } while (0)
; #define PG8_LDB(dst, b, h) do { _Pragma("unroll") for (int n = 0; n < 2; ++n) _Pragma("unroll") for (int k = 0; k < 2; ++k) dst[n][k] = *(const PG8_LAS bf16x8*)(lds + PG8_SB(b, h) + boff + n * 2048 + k * 1024); } while (0)
; #define PG8_MMA(ai, bj, At, Bt) do { __builtin_amdgcn_s_setprio(1); _Pragma("unroll") for (int m = 0; m < 4; ++m) _Pragma("unroll") for (int n = 0; n < 2; ++n) _Pragma("unroll") for (int k = 0; k < 2; ++k) \
;         acc[ai][bj][m][n] = __builtin_amdgcn_mfma_f32_16x16x32_bf16(Bt[n][k], At[m][k], acc[ai][bj][m][n], 0, 0, 0); __builtin_amdgcn_s_setprio(0); } while (0)
; template <class Epi, class Sched, bool ALIGN_EPI = false, bool SP2 = false>
; __device__ __forceinline__ void gemm_phase(PG8_LAS unsigned char* lds, const Gemm g, const Sched& S, const Epi& E, const int tid_in) {
;     ...
;         const bool has_next = S.next(ui + 1, nxt);
;         const char* nA = has_next ? (const char*)g.A + (size_t)nxt.pm * tstepA : cA; const char* nB = has_next ? (const char*)g.Bt + (size_t)nxt.pn * tstepB : cB;
;         for (int t = 0; t < nt; t += 2) {
;             const bool last = (t == nt - 2);
;             const char* a1 = cA + (size_t)(t + 1) * kstep;
;             const char* a2 = last ? nA : cA + (size_t)(t + 2) * kstep; const char* b2 = last ? nB : cB + (size_t)(t + 2) * kstep;
;             const char* a3 = a2 + kstep; const char* b3 = b2 + kstep;
;             if (last && has_next) S.a_ready(nxt);
;             if constexpr (SP2) {
;             PG8_LDB(B0, 0, 0); PG8_LDB(B1, 0, 1); PG8_SCHED; PG8_LDA(At, 0, 0); PG8_STAGE(PG8_SA(1, 1), a1 + hstepA, voffA);
;             PG8_WAIT_V(8); PG8_WAIT_L(0); PG8_BAR; PG8_MMA(0, 0, At, B0); PG8_MMA(0, 1, At, B1); PG8_BAR; PG8_SCHED;
;             PG8_LDA(At, 0, 1); PG8_STAGE(PG8_SB(0, 0), b2, voffB); PG8_STAGE(PG8_SB(0, 1), b2 + hstepB, voffB); PG8_STAGE(PG8_SA(0, 0), a2, voffA);
.LBB0_1433:
	s_ashr_i32 s39, s38, 31
	s_lshl_b64 s[12:13], s[38:39], 22
	s_add_u32 s42, s15, s12
	s_addc_u32 s43, s18, s13
	s_and_b64 s[12:13], s[36:37], exec
	s_cselect_b32 s39, s43, s47
	s_cselect_b32 s62, s42, s46
	s_add_u32 s63, s46, 0x100
	s_addc_u32 s64, s47, 0
	s_mov_b32 s65, -2
	s_add_u32 s36, s44, 0x100
	s_addc_u32 s37, s45, 0
	s_add_i32 s12, 0, 0x10000
	s_cmp_eq_u32 s65, 64
	s_cselect_b32 s49, s41, s37
	s_cselect_b32 s48, s40, s36
	s_cselect_b32 s47, s39, s64
	s_cselect_b32 s46, s62, s63
	s_add_i32 s66, 0, 0x14000
	v_add_u32_e32 v140, s12, v247
	v_add_u32_e32 v156, s66, v247
	ds_read_b128 v[128:131], v140
	ds_read_b128 v[132:135], v140 offset:1024
	ds_read_b128 v[136:139], v140 offset:2048
	ds_read_b128 v[140:143], v140 offset:3072
	ds_read_b128 v[144:147], v156
	ds_read_b128 v[148:151], v156 offset:1024
	ds_read_b128 v[152:155], v156 offset:2048
	ds_read_b128 v[156:159], v156 offset:3072
	v_lshl_add_u64 v[204:205], s[44:45], 0, v[190:191]
	s_add_i32 m0, s51, 0xc000
	ds_read_b128 v[160:163], v249
	ds_read_b128 v[164:167], v249 offset:1024
	ds_read_b128 v[168:171], v249 offset:2048
	ds_read_b128 v[172:175], v249 offset:3072
	ds_read_b128 v[176:179], v249 offset:4096
	ds_read_b128 v[180:183], v249 offset:5120
	ds_read_b128 v[194:197], v249 offset:6144
	ds_read_b128 v[200:203], v249 offset:7168
	global_load_lds_dwordx4 v[204:205], off
	v_lshl_add_u64 v[204:205], s[44:45], 0, v[198:199]
	s_add_i32 m0, s51, 0xe000
	s_nop 0
	global_load_lds_dwordx4 v[204:205], off
	s_waitcnt vmcnt(8)
	s_waitcnt lgkmcnt(0)
	s_barrier
	s_setprio 1
	s_waitcnt lgkmcnt(0)
	v_mfma_f32_16x16x32_bf16 v[124:127], v[128:131], v[160:163], 0
	v_mfma_f32_16x16x32_bf16 v[120:123], v[136:139], v[160:163], 0
	v_mfma_f32_16x16x32_bf16 v[108:111], v[128:131], v[168:171], 0
	v_mfma_f32_16x16x32_bf16 v[104:107], v[136:139], v[168:171], 0
	v_mfma_f32_16x16x32_bf16 v[96:99], v[128:131], v[176:179], 0
	v_mfma_f32_16x16x32_bf16 v[88:91], v[136:139], v[176:179], 0
	v_mfma_f32_16x16x32_bf16 v[80:83], v[128:131], v[194:197], 0
	v_mfma_f32_16x16x32_bf16 v[72:75], v[136:139], v[194:197], 0
	v_mfma_f32_16x16x32_bf16 v[124:127], v[132:135], v[164:167], v[124:127]
	v_mfma_f32_16x16x32_bf16 v[120:123], v[140:143], v[164:167], v[120:123]
	v_mfma_f32_16x16x32_bf16 v[108:111], v[132:135], v[172:175], v[108:111]
	v_mfma_f32_16x16x32_bf16 v[104:107], v[140:143], v[172:175], v[104:107]
	v_mfma_f32_16x16x32_bf16 v[96:99], v[132:135], v[180:183], v[96:99]
	v_mfma_f32_16x16x32_bf16 v[88:91], v[140:143], v[180:183], v[88:91]
	v_mfma_f32_16x16x32_bf16 v[80:83], v[132:135], v[200:203], v[80:83]
	v_mfma_f32_16x16x32_bf16 v[72:75], v[140:143], v[200:203], v[72:75]
	s_setprio 0
	s_setprio 1
	v_mfma_f32_16x16x32_bf16 v[116:119], v[144:147], v[160:163], 0
	v_mfma_f32_16x16x32_bf16 v[112:115], v[152:155], v[160:163], 0
	v_mfma_f32_16x16x32_bf16 v[100:103], v[144:147], v[168:171], 0
	v_mfma_f32_16x16x32_bf16 v[92:95], v[152:155], v[168:171], 0
	v_mfma_f32_16x16x32_bf16 v[84:87], v[144:147], v[176:179], 0
	v_mfma_f32_16x16x32_bf16 v[76:79], v[152:155], v[176:179], 0
	v_mfma_f32_16x16x32_bf16 v[68:71], v[144:147], v[194:197], 0
	v_mfma_f32_16x16x32_bf16 v[64:67], v[152:155], v[194:197], 0
	v_mfma_f32_16x16x32_bf16 v[116:119], v[148:151], v[164:167], v[116:119]
	v_mfma_f32_16x16x32_bf16 v[112:115], v[156:159], v[164:167], v[112:115]
	v_mfma_f32_16x16x32_bf16 v[100:103], v[148:151], v[172:175], v[100:103]
	v_mfma_f32_16x16x32_bf16 v[92:95], v[156:159], v[172:175], v[92:95]
	v_mfma_f32_16x16x32_bf16 v[84:87], v[148:151], v[180:183], v[84:87]
	v_mfma_f32_16x16x32_bf16 v[76:79], v[156:159], v[180:183], v[76:79]
	v_mfma_f32_16x16x32_bf16 v[68:71], v[148:151], v[200:203], v[68:71]
	v_mfma_f32_16x16x32_bf16 v[64:67], v[156:159], v[200:203], v[64:67]
	s_setprio 0
	s_barrier
	s_add_i32 s12, s12, s50
	v_lshl_add_u64 v[204:205], s[46:47], 0, v[192:193]
	s_mov_b32 m0, s12
	ds_read_b128 v[160:163], v249 offset:16384
	ds_read_b128 v[164:167], v249 offset:17408
	ds_read_b128 v[168:171], v249 offset:18432
	ds_read_b128 v[172:175], v249 offset:19456
	ds_read_b128 v[176:179], v249 offset:20480
	ds_read_b128 v[180:183], v249 offset:21504
	ds_read_b128 v[194:197], v249 offset:22528
	ds_read_b128 v[200:203], v249 offset:23552
	global_load_lds_dwordx4 v[204:205], off
	s_add_i32 m0, s12, 0x2000
	s_add_u32 s12, s46, 0x200000
	v_lshl_add_u64 v[206:207], s[46:47], 0, v[184:185]
	s_addc_u32 s13, s47, 0
	s_add_i32 s44, s66, s50
	global_load_lds_dwordx4 v[206:207], off
	v_lshl_add_u64 v[208:209], s[12:13], 0, v[192:193]
	s_mov_b32 m0, s44
	v_lshl_add_u64 v[210:211], s[48:49], 0, v[186:187]
	global_load_lds_dwordx4 v[208:209], off
	v_lshl_add_u64 v[208:209], s[12:13], 0, v[184:185]
	s_add_i32 m0, s44, 0x2000
	s_nop 0
	global_load_lds_dwordx4 v[208:209], off
	v_lshl_add_u64 v[208:209], s[48:49], 0, v[188:189]
	s_mov_b32 m0, s51
	s_nop 0
	global_load_lds_dwordx4 v[208:209], off
	s_mov_b32 m0, s52
	s_nop 0
	global_load_lds_dwordx4 v[210:211], off
	s_waitcnt vmcnt(8)
	s_waitcnt lgkmcnt(0)
	s_barrier
; #define PG8_STAGE(bufoff, gbase, voff) do { _Pragma("unroll") for (int _i = 0; _i < 2; ++_i) \
;         __builtin_amdgcn_global_load_lds((const unsigned*)((const char*)(gbase) + (voff)[_i]), (PG8_LAS unsigned*)(lds + (bufoff) + ldsw + _i * 8192), 16, 0, 0); } while (0)
; #define PG8_LDA(dst, b, h) do { _Pragma("unroll") for (int m = 0; m < 4; ++m) _Pragma("unroll") for (int k = 0; k < 2; ++k) dst[m][k] = *(const PG8_LAS bf16x8*)(lds + PG8_SA(b, h) + aoff + m * 2048 + k * 1024); } while (0)
; #define PG8_LDB(dst, b, h) do { _Pragma("unroll") for (int n = 0; n < 2; ++n) _Pragma("unroll") for (int k = 0; k < 2; ++k) dst[n][k] = *(const PG8_LAS bf16x8*)(lds + PG8_SB(b, h) + boff + n * 2048 + k * 1024); } while (0)
; #define PG8_MMA(ai, bj, At, Bt) do { __builtin_amdgcn_s_setprio(1); _Pragma("unroll") for (int m = 0; m < 4; ++m) _Pragma("unroll") for (int n = 0; n < 2; ++n) _Pragma("unroll") for (int k = 0; k < 2; ++k) \
;         acc[ai][bj][m][n] = __builtin_amdgcn_mfma_f32_16x16x32_bf16(Bt[n][k], At[m][k], acc[ai][bj][m][n], 0, 0, 0); __builtin_amdgcn_s_setprio(0); } while (0)
; #define PG8_WAIT_V(n) asm volatile("s_waitcnt vmcnt(" #n ")" ::: "memory")
; #define PG8_WAIT_L(n) asm volatile("s_waitcnt lgkmcnt(" #n ")" ::: "memory")
; #define PG8_BAR __builtin_amdgcn_s_barrier()
; #define PG8_SCHED __builtin_amdgcn_sched_barrier(0)
; template <class Epi, class Sched, bool ALIGN_EPI = false, bool SP2 = false>
; __device__ __forceinline__ void gemm_phase(PG8_LAS unsigned char* lds, const Gemm g, const Sched& S, const Epi& E, const int tid_in) {
;     ...
;             PG8_WAIT_V(8); PG8_WAIT_L(0); PG8_BAR; PG8_MMA(1, 0, At, B0); PG8_MMA(1, 1, At, B1); PG8_BAR; PG8_SCHED;
;             PG8_LDB(B0, 1, 0); PG8_LDB(B1, 1, 1); PG8_SCHED; PG8_LDA(At, 1, 0); PG8_STAGE(PG8_SA(0, 1), a2 + hstepA, voffA);
;             PG8_WAIT_V(8); PG8_WAIT_L(0); PG8_BAR; PG8_MMA(0, 0, At, B0); PG8_MMA(0, 1, At, B1); PG8_BAR; PG8_SCHED;
	s_setprio 1
	s_waitcnt lgkmcnt(0)
	v_mfma_f32_16x16x32_bf16 v[60:63], v[128:131], v[160:163], 0
	v_mfma_f32_16x16x32_bf16 v[56:59], v[136:139], v[160:163], 0
	v_mfma_f32_16x16x32_bf16 v[48:51], v[128:131], v[168:171], 0
	v_mfma_f32_16x16x32_bf16 v[40:43], v[136:139], v[168:171], 0
	v_mfma_f32_16x16x32_bf16 v[32:35], v[128:131], v[176:179], 0
	v_mfma_f32_16x16x32_bf16 v[24:27], v[136:139], v[176:179], 0
	v_mfma_f32_16x16x32_bf16 v[16:19], v[128:131], v[194:197], 0
	v_mfma_f32_16x16x32_bf16 v[8:11], v[136:139], v[194:197], 0
	v_mfma_f32_16x16x32_bf16 v[60:63], v[132:135], v[164:167], v[60:63]
	v_mfma_f32_16x16x32_bf16 v[56:59], v[140:143], v[164:167], v[56:59]
	v_mfma_f32_16x16x32_bf16 v[48:51], v[132:135], v[172:175], v[48:51]
	v_mfma_f32_16x16x32_bf16 v[40:43], v[140:143], v[172:175], v[40:43]
	v_mfma_f32_16x16x32_bf16 v[32:35], v[132:135], v[180:183], v[32:35]
	v_mfma_f32_16x16x32_bf16 v[24:27], v[140:143], v[180:183], v[24:27]
	v_mfma_f32_16x16x32_bf16 v[16:19], v[132:135], v[200:203], v[16:19]
	v_mfma_f32_16x16x32_bf16 v[8:11], v[140:143], v[200:203], v[8:11]
	s_setprio 0
	s_setprio 1
	v_mfma_f32_16x16x32_bf16 v[52:55], v[144:147], v[160:163], 0
	v_mfma_f32_16x16x32_bf16 v[44:47], v[152:155], v[160:163], 0
	v_mfma_f32_16x16x32_bf16 v[36:39], v[144:147], v[168:171], 0
	v_mfma_f32_16x16x32_bf16 v[28:31], v[152:155], v[168:171], 0
	v_mfma_f32_16x16x32_bf16 v[20:23], v[144:147], v[176:179], 0
	v_mfma_f32_16x16x32_bf16 v[12:15], v[152:155], v[176:179], 0
	v_mfma_f32_16x16x32_bf16 v[4:7], v[144:147], v[194:197], 0
	v_mfma_f32_16x16x32_bf16 v[0:3], v[152:155], v[194:197], 0
	v_mfma_f32_16x16x32_bf16 v[52:55], v[148:151], v[164:167], v[52:55]
	v_mfma_f32_16x16x32_bf16 v[44:47], v[156:159], v[164:167], v[44:47]
	v_mfma_f32_16x16x32_bf16 v[36:39], v[148:151], v[172:175], v[36:39]
	v_mfma_f32_16x16x32_bf16 v[28:31], v[156:159], v[172:175], v[28:31]
	v_mfma_f32_16x16x32_bf16 v[20:23], v[148:151], v[180:183], v[20:23]
	v_mfma_f32_16x16x32_bf16 v[12:15], v[156:159], v[180:183], v[12:15]
	v_mfma_f32_16x16x32_bf16 v[4:7], v[148:151], v[200:203], v[4:7]
	v_mfma_f32_16x16x32_bf16 v[0:3], v[156:159], v[200:203], v[0:3]
	s_setprio 0
	s_barrier
	s_add_i32 s44, 0, 0x18000
	s_add_i32 s45, 0, 0x1c000
	v_add_u32_e32 v140, s44, v247
	v_add_u32_e32 v156, s45, v247
	ds_read_b128 v[128:131], v140
	ds_read_b128 v[132:135], v140 offset:1024
	ds_read_b128 v[136:139], v140 offset:2048
	ds_read_b128 v[140:143], v140 offset:3072
	ds_read_b128 v[144:147], v156
	ds_read_b128 v[148:151], v156 offset:1024
	ds_read_b128 v[152:155], v156 offset:2048
	ds_read_b128 v[156:159], v156 offset:3072
	s_add_u32 s12, s48, 0x110000
	s_addc_u32 s13, s49, 0
	s_mov_b32 m0, s53
	v_lshl_add_u64 v[212:213], s[12:13], 0, v[188:189]
	ds_read_b128 v[160:163], v249 offset:32768
	ds_read_b128 v[164:167], v249 offset:33792
	ds_read_b128 v[168:171], v249 offset:34816
	ds_read_b128 v[172:175], v249 offset:35840
	ds_read_b128 v[176:179], v249 offset:36864
	ds_read_b128 v[180:183], v249 offset:37888
	ds_read_b128 v[194:197], v249 offset:38912
	ds_read_b128 v[200:203], v249 offset:39936
	global_load_lds_dwordx4 v[212:213], off
	v_lshl_add_u64 v[212:213], s[12:13], 0, v[186:187]
	s_mov_b32 m0, s54
	s_nop 0
	global_load_lds_dwordx4 v[212:213], off
	s_waitcnt vmcnt(8)
	s_waitcnt lgkmcnt(0)
	s_barrier
	s_setprio 1
	s_waitcnt lgkmcnt(0)
	v_mfma_f32_16x16x32_bf16 v[124:127], v[128:131], v[160:163], v[124:127]
	v_mfma_f32_16x16x32_bf16 v[120:123], v[136:139], v[160:163], v[120:123]
	v_mfma_f32_16x16x32_bf16 v[108:111], v[128:131], v[168:171], v[108:111]
	v_mfma_f32_16x16x32_bf16 v[104:107], v[136:139], v[168:171], v[104:107]
	v_mfma_f32_16x16x32_bf16 v[96:99], v[128:131], v[176:179], v[96:99]
	v_mfma_f32_16x16x32_bf16 v[88:91], v[136:139], v[176:179], v[88:91]
	v_mfma_f32_16x16x32_bf16 v[80:83], v[128:131], v[194:197], v[80:83]
	v_mfma_f32_16x16x32_bf16 v[72:75], v[136:139], v[194:197], v[72:75]
	v_mfma_f32_16x16x32_bf16 v[124:127], v[132:135], v[164:167], v[124:127]
	v_mfma_f32_16x16x32_bf16 v[120:123], v[140:143], v[164:167], v[120:123]
	v_mfma_f32_16x16x32_bf16 v[108:111], v[132:135], v[172:175], v[108:111]
	v_mfma_f32_16x16x32_bf16 v[104:107], v[140:143], v[172:175], v[104:107]
	v_mfma_f32_16x16x32_bf16 v[96:99], v[132:135], v[180:183], v[96:99]
	v_mfma_f32_16x16x32_bf16 v[88:91], v[140:143], v[180:183], v[88:91]
	v_mfma_f32_16x16x32_bf16 v[80:83], v[132:135], v[200:203], v[80:83]
	v_mfma_f32_16x16x32_bf16 v[72:75], v[140:143], v[200:203], v[72:75]
	s_setprio 0
	s_setprio 1
	v_mfma_f32_16x16x32_bf16 v[116:119], v[144:147], v[160:163], v[116:119]
	v_mfma_f32_16x16x32_bf16 v[112:115], v[152:155], v[160:163], v[112:115]
	v_mfma_f32_16x16x32_bf16 v[100:103], v[144:147], v[168:171], v[100:103]
	v_mfma_f32_16x16x32_bf16 v[92:95], v[152:155], v[168:171], v[92:95]
	v_mfma_f32_16x16x32_bf16 v[84:87], v[144:147], v[176:179], v[84:87]
	v_mfma_f32_16x16x32_bf16 v[76:79], v[152:155], v[176:179], v[76:79]
	v_mfma_f32_16x16x32_bf16 v[68:71], v[144:147], v[194:197], v[68:71]
	v_mfma_f32_16x16x32_bf16 v[64:67], v[152:155], v[194:197], v[64:67]
	v_mfma_f32_16x16x32_bf16 v[116:119], v[148:151], v[164:167], v[116:119]
	v_mfma_f32_16x16x32_bf16 v[112:115], v[156:159], v[164:167], v[112:115]
	v_mfma_f32_16x16x32_bf16 v[100:103], v[148:151], v[172:175], v[100:103]
	v_mfma_f32_16x16x32_bf16 v[92:95], v[156:159], v[172:175], v[92:95]
	v_mfma_f32_16x16x32_bf16 v[84:87], v[148:151], v[180:183], v[84:87]
	v_mfma_f32_16x16x32_bf16 v[76:79], v[156:159], v[180:183], v[76:79]
	v_mfma_f32_16x16x32_bf16 v[68:71], v[148:151], v[200:203], v[68:71]
	v_mfma_f32_16x16x32_bf16 v[64:67], v[156:159], v[200:203], v[64:67]
	s_setprio 0
	s_barrier
; #define PG8_STAGE(bufoff, gbase, voff) do { _Pragma("unroll") for (int _i = 0; _i < 2; ++_i) \
;         __builtin_amdgcn_global_load_lds((const unsigned*)((const char*)(gbase) + (voff)[_i]), (PG8_LAS unsigned*)(lds + (bufoff) + ldsw + _i * 8192), 16, 0, 0); } while (0)
; #define PG8_LDA(dst, b, h) do { _Pragma("unroll") for (int m = 0; m < 4; ++m) _Pragma("unroll") for (int k = 0; k < 2; ++k) dst[m][k] = *(const PG8_LAS bf16x8*)(lds + PG8_SA(b, h) + aoff + m * 2048 + k * 1024); } while (0)
; #define PG8_LDB(dst, b, h) do { _Pragma("unroll") for (int n = 0; n < 2; ++n) _Pragma("unroll") for (int k = 0; k < 2; ++k) dst[n][k] = *(const PG8_LAS bf16x8*)(lds + PG8_SB(b, h) + boff + n * 2048 + k * 1024); } while (0)
; #define PG8_MMA(ai, bj, At, Bt) do { __builtin_amdgcn_s_setprio(1); _Pragma("unroll") for (int m = 0; m < 4; ++m) _Pragma("unroll") for (int n = 0; n < 2; ++n) _Pragma("unroll") for (int k = 0; k < 2; ++k) \
;         acc[ai][bj][m][n] = __builtin_amdgcn_mfma_f32_16x16x32_bf16(Bt[n][k], At[m][k], acc[ai][bj][m][n], 0, 0, 0); __builtin_amdgcn_s_setprio(0); } while (0)
; #define PG8_WAIT_V(n) asm volatile("s_waitcnt vmcnt(" #n ")" ::: "memory")
; #define PG8_WAIT_L(n) asm volatile("s_waitcnt lgkmcnt(" #n ")" ::: "memory")
; #define PG8_BAR __builtin_amdgcn_s_barrier()
; template <class Epi, class Sched, bool ALIGN_EPI = false, bool SP2 = false>
; __device__ __forceinline__ void gemm_phase(PG8_LAS unsigned char* lds, const Gemm g, const Sched& S, const Epi& E, const int tid_in) {
;     ...
;         for (int t = 0; t < nt; t += 2) {
;             const bool last = (t == nt - 2);
;             const char* a1 = cA + (size_t)(t + 1) * kstep;
;             const char* a2 = last ? nA : cA + (size_t)(t + 2) * kstep; const char* b2 = last ? nB : cB + (size_t)(t + 2) * kstep;
;             const char* a3 = a2 + kstep; const char* b3 = b2 + kstep;
;             if (last && has_next) S.a_ready(nxt);
;             if constexpr (SP2) {
;             PG8_LDB(B0, 0, 0); PG8_LDB(B1, 0, 1); PG8_SCHED; PG8_LDA(At, 0, 0); PG8_STAGE(PG8_SA(1, 1), a1 + hstepA, voffA);
;     ...
;             PG8_LDA(At, 1, 1); PG8_STAGE(PG8_SB(1, 0), b3, voffB); PG8_STAGE(PG8_SB(1, 1), b3 + hstepB, voffB); PG8_STAGE(PG8_SA(1, 0), a3, voffA);
;             PG8_WAIT_V(8); PG8_WAIT_L(0); PG8_BAR; PG8_MMA(1, 0, At, B0); PG8_MMA(1, 1, At, B1); PG8_BAR; PG8_SCHED;
	s_add_i32 s12, s44, s50
	v_lshl_add_u64 v[204:205], v[204:205], 0, s[26:27]
	s_mov_b32 m0, s12
	ds_read_b128 v[160:163], v249 offset:49152
	ds_read_b128 v[164:167], v249 offset:50176
	ds_read_b128 v[168:171], v249 offset:51200
	ds_read_b128 v[172:175], v249 offset:52224
	ds_read_b128 v[176:179], v249 offset:53248
	ds_read_b128 v[180:183], v249 offset:54272
	ds_read_b128 v[194:197], v249 offset:55296
	ds_read_b128 v[200:203], v249 offset:56320
	global_load_lds_dwordx4 v[204:205], off
	s_add_i32 m0, s12, 0x2000
	s_add_u32 s12, s46, 0x200080
	v_lshl_add_u64 v[204:205], v[206:207], 0, s[26:27]
	s_addc_u32 s13, s47, 0
	s_add_i32 s44, s45, s50
	global_load_lds_dwordx4 v[204:205], off
	v_lshl_add_u64 v[204:205], s[12:13], 0, v[192:193]
	s_mov_b32 m0, s44
	s_nop 0
	global_load_lds_dwordx4 v[204:205], off
	v_lshl_add_u64 v[204:205], s[12:13], 0, v[184:185]
	s_add_i32 m0, s44, 0x2000
	s_nop 0
	global_load_lds_dwordx4 v[204:205], off
	v_lshl_add_u64 v[204:205], v[208:209], 0, s[26:27]
	s_mov_b32 m0, s55
	s_nop 0
	global_load_lds_dwordx4 v[204:205], off
	v_lshl_add_u64 v[204:205], v[210:211], 0, s[26:27]
	s_mov_b32 m0, s56
	s_nop 0
	global_load_lds_dwordx4 v[204:205], off
	s_waitcnt vmcnt(8)
	s_waitcnt lgkmcnt(0)
	s_barrier
	s_setprio 1
	s_waitcnt lgkmcnt(0)
	v_mfma_f32_16x16x32_bf16 v[60:63], v[128:131], v[160:163], v[60:63]
	v_mfma_f32_16x16x32_bf16 v[56:59], v[136:139], v[160:163], v[56:59]
	v_mfma_f32_16x16x32_bf16 v[48:51], v[128:131], v[168:171], v[48:51]
	v_mfma_f32_16x16x32_bf16 v[40:43], v[136:139], v[168:171], v[40:43]
	v_mfma_f32_16x16x32_bf16 v[32:35], v[128:131], v[176:179], v[32:35]
	v_mfma_f32_16x16x32_bf16 v[24:27], v[136:139], v[176:179], v[24:27]
	v_mfma_f32_16x16x32_bf16 v[16:19], v[128:131], v[194:197], v[16:19]
	v_mfma_f32_16x16x32_bf16 v[8:11], v[136:139], v[194:197], v[8:11]
	v_mfma_f32_16x16x32_bf16 v[60:63], v[132:135], v[164:167], v[60:63]
	v_mfma_f32_16x16x32_bf16 v[56:59], v[140:143], v[164:167], v[56:59]
	v_mfma_f32_16x16x32_bf16 v[48:51], v[132:135], v[172:175], v[48:51]
	v_mfma_f32_16x16x32_bf16 v[40:43], v[140:143], v[172:175], v[40:43]
	v_mfma_f32_16x16x32_bf16 v[32:35], v[132:135], v[180:183], v[32:35]
	v_mfma_f32_16x16x32_bf16 v[24:27], v[140:143], v[180:183], v[24:27]
	v_mfma_f32_16x16x32_bf16 v[16:19], v[132:135], v[200:203], v[16:19]
	v_mfma_f32_16x16x32_bf16 v[8:11], v[140:143], v[200:203], v[8:11]
	s_setprio 0
	s_setprio 1
	v_mfma_f32_16x16x32_bf16 v[52:55], v[144:147], v[160:163], v[52:55]
	v_mfma_f32_16x16x32_bf16 v[44:47], v[152:155], v[160:163], v[44:47]
	v_mfma_f32_16x16x32_bf16 v[36:39], v[144:147], v[168:171], v[36:39]
	v_mfma_f32_16x16x32_bf16 v[28:31], v[152:155], v[168:171], v[28:31]
	v_mfma_f32_16x16x32_bf16 v[20:23], v[144:147], v[176:179], v[20:23]
	v_mfma_f32_16x16x32_bf16 v[12:15], v[152:155], v[176:179], v[12:15]
	v_mfma_f32_16x16x32_bf16 v[4:7], v[144:147], v[194:197], v[4:7]
	v_mfma_f32_16x16x32_bf16 v[0:3], v[152:155], v[194:197], v[0:3]
	v_mfma_f32_16x16x32_bf16 v[52:55], v[148:151], v[164:167], v[52:55]
	v_mfma_f32_16x16x32_bf16 v[44:47], v[156:159], v[164:167], v[44:47]
	v_mfma_f32_16x16x32_bf16 v[36:39], v[148:151], v[172:175], v[36:39]
	v_mfma_f32_16x16x32_bf16 v[28:31], v[156:159], v[172:175], v[28:31]
	v_mfma_f32_16x16x32_bf16 v[20:23], v[148:151], v[180:183], v[20:23]
	v_mfma_f32_16x16x32_bf16 v[12:15], v[156:159], v[180:183], v[12:15]
	v_mfma_f32_16x16x32_bf16 v[4:7], v[148:151], v[200:203], v[4:7]
	v_mfma_f32_16x16x32_bf16 v[0:3], v[156:159], v[200:203], v[0:3]
	s_setprio 0
	s_barrier
	s_add_i32 s65, s65, 2
	s_add_u32 s63, s63, 0x100
	s_addc_u32 s64, s64, 0
	s_cmpk_gt_u32 s65, 0x41
	s_mov_b64 s[44:45], s[36:37]
	.p2align 6
.LBB0_1434:
	s_add_u32 s36, s44, 0x100
	s_addc_u32 s37, s45, 0
	s_add_i32 s12, 0, 0x10000
	s_cmp_eq_u32 s65, 64
	s_cselect_b32 s49, s41, s37
	s_cselect_b32 s48, s40, s36
	s_cselect_b32 s47, s39, s64
	s_cselect_b32 s46, s62, s63
	s_add_i32 s66, 0, 0x14000
	v_add_u32_e32 v140, s12, v247
	v_add_u32_e32 v156, s66, v247
	ds_read_b128 v[128:131], v140
	ds_read_b128 v[132:135], v140 offset:1024
	ds_read_b128 v[136:139], v140 offset:2048
	ds_read_b128 v[140:143], v140 offset:3072
	ds_read_b128 v[144:147], v156
	ds_read_b128 v[148:151], v156 offset:1024
	ds_read_b128 v[152:155], v156 offset:2048
	ds_read_b128 v[156:159], v156 offset:3072
	v_lshl_add_u64 v[204:205], s[44:45], 0, v[190:191]
	s_add_i32 m0, s51, 0xc000
	ds_read_b128 v[160:163], v249
	ds_read_b128 v[164:167], v249 offset:1024
	ds_read_b128 v[168:171], v249 offset:2048
	ds_read_b128 v[172:175], v249 offset:3072
	ds_read_b128 v[176:179], v249 offset:4096
	ds_read_b128 v[180:183], v249 offset:5120
	ds_read_b128 v[194:197], v249 offset:6144
	ds_read_b128 v[200:203], v249 offset:7168
	global_load_lds_dwordx4 v[204:205], off
	v_lshl_add_u64 v[204:205], s[44:45], 0, v[198:199]
	s_add_i32 m0, s51, 0xe000
	s_nop 0
	global_load_lds_dwordx4 v[204:205], off
	s_waitcnt vmcnt(8)
	s_waitcnt lgkmcnt(0)
	s_barrier
; #define PG8_STAGE(bufoff, gbase, voff) do { _Pragma("unroll") for (int _i = 0; _i < 2; ++_i) \
;         __builtin_amdgcn_global_load_lds((const unsigned*)((const char*)(gbase) + (voff)[_i]), (PG8_LAS unsigned*)(lds + (bufoff) + ldsw + _i * 8192), 16, 0, 0); } while (0)
; #define PG8_LDA(dst, b, h) do { _Pragma("unroll") for (int m = 0; m < 4; ++m) _Pragma("unroll") for (int k = 0; k < 2; ++k) dst[m][k] = *(const PG8_LAS bf16x8*)(lds + PG8_SA(b, h) + aoff + m * 2048 + k * 1024); } while (0)
; #define PG8_MMA(ai, bj, At, Bt) do { __builtin_amdgcn_s_setprio(1); _Pragma("unroll") for (int m = 0; m < 4; ++m) _Pragma("unroll") for (int n = 0; n < 2; ++n) _Pragma("unroll") for (int k = 0; k < 2; ++k) \
;         acc[ai][bj][m][n] = __builtin_amdgcn_mfma_f32_16x16x32_bf16(Bt[n][k], At[m][k], acc[ai][bj][m][n], 0, 0, 0); __builtin_amdgcn_s_setprio(0); } while (0)
; #define PG8_WAIT_V(n) asm volatile("s_waitcnt vmcnt(" #n ")" ::: "memory")
; #define PG8_WAIT_L(n) asm volatile("s_waitcnt lgkmcnt(" #n ")" ::: "memory")
; #define PG8_BAR __builtin_amdgcn_s_barrier()
; #define PG8_SCHED __builtin_amdgcn_sched_barrier(0)
; template <class Epi, class Sched, bool ALIGN_EPI = false, bool SP2 = false>
; __device__ __forceinline__ void gemm_phase(PG8_LAS unsigned char* lds, const Gemm g, const Sched& S, const Epi& E, const int tid_in) {
;     ...
;             PG8_WAIT_V(8); PG8_WAIT_L(0); PG8_BAR; PG8_MMA(0, 0, At, B0); PG8_MMA(0, 1, At, B1); PG8_BAR; PG8_SCHED;
;             PG8_LDA(At, 0, 1); PG8_STAGE(PG8_SB(0, 0), b2, voffB); PG8_STAGE(PG8_SB(0, 1), b2 + hstepB, voffB); PG8_STAGE(PG8_SA(0, 0), a2, voffA);
;             PG8_WAIT_V(8); PG8_WAIT_L(0); PG8_BAR; PG8_MMA(1, 0, At, B0); PG8_MMA(1, 1, At, B1); PG8_BAR; PG8_SCHED;
	s_setprio 1
	s_waitcnt lgkmcnt(0)
	v_mfma_f32_16x16x32_bf16 v[124:127], v[128:131], v[160:163], v[124:127]
	v_mfma_f32_16x16x32_bf16 v[120:123], v[136:139], v[160:163], v[120:123]
	v_mfma_f32_16x16x32_bf16 v[108:111], v[128:131], v[168:171], v[108:111]
	v_mfma_f32_16x16x32_bf16 v[104:107], v[136:139], v[168:171], v[104:107]
	v_mfma_f32_16x16x32_bf16 v[96:99], v[128:131], v[176:179], v[96:99]
	v_mfma_f32_16x16x32_bf16 v[88:91], v[136:139], v[176:179], v[88:91]
	v_mfma_f32_16x16x32_bf16 v[80:83], v[128:131], v[194:197], v[80:83]
	v_mfma_f32_16x16x32_bf16 v[72:75], v[136:139], v[194:197], v[72:75]
	v_mfma_f32_16x16x32_bf16 v[124:127], v[132:135], v[164:167], v[124:127]
	v_mfma_f32_16x16x32_bf16 v[120:123], v[140:143], v[164:167], v[120:123]
	v_mfma_f32_16x16x32_bf16 v[108:111], v[132:135], v[172:175], v[108:111]
	v_mfma_f32_16x16x32_bf16 v[104:107], v[140:143], v[172:175], v[104:107]
	v_mfma_f32_16x16x32_bf16 v[96:99], v[132:135], v[180:183], v[96:99]
	v_mfma_f32_16x16x32_bf16 v[88:91], v[140:143], v[180:183], v[88:91]
	v_mfma_f32_16x16x32_bf16 v[80:83], v[132:135], v[200:203], v[80:83]
	v_mfma_f32_16x16x32_bf16 v[72:75], v[140:143], v[200:203], v[72:75]
	v_mfma_f32_16x16x32_bf16 v[116:119], v[144:147], v[160:163], v[116:119]
	v_mfma_f32_16x16x32_bf16 v[112:115], v[152:155], v[160:163], v[112:115]
	v_mfma_f32_16x16x32_bf16 v[100:103], v[144:147], v[168:171], v[100:103]
	v_mfma_f32_16x16x32_bf16 v[92:95], v[152:155], v[168:171], v[92:95]
	v_mfma_f32_16x16x32_bf16 v[84:87], v[144:147], v[176:179], v[84:87]
	v_mfma_f32_16x16x32_bf16 v[76:79], v[152:155], v[176:179], v[76:79]
	v_mfma_f32_16x16x32_bf16 v[68:71], v[144:147], v[194:197], v[68:71]
	v_mfma_f32_16x16x32_bf16 v[64:67], v[152:155], v[194:197], v[64:67]
	v_mfma_f32_16x16x32_bf16 v[116:119], v[148:151], v[164:167], v[116:119]
	v_mfma_f32_16x16x32_bf16 v[112:115], v[156:159], v[164:167], v[112:115]
	v_mfma_f32_16x16x32_bf16 v[100:103], v[148:151], v[172:175], v[100:103]
	v_mfma_f32_16x16x32_bf16 v[92:95], v[156:159], v[172:175], v[92:95]
	v_mfma_f32_16x16x32_bf16 v[84:87], v[148:151], v[180:183], v[84:87]
	v_mfma_f32_16x16x32_bf16 v[76:79], v[156:159], v[180:183], v[76:79]
	v_mfma_f32_16x16x32_bf16 v[68:71], v[148:151], v[200:203], v[68:71]
	v_mfma_f32_16x16x32_bf16 v[64:67], v[156:159], v[200:203], v[64:67]
	s_setprio 0
	s_barrier
	s_add_i32 s12, s12, s50
	v_lshl_add_u64 v[204:205], s[46:47], 0, v[192:193]
	s_mov_b32 m0, s12
	ds_read_b128 v[160:163], v249 offset:16384
	ds_read_b128 v[164:167], v249 offset:17408
	ds_read_b128 v[168:171], v249 offset:18432
	ds_read_b128 v[172:175], v249 offset:19456
	ds_read_b128 v[176:179], v249 offset:20480
	ds_read_b128 v[180:183], v249 offset:21504
	ds_read_b128 v[194:197], v249 offset:22528
	ds_read_b128 v[200:203], v249 offset:23552
	global_load_lds_dwordx4 v[204:205], off
	s_add_i32 m0, s12, 0x2000
	s_add_u32 s12, s46, 0x200000
	v_lshl_add_u64 v[206:207], s[46:47], 0, v[184:185]
	s_addc_u32 s13, s47, 0
	s_add_i32 s44, s66, s50
	global_load_lds_dwordx4 v[206:207], off
	v_lshl_add_u64 v[208:209], s[12:13], 0, v[192:193]
	s_mov_b32 m0, s44
	v_lshl_add_u64 v[210:211], s[48:49], 0, v[186:187]
	global_load_lds_dwordx4 v[208:209], off
	v_lshl_add_u64 v[208:209], s[12:13], 0, v[184:185]
	s_add_i32 m0, s44, 0x2000
	s_nop 0
	global_load_lds_dwordx4 v[208:209], off
	v_lshl_add_u64 v[208:209], s[48:49], 0, v[188:189]
	s_mov_b32 m0, s51
	s_nop 0
	global_load_lds_dwordx4 v[208:209], off
	s_mov_b32 m0, s52
	s_nop 0
	global_load_lds_dwordx4 v[210:211], off
	s_waitcnt vmcnt(8)
	s_waitcnt lgkmcnt(0)
	s_barrier
	s_setprio 1
	s_waitcnt lgkmcnt(0)
	v_mfma_f32_16x16x32_bf16 v[60:63], v[128:131], v[160:163], v[60:63]
	v_mfma_f32_16x16x32_bf16 v[56:59], v[136:139], v[160:163], v[56:59]
	v_mfma_f32_16x16x32_bf16 v[48:51], v[128:131], v[168:171], v[48:51]
	v_mfma_f32_16x16x32_bf16 v[40:43], v[136:139], v[168:171], v[40:43]
	v_mfma_f32_16x16x32_bf16 v[32:35], v[128:131], v[176:179], v[32:35]
	v_mfma_f32_16x16x32_bf16 v[24:27], v[136:139], v[176:179], v[24:27]
	v_mfma_f32_16x16x32_bf16 v[16:19], v[128:131], v[194:197], v[16:19]
	v_mfma_f32_16x16x32_bf16 v[8:11], v[136:139], v[194:197], v[8:11]
	v_mfma_f32_16x16x32_bf16 v[60:63], v[132:135], v[164:167], v[60:63]
	v_mfma_f32_16x16x32_bf16 v[56:59], v[140:143], v[164:167], v[56:59]
	v_mfma_f32_16x16x32_bf16 v[48:51], v[132:135], v[172:175], v[48:51]
	v_mfma_f32_16x16x32_bf16 v[40:43], v[140:143], v[172:175], v[40:43]
	v_mfma_f32_16x16x32_bf16 v[32:35], v[132:135], v[180:183], v[32:35]
	v_mfma_f32_16x16x32_bf16 v[24:27], v[140:143], v[180:183], v[24:27]
	v_mfma_f32_16x16x32_bf16 v[16:19], v[132:135], v[200:203], v[16:19]
	v_mfma_f32_16x16x32_bf16 v[8:11], v[140:143], v[200:203], v[8:11]
	v_mfma_f32_16x16x32_bf16 v[52:55], v[144:147], v[160:163], v[52:55]
	v_mfma_f32_16x16x32_bf16 v[44:47], v[152:155], v[160:163], v[44:47]
	v_mfma_f32_16x16x32_bf16 v[36:39], v[144:147], v[168:171], v[36:39]
	v_mfma_f32_16x16x32_bf16 v[28:31], v[152:155], v[168:171], v[28:31]
	v_mfma_f32_16x16x32_bf16 v[20:23], v[144:147], v[176:179], v[20:23]
	v_mfma_f32_16x16x32_bf16 v[12:15], v[152:155], v[176:179], v[12:15]
	v_mfma_f32_16x16x32_bf16 v[4:7], v[144:147], v[194:197], v[4:7]
	v_mfma_f32_16x16x32_bf16 v[0:3], v[152:155], v[194:197], v[0:3]
	v_mfma_f32_16x16x32_bf16 v[52:55], v[148:151], v[164:167], v[52:55]
	v_mfma_f32_16x16x32_bf16 v[44:47], v[156:159], v[164:167], v[44:47]
	v_mfma_f32_16x16x32_bf16 v[36:39], v[148:151], v[172:175], v[36:39]
	v_mfma_f32_16x16x32_bf16 v[28:31], v[156:159], v[172:175], v[28:31]
	v_mfma_f32_16x16x32_bf16 v[20:23], v[148:151], v[180:183], v[20:23]
	v_mfma_f32_16x16x32_bf16 v[12:15], v[156:159], v[180:183], v[12:15]
	v_mfma_f32_16x16x32_bf16 v[4:7], v[148:151], v[200:203], v[4:7]
	v_mfma_f32_16x16x32_bf16 v[0:3], v[156:159], v[200:203], v[0:3]
	s_setprio 0
	s_barrier
; #define PG8_STAGE(bufoff, gbase, voff) do { _Pragma("unroll") for (int _i = 0; _i < 2; ++_i) \
;         __builtin_amdgcn_global_load_lds((const unsigned*)((const char*)(gbase) + (voff)[_i]), (PG8_LAS unsigned*)(lds + (bufoff) + ldsw + _i * 8192), 16, 0, 0); } while (0)
; #define PG8_LDA(dst, b, h) do { _Pragma("unroll") for (int m = 0; m < 4; ++m) _Pragma("unroll") for (int k = 0; k < 2; ++k) dst[m][k] = *(const PG8_LAS bf16x8*)(lds + PG8_SA(b, h) + aoff + m * 2048 + k * 1024); } while (0)
; #define PG8_LDB(dst, b, h) do { _Pragma("unroll") for (int n = 0; n < 2; ++n) _Pragma("unroll") for (int k = 0; k < 2; ++k) dst[n][k] = *(const PG8_LAS bf16x8*)(lds + PG8_SB(b, h) + boff + n * 2048 + k * 1024); } while (0)
; #define PG8_MMA(ai, bj, At, Bt) do { __builtin_amdgcn_s_setprio(1); _Pragma("unroll") for (int m = 0; m < 4; ++m) _Pragma("unroll") for (int n = 0; n < 2; ++n) _Pragma("unroll") for (int k = 0; k < 2; ++k) \
;         acc[ai][bj][m][n] = __builtin_amdgcn_mfma_f32_16x16x32_bf16(Bt[n][k], At[m][k], acc[ai][bj][m][n], 0, 0, 0); __builtin_amdgcn_s_setprio(0); } while (0)
; #define PG8_WAIT_V(n) asm volatile("s_waitcnt vmcnt(" #n ")" ::: "memory")
; #define PG8_WAIT_L(n) asm volatile("s_waitcnt lgkmcnt(" #n ")" ::: "memory")
; #define PG8_BAR __builtin_amdgcn_s_barrier()
; #define PG8_SCHED __builtin_amdgcn_sched_barrier(0)
; template <class Epi, class Sched, bool ALIGN_EPI = false, bool SP2 = false>
; __device__ __forceinline__ void gemm_phase(PG8_LAS unsigned char* lds, const Gemm g, const Sched& S, const Epi& E, const int tid_in) {
;     ...
;             PG8_LDB(B0, 1, 0); PG8_LDB(B1, 1, 1); PG8_SCHED; PG8_LDA(At, 1, 0); PG8_STAGE(PG8_SA(0, 1), a2 + hstepA, voffA);
;             PG8_WAIT_V(8); PG8_WAIT_L(0); PG8_BAR; PG8_MMA(0, 0, At, B0); PG8_MMA(0, 1, At, B1); PG8_BAR; PG8_SCHED;
	s_add_i32 s44, 0, 0x18000
	s_add_i32 s45, 0, 0x1c000
	v_add_u32_e32 v140, s44, v247
	v_add_u32_e32 v156, s45, v247
	ds_read_b128 v[128:131], v140
	ds_read_b128 v[132:135], v140 offset:1024
	ds_read_b128 v[136:139], v140 offset:2048
	ds_read_b128 v[140:143], v140 offset:3072
	ds_read_b128 v[144:147], v156
	ds_read_b128 v[148:151], v156 offset:1024
	ds_read_b128 v[152:155], v156 offset:2048
	ds_read_b128 v[156:159], v156 offset:3072
	s_add_u32 s12, s48, 0x110000
	s_addc_u32 s13, s49, 0
	s_mov_b32 m0, s53
	v_lshl_add_u64 v[212:213], s[12:13], 0, v[188:189]
	ds_read_b128 v[160:163], v249 offset:32768
	ds_read_b128 v[164:167], v249 offset:33792
	ds_read_b128 v[168:171], v249 offset:34816
	ds_read_b128 v[172:175], v249 offset:35840
	ds_read_b128 v[176:179], v249 offset:36864
	ds_read_b128 v[180:183], v249 offset:37888
	ds_read_b128 v[194:197], v249 offset:38912
	ds_read_b128 v[200:203], v249 offset:39936
	global_load_lds_dwordx4 v[212:213], off
	v_lshl_add_u64 v[212:213], s[12:13], 0, v[186:187]
	s_mov_b32 m0, s54
	s_nop 0
	global_load_lds_dwordx4 v[212:213], off
	s_waitcnt vmcnt(8)
	s_waitcnt lgkmcnt(0)
	s_barrier
	s_setprio 1
	s_waitcnt lgkmcnt(0)
	v_mfma_f32_16x16x32_bf16 v[124:127], v[128:131], v[160:163], v[124:127]
	v_mfma_f32_16x16x32_bf16 v[120:123], v[136:139], v[160:163], v[120:123]
	v_mfma_f32_16x16x32_bf16 v[108:111], v[128:131], v[168:171], v[108:111]
	v_mfma_f32_16x16x32_bf16 v[104:107], v[136:139], v[168:171], v[104:107]
	v_mfma_f32_16x16x32_bf16 v[96:99], v[128:131], v[176:179], v[96:99]
	v_mfma_f32_16x16x32_bf16 v[88:91], v[136:139], v[176:179], v[88:91]
	v_mfma_f32_16x16x32_bf16 v[80:83], v[128:131], v[194:197], v[80:83]
	v_mfma_f32_16x16x32_bf16 v[72:75], v[136:139], v[194:197], v[72:75]
	v_mfma_f32_16x16x32_bf16 v[124:127], v[132:135], v[164:167], v[124:127]
	v_mfma_f32_16x16x32_bf16 v[120:123], v[140:143], v[164:167], v[120:123]
	v_mfma_f32_16x16x32_bf16 v[108:111], v[132:135], v[172:175], v[108:111]
	v_mfma_f32_16x16x32_bf16 v[104:107], v[140:143], v[172:175], v[104:107]
	v_mfma_f32_16x16x32_bf16 v[96:99], v[132:135], v[180:183], v[96:99]
	v_mfma_f32_16x16x32_bf16 v[88:91], v[140:143], v[180:183], v[88:91]
	v_mfma_f32_16x16x32_bf16 v[80:83], v[132:135], v[200:203], v[80:83]
	v_mfma_f32_16x16x32_bf16 v[72:75], v[140:143], v[200:203], v[72:75]
	v_mfma_f32_16x16x32_bf16 v[116:119], v[144:147], v[160:163], v[116:119]
	v_mfma_f32_16x16x32_bf16 v[112:115], v[152:155], v[160:163], v[112:115]
	v_mfma_f32_16x16x32_bf16 v[100:103], v[144:147], v[168:171], v[100:103]
	v_mfma_f32_16x16x32_bf16 v[92:95], v[152:155], v[168:171], v[92:95]
	v_mfma_f32_16x16x32_bf16 v[84:87], v[144:147], v[176:179], v[84:87]
	v_mfma_f32_16x16x32_bf16 v[76:79], v[152:155], v[176:179], v[76:79]
	v_mfma_f32_16x16x32_bf16 v[68:71], v[144:147], v[194:197], v[68:71]
	v_mfma_f32_16x16x32_bf16 v[64:67], v[152:155], v[194:197], v[64:67]
	v_mfma_f32_16x16x32_bf16 v[116:119], v[148:151], v[164:167], v[116:119]
	v_mfma_f32_16x16x32_bf16 v[112:115], v[156:159], v[164:167], v[112:115]
	v_mfma_f32_16x16x32_bf16 v[100:103], v[148:151], v[172:175], v[100:103]
	v_mfma_f32_16x16x32_bf16 v[92:95], v[156:159], v[172:175], v[92:95]
	v_mfma_f32_16x16x32_bf16 v[84:87], v[148:151], v[180:183], v[84:87]
	v_mfma_f32_16x16x32_bf16 v[76:79], v[156:159], v[180:183], v[76:79]
	v_mfma_f32_16x16x32_bf16 v[68:71], v[148:151], v[200:203], v[68:71]
	v_mfma_f32_16x16x32_bf16 v[64:67], v[156:159], v[200:203], v[64:67]
	s_setprio 0
	s_barrier
; #define PG8_STAGE(bufoff, gbase, voff) do { _Pragma("unroll") for (int _i = 0; _i < 2; ++_i) \
;         __builtin_amdgcn_global_load_lds((const unsigned*)((const char*)(gbase) + (voff)[_i]), (PG8_LAS unsigned*)(lds + (bufoff) + ldsw + _i * 8192), 16, 0, 0); } while (0)
; #define PG8_LDA(dst, b, h) do { _Pragma("unroll") for (int m = 0; m < 4; ++m) _Pragma("unroll") for (int k = 0; k < 2; ++k) dst[m][k] = *(const PG8_LAS bf16x8*)(lds + PG8_SA(b, h) + aoff + m * 2048 + k * 1024); } while (0)
; #define PG8_MMA(ai, bj, At, Bt) do { __builtin_amdgcn_s_setprio(1); _Pragma("unroll") for (int m = 0; m < 4; ++m) _Pragma("unroll") for (int n = 0; n < 2; ++n) _Pragma("unroll") for (int k = 0; k < 2; ++k) \
;         acc[ai][bj][m][n] = __builtin_amdgcn_mfma_f32_16x16x32_bf16(Bt[n][k], At[m][k], acc[ai][bj][m][n], 0, 0, 0); __builtin_amdgcn_s_setprio(0); } while (0)
; #define PG8_WAIT_V(n) asm volatile("s_waitcnt vmcnt(" #n ")" ::: "memory")
; #define PG8_WAIT_L(n) asm volatile("s_waitcnt lgkmcnt(" #n ")" ::: "memory")
; #define PG8_BAR __builtin_amdgcn_s_barrier()
; #define PG8_SCHED __builtin_amdgcn_sched_barrier(0)
; template <class Epi, class Sched, bool ALIGN_EPI = false, bool SP2 = false>
; __device__ __forceinline__ void gemm_phase(PG8_LAS unsigned char* lds, const Gemm g, const Sched& S, const Epi& E, const int tid_in) {
;     ...
;         for (int t = 0; t < nt; t += 2) {
;             const bool last = (t == nt - 2);
;             const char* a1 = cA + (size_t)(t + 1) * kstep;
;             const char* a2 = last ? nA : cA + (size_t)(t + 2) * kstep; const char* b2 = last ? nB : cB + (size_t)(t + 2) * kstep;
;             const char* a3 = a2 + kstep; const char* b3 = b2 + kstep;
;             if (last && has_next) S.a_ready(nxt);
;     ...
;             PG8_LDA(At, 1, 1); PG8_STAGE(PG8_SB(1, 0), b3, voffB); PG8_STAGE(PG8_SB(1, 1), b3 + hstepB, voffB); PG8_STAGE(PG8_SA(1, 0), a3, voffA);
;             PG8_WAIT_V(8); PG8_WAIT_L(0); PG8_BAR; PG8_MMA(1, 0, At, B0); PG8_MMA(1, 1, At, B1); PG8_BAR; PG8_SCHED;
	s_add_i32 s12, s44, s50
	v_lshl_add_u64 v[204:205], v[204:205], 0, s[26:27]
	s_mov_b32 m0, s12
	ds_read_b128 v[160:163], v249 offset:49152
	ds_read_b128 v[164:167], v249 offset:50176
	ds_read_b128 v[168:171], v249 offset:51200
	ds_read_b128 v[172:175], v249 offset:52224
	ds_read_b128 v[176:179], v249 offset:53248
	ds_read_b128 v[180:183], v249 offset:54272
	ds_read_b128 v[194:197], v249 offset:55296
	ds_read_b128 v[200:203], v249 offset:56320
	global_load_lds_dwordx4 v[204:205], off
	s_add_i32 m0, s12, 0x2000
	s_add_u32 s12, s46, 0x200080
	v_lshl_add_u64 v[204:205], v[206:207], 0, s[26:27]
	s_addc_u32 s13, s47, 0
	s_add_i32 s44, s45, s50
	global_load_lds_dwordx4 v[204:205], off
	v_lshl_add_u64 v[204:205], s[12:13], 0, v[192:193]
	s_mov_b32 m0, s44
	s_nop 0
	global_load_lds_dwordx4 v[204:205], off
	v_lshl_add_u64 v[204:205], s[12:13], 0, v[184:185]
	s_add_i32 m0, s44, 0x2000
	s_nop 0
	global_load_lds_dwordx4 v[204:205], off
	v_lshl_add_u64 v[204:205], v[208:209], 0, s[26:27]
	s_mov_b32 m0, s55
	s_nop 0
	global_load_lds_dwordx4 v[204:205], off
	v_lshl_add_u64 v[204:205], v[210:211], 0, s[26:27]
	s_mov_b32 m0, s56
	s_nop 0
	global_load_lds_dwordx4 v[204:205], off
	s_waitcnt vmcnt(8)
	s_waitcnt lgkmcnt(0)
	s_barrier
	s_setprio 1
	s_waitcnt lgkmcnt(0)
	v_mfma_f32_16x16x32_bf16 v[60:63], v[128:131], v[160:163], v[60:63]
	v_mfma_f32_16x16x32_bf16 v[56:59], v[136:139], v[160:163], v[56:59]
	v_mfma_f32_16x16x32_bf16 v[48:51], v[128:131], v[168:171], v[48:51]
	v_mfma_f32_16x16x32_bf16 v[40:43], v[136:139], v[168:171], v[40:43]
	v_mfma_f32_16x16x32_bf16 v[32:35], v[128:131], v[176:179], v[32:35]
	v_mfma_f32_16x16x32_bf16 v[24:27], v[136:139], v[176:179], v[24:27]
	v_mfma_f32_16x16x32_bf16 v[16:19], v[128:131], v[194:197], v[16:19]
	v_mfma_f32_16x16x32_bf16 v[8:11], v[136:139], v[194:197], v[8:11]
	v_mfma_f32_16x16x32_bf16 v[60:63], v[132:135], v[164:167], v[60:63]
	v_mfma_f32_16x16x32_bf16 v[56:59], v[140:143], v[164:167], v[56:59]
	v_mfma_f32_16x16x32_bf16 v[48:51], v[132:135], v[172:175], v[48:51]
	v_mfma_f32_16x16x32_bf16 v[40:43], v[140:143], v[172:175], v[40:43]
	v_mfma_f32_16x16x32_bf16 v[32:35], v[132:135], v[180:183], v[32:35]
	v_mfma_f32_16x16x32_bf16 v[24:27], v[140:143], v[180:183], v[24:27]
	v_mfma_f32_16x16x32_bf16 v[16:19], v[132:135], v[200:203], v[16:19]
	v_mfma_f32_16x16x32_bf16 v[8:11], v[140:143], v[200:203], v[8:11]
	v_mfma_f32_16x16x32_bf16 v[52:55], v[144:147], v[160:163], v[52:55]
	v_mfma_f32_16x16x32_bf16 v[44:47], v[152:155], v[160:163], v[44:47]
	v_mfma_f32_16x16x32_bf16 v[36:39], v[144:147], v[168:171], v[36:39]
	v_mfma_f32_16x16x32_bf16 v[28:31], v[152:155], v[168:171], v[28:31]
	v_mfma_f32_16x16x32_bf16 v[20:23], v[144:147], v[176:179], v[20:23]
	v_mfma_f32_16x16x32_bf16 v[12:15], v[152:155], v[176:179], v[12:15]
	v_mfma_f32_16x16x32_bf16 v[4:7], v[144:147], v[194:197], v[4:7]
	v_mfma_f32_16x16x32_bf16 v[0:3], v[152:155], v[194:197], v[0:3]
	v_mfma_f32_16x16x32_bf16 v[52:55], v[148:151], v[164:167], v[52:55]
	v_mfma_f32_16x16x32_bf16 v[44:47], v[156:159], v[164:167], v[44:47]
	v_mfma_f32_16x16x32_bf16 v[36:39], v[148:151], v[172:175], v[36:39]
	v_mfma_f32_16x16x32_bf16 v[28:31], v[156:159], v[172:175], v[28:31]
	v_mfma_f32_16x16x32_bf16 v[20:23], v[148:151], v[180:183], v[20:23]
	v_mfma_f32_16x16x32_bf16 v[12:15], v[156:159], v[180:183], v[12:15]
	v_mfma_f32_16x16x32_bf16 v[4:7], v[148:151], v[200:203], v[4:7]
	v_mfma_f32_16x16x32_bf16 v[0:3], v[156:159], v[200:203], v[0:3]
	s_setprio 0
	s_barrier
	s_add_i32 s65, s65, 2
	s_add_u32 s63, s63, 0x100
	s_addc_u32 s64, s64, 0
	s_cmpk_gt_u32 s65, 0x41
	s_mov_b64 s[44:45], s[36:37]
	s_cbranch_scc0 .LBB0_1434
	s_and_b64 vcc, exec, s[30:31]
	s_cbranch_vccz .LBB0_1437
	s_barrier

; #define PG8_STAGE(bufoff, gbase, voff) do { _Pragma("unroll") for (int _i = 0; _i < 2; ++_i) \
;         __builtin_amdgcn_global_load_lds((const unsigned*)((const char*)(gbase) + (voff)[_i]), (PG8_LAS unsigned*)(lds + (bufoff) + ldsw + _i * 8192), 16, 0, 0); } while (0)
; #define PG8_LDA(dst, b, h) do { _Pragma("unroll") for (int m = 0; m < 4; ++m) _Pragma("unroll") for (int k = 0; k < 2; ++k) dst[m][k] = *(const PG8_LAS bf16x8*)(lds + PG8_SA(b, h) + aoff + m * 2048 + k * 1024); } while (0)
; #define PG8_LDB(dst, b, h) do { _Pragma("unroll") for (int n = 0; n < 2; ++n) _Pragma("unroll") for (int k = 0; k < 2; ++k) dst[n][k] = *(const PG8_LAS bf16x8*)(lds + PG8_SB(b, h) + boff + n * 2048 + k * 1024); } while (0)
; #define PG8_MMA(ai, bj, At, Bt) do { __builtin_amdgcn_s_setprio(1); _Pragma("unroll") for (int m = 0; m < 4; ++m) _Pragma("unroll") for (int n = 0; n < 2; ++n) _Pragma("unroll") for (int k = 0; k < 2; ++k) \
;         acc[ai][bj][m][n] = __builtin_amdgcn_mfma_f32_16x16x32_bf16(Bt[n][k], At[m][k], acc[ai][bj][m][n], 0, 0, 0); __builtin_amdgcn_s_setprio(0); } while (0)
; template <class Epi, class Sched, bool ALIGN_EPI = false, bool SP2 = false>
; __device__ __forceinline__ void gemm_phase(PG8_LAS unsigned char* lds, const Gemm g, const Sched& S, const Epi& E, const int tid_in) {
;     ...
;         const bool has_next = S.next(ui + 1, nxt);
;         const char* nA = has_next ? (const char*)g.A + (size_t)nxt.pm * tstepA : cA; const char* nB = has_next ? (const char*)g.Bt + (size_t)nxt.pn * tstepB : cB;
;         for (int t = 0; t < nt; t += 2) {
;             const bool last = (t == nt - 2);
;             const char* a1 = cA + (size_t)(t + 1) * kstep;
;             const char* a2 = last ? nA : cA + (size_t)(t + 2) * kstep; const char* b2 = last ? nB : cB + (size_t)(t + 2) * kstep;
;             const char* a3 = a2 + kstep; const char* b3 = b2 + kstep;
;             if (last && has_next) S.a_ready(nxt);
;             if constexpr (SP2) {
;             PG8_LDB(B0, 0, 0); PG8_LDB(B1, 0, 1); PG8_SCHED; PG8_LDA(At, 0, 0); PG8_STAGE(PG8_SA(1, 1), a1 + hstepA, voffA);
;             PG8_WAIT_V(8); PG8_WAIT_L(0); PG8_BAR; PG8_MMA(0, 0, At, B0); PG8_MMA(0, 1, At, B1); PG8_BAR; PG8_SCHED;
;             PG8_LDA(At, 0, 1); PG8_STAGE(PG8_SB(0, 0), b2, voffB); PG8_STAGE(PG8_SB(0, 1), b2 + hstepB, voffB); PG8_STAGE(PG8_SA(0, 0), a2, voffA);
.LBB0_1483:
	s_mov_b32 s38, s37
	s_ashr_i32 s39, s37, 31
	s_mov_b32 s36, s13
	s_lshl_b64 s[12:13], s[38:39], 20
	s_add_u32 s46, s10, s12
	s_addc_u32 s47, s11, s13
	s_and_b64 s[12:13], s[44:45], exec
	s_cselect_b32 s39, s47, s51
	s_cselect_b32 s41, s46, s50
	s_ashr_i32 s37, s36, 31
	s_lshl_b64 s[12:13], s[36:37], 20
	s_add_u32 s48, s15, s12
	s_addc_u32 s49, s18, s13
	s_and_b64 s[12:13], s[44:45], exec
	s_cselect_b32 s37, s49, s53
	s_cselect_b32 s64, s48, s52
	s_add_u32 s50, s50, 0x80080
	s_addc_u32 s51, s51, 0
	s_add_u32 s65, s52, 0x100
	s_addc_u32 s66, s53, 0
	s_mov_b32 s67, -2
	s_add_u32 s12, s50, 0xfff80080
	s_addc_u32 s13, s51, -1
	s_add_i32 s68, 0, 0x10000
	s_cmp_eq_u32 s67, 28
	s_cselect_b32 s55, s39, s13
	s_cselect_b32 s54, s41, s12
	v_add_u32_e32 v138, s68, v141
	s_cselect_b32 s53, s37, s66
	s_cselect_b32 s52, s64, s65
	s_add_i32 s69, 0, 0x14000
	ds_read_b128 v[144:147], v138
	ds_read_b128 v[148:151], v138 offset:1024
	ds_read_b128 v[152:155], v138 offset:2048
	ds_read_b128 v[156:159], v138 offset:3072
	v_add_u32_e32 v138, s69, v141
	ds_read_b128 v[160:163], v138
	ds_read_b128 v[164:167], v138 offset:1024
	ds_read_b128 v[168:171], v138 offset:2048
	ds_read_b128 v[172:175], v138 offset:3072
	v_lshl_add_u64 v[138:139], s[50:51], 0, v[134:135]
	s_add_i32 m0, s43, 0xc000
	ds_read_b128 v[176:179], v143
	ds_read_b128 v[180:183], v143 offset:1024
	ds_read_b128 v[184:187], v143 offset:2048
	ds_read_b128 v[188:191], v143 offset:3072
	ds_read_b128 v[194:197], v143 offset:4096
	ds_read_b128 v[198:201], v143 offset:5120
	ds_read_b128 v[202:205], v143 offset:6144
	ds_read_b128 v[206:209], v143 offset:7168
	global_load_lds_dwordx4 v[138:139], off
	v_lshl_add_u64 v[138:139], s[50:51], 0, v[136:137]
	s_add_i32 m0, s43, 0xe000
	s_nop 0
	global_load_lds_dwordx4 v[138:139], off
	s_waitcnt vmcnt(8)
	s_waitcnt lgkmcnt(0)
	s_barrier
	s_setprio 1
	s_waitcnt lgkmcnt(0)
	v_mfma_f32_16x16x32_bf16 v[124:127], v[144:147], v[176:179], 0
	v_mfma_f32_16x16x32_bf16 v[120:123], v[152:155], v[176:179], 0
	v_mfma_f32_16x16x32_bf16 v[108:111], v[144:147], v[184:187], 0
	v_mfma_f32_16x16x32_bf16 v[104:107], v[152:155], v[184:187], 0
	v_mfma_f32_16x16x32_bf16 v[92:95], v[144:147], v[194:197], 0
	v_mfma_f32_16x16x32_bf16 v[88:91], v[152:155], v[194:197], 0
	v_mfma_f32_16x16x32_bf16 v[76:79], v[144:147], v[202:205], 0
	v_mfma_f32_16x16x32_bf16 v[72:75], v[152:155], v[202:205], 0
	v_mfma_f32_16x16x32_bf16 v[124:127], v[148:151], v[180:183], v[124:127]
	v_mfma_f32_16x16x32_bf16 v[120:123], v[156:159], v[180:183], v[120:123]
	v_mfma_f32_16x16x32_bf16 v[108:111], v[148:151], v[188:191], v[108:111]
	v_mfma_f32_16x16x32_bf16 v[104:107], v[156:159], v[188:191], v[104:107]
	v_mfma_f32_16x16x32_bf16 v[92:95], v[148:151], v[198:201], v[92:95]
	v_mfma_f32_16x16x32_bf16 v[88:91], v[156:159], v[198:201], v[88:91]
	v_mfma_f32_16x16x32_bf16 v[76:79], v[148:151], v[206:209], v[76:79]
	v_mfma_f32_16x16x32_bf16 v[72:75], v[156:159], v[206:209], v[72:75]
	s_setprio 0
	s_setprio 1
	v_mfma_f32_16x16x32_bf16 v[116:119], v[160:163], v[176:179], 0
	v_mfma_f32_16x16x32_bf16 v[112:115], v[168:171], v[176:179], 0
	v_mfma_f32_16x16x32_bf16 v[100:103], v[160:163], v[184:187], 0
	v_mfma_f32_16x16x32_bf16 v[96:99], v[168:171], v[184:187], 0
	v_mfma_f32_16x16x32_bf16 v[84:87], v[160:163], v[194:197], 0
	v_mfma_f32_16x16x32_bf16 v[80:83], v[168:171], v[194:197], 0
	v_mfma_f32_16x16x32_bf16 v[68:71], v[160:163], v[202:205], 0
	v_mfma_f32_16x16x32_bf16 v[64:67], v[168:171], v[202:205], 0
	v_mfma_f32_16x16x32_bf16 v[116:119], v[164:167], v[180:183], v[116:119]
	v_mfma_f32_16x16x32_bf16 v[112:115], v[172:175], v[180:183], v[112:115]
	v_mfma_f32_16x16x32_bf16 v[100:103], v[164:167], v[188:191], v[100:103]
	v_mfma_f32_16x16x32_bf16 v[96:99], v[172:175], v[188:191], v[96:99]
	v_mfma_f32_16x16x32_bf16 v[84:87], v[164:167], v[198:201], v[84:87]
	v_mfma_f32_16x16x32_bf16 v[80:83], v[172:175], v[198:201], v[80:83]
	v_mfma_f32_16x16x32_bf16 v[68:71], v[164:167], v[206:209], v[68:71]
	v_mfma_f32_16x16x32_bf16 v[64:67], v[172:175], v[206:209], v[64:67]
	s_setprio 0
	s_barrier
	s_add_i32 s12, s68, s56
	v_lshl_add_u64 v[138:139], s[52:53], 0, v[192:193]
	s_mov_b32 m0, s12
	ds_read_b128 v[176:179], v143 offset:16384
	ds_read_b128 v[180:183], v143 offset:17408
	ds_read_b128 v[184:187], v143 offset:18432
	ds_read_b128 v[188:191], v143 offset:19456
	ds_read_b128 v[194:197], v143 offset:20480
	ds_read_b128 v[198:201], v143 offset:21504
	ds_read_b128 v[202:205], v143 offset:22528
	ds_read_b128 v[206:209], v143 offset:23552
	global_load_lds_dwordx4 v[138:139], off
	s_add_i32 m0, s12, 0x2000
	s_add_u32 s12, s52, 0x80000
	v_lshl_add_u64 v[210:211], s[52:53], 0, v[132:133]
	s_addc_u32 s13, s53, 0
	s_add_i32 s68, s69, s56
	global_load_lds_dwordx4 v[210:211], off
	v_lshl_add_u64 v[212:213], s[12:13], 0, v[192:193]
	s_mov_b32 m0, s68
	v_lshl_add_u64 v[214:215], s[54:55], 0, v[130:131]
	global_load_lds_dwordx4 v[212:213], off
	v_lshl_add_u64 v[212:213], s[12:13], 0, v[132:133]
	s_add_i32 m0, s68, 0x2000
	s_nop 0
	global_load_lds_dwordx4 v[212:213], off
	v_lshl_add_u64 v[212:213], s[54:55], 0, v[128:129]
	s_mov_b32 m0, s43
	s_nop 0
	global_load_lds_dwordx4 v[212:213], off
	s_mov_b32 m0, s57
	s_nop 0
	global_load_lds_dwordx4 v[214:215], off
	s_waitcnt vmcnt(8)
	s_waitcnt lgkmcnt(0)
	s_barrier
; #define PG8_STAGE(bufoff, gbase, voff) do { _Pragma("unroll") for (int _i = 0; _i < 2; ++_i) \
;         __builtin_amdgcn_global_load_lds((const unsigned*)((const char*)(gbase) + (voff)[_i]), (PG8_LAS unsigned*)(lds + (bufoff) + ldsw + _i * 8192), 16, 0, 0); } while (0)
; #define PG8_LDA(dst, b, h) do { _Pragma("unroll") for (int m = 0; m < 4; ++m) _Pragma("unroll") for (int k = 0; k < 2; ++k) dst[m][k] = *(const PG8_LAS bf16x8*)(lds + PG8_SA(b, h) + aoff + m * 2048 + k * 1024); } while (0)
; #define PG8_LDB(dst, b, h) do { _Pragma("unroll") for (int n = 0; n < 2; ++n) _Pragma("unroll") for (int k = 0; k < 2; ++k) dst[n][k] = *(const PG8_LAS bf16x8*)(lds + PG8_SB(b, h) + boff + n * 2048 + k * 1024); } while (0)
; #define PG8_MMA(ai, bj, At, Bt) do { __builtin_amdgcn_s_setprio(1); _Pragma("unroll") for (int m = 0; m < 4; ++m) _Pragma("unroll") for (int n = 0; n < 2; ++n) _Pragma("unroll") for (int k = 0; k < 2; ++k) \
;         acc[ai][bj][m][n] = __builtin_amdgcn_mfma_f32_16x16x32_bf16(Bt[n][k], At[m][k], acc[ai][bj][m][n], 0, 0, 0); __builtin_amdgcn_s_setprio(0); } while (0)
; #define PG8_WAIT_V(n) asm volatile("s_waitcnt vmcnt(" #n ")" ::: "memory")
; #define PG8_WAIT_L(n) asm volatile("s_waitcnt lgkmcnt(" #n ")" ::: "memory")
; #define PG8_BAR __builtin_amdgcn_s_barrier()
; #define PG8_SCHED __builtin_amdgcn_sched_barrier(0)
; template <class Epi, class Sched, bool ALIGN_EPI = false, bool SP2 = false>
; __device__ __forceinline__ void gemm_phase(PG8_LAS unsigned char* lds, const Gemm g, const Sched& S, const Epi& E, const int tid_in) {
;     ...
;             PG8_WAIT_V(8); PG8_WAIT_L(0); PG8_BAR; PG8_MMA(1, 0, At, B0); PG8_MMA(1, 1, At, B1); PG8_BAR; PG8_SCHED;
;             PG8_LDB(B0, 1, 0); PG8_LDB(B1, 1, 1); PG8_SCHED; PG8_LDA(At, 1, 0); PG8_STAGE(PG8_SA(0, 1), a2 + hstepA, voffA);
;             PG8_WAIT_V(8); PG8_WAIT_L(0); PG8_BAR; PG8_MMA(0, 0, At, B0); PG8_MMA(0, 1, At, B1); PG8_BAR; PG8_SCHED;
	s_setprio 1
	s_waitcnt lgkmcnt(0)
	v_mfma_f32_16x16x32_bf16 v[60:63], v[144:147], v[176:179], 0
	v_mfma_f32_16x16x32_bf16 v[56:59], v[152:155], v[176:179], 0
	v_mfma_f32_16x16x32_bf16 v[44:47], v[144:147], v[184:187], 0
	v_mfma_f32_16x16x32_bf16 v[40:43], v[152:155], v[184:187], 0
	v_mfma_f32_16x16x32_bf16 v[28:31], v[144:147], v[194:197], 0
	v_mfma_f32_16x16x32_bf16 v[24:27], v[152:155], v[194:197], 0
	v_mfma_f32_16x16x32_bf16 v[12:15], v[144:147], v[202:205], 0
	v_mfma_f32_16x16x32_bf16 v[8:11], v[152:155], v[202:205], 0
	v_mfma_f32_16x16x32_bf16 v[60:63], v[148:151], v[180:183], v[60:63]
	v_mfma_f32_16x16x32_bf16 v[56:59], v[156:159], v[180:183], v[56:59]
	v_mfma_f32_16x16x32_bf16 v[44:47], v[148:151], v[188:191], v[44:47]
	v_mfma_f32_16x16x32_bf16 v[40:43], v[156:159], v[188:191], v[40:43]
	v_mfma_f32_16x16x32_bf16 v[28:31], v[148:151], v[198:201], v[28:31]
	v_mfma_f32_16x16x32_bf16 v[24:27], v[156:159], v[198:201], v[24:27]
	v_mfma_f32_16x16x32_bf16 v[12:15], v[148:151], v[206:209], v[12:15]
	v_mfma_f32_16x16x32_bf16 v[8:11], v[156:159], v[206:209], v[8:11]
	s_setprio 0
	s_setprio 1
	v_mfma_f32_16x16x32_bf16 v[52:55], v[160:163], v[176:179], 0
	v_mfma_f32_16x16x32_bf16 v[48:51], v[168:171], v[176:179], 0
	v_mfma_f32_16x16x32_bf16 v[36:39], v[160:163], v[184:187], 0
	v_mfma_f32_16x16x32_bf16 v[32:35], v[168:171], v[184:187], 0
	v_mfma_f32_16x16x32_bf16 v[20:23], v[160:163], v[194:197], 0
	v_mfma_f32_16x16x32_bf16 v[16:19], v[168:171], v[194:197], 0
	v_mfma_f32_16x16x32_bf16 v[4:7], v[160:163], v[202:205], 0
	v_mfma_f32_16x16x32_bf16 v[0:3], v[168:171], v[202:205], 0
	v_mfma_f32_16x16x32_bf16 v[52:55], v[164:167], v[180:183], v[52:55]
	v_mfma_f32_16x16x32_bf16 v[48:51], v[172:175], v[180:183], v[48:51]
	v_mfma_f32_16x16x32_bf16 v[36:39], v[164:167], v[188:191], v[36:39]
	v_mfma_f32_16x16x32_bf16 v[32:35], v[172:175], v[188:191], v[32:35]
	v_mfma_f32_16x16x32_bf16 v[20:23], v[164:167], v[198:201], v[20:23]
	v_mfma_f32_16x16x32_bf16 v[16:19], v[172:175], v[198:201], v[16:19]
	v_mfma_f32_16x16x32_bf16 v[4:7], v[164:167], v[206:209], v[4:7]
	v_mfma_f32_16x16x32_bf16 v[0:3], v[172:175], v[206:209], v[0:3]
	s_setprio 0
	s_barrier
	s_add_i32 s68, 0, 0x18000
	s_add_i32 s69, 0, 0x1c000
	v_add_u32_e32 v156, s68, v141
	v_add_u32_e32 v172, s69, v141
	ds_read_b128 v[144:147], v156
	ds_read_b128 v[148:151], v156 offset:1024
	ds_read_b128 v[152:155], v156 offset:2048
	ds_read_b128 v[156:159], v156 offset:3072
	ds_read_b128 v[160:163], v172
	ds_read_b128 v[164:167], v172 offset:1024
	ds_read_b128 v[168:171], v172 offset:2048
	ds_read_b128 v[172:175], v172 offset:3072
	s_add_u32 s12, s54, 0x80000
	s_addc_u32 s13, s55, 0
	s_mov_b32 m0, s58
	v_lshl_add_u64 v[216:217], s[12:13], 0, v[128:129]
	ds_read_b128 v[176:179], v143 offset:32768
	ds_read_b128 v[180:183], v143 offset:33792
	ds_read_b128 v[184:187], v143 offset:34816
	ds_read_b128 v[188:191], v143 offset:35840
	ds_read_b128 v[194:197], v143 offset:36864
	ds_read_b128 v[198:201], v143 offset:37888
	ds_read_b128 v[202:205], v143 offset:38912
	ds_read_b128 v[206:209], v143 offset:39936
	global_load_lds_dwordx4 v[216:217], off
	v_lshl_add_u64 v[216:217], s[12:13], 0, v[130:131]
	s_mov_b32 m0, s59
	s_nop 0
	global_load_lds_dwordx4 v[216:217], off
	s_waitcnt vmcnt(8)
	s_waitcnt lgkmcnt(0)
	s_barrier
	s_setprio 1
	s_waitcnt lgkmcnt(0)
	v_mfma_f32_16x16x32_bf16 v[124:127], v[144:147], v[176:179], v[124:127]
	v_mfma_f32_16x16x32_bf16 v[120:123], v[152:155], v[176:179], v[120:123]
	v_mfma_f32_16x16x32_bf16 v[108:111], v[144:147], v[184:187], v[108:111]
	v_mfma_f32_16x16x32_bf16 v[104:107], v[152:155], v[184:187], v[104:107]
	v_mfma_f32_16x16x32_bf16 v[92:95], v[144:147], v[194:197], v[92:95]
	v_mfma_f32_16x16x32_bf16 v[88:91], v[152:155], v[194:197], v[88:91]
	v_mfma_f32_16x16x32_bf16 v[76:79], v[144:147], v[202:205], v[76:79]
	v_mfma_f32_16x16x32_bf16 v[72:75], v[152:155], v[202:205], v[72:75]
	v_mfma_f32_16x16x32_bf16 v[124:127], v[148:151], v[180:183], v[124:127]
	v_mfma_f32_16x16x32_bf16 v[120:123], v[156:159], v[180:183], v[120:123]
	v_mfma_f32_16x16x32_bf16 v[108:111], v[148:151], v[188:191], v[108:111]
	v_mfma_f32_16x16x32_bf16 v[104:107], v[156:159], v[188:191], v[104:107]
	v_mfma_f32_16x16x32_bf16 v[92:95], v[148:151], v[198:201], v[92:95]
	v_mfma_f32_16x16x32_bf16 v[88:91], v[156:159], v[198:201], v[88:91]
	v_mfma_f32_16x16x32_bf16 v[76:79], v[148:151], v[206:209], v[76:79]
	v_mfma_f32_16x16x32_bf16 v[72:75], v[156:159], v[206:209], v[72:75]
	s_setprio 0
	s_setprio 1
	v_mfma_f32_16x16x32_bf16 v[116:119], v[160:163], v[176:179], v[116:119]
	v_mfma_f32_16x16x32_bf16 v[112:115], v[168:171], v[176:179], v[112:115]
	v_mfma_f32_16x16x32_bf16 v[100:103], v[160:163], v[184:187], v[100:103]
	v_mfma_f32_16x16x32_bf16 v[96:99], v[168:171], v[184:187], v[96:99]
	v_mfma_f32_16x16x32_bf16 v[84:87], v[160:163], v[194:197], v[84:87]
	v_mfma_f32_16x16x32_bf16 v[80:83], v[168:171], v[194:197], v[80:83]
	v_mfma_f32_16x16x32_bf16 v[68:71], v[160:163], v[202:205], v[68:71]
	v_mfma_f32_16x16x32_bf16 v[64:67], v[168:171], v[202:205], v[64:67]
	v_mfma_f32_16x16x32_bf16 v[116:119], v[164:167], v[180:183], v[116:119]
	v_mfma_f32_16x16x32_bf16 v[112:115], v[172:175], v[180:183], v[112:115]
	v_mfma_f32_16x16x32_bf16 v[100:103], v[164:167], v[188:191], v[100:103]
	v_mfma_f32_16x16x32_bf16 v[96:99], v[172:175], v[188:191], v[96:99]
	v_mfma_f32_16x16x32_bf16 v[84:87], v[164:167], v[198:201], v[84:87]
	v_mfma_f32_16x16x32_bf16 v[80:83], v[172:175], v[198:201], v[80:83]
	v_mfma_f32_16x16x32_bf16 v[68:71], v[164:167], v[206:209], v[68:71]
	v_mfma_f32_16x16x32_bf16 v[64:67], v[172:175], v[206:209], v[64:67]
	s_setprio 0
	s_barrier
; #define PG8_STAGE(bufoff, gbase, voff) do { _Pragma("unroll") for (int _i = 0; _i < 2; ++_i) \
;         __builtin_amdgcn_global_load_lds((const unsigned*)((const char*)(gbase) + (voff)[_i]), (PG8_LAS unsigned*)(lds + (bufoff) + ldsw + _i * 8192), 16, 0, 0); } while (0)
; #define PG8_LDA(dst, b, h) do { _Pragma("unroll") for (int m = 0; m < 4; ++m) _Pragma("unroll") for (int k = 0; k < 2; ++k) dst[m][k] = *(const PG8_LAS bf16x8*)(lds + PG8_SA(b, h) + aoff + m * 2048 + k * 1024); } while (0)
; #define PG8_LDB(dst, b, h) do { _Pragma("unroll") for (int n = 0; n < 2; ++n) _Pragma("unroll") for (int k = 0; k < 2; ++k) dst[n][k] = *(const PG8_LAS bf16x8*)(lds + PG8_SB(b, h) + boff + n * 2048 + k * 1024); } while (0)
; #define PG8_MMA(ai, bj, At, Bt) do { __builtin_amdgcn_s_setprio(1); _Pragma("unroll") for (int m = 0; m < 4; ++m) _Pragma("unroll") for (int n = 0; n < 2; ++n) _Pragma("unroll") for (int k = 0; k < 2; ++k) \
;         acc[ai][bj][m][n] = __builtin_amdgcn_mfma_f32_16x16x32_bf16(Bt[n][k], At[m][k], acc[ai][bj][m][n], 0, 0, 0); __builtin_amdgcn_s_setprio(0); } while (0)
; #define PG8_WAIT_V(n) asm volatile("s_waitcnt vmcnt(" #n ")" ::: "memory")
; #define PG8_WAIT_L(n) asm volatile("s_waitcnt lgkmcnt(" #n ")" ::: "memory")
; #define PG8_BAR __builtin_amdgcn_s_barrier()
; template <class Epi, class Sched, bool ALIGN_EPI = false, bool SP2 = false>
; __device__ __forceinline__ void gemm_phase(PG8_LAS unsigned char* lds, const Gemm g, const Sched& S, const Epi& E, const int tid_in) {
;     ...
;         for (int t = 0; t < nt; t += 2) {
;             const bool last = (t == nt - 2);
;             const char* a1 = cA + (size_t)(t + 1) * kstep;
;             const char* a2 = last ? nA : cA + (size_t)(t + 2) * kstep; const char* b2 = last ? nB : cB + (size_t)(t + 2) * kstep;
;             const char* a3 = a2 + kstep; const char* b3 = b2 + kstep;
;             if (last && has_next) S.a_ready(nxt);
;             if constexpr (SP2) {
;             PG8_LDB(B0, 0, 0); PG8_LDB(B1, 0, 1); PG8_SCHED; PG8_LDA(At, 0, 0); PG8_STAGE(PG8_SA(1, 1), a1 + hstepA, voffA);
;     ...
;             PG8_LDA(At, 1, 1); PG8_STAGE(PG8_SB(1, 0), b3, voffB); PG8_STAGE(PG8_SB(1, 1), b3 + hstepB, voffB); PG8_STAGE(PG8_SA(1, 0), a3, voffA);
;             PG8_WAIT_V(8); PG8_WAIT_L(0); PG8_BAR; PG8_MMA(1, 0, At, B0); PG8_MMA(1, 1, At, B1); PG8_BAR; PG8_SCHED;
	s_add_i32 s12, s68, s56
	v_lshl_add_u64 v[138:139], v[138:139], 0, s[26:27]
	s_mov_b32 m0, s12
	ds_read_b128 v[176:179], v143 offset:49152
	ds_read_b128 v[180:183], v143 offset:50176
	ds_read_b128 v[184:187], v143 offset:51200
	ds_read_b128 v[188:191], v143 offset:52224
	ds_read_b128 v[194:197], v143 offset:53248
	ds_read_b128 v[198:201], v143 offset:54272
	ds_read_b128 v[202:205], v143 offset:55296
	ds_read_b128 v[206:209], v143 offset:56320
	global_load_lds_dwordx4 v[138:139], off
	s_add_i32 m0, s12, 0x2000
	s_add_u32 s12, s52, 0x80080
	v_lshl_add_u64 v[138:139], v[210:211], 0, s[26:27]
	s_addc_u32 s13, s53, 0
	s_add_i32 s52, s69, s56
	global_load_lds_dwordx4 v[138:139], off
	v_lshl_add_u64 v[138:139], s[12:13], 0, v[192:193]
	s_mov_b32 m0, s52
	s_nop 0
	global_load_lds_dwordx4 v[138:139], off
	v_lshl_add_u64 v[138:139], s[12:13], 0, v[132:133]
	s_add_i32 m0, s52, 0x2000
	s_nop 0
	global_load_lds_dwordx4 v[138:139], off
	v_lshl_add_u64 v[138:139], v[212:213], 0, s[26:27]
	s_mov_b32 m0, s61
	s_nop 0
	global_load_lds_dwordx4 v[138:139], off
	v_lshl_add_u64 v[138:139], v[214:215], 0, s[26:27]
	s_mov_b32 m0, s62
	s_nop 0
	global_load_lds_dwordx4 v[138:139], off
	s_waitcnt vmcnt(8)
	s_waitcnt lgkmcnt(0)
	s_barrier
	s_setprio 1
	s_waitcnt lgkmcnt(0)
	v_mfma_f32_16x16x32_bf16 v[60:63], v[144:147], v[176:179], v[60:63]
	v_mfma_f32_16x16x32_bf16 v[56:59], v[152:155], v[176:179], v[56:59]
	v_mfma_f32_16x16x32_bf16 v[44:47], v[144:147], v[184:187], v[44:47]
	v_mfma_f32_16x16x32_bf16 v[40:43], v[152:155], v[184:187], v[40:43]
	v_mfma_f32_16x16x32_bf16 v[28:31], v[144:147], v[194:197], v[28:31]
	v_mfma_f32_16x16x32_bf16 v[24:27], v[152:155], v[194:197], v[24:27]
	v_mfma_f32_16x16x32_bf16 v[12:15], v[144:147], v[202:205], v[12:15]
	v_mfma_f32_16x16x32_bf16 v[8:11], v[152:155], v[202:205], v[8:11]
	v_mfma_f32_16x16x32_bf16 v[60:63], v[148:151], v[180:183], v[60:63]
	v_mfma_f32_16x16x32_bf16 v[56:59], v[156:159], v[180:183], v[56:59]
	v_mfma_f32_16x16x32_bf16 v[44:47], v[148:151], v[188:191], v[44:47]
	v_mfma_f32_16x16x32_bf16 v[40:43], v[156:159], v[188:191], v[40:43]
	v_mfma_f32_16x16x32_bf16 v[28:31], v[148:151], v[198:201], v[28:31]
	v_mfma_f32_16x16x32_bf16 v[24:27], v[156:159], v[198:201], v[24:27]
	v_mfma_f32_16x16x32_bf16 v[12:15], v[148:151], v[206:209], v[12:15]
	v_mfma_f32_16x16x32_bf16 v[8:11], v[156:159], v[206:209], v[8:11]
	s_setprio 0
	s_setprio 1
	v_mfma_f32_16x16x32_bf16 v[52:55], v[160:163], v[176:179], v[52:55]
	v_mfma_f32_16x16x32_bf16 v[48:51], v[168:171], v[176:179], v[48:51]
	v_mfma_f32_16x16x32_bf16 v[36:39], v[160:163], v[184:187], v[36:39]
	v_mfma_f32_16x16x32_bf16 v[32:35], v[168:171], v[184:187], v[32:35]
	v_mfma_f32_16x16x32_bf16 v[20:23], v[160:163], v[194:197], v[20:23]
	v_mfma_f32_16x16x32_bf16 v[16:19], v[168:171], v[194:197], v[16:19]
	v_mfma_f32_16x16x32_bf16 v[4:7], v[160:163], v[202:205], v[4:7]
	v_mfma_f32_16x16x32_bf16 v[0:3], v[168:171], v[202:205], v[0:3]
	v_mfma_f32_16x16x32_bf16 v[52:55], v[164:167], v[180:183], v[52:55]
	v_mfma_f32_16x16x32_bf16 v[48:51], v[172:175], v[180:183], v[48:51]
	v_mfma_f32_16x16x32_bf16 v[36:39], v[164:167], v[188:191], v[36:39]
	v_mfma_f32_16x16x32_bf16 v[32:35], v[172:175], v[188:191], v[32:35]
	v_mfma_f32_16x16x32_bf16 v[20:23], v[164:167], v[198:201], v[20:23]
	v_mfma_f32_16x16x32_bf16 v[16:19], v[172:175], v[198:201], v[16:19]
	v_mfma_f32_16x16x32_bf16 v[4:7], v[164:167], v[206:209], v[4:7]
	v_mfma_f32_16x16x32_bf16 v[0:3], v[172:175], v[206:209], v[0:3]
	s_setprio 0
	s_barrier
	s_add_i32 s67, s67, 2
	s_add_u32 s50, s50, 0x100
	s_addc_u32 s51, s51, 0
	s_add_u32 s65, s65, 0x100
	s_addc_u32 s66, s66, 0
	s_cmp_gt_u32 s67, 29
	.p2align 6
.LBB0_1484:
	s_add_u32 s12, s50, 0xfff80080
	s_addc_u32 s13, s51, -1
	s_add_i32 s68, 0, 0x10000
	s_cmp_eq_u32 s67, 28
	s_cselect_b32 s55, s39, s13
	s_cselect_b32 s54, s41, s12
	v_add_u32_e32 v138, s68, v141
	s_cselect_b32 s53, s37, s66
	s_cselect_b32 s52, s64, s65
	s_add_i32 s69, 0, 0x14000
	ds_read_b128 v[144:147], v138
	ds_read_b128 v[148:151], v138 offset:1024
	ds_read_b128 v[152:155], v138 offset:2048
	ds_read_b128 v[156:159], v138 offset:3072
	v_add_u32_e32 v138, s69, v141
	ds_read_b128 v[160:163], v138
	ds_read_b128 v[164:167], v138 offset:1024
	ds_read_b128 v[168:171], v138 offset:2048
	ds_read_b128 v[172:175], v138 offset:3072
	v_lshl_add_u64 v[138:139], s[50:51], 0, v[134:135]
	s_add_i32 m0, s43, 0xc000
	ds_read_b128 v[176:179], v143
	ds_read_b128 v[180:183], v143 offset:1024
	ds_read_b128 v[184:187], v143 offset:2048
	ds_read_b128 v[188:191], v143 offset:3072
	ds_read_b128 v[194:197], v143 offset:4096
	ds_read_b128 v[198:201], v143 offset:5120
	ds_read_b128 v[202:205], v143 offset:6144
	ds_read_b128 v[206:209], v143 offset:7168
	global_load_lds_dwordx4 v[138:139], off
	v_lshl_add_u64 v[138:139], s[50:51], 0, v[136:137]
	s_add_i32 m0, s43, 0xe000
	s_nop 0
	global_load_lds_dwordx4 v[138:139], off
	s_waitcnt vmcnt(8)
	s_waitcnt lgkmcnt(0)
	s_barrier
; #define PG8_STAGE(bufoff, gbase, voff) do { _Pragma("unroll") for (int _i = 0; _i < 2; ++_i) \
;         __builtin_amdgcn_global_load_lds((const unsigned*)((const char*)(gbase) + (voff)[_i]), (PG8_LAS unsigned*)(lds + (bufoff) + ldsw + _i * 8192), 16, 0, 0); } while (0)
; #define PG8_LDA(dst, b, h) do { _Pragma("unroll") for (int m = 0; m < 4; ++m) _Pragma("unroll") for (int k = 0; k < 2; ++k) dst[m][k] = *(const PG8_LAS bf16x8*)(lds + PG8_SA(b, h) + aoff + m * 2048 + k * 1024); } while (0)
; #define PG8_MMA(ai, bj, At, Bt) do { __builtin_amdgcn_s_setprio(1); _Pragma("unroll") for (int m = 0; m < 4; ++m) _Pragma("unroll") for (int n = 0; n < 2; ++n) _Pragma("unroll") for (int k = 0; k < 2; ++k) \
;         acc[ai][bj][m][n] = __builtin_amdgcn_mfma_f32_16x16x32_bf16(Bt[n][k], At[m][k], acc[ai][bj][m][n], 0, 0, 0); __builtin_amdgcn_s_setprio(0); } while (0)
; #define PG8_WAIT_V(n) asm volatile("s_waitcnt vmcnt(" #n ")" ::: "memory")
; #define PG8_WAIT_L(n) asm volatile("s_waitcnt lgkmcnt(" #n ")" ::: "memory")
; #define PG8_BAR __builtin_amdgcn_s_barrier()
; #define PG8_SCHED __builtin_amdgcn_sched_barrier(0)
; template <class Epi, class Sched, bool ALIGN_EPI = false, bool SP2 = false>
; __device__ __forceinline__ void gemm_phase(PG8_LAS unsigned char* lds, const Gemm g, const Sched& S, const Epi& E, const int tid_in) {
;     ...
;             PG8_WAIT_V(8); PG8_WAIT_L(0); PG8_BAR; PG8_MMA(0, 0, At, B0); PG8_MMA(0, 1, At, B1); PG8_BAR; PG8_SCHED;
;             PG8_LDA(At, 0, 1); PG8_STAGE(PG8_SB(0, 0), b2, voffB); PG8_STAGE(PG8_SB(0, 1), b2 + hstepB, voffB); PG8_STAGE(PG8_SA(0, 0), a2, voffA);
;             PG8_WAIT_V(8); PG8_WAIT_L(0); PG8_BAR; PG8_MMA(1, 0, At, B0); PG8_MMA(1, 1, At, B1); PG8_BAR; PG8_SCHED;
	s_setprio 1
	s_waitcnt lgkmcnt(0)
	v_mfma_f32_16x16x32_bf16 v[124:127], v[144:147], v[176:179], v[124:127]
	v_mfma_f32_16x16x32_bf16 v[120:123], v[152:155], v[176:179], v[120:123]
	v_mfma_f32_16x16x32_bf16 v[108:111], v[144:147], v[184:187], v[108:111]
	v_mfma_f32_16x16x32_bf16 v[104:107], v[152:155], v[184:187], v[104:107]
	v_mfma_f32_16x16x32_bf16 v[92:95], v[144:147], v[194:197], v[92:95]
	v_mfma_f32_16x16x32_bf16 v[88:91], v[152:155], v[194:197], v[88:91]
	v_mfma_f32_16x16x32_bf16 v[76:79], v[144:147], v[202:205], v[76:79]
	v_mfma_f32_16x16x32_bf16 v[72:75], v[152:155], v[202:205], v[72:75]
	v_mfma_f32_16x16x32_bf16 v[124:127], v[148:151], v[180:183], v[124:127]
	v_mfma_f32_16x16x32_bf16 v[120:123], v[156:159], v[180:183], v[120:123]
	v_mfma_f32_16x16x32_bf16 v[108:111], v[148:151], v[188:191], v[108:111]
	v_mfma_f32_16x16x32_bf16 v[104:107], v[156:159], v[188:191], v[104:107]
	v_mfma_f32_16x16x32_bf16 v[92:95], v[148:151], v[198:201], v[92:95]
	v_mfma_f32_16x16x32_bf16 v[88:91], v[156:159], v[198:201], v[88:91]
	v_mfma_f32_16x16x32_bf16 v[76:79], v[148:151], v[206:209], v[76:79]
	v_mfma_f32_16x16x32_bf16 v[72:75], v[156:159], v[206:209], v[72:75]
	v_mfma_f32_16x16x32_bf16 v[116:119], v[160:163], v[176:179], v[116:119]
	v_mfma_f32_16x16x32_bf16 v[112:115], v[168:171], v[176:179], v[112:115]
	v_mfma_f32_16x16x32_bf16 v[100:103], v[160:163], v[184:187], v[100:103]
	v_mfma_f32_16x16x32_bf16 v[96:99], v[168:171], v[184:187], v[96:99]
	v_mfma_f32_16x16x32_bf16 v[84:87], v[160:163], v[194:197], v[84:87]
	v_mfma_f32_16x16x32_bf16 v[80:83], v[168:171], v[194:197], v[80:83]
	v_mfma_f32_16x16x32_bf16 v[68:71], v[160:163], v[202:205], v[68:71]
	v_mfma_f32_16x16x32_bf16 v[64:67], v[168:171], v[202:205], v[64:67]
	v_mfma_f32_16x16x32_bf16 v[116:119], v[164:167], v[180:183], v[116:119]
	v_mfma_f32_16x16x32_bf16 v[112:115], v[172:175], v[180:183], v[112:115]
	v_mfma_f32_16x16x32_bf16 v[100:103], v[164:167], v[188:191], v[100:103]
	v_mfma_f32_16x16x32_bf16 v[96:99], v[172:175], v[188:191], v[96:99]
	v_mfma_f32_16x16x32_bf16 v[84:87], v[164:167], v[198:201], v[84:87]
	v_mfma_f32_16x16x32_bf16 v[80:83], v[172:175], v[198:201], v[80:83]
	v_mfma_f32_16x16x32_bf16 v[68:71], v[164:167], v[206:209], v[68:71]
	v_mfma_f32_16x16x32_bf16 v[64:67], v[172:175], v[206:209], v[64:67]
	s_setprio 0
	s_barrier
	s_add_i32 s12, s68, s56
	v_lshl_add_u64 v[138:139], s[52:53], 0, v[192:193]
	s_mov_b32 m0, s12
	ds_read_b128 v[176:179], v143 offset:16384
	ds_read_b128 v[180:183], v143 offset:17408
	ds_read_b128 v[184:187], v143 offset:18432
	ds_read_b128 v[188:191], v143 offset:19456
	ds_read_b128 v[194:197], v143 offset:20480
	ds_read_b128 v[198:201], v143 offset:21504
	ds_read_b128 v[202:205], v143 offset:22528
	ds_read_b128 v[206:209], v143 offset:23552
	global_load_lds_dwordx4 v[138:139], off
	s_add_i32 m0, s12, 0x2000
	s_add_u32 s12, s52, 0x80000
	v_lshl_add_u64 v[210:211], s[52:53], 0, v[132:133]
	s_addc_u32 s13, s53, 0
	s_add_i32 s68, s69, s56
	global_load_lds_dwordx4 v[210:211], off
	v_lshl_add_u64 v[212:213], s[12:13], 0, v[192:193]
	s_mov_b32 m0, s68
	v_lshl_add_u64 v[214:215], s[54:55], 0, v[130:131]
	global_load_lds_dwordx4 v[212:213], off
	v_lshl_add_u64 v[212:213], s[12:13], 0, v[132:133]
	s_add_i32 m0, s68, 0x2000
	s_nop 0
	global_load_lds_dwordx4 v[212:213], off
	v_lshl_add_u64 v[212:213], s[54:55], 0, v[128:129]
	s_mov_b32 m0, s43
	s_nop 0
	global_load_lds_dwordx4 v[212:213], off
	s_mov_b32 m0, s57
	s_nop 0
	global_load_lds_dwordx4 v[214:215], off
	s_waitcnt vmcnt(8)
	s_waitcnt lgkmcnt(0)
	s_barrier
	s_setprio 1
	s_waitcnt lgkmcnt(0)
	v_mfma_f32_16x16x32_bf16 v[60:63], v[144:147], v[176:179], v[60:63]
	v_mfma_f32_16x16x32_bf16 v[56:59], v[152:155], v[176:179], v[56:59]
	v_mfma_f32_16x16x32_bf16 v[44:47], v[144:147], v[184:187], v[44:47]
	v_mfma_f32_16x16x32_bf16 v[40:43], v[152:155], v[184:187], v[40:43]
	v_mfma_f32_16x16x32_bf16 v[28:31], v[144:147], v[194:197], v[28:31]
	v_mfma_f32_16x16x32_bf16 v[24:27], v[152:155], v[194:197], v[24:27]
	v_mfma_f32_16x16x32_bf16 v[12:15], v[144:147], v[202:205], v[12:15]
	v_mfma_f32_16x16x32_bf16 v[8:11], v[152:155], v[202:205], v[8:11]
	v_mfma_f32_16x16x32_bf16 v[60:63], v[148:151], v[180:183], v[60:63]
	v_mfma_f32_16x16x32_bf16 v[56:59], v[156:159], v[180:183], v[56:59]
	v_mfma_f32_16x16x32_bf16 v[44:47], v[148:151], v[188:191], v[44:47]
	v_mfma_f32_16x16x32_bf16 v[40:43], v[156:159], v[188:191], v[40:43]
	v_mfma_f32_16x16x32_bf16 v[28:31], v[148:151], v[198:201], v[28:31]
	v_mfma_f32_16x16x32_bf16 v[24:27], v[156:159], v[198:201], v[24:27]
	v_mfma_f32_16x16x32_bf16 v[12:15], v[148:151], v[206:209], v[12:15]
	v_mfma_f32_16x16x32_bf16 v[8:11], v[156:159], v[206:209], v[8:11]
	v_mfma_f32_16x16x32_bf16 v[52:55], v[160:163], v[176:179], v[52:55]
	v_mfma_f32_16x16x32_bf16 v[48:51], v[168:171], v[176:179], v[48:51]
	v_mfma_f32_16x16x32_bf16 v[36:39], v[160:163], v[184:187], v[36:39]
	v_mfma_f32_16x16x32_bf16 v[32:35], v[168:171], v[184:187], v[32:35]
	v_mfma_f32_16x16x32_bf16 v[20:23], v[160:163], v[194:197], v[20:23]
	v_mfma_f32_16x16x32_bf16 v[16:19], v[168:171], v[194:197], v[16:19]
	v_mfma_f32_16x16x32_bf16 v[4:7], v[160:163], v[202:205], v[4:7]
	v_mfma_f32_16x16x32_bf16 v[0:3], v[168:171], v[202:205], v[0:3]
	v_mfma_f32_16x16x32_bf16 v[52:55], v[164:167], v[180:183], v[52:55]
	v_mfma_f32_16x16x32_bf16 v[48:51], v[172:175], v[180:183], v[48:51]
	v_mfma_f32_16x16x32_bf16 v[36:39], v[164:167], v[188:191], v[36:39]
	v_mfma_f32_16x16x32_bf16 v[32:35], v[172:175], v[188:191], v[32:35]
	v_mfma_f32_16x16x32_bf16 v[20:23], v[164:167], v[198:201], v[20:23]
	v_mfma_f32_16x16x32_bf16 v[16:19], v[172:175], v[198:201], v[16:19]
	v_mfma_f32_16x16x32_bf16 v[4:7], v[164:167], v[206:209], v[4:7]
	v_mfma_f32_16x16x32_bf16 v[0:3], v[172:175], v[206:209], v[0:3]
	s_setprio 0
	s_barrier
; #define PG8_STAGE(bufoff, gbase, voff) do { _Pragma("unroll") for (int _i = 0; _i < 2; ++_i) \
;         __builtin_amdgcn_global_load_lds((const unsigned*)((const char*)(gbase) + (voff)[_i]), (PG8_LAS unsigned*)(lds + (bufoff) + ldsw + _i * 8192), 16, 0, 0); } while (0)
; #define PG8_LDA(dst, b, h) do { _Pragma("unroll") for (int m = 0; m < 4; ++m) _Pragma("unroll") for (int k = 0; k < 2; ++k) dst[m][k] = *(const PG8_LAS bf16x8*)(lds + PG8_SA(b, h) + aoff + m * 2048 + k * 1024); } while (0)
; #define PG8_LDB(dst, b, h) do { _Pragma("unroll") for (int n = 0; n < 2; ++n) _Pragma("unroll") for (int k = 0; k < 2; ++k) dst[n][k] = *(const PG8_LAS bf16x8*)(lds + PG8_SB(b, h) + boff + n * 2048 + k * 1024); } while (0)
; #define PG8_MMA(ai, bj, At, Bt) do { __builtin_amdgcn_s_setprio(1); _Pragma("unroll") for (int m = 0; m < 4; ++m) _Pragma("unroll") for (int n = 0; n < 2; ++n) _Pragma("unroll") for (int k = 0; k < 2; ++k) \
;         acc[ai][bj][m][n] = __builtin_amdgcn_mfma_f32_16x16x32_bf16(Bt[n][k], At[m][k], acc[ai][bj][m][n], 0, 0, 0); __builtin_amdgcn_s_setprio(0); } while (0)
; #define PG8_WAIT_V(n) asm volatile("s_waitcnt vmcnt(" #n ")" ::: "memory")
; #define PG8_WAIT_L(n) asm volatile("s_waitcnt lgkmcnt(" #n ")" ::: "memory")
; #define PG8_BAR __builtin_amdgcn_s_barrier()
; #define PG8_SCHED __builtin_amdgcn_sched_barrier(0)
; template <class Epi, class Sched, bool ALIGN_EPI = false, bool SP2 = false>
; __device__ __forceinline__ void gemm_phase(PG8_LAS unsigned char* lds, const Gemm g, const Sched& S, const Epi& E, const int tid_in) {
;     ...
;             PG8_LDB(B0, 1, 0); PG8_LDB(B1, 1, 1); PG8_SCHED; PG8_LDA(At, 1, 0); PG8_STAGE(PG8_SA(0, 1), a2 + hstepA, voffA);
;             PG8_WAIT_V(8); PG8_WAIT_L(0); PG8_BAR; PG8_MMA(0, 0, At, B0); PG8_MMA(0, 1, At, B1); PG8_BAR; PG8_SCHED;
	s_add_i32 s68, 0, 0x18000
	s_add_i32 s69, 0, 0x1c000
	v_add_u32_e32 v156, s68, v141
	v_add_u32_e32 v172, s69, v141
	ds_read_b128 v[144:147], v156
	ds_read_b128 v[148:151], v156 offset:1024
	ds_read_b128 v[152:155], v156 offset:2048
	ds_read_b128 v[156:159], v156 offset:3072
	ds_read_b128 v[160:163], v172
	ds_read_b128 v[164:167], v172 offset:1024
	ds_read_b128 v[168:171], v172 offset:2048
	ds_read_b128 v[172:175], v172 offset:3072
	s_add_u32 s12, s54, 0x80000
	s_addc_u32 s13, s55, 0
	s_mov_b32 m0, s58
	v_lshl_add_u64 v[216:217], s[12:13], 0, v[128:129]
	ds_read_b128 v[176:179], v143 offset:32768
	ds_read_b128 v[180:183], v143 offset:33792
	ds_read_b128 v[184:187], v143 offset:34816
	ds_read_b128 v[188:191], v143 offset:35840
	ds_read_b128 v[194:197], v143 offset:36864
	ds_read_b128 v[198:201], v143 offset:37888
	ds_read_b128 v[202:205], v143 offset:38912
	ds_read_b128 v[206:209], v143 offset:39936
	global_load_lds_dwordx4 v[216:217], off
	v_lshl_add_u64 v[216:217], s[12:13], 0, v[130:131]
	s_mov_b32 m0, s59
	s_nop 0
	global_load_lds_dwordx4 v[216:217], off
	s_waitcnt vmcnt(8)
	s_waitcnt lgkmcnt(0)
	s_barrier
	s_setprio 1
	s_waitcnt lgkmcnt(0)
	v_mfma_f32_16x16x32_bf16 v[124:127], v[144:147], v[176:179], v[124:127]
	v_mfma_f32_16x16x32_bf16 v[120:123], v[152:155], v[176:179], v[120:123]
	v_mfma_f32_16x16x32_bf16 v[108:111], v[144:147], v[184:187], v[108:111]
	v_mfma_f32_16x16x32_bf16 v[104:107], v[152:155], v[184:187], v[104:107]
	v_mfma_f32_16x16x32_bf16 v[92:95], v[144:147], v[194:197], v[92:95]
	v_mfma_f32_16x16x32_bf16 v[88:91], v[152:155], v[194:197], v[88:91]
	v_mfma_f32_16x16x32_bf16 v[76:79], v[144:147], v[202:205], v[76:79]
	v_mfma_f32_16x16x32_bf16 v[72:75], v[152:155], v[202:205], v[72:75]
	v_mfma_f32_16x16x32_bf16 v[124:127], v[148:151], v[180:183], v[124:127]
	v_mfma_f32_16x16x32_bf16 v[120:123], v[156:159], v[180:183], v[120:123]
	v_mfma_f32_16x16x32_bf16 v[108:111], v[148:151], v[188:191], v[108:111]
	v_mfma_f32_16x16x32_bf16 v[104:107], v[156:159], v[188:191], v[104:107]
	v_mfma_f32_16x16x32_bf16 v[92:95], v[148:151], v[198:201], v[92:95]
	v_mfma_f32_16x16x32_bf16 v[88:91], v[156:159], v[198:201], v[88:91]
	v_mfma_f32_16x16x32_bf16 v[76:79], v[148:151], v[206:209], v[76:79]
	v_mfma_f32_16x16x32_bf16 v[72:75], v[156:159], v[206:209], v[72:75]
	v_mfma_f32_16x16x32_bf16 v[116:119], v[160:163], v[176:179], v[116:119]
	v_mfma_f32_16x16x32_bf16 v[112:115], v[168:171], v[176:179], v[112:115]
	v_mfma_f32_16x16x32_bf16 v[100:103], v[160:163], v[184:187], v[100:103]
	v_mfma_f32_16x16x32_bf16 v[96:99], v[168:171], v[184:187], v[96:99]
	v_mfma_f32_16x16x32_bf16 v[84:87], v[160:163], v[194:197], v[84:87]
	v_mfma_f32_16x16x32_bf16 v[80:83], v[168:171], v[194:197], v[80:83]
	v_mfma_f32_16x16x32_bf16 v[68:71], v[160:163], v[202:205], v[68:71]
	v_mfma_f32_16x16x32_bf16 v[64:67], v[168:171], v[202:205], v[64:67]
	v_mfma_f32_16x16x32_bf16 v[116:119], v[164:167], v[180:183], v[116:119]
	v_mfma_f32_16x16x32_bf16 v[112:115], v[172:175], v[180:183], v[112:115]
	v_mfma_f32_16x16x32_bf16 v[100:103], v[164:167], v[188:191], v[100:103]
	v_mfma_f32_16x16x32_bf16 v[96:99], v[172:175], v[188:191], v[96:99]
	v_mfma_f32_16x16x32_bf16 v[84:87], v[164:167], v[198:201], v[84:87]
	v_mfma_f32_16x16x32_bf16 v[80:83], v[172:175], v[198:201], v[80:83]
	v_mfma_f32_16x16x32_bf16 v[68:71], v[164:167], v[206:209], v[68:71]
	v_mfma_f32_16x16x32_bf16 v[64:67], v[172:175], v[206:209], v[64:67]
	s_setprio 0
	s_barrier
; #define PG8_STAGE(bufoff, gbase, voff) do { _Pragma("unroll") for (int _i = 0; _i < 2; ++_i) \
;         __builtin_amdgcn_global_load_lds((const unsigned*)((const char*)(gbase) + (voff)[_i]), (PG8_LAS unsigned*)(lds + (bufoff) + ldsw + _i * 8192), 16, 0, 0); } while (0)
; #define PG8_LDA(dst, b, h) do { _Pragma("unroll") for (int m = 0; m < 4; ++m) _Pragma("unroll") for (int k = 0; k < 2; ++k) dst[m][k] = *(const PG8_LAS bf16x8*)(lds + PG8_SA(b, h) + aoff + m * 2048 + k * 1024); } while (0)
; #define PG8_MMA(ai, bj, At, Bt) do { __builtin_amdgcn_s_setprio(1); _Pragma("unroll") for (int m = 0; m < 4; ++m) _Pragma("unroll") for (int n = 0; n < 2; ++n) _Pragma("unroll") for (int k = 0; k < 2; ++k) \
;         acc[ai][bj][m][n] = __builtin_amdgcn_mfma_f32_16x16x32_bf16(Bt[n][k], At[m][k], acc[ai][bj][m][n], 0, 0, 0); __builtin_amdgcn_s_setprio(0); } while (0)
; #define PG8_WAIT_V(n) asm volatile("s_waitcnt vmcnt(" #n ")" ::: "memory")
; #define PG8_WAIT_L(n) asm volatile("s_waitcnt lgkmcnt(" #n ")" ::: "memory")
; #define PG8_BAR __builtin_amdgcn_s_barrier()
; #define PG8_SCHED __builtin_amdgcn_sched_barrier(0)
; template <class Epi, class Sched, bool ALIGN_EPI = false, bool SP2 = false>
; __device__ __forceinline__ void gemm_phase(PG8_LAS unsigned char* lds, const Gemm g, const Sched& S, const Epi& E, const int tid_in) {
;     ...
;         for (int t = 0; t < nt; t += 2) {
;             const bool last = (t == nt - 2);
;             const char* a1 = cA + (size_t)(t + 1) * kstep;
;             const char* a2 = last ? nA : cA + (size_t)(t + 2) * kstep; const char* b2 = last ? nB : cB + (size_t)(t + 2) * kstep;
;             const char* a3 = a2 + kstep; const char* b3 = b2 + kstep;
;             if (last && has_next) S.a_ready(nxt);
;     ...
;             PG8_LDA(At, 1, 1); PG8_STAGE(PG8_SB(1, 0), b3, voffB); PG8_STAGE(PG8_SB(1, 1), b3 + hstepB, voffB); PG8_STAGE(PG8_SA(1, 0), a3, voffA);
;             PG8_WAIT_V(8); PG8_WAIT_L(0); PG8_BAR; PG8_MMA(1, 0, At, B0); PG8_MMA(1, 1, At, B1); PG8_BAR; PG8_SCHED;
	s_add_i32 s12, s68, s56
	v_lshl_add_u64 v[138:139], v[138:139], 0, s[26:27]
	s_mov_b32 m0, s12
	ds_read_b128 v[176:179], v143 offset:49152
	ds_read_b128 v[180:183], v143 offset:50176
	ds_read_b128 v[184:187], v143 offset:51200
	ds_read_b128 v[188:191], v143 offset:52224
	ds_read_b128 v[194:197], v143 offset:53248
	ds_read_b128 v[198:201], v143 offset:54272
	ds_read_b128 v[202:205], v143 offset:55296
	ds_read_b128 v[206:209], v143 offset:56320
	global_load_lds_dwordx4 v[138:139], off
	s_add_i32 m0, s12, 0x2000
	s_add_u32 s12, s52, 0x80080
	v_lshl_add_u64 v[138:139], v[210:211], 0, s[26:27]
	s_addc_u32 s13, s53, 0
	s_add_i32 s52, s69, s56
	global_load_lds_dwordx4 v[138:139], off
	v_lshl_add_u64 v[138:139], s[12:13], 0, v[192:193]
	s_mov_b32 m0, s52
	s_nop 0
	global_load_lds_dwordx4 v[138:139], off
	v_lshl_add_u64 v[138:139], s[12:13], 0, v[132:133]
	s_add_i32 m0, s52, 0x2000
	s_nop 0
	global_load_lds_dwordx4 v[138:139], off
	v_lshl_add_u64 v[138:139], v[212:213], 0, s[26:27]
	s_mov_b32 m0, s61
	s_nop 0
	global_load_lds_dwordx4 v[138:139], off
	v_lshl_add_u64 v[138:139], v[214:215], 0, s[26:27]
	s_mov_b32 m0, s62
	s_nop 0
	global_load_lds_dwordx4 v[138:139], off
	s_waitcnt vmcnt(8)
	s_waitcnt lgkmcnt(0)
	s_barrier
	s_setprio 1
	s_waitcnt lgkmcnt(0)
	v_mfma_f32_16x16x32_bf16 v[60:63], v[144:147], v[176:179], v[60:63]
	v_mfma_f32_16x16x32_bf16 v[56:59], v[152:155], v[176:179], v[56:59]
	v_mfma_f32_16x16x32_bf16 v[44:47], v[144:147], v[184:187], v[44:47]
	v_mfma_f32_16x16x32_bf16 v[40:43], v[152:155], v[184:187], v[40:43]
	v_mfma_f32_16x16x32_bf16 v[28:31], v[144:147], v[194:197], v[28:31]
	v_mfma_f32_16x16x32_bf16 v[24:27], v[152:155], v[194:197], v[24:27]
	v_mfma_f32_16x16x32_bf16 v[12:15], v[144:147], v[202:205], v[12:15]
	v_mfma_f32_16x16x32_bf16 v[8:11], v[152:155], v[202:205], v[8:11]
	v_mfma_f32_16x16x32_bf16 v[60:63], v[148:151], v[180:183], v[60:63]
	v_mfma_f32_16x16x32_bf16 v[56:59], v[156:159], v[180:183], v[56:59]
	v_mfma_f32_16x16x32_bf16 v[44:47], v[148:151], v[188:191], v[44:47]
	v_mfma_f32_16x16x32_bf16 v[40:43], v[156:159], v[188:191], v[40:43]
	v_mfma_f32_16x16x32_bf16 v[28:31], v[148:151], v[198:201], v[28:31]
	v_mfma_f32_16x16x32_bf16 v[24:27], v[156:159], v[198:201], v[24:27]
	v_mfma_f32_16x16x32_bf16 v[12:15], v[148:151], v[206:209], v[12:15]
	v_mfma_f32_16x16x32_bf16 v[8:11], v[156:159], v[206:209], v[8:11]
	v_mfma_f32_16x16x32_bf16 v[52:55], v[160:163], v[176:179], v[52:55]
	v_mfma_f32_16x16x32_bf16 v[48:51], v[168:171], v[176:179], v[48:51]
	v_mfma_f32_16x16x32_bf16 v[36:39], v[160:163], v[184:187], v[36:39]
	v_mfma_f32_16x16x32_bf16 v[32:35], v[168:171], v[184:187], v[32:35]
	v_mfma_f32_16x16x32_bf16 v[20:23], v[160:163], v[194:197], v[20:23]
	v_mfma_f32_16x16x32_bf16 v[16:19], v[168:171], v[194:197], v[16:19]
	v_mfma_f32_16x16x32_bf16 v[4:7], v[160:163], v[202:205], v[4:7]
	v_mfma_f32_16x16x32_bf16 v[0:3], v[168:171], v[202:205], v[0:3]
	v_mfma_f32_16x16x32_bf16 v[52:55], v[164:167], v[180:183], v[52:55]
	v_mfma_f32_16x16x32_bf16 v[48:51], v[172:175], v[180:183], v[48:51]
	v_mfma_f32_16x16x32_bf16 v[36:39], v[164:167], v[188:191], v[36:39]
	v_mfma_f32_16x16x32_bf16 v[32:35], v[172:175], v[188:191], v[32:35]
	v_mfma_f32_16x16x32_bf16 v[20:23], v[164:167], v[198:201], v[20:23]
	v_mfma_f32_16x16x32_bf16 v[16:19], v[172:175], v[198:201], v[16:19]
	v_mfma_f32_16x16x32_bf16 v[4:7], v[164:167], v[206:209], v[4:7]
	v_mfma_f32_16x16x32_bf16 v[0:3], v[172:175], v[206:209], v[0:3]
	s_setprio 0
	s_barrier
	s_add_i32 s67, s67, 2
	s_add_u32 s50, s50, 0x100
	s_addc_u32 s51, s51, 0
	s_add_u32 s65, s65, 0x100
	s_addc_u32 s66, s66, 0
	s_cmp_gt_u32 s67, 29
	s_cbranch_scc0 .LBB0_1484
	s_and_b64 vcc, exec, s[30:31]
	s_cbranch_vccz .LBB0_1487
	s_barrier

; #define PG8_STAGE(bufoff, gbase, voff) do { _Pragma("unroll") for (int _i = 0; _i < 2; ++_i) \
;         __builtin_amdgcn_global_load_lds((const unsigned*)((const char*)(gbase) + (voff)[_i]), (PG8_LAS unsigned*)(lds + (bufoff) + ldsw + _i * 8192), 16, 0, 0); } while (0)
; #define PG8_LDA(dst, b, h) do { _Pragma("unroll") for (int m = 0; m < 4; ++m) _Pragma("unroll") for (int k = 0; k < 2; ++k) dst[m][k] = *(const PG8_LAS bf16x8*)(lds + PG8_SA(b, h) + aoff + m * 2048 + k * 1024); } while (0)
; #define PG8_LDB(dst, b, h) do { _Pragma("unroll") for (int n = 0; n < 2; ++n) _Pragma("unroll") for (int k = 0; k < 2; ++k) dst[n][k] = *(const PG8_LAS bf16x8*)(lds + PG8_SB(b, h) + boff + n * 2048 + k * 1024); } while (0)
; #define PG8_MMA(ai, bj, At, Bt) do { __builtin_amdgcn_s_setprio(1); _Pragma("unroll") for (int m = 0; m < 4; ++m) _Pragma("unroll") for (int n = 0; n < 2; ++n) _Pragma("unroll") for (int k = 0; k < 2; ++k) \
;         acc[ai][bj][m][n] = __builtin_amdgcn_mfma_f32_16x16x32_bf16(Bt[n][k], At[m][k], acc[ai][bj][m][n], 0, 0, 0); __builtin_amdgcn_s_setprio(0); } while (0)
; template <class Epi, class Sched, bool ALIGN_EPI = false, bool SP2 = false>
; __device__ __forceinline__ void gemm_phase(PG8_LAS unsigned char* lds, const Gemm g, const Sched& S, const Epi& E, const int tid_in) {
;     ...
;         const bool has_next = S.next(ui + 1, nxt);
;         const char* nA = has_next ? (const char*)g.A + (size_t)nxt.pm * tstepA : cA; const char* nB = has_next ? (const char*)g.Bt + (size_t)nxt.pn * tstepB : cB;
;         for (int t = 0; t < nt; t += 2) {
;             const bool last = (t == nt - 2);
;             const char* a1 = cA + (size_t)(t + 1) * kstep;
;             const char* a2 = last ? nA : cA + (size_t)(t + 2) * kstep; const char* b2 = last ? nB : cB + (size_t)(t + 2) * kstep;
;             const char* a3 = a2 + kstep; const char* b3 = b2 + kstep;
;             if (last && has_next) S.a_ready(nxt);
;             if constexpr (SP2) {
;             PG8_LDB(B0, 0, 0); PG8_LDB(B1, 0, 1); PG8_SCHED; PG8_LDA(At, 0, 0); PG8_STAGE(PG8_SA(1, 1), a1 + hstepA, voffA);
;             PG8_WAIT_V(8); PG8_WAIT_L(0); PG8_BAR; PG8_MMA(0, 0, At, B0); PG8_MMA(0, 1, At, B1); PG8_BAR; PG8_SCHED;
;             PG8_LDA(At, 0, 1); PG8_STAGE(PG8_SB(0, 0), b2, voffB); PG8_STAGE(PG8_SB(0, 1), b2 + hstepB, voffB); PG8_STAGE(PG8_SA(0, 0), a2, voffA);
.LBB0_1560:
	s_ashr_i32 s47, s46, 31
	s_lshl_b64 s[12:13], s[46:47], 22
	s_add_u32 s50, s62, s12
	s_addc_u32 s51, s63, s13
	s_and_b64 s[12:13], s[38:39], exec
	s_cselect_b32 s47, s51, s57
	s_cselect_b32 s53, s50, s56
	s_add_u32 s73, s56, 0x100
	s_addc_u32 s74, s57, 0
	s_mov_b32 s75, -2
	s_add_u32 s38, s54, 0x100
	s_addc_u32 s39, s55, 0
	s_add_i32 s12, 0, 0x10000
	s_cmp_eq_u32 s75, 56
	s_cselect_b32 s59, s49, s39
	s_cselect_b32 s58, s48, s38
	s_cselect_b32 s57, s47, s74
	s_cselect_b32 s56, s53, s73
	s_add_i32 s76, 0, 0x14000
	v_add_u32_e32 v116, s12, v228
	v_add_u32_e32 v156, s76, v228
	ds_read_b128 v[88:91], v116
	ds_read_b128 v[92:95], v116 offset:1024
	ds_read_b128 v[112:115], v116 offset:2048
	ds_read_b128 v[116:119], v116 offset:3072
	ds_read_b128 v[132:135], v156
	ds_read_b128 v[140:143], v156 offset:1024
	ds_read_b128 v[144:147], v156 offset:2048
	ds_read_b128 v[156:159], v156 offset:3072
	v_lshl_add_u64 v[204:205], s[54:55], 0, v[200:201]
	s_add_i32 m0, s64, 0xc000
	ds_read_b128 v[160:163], v230
	ds_read_b128 v[164:167], v230 offset:1024
	ds_read_b128 v[168:171], v230 offset:2048
	ds_read_b128 v[172:175], v230 offset:3072
	ds_read_b128 v[176:179], v230 offset:4096
	ds_read_b128 v[180:183], v230 offset:5120
	ds_read_b128 v[184:187], v230 offset:6144
	ds_read_b128 v[194:197], v230 offset:7168
	global_load_lds_dwordx4 v[204:205], off
	v_lshl_add_u64 v[204:205], s[54:55], 0, v[202:203]
	s_add_i32 m0, s64, 0xe000
	s_nop 0
	global_load_lds_dwordx4 v[204:205], off
	s_waitcnt vmcnt(8)
	s_waitcnt lgkmcnt(0)
	s_barrier
	s_setprio 1
	s_waitcnt lgkmcnt(0)
	v_mfma_f32_16x16x32_bf16 v[152:155], v[88:91], v[160:163], 0
	v_mfma_f32_16x16x32_bf16 v[148:151], v[112:115], v[160:163], 0
	v_mfma_f32_16x16x32_bf16 v[124:127], v[88:91], v[168:171], 0
	v_mfma_f32_16x16x32_bf16 v[120:123], v[112:115], v[168:171], 0
	v_mfma_f32_16x16x32_bf16 v[100:103], v[88:91], v[176:179], 0
	v_mfma_f32_16x16x32_bf16 v[96:99], v[112:115], v[176:179], 0
	v_mfma_f32_16x16x32_bf16 v[76:79], v[88:91], v[184:187], 0
	v_mfma_f32_16x16x32_bf16 v[72:75], v[112:115], v[184:187], 0
	v_mfma_f32_16x16x32_bf16 v[152:155], v[92:95], v[164:167], v[152:155]
	v_mfma_f32_16x16x32_bf16 v[148:151], v[116:119], v[164:167], v[148:151]
	v_mfma_f32_16x16x32_bf16 v[124:127], v[92:95], v[172:175], v[124:127]
	v_mfma_f32_16x16x32_bf16 v[120:123], v[116:119], v[172:175], v[120:123]
	v_mfma_f32_16x16x32_bf16 v[100:103], v[92:95], v[180:183], v[100:103]
	v_mfma_f32_16x16x32_bf16 v[96:99], v[116:119], v[180:183], v[96:99]
	v_mfma_f32_16x16x32_bf16 v[76:79], v[92:95], v[194:197], v[76:79]
	v_mfma_f32_16x16x32_bf16 v[72:75], v[116:119], v[194:197], v[72:75]
	s_setprio 0
	s_setprio 1
	v_mfma_f32_16x16x32_bf16 v[136:139], v[132:135], v[160:163], 0
	v_mfma_f32_16x16x32_bf16 v[128:131], v[144:147], v[160:163], 0
	v_mfma_f32_16x16x32_bf16 v[108:111], v[132:135], v[168:171], 0
	v_mfma_f32_16x16x32_bf16 v[104:107], v[144:147], v[168:171], 0
	v_mfma_f32_16x16x32_bf16 v[84:87], v[132:135], v[176:179], 0
	v_mfma_f32_16x16x32_bf16 v[80:83], v[144:147], v[176:179], 0
	v_mfma_f32_16x16x32_bf16 v[68:71], v[132:135], v[184:187], 0
	v_mfma_f32_16x16x32_bf16 v[64:67], v[144:147], v[184:187], 0
	v_mfma_f32_16x16x32_bf16 v[136:139], v[140:143], v[164:167], v[136:139]
	v_mfma_f32_16x16x32_bf16 v[128:131], v[156:159], v[164:167], v[128:131]
	v_mfma_f32_16x16x32_bf16 v[108:111], v[140:143], v[172:175], v[108:111]
	v_mfma_f32_16x16x32_bf16 v[104:107], v[156:159], v[172:175], v[104:107]
	v_mfma_f32_16x16x32_bf16 v[84:87], v[140:143], v[180:183], v[84:87]
	v_mfma_f32_16x16x32_bf16 v[80:83], v[156:159], v[180:183], v[80:83]
	v_mfma_f32_16x16x32_bf16 v[68:71], v[140:143], v[194:197], v[68:71]
	v_mfma_f32_16x16x32_bf16 v[64:67], v[156:159], v[194:197], v[64:67]
	s_setprio 0
	s_barrier
	s_add_i32 s12, s12, s61
	v_lshl_add_u64 v[204:205], s[56:57], 0, v[192:193]
	s_mov_b32 m0, s12
	ds_read_b128 v[160:163], v230 offset:16384
	ds_read_b128 v[164:167], v230 offset:17408
	ds_read_b128 v[168:171], v230 offset:18432
	ds_read_b128 v[172:175], v230 offset:19456
	ds_read_b128 v[176:179], v230 offset:20480
	ds_read_b128 v[180:183], v230 offset:21504
	ds_read_b128 v[184:187], v230 offset:22528
	ds_read_b128 v[194:197], v230 offset:23552
	global_load_lds_dwordx4 v[204:205], off
	s_add_i32 m0, s12, 0x2000
	s_add_u32 s12, s56, 0x200000
	v_lshl_add_u64 v[206:207], s[56:57], 0, v[198:199]
	s_addc_u32 s13, s57, 0
	s_add_i32 s54, s76, s61
	global_load_lds_dwordx4 v[206:207], off
	v_lshl_add_u64 v[208:209], s[12:13], 0, v[192:193]
	s_mov_b32 m0, s54
	v_lshl_add_u64 v[210:211], s[58:59], 0, v[190:191]
	global_load_lds_dwordx4 v[208:209], off
	v_lshl_add_u64 v[208:209], s[12:13], 0, v[198:199]
	s_add_i32 m0, s54, 0x2000
	s_nop 0
	global_load_lds_dwordx4 v[208:209], off
	v_lshl_add_u64 v[208:209], s[58:59], 0, v[188:189]
	s_mov_b32 m0, s64
	s_nop 0
	global_load_lds_dwordx4 v[208:209], off
	s_mov_b32 m0, s65
	s_nop 0
	global_load_lds_dwordx4 v[210:211], off
	s_waitcnt vmcnt(8)
	s_waitcnt lgkmcnt(0)
	s_barrier
; #define PG8_STAGE(bufoff, gbase, voff) do { _Pragma("unroll") for (int _i = 0; _i < 2; ++_i) \
;         __builtin_amdgcn_global_load_lds((const unsigned*)((const char*)(gbase) + (voff)[_i]), (PG8_LAS unsigned*)(lds + (bufoff) + ldsw + _i * 8192), 16, 0, 0); } while (0)
; #define PG8_LDA(dst, b, h) do { _Pragma("unroll") for (int m = 0; m < 4; ++m) _Pragma("unroll") for (int k = 0; k < 2; ++k) dst[m][k] = *(const PG8_LAS bf16x8*)(lds + PG8_SA(b, h) + aoff + m * 2048 + k * 1024); } while (0)
; #define PG8_LDB(dst, b, h) do { _Pragma("unroll") for (int n = 0; n < 2; ++n) _Pragma("unroll") for (int k = 0; k < 2; ++k) dst[n][k] = *(const PG8_LAS bf16x8*)(lds + PG8_SB(b, h) + boff + n * 2048 + k * 1024); } while (0)
; #define PG8_MMA(ai, bj, At, Bt) do { __builtin_amdgcn_s_setprio(1); _Pragma("unroll") for (int m = 0; m < 4; ++m) _Pragma("unroll") for (int n = 0; n < 2; ++n) _Pragma("unroll") for (int k = 0; k < 2; ++k) \
;         acc[ai][bj][m][n] = __builtin_amdgcn_mfma_f32_16x16x32_bf16(Bt[n][k], At[m][k], acc[ai][bj][m][n], 0, 0, 0); __builtin_amdgcn_s_setprio(0); } while (0)
; #define PG8_WAIT_V(n) asm volatile("s_waitcnt vmcnt(" #n ")" ::: "memory")
; #define PG8_WAIT_L(n) asm volatile("s_waitcnt lgkmcnt(" #n ")" ::: "memory")
; #define PG8_BAR __builtin_amdgcn_s_barrier()
; #define PG8_SCHED __builtin_amdgcn_sched_barrier(0)
; template <class Epi, class Sched, bool ALIGN_EPI = false, bool SP2 = false>
; __device__ __forceinline__ void gemm_phase(PG8_LAS unsigned char* lds, const Gemm g, const Sched& S, const Epi& E, const int tid_in) {
;     ...
;             PG8_WAIT_V(8); PG8_WAIT_L(0); PG8_BAR; PG8_MMA(1, 0, At, B0); PG8_MMA(1, 1, At, B1); PG8_BAR; PG8_SCHED;
;             PG8_LDB(B0, 1, 0); PG8_LDB(B1, 1, 1); PG8_SCHED; PG8_LDA(At, 1, 0); PG8_STAGE(PG8_SA(0, 1), a2 + hstepA, voffA);
;             PG8_WAIT_V(8); PG8_WAIT_L(0); PG8_BAR; PG8_MMA(0, 0, At, B0); PG8_MMA(0, 1, At, B1); PG8_BAR; PG8_SCHED;
	s_setprio 1
	s_waitcnt lgkmcnt(0)
	v_mfma_f32_16x16x32_bf16 v[60:63], v[88:91], v[160:163], 0
	v_mfma_f32_16x16x32_bf16 v[56:59], v[112:115], v[160:163], 0
	v_mfma_f32_16x16x32_bf16 v[44:47], v[88:91], v[168:171], 0
	v_mfma_f32_16x16x32_bf16 v[40:43], v[112:115], v[168:171], 0
	v_mfma_f32_16x16x32_bf16 v[28:31], v[88:91], v[176:179], 0
	v_mfma_f32_16x16x32_bf16 v[24:27], v[112:115], v[176:179], 0
	v_mfma_f32_16x16x32_bf16 v[12:15], v[88:91], v[184:187], 0
	v_mfma_f32_16x16x32_bf16 v[8:11], v[112:115], v[184:187], 0
	v_mfma_f32_16x16x32_bf16 v[60:63], v[92:95], v[164:167], v[60:63]
	v_mfma_f32_16x16x32_bf16 v[56:59], v[116:119], v[164:167], v[56:59]
	v_mfma_f32_16x16x32_bf16 v[44:47], v[92:95], v[172:175], v[44:47]
	v_mfma_f32_16x16x32_bf16 v[40:43], v[116:119], v[172:175], v[40:43]
	v_mfma_f32_16x16x32_bf16 v[28:31], v[92:95], v[180:183], v[28:31]
	v_mfma_f32_16x16x32_bf16 v[24:27], v[116:119], v[180:183], v[24:27]
	v_mfma_f32_16x16x32_bf16 v[12:15], v[92:95], v[194:197], v[12:15]
	v_mfma_f32_16x16x32_bf16 v[8:11], v[116:119], v[194:197], v[8:11]
	s_setprio 0
	s_setprio 1
	v_mfma_f32_16x16x32_bf16 v[52:55], v[132:135], v[160:163], 0
	v_mfma_f32_16x16x32_bf16 v[48:51], v[144:147], v[160:163], 0
	v_mfma_f32_16x16x32_bf16 v[36:39], v[132:135], v[168:171], 0
	v_mfma_f32_16x16x32_bf16 v[32:35], v[144:147], v[168:171], 0
	v_mfma_f32_16x16x32_bf16 v[20:23], v[132:135], v[176:179], 0
	v_mfma_f32_16x16x32_bf16 v[16:19], v[144:147], v[176:179], 0
	v_mfma_f32_16x16x32_bf16 v[4:7], v[132:135], v[184:187], 0
	v_mfma_f32_16x16x32_bf16 v[0:3], v[144:147], v[184:187], 0
	v_mfma_f32_16x16x32_bf16 v[52:55], v[140:143], v[164:167], v[52:55]
	v_mfma_f32_16x16x32_bf16 v[48:51], v[156:159], v[164:167], v[48:51]
	v_mfma_f32_16x16x32_bf16 v[36:39], v[140:143], v[172:175], v[36:39]
	v_mfma_f32_16x16x32_bf16 v[32:35], v[156:159], v[172:175], v[32:35]
	v_mfma_f32_16x16x32_bf16 v[20:23], v[140:143], v[180:183], v[20:23]
	v_mfma_f32_16x16x32_bf16 v[16:19], v[156:159], v[180:183], v[16:19]
	v_mfma_f32_16x16x32_bf16 v[4:7], v[140:143], v[194:197], v[4:7]
	v_mfma_f32_16x16x32_bf16 v[0:3], v[156:159], v[194:197], v[0:3]
	s_setprio 0
	s_barrier
	s_add_i32 s54, 0, 0x18000
	s_add_i32 s55, 0, 0x1c000
	v_add_u32_e32 v116, s54, v228
	v_add_u32_e32 v156, s55, v228
	ds_read_b128 v[88:91], v116
	ds_read_b128 v[92:95], v116 offset:1024
	ds_read_b128 v[112:115], v116 offset:2048
	ds_read_b128 v[116:119], v116 offset:3072
	ds_read_b128 v[132:135], v156
	ds_read_b128 v[140:143], v156 offset:1024
	ds_read_b128 v[144:147], v156 offset:2048
	ds_read_b128 v[156:159], v156 offset:3072
	s_add_u32 s12, s58, 0xf0000
	s_addc_u32 s13, s59, 0
	s_mov_b32 m0, s66
	v_lshl_add_u64 v[212:213], s[12:13], 0, v[188:189]
	ds_read_b128 v[160:163], v230 offset:32768
	ds_read_b128 v[164:167], v230 offset:33792
	ds_read_b128 v[168:171], v230 offset:34816
	ds_read_b128 v[172:175], v230 offset:35840
	ds_read_b128 v[176:179], v230 offset:36864
	ds_read_b128 v[180:183], v230 offset:37888
	ds_read_b128 v[184:187], v230 offset:38912
	ds_read_b128 v[194:197], v230 offset:39936
	global_load_lds_dwordx4 v[212:213], off
	v_lshl_add_u64 v[212:213], s[12:13], 0, v[190:191]
	s_mov_b32 m0, s67
	s_nop 0
	global_load_lds_dwordx4 v[212:213], off
	s_waitcnt vmcnt(8)
	s_waitcnt lgkmcnt(0)
	s_barrier
	s_setprio 1
	s_waitcnt lgkmcnt(0)
	v_mfma_f32_16x16x32_bf16 v[152:155], v[88:91], v[160:163], v[152:155]
	v_mfma_f32_16x16x32_bf16 v[148:151], v[112:115], v[160:163], v[148:151]
	v_mfma_f32_16x16x32_bf16 v[124:127], v[88:91], v[168:171], v[124:127]
	v_mfma_f32_16x16x32_bf16 v[120:123], v[112:115], v[168:171], v[120:123]
	v_mfma_f32_16x16x32_bf16 v[100:103], v[88:91], v[176:179], v[100:103]
	v_mfma_f32_16x16x32_bf16 v[96:99], v[112:115], v[176:179], v[96:99]
	v_mfma_f32_16x16x32_bf16 v[76:79], v[88:91], v[184:187], v[76:79]
	v_mfma_f32_16x16x32_bf16 v[72:75], v[112:115], v[184:187], v[72:75]
	v_mfma_f32_16x16x32_bf16 v[152:155], v[92:95], v[164:167], v[152:155]
	v_mfma_f32_16x16x32_bf16 v[148:151], v[116:119], v[164:167], v[148:151]
	v_mfma_f32_16x16x32_bf16 v[124:127], v[92:95], v[172:175], v[124:127]
	v_mfma_f32_16x16x32_bf16 v[120:123], v[116:119], v[172:175], v[120:123]
	v_mfma_f32_16x16x32_bf16 v[100:103], v[92:95], v[180:183], v[100:103]
	v_mfma_f32_16x16x32_bf16 v[96:99], v[116:119], v[180:183], v[96:99]
	v_mfma_f32_16x16x32_bf16 v[76:79], v[92:95], v[194:197], v[76:79]
	v_mfma_f32_16x16x32_bf16 v[72:75], v[116:119], v[194:197], v[72:75]
	s_setprio 0
	s_setprio 1
	v_mfma_f32_16x16x32_bf16 v[136:139], v[132:135], v[160:163], v[136:139]
	v_mfma_f32_16x16x32_bf16 v[128:131], v[144:147], v[160:163], v[128:131]
	v_mfma_f32_16x16x32_bf16 v[108:111], v[132:135], v[168:171], v[108:111]
	v_mfma_f32_16x16x32_bf16 v[104:107], v[144:147], v[168:171], v[104:107]
	v_mfma_f32_16x16x32_bf16 v[84:87], v[132:135], v[176:179], v[84:87]
	v_mfma_f32_16x16x32_bf16 v[80:83], v[144:147], v[176:179], v[80:83]
	v_mfma_f32_16x16x32_bf16 v[68:71], v[132:135], v[184:187], v[68:71]
	v_mfma_f32_16x16x32_bf16 v[64:67], v[144:147], v[184:187], v[64:67]
	v_mfma_f32_16x16x32_bf16 v[136:139], v[140:143], v[164:167], v[136:139]
	v_mfma_f32_16x16x32_bf16 v[128:131], v[156:159], v[164:167], v[128:131]
	v_mfma_f32_16x16x32_bf16 v[108:111], v[140:143], v[172:175], v[108:111]
	v_mfma_f32_16x16x32_bf16 v[104:107], v[156:159], v[172:175], v[104:107]
	v_mfma_f32_16x16x32_bf16 v[84:87], v[140:143], v[180:183], v[84:87]
	v_mfma_f32_16x16x32_bf16 v[80:83], v[156:159], v[180:183], v[80:83]
	v_mfma_f32_16x16x32_bf16 v[68:71], v[140:143], v[194:197], v[68:71]
	v_mfma_f32_16x16x32_bf16 v[64:67], v[156:159], v[194:197], v[64:67]
	s_setprio 0
	s_barrier
; #define PG8_STAGE(bufoff, gbase, voff) do { _Pragma("unroll") for (int _i = 0; _i < 2; ++_i) \
;         __builtin_amdgcn_global_load_lds((const unsigned*)((const char*)(gbase) + (voff)[_i]), (PG8_LAS unsigned*)(lds + (bufoff) + ldsw + _i * 8192), 16, 0, 0); } while (0)
; #define PG8_LDA(dst, b, h) do { _Pragma("unroll") for (int m = 0; m < 4; ++m) _Pragma("unroll") for (int k = 0; k < 2; ++k) dst[m][k] = *(const PG8_LAS bf16x8*)(lds + PG8_SA(b, h) + aoff + m * 2048 + k * 1024); } while (0)
; #define PG8_WAIT_V(n) asm volatile("s_waitcnt vmcnt(" #n ")" ::: "memory")
; #define PG8_WAIT_L(n) asm volatile("s_waitcnt lgkmcnt(" #n ")" ::: "memory")
; #define PG8_BAR __builtin_amdgcn_s_barrier()
; template <class Epi, class Sched, bool ALIGN_EPI = false, bool SP2 = false>
; __device__ __forceinline__ void gemm_phase(PG8_LAS unsigned char* lds, const Gemm g, const Sched& S, const Epi& E, const int tid_in) {
;     ...
;         for (int t = 0; t < nt; t += 2) {
;             const bool last = (t == nt - 2);
;             const char* a1 = cA + (size_t)(t + 1) * kstep;
;             const char* a2 = last ? nA : cA + (size_t)(t + 2) * kstep; const char* b2 = last ? nB : cB + (size_t)(t + 2) * kstep;
;             const char* a3 = a2 + kstep; const char* b3 = b2 + kstep;
;             if (last && has_next) S.a_ready(nxt);
;             if constexpr (SP2) {
;             PG8_LDB(B0, 0, 0); PG8_LDB(B1, 0, 1); PG8_SCHED; PG8_LDA(At, 0, 0); PG8_STAGE(PG8_SA(1, 1), a1 + hstepA, voffA);
;             PG8_WAIT_V(8); PG8_WAIT_L(0); PG8_BAR; PG8_MMA(0, 0, At, B0); PG8_MMA(0, 1, At, B1); PG8_BAR; PG8_SCHED;
;             PG8_LDA(At, 0, 1); PG8_STAGE(PG8_SB(0, 0), b2, voffB); PG8_STAGE(PG8_SB(0, 1), b2 + hstepB, voffB); PG8_STAGE(PG8_SA(0, 0), a2, voffA);
;             PG8_WAIT_V(8); PG8_WAIT_L(0); PG8_BAR; PG8_MMA(1, 0, At, B0); PG8_MMA(1, 1, At, B1); PG8_BAR; PG8_SCHED;
;             PG8_LDB(B0, 1, 0); PG8_LDB(B1, 1, 1); PG8_SCHED; PG8_LDA(At, 1, 0); PG8_STAGE(PG8_SA(0, 1), a2 + hstepA, voffA);
;             PG8_WAIT_V(8); PG8_WAIT_L(0); PG8_BAR; PG8_MMA(0, 0, At, B0); PG8_MMA(0, 1, At, B1); PG8_BAR; PG8_SCHED;
;             PG8_LDA(At, 1, 1); PG8_STAGE(PG8_SB(1, 0), b3, voffB); PG8_STAGE(PG8_SB(1, 1), b3 + hstepB, voffB); PG8_STAGE(PG8_SA(1, 0), a3, voffA);
;             PG8_WAIT_V(8); PG8_WAIT_L(0); PG8_BAR; PG8_MMA(1, 0, At, B0); PG8_MMA(1, 1, At, B1); PG8_BAR; PG8_SCHED;
	s_add_i32 s12, s54, s61
	v_lshl_add_u64 v[204:205], v[204:205], 0, s[26:27]
	s_mov_b32 m0, s12
	ds_read_b128 v[160:163], v230 offset:49152
	ds_read_b128 v[164:167], v230 offset:50176
	ds_read_b128 v[168:171], v230 offset:51200
	ds_read_b128 v[172:175], v230 offset:52224
	ds_read_b128 v[176:179], v230 offset:53248
	ds_read_b128 v[180:183], v230 offset:54272
	ds_read_b128 v[184:187], v230 offset:55296
	ds_read_b128 v[194:197], v230 offset:56320
	global_load_lds_dwordx4 v[204:205], off
	s_add_i32 m0, s12, 0x2000
	s_add_u32 s12, s56, 0x200080
	v_lshl_add_u64 v[204:205], v[206:207], 0, s[26:27]
	s_addc_u32 s13, s57, 0
	s_add_i32 s54, s55, s61
	global_load_lds_dwordx4 v[204:205], off
	v_lshl_add_u64 v[204:205], s[12:13], 0, v[192:193]
	s_mov_b32 m0, s54
	s_nop 0
	global_load_lds_dwordx4 v[204:205], off
	v_lshl_add_u64 v[204:205], s[12:13], 0, v[198:199]
	s_add_i32 m0, s54, 0x2000
	s_nop 0
	global_load_lds_dwordx4 v[204:205], off
	v_lshl_add_u64 v[204:205], v[208:209], 0, s[26:27]
	s_mov_b32 m0, s69
	s_nop 0
	global_load_lds_dwordx4 v[204:205], off
	v_lshl_add_u64 v[204:205], v[210:211], 0, s[26:27]
	s_mov_b32 m0, s70
	s_nop 0
	global_load_lds_dwordx4 v[204:205], off
	s_waitcnt vmcnt(8)
	s_waitcnt lgkmcnt(0)
	s_barrier
	s_setprio 1
	s_waitcnt lgkmcnt(0)
	v_mfma_f32_16x16x32_bf16 v[60:63], v[88:91], v[160:163], v[60:63]
	v_mfma_f32_16x16x32_bf16 v[56:59], v[112:115], v[160:163], v[56:59]
	v_mfma_f32_16x16x32_bf16 v[44:47], v[88:91], v[168:171], v[44:47]
	v_mfma_f32_16x16x32_bf16 v[40:43], v[112:115], v[168:171], v[40:43]
	v_mfma_f32_16x16x32_bf16 v[28:31], v[88:91], v[176:179], v[28:31]
	v_mfma_f32_16x16x32_bf16 v[24:27], v[112:115], v[176:179], v[24:27]
	v_mfma_f32_16x16x32_bf16 v[12:15], v[88:91], v[184:187], v[12:15]
	v_mfma_f32_16x16x32_bf16 v[8:11], v[112:115], v[184:187], v[8:11]
	v_mfma_f32_16x16x32_bf16 v[60:63], v[92:95], v[164:167], v[60:63]
	v_mfma_f32_16x16x32_bf16 v[56:59], v[116:119], v[164:167], v[56:59]
	v_mfma_f32_16x16x32_bf16 v[44:47], v[92:95], v[172:175], v[44:47]
	v_mfma_f32_16x16x32_bf16 v[40:43], v[116:119], v[172:175], v[40:43]
	v_mfma_f32_16x16x32_bf16 v[28:31], v[92:95], v[180:183], v[28:31]
	v_mfma_f32_16x16x32_bf16 v[24:27], v[116:119], v[180:183], v[24:27]
	v_mfma_f32_16x16x32_bf16 v[12:15], v[92:95], v[194:197], v[12:15]
	v_mfma_f32_16x16x32_bf16 v[8:11], v[116:119], v[194:197], v[8:11]
	s_setprio 0
	s_setprio 1
	v_mfma_f32_16x16x32_bf16 v[52:55], v[132:135], v[160:163], v[52:55]
	v_mfma_f32_16x16x32_bf16 v[48:51], v[144:147], v[160:163], v[48:51]
	v_mfma_f32_16x16x32_bf16 v[36:39], v[132:135], v[168:171], v[36:39]
	v_mfma_f32_16x16x32_bf16 v[32:35], v[144:147], v[168:171], v[32:35]
	v_mfma_f32_16x16x32_bf16 v[20:23], v[132:135], v[176:179], v[20:23]
	v_mfma_f32_16x16x32_bf16 v[16:19], v[144:147], v[176:179], v[16:19]
	v_mfma_f32_16x16x32_bf16 v[4:7], v[132:135], v[184:187], v[4:7]
	v_mfma_f32_16x16x32_bf16 v[0:3], v[144:147], v[184:187], v[0:3]
	v_mfma_f32_16x16x32_bf16 v[52:55], v[140:143], v[164:167], v[52:55]
	v_mfma_f32_16x16x32_bf16 v[48:51], v[156:159], v[164:167], v[48:51]
	v_mfma_f32_16x16x32_bf16 v[36:39], v[140:143], v[172:175], v[36:39]
	v_mfma_f32_16x16x32_bf16 v[32:35], v[156:159], v[172:175], v[32:35]
	v_mfma_f32_16x16x32_bf16 v[20:23], v[140:143], v[180:183], v[20:23]
	v_mfma_f32_16x16x32_bf16 v[16:19], v[156:159], v[180:183], v[16:19]
	v_mfma_f32_16x16x32_bf16 v[4:7], v[140:143], v[194:197], v[4:7]
	v_mfma_f32_16x16x32_bf16 v[0:3], v[156:159], v[194:197], v[0:3]
	s_setprio 0
	s_barrier
	s_add_i32 s75, s75, 2
	s_add_u32 s73, s73, 0x100
	s_addc_u32 s74, s74, 0
	s_cmp_gt_u32 s75, 57
	s_mov_b64 s[54:55], s[38:39]
	.p2align 6
.LBB0_1561:
	s_add_u32 s38, s54, 0x100
	s_addc_u32 s39, s55, 0
	s_add_i32 s12, 0, 0x10000
	s_cmp_eq_u32 s75, 56
	s_cselect_b32 s59, s49, s39
	s_cselect_b32 s58, s48, s38
	s_cselect_b32 s57, s47, s74
	s_cselect_b32 s56, s53, s73
	s_add_i32 s76, 0, 0x14000
	v_add_u32_e32 v116, s12, v228
	v_add_u32_e32 v156, s76, v228
	ds_read_b128 v[88:91], v116
	ds_read_b128 v[92:95], v116 offset:1024
	ds_read_b128 v[112:115], v116 offset:2048
	ds_read_b128 v[116:119], v116 offset:3072
	ds_read_b128 v[132:135], v156
	ds_read_b128 v[140:143], v156 offset:1024
	ds_read_b128 v[144:147], v156 offset:2048
	ds_read_b128 v[156:159], v156 offset:3072
	v_lshl_add_u64 v[204:205], s[54:55], 0, v[200:201]
	s_add_i32 m0, s64, 0xc000
	ds_read_b128 v[160:163], v230
	ds_read_b128 v[164:167], v230 offset:1024
	ds_read_b128 v[168:171], v230 offset:2048
	ds_read_b128 v[172:175], v230 offset:3072
	ds_read_b128 v[176:179], v230 offset:4096
	ds_read_b128 v[180:183], v230 offset:5120
	ds_read_b128 v[184:187], v230 offset:6144
	ds_read_b128 v[194:197], v230 offset:7168
	global_load_lds_dwordx4 v[204:205], off
	v_lshl_add_u64 v[204:205], s[54:55], 0, v[202:203]
	s_add_i32 m0, s64, 0xe000
	s_nop 0
	global_load_lds_dwordx4 v[204:205], off
	s_waitcnt vmcnt(8)
	s_waitcnt lgkmcnt(0)
	s_barrier
; #define PG8_STAGE(bufoff, gbase, voff) do { _Pragma("unroll") for (int _i = 0; _i < 2; ++_i) \
;         __builtin_amdgcn_global_load_lds((const unsigned*)((const char*)(gbase) + (voff)[_i]), (PG8_LAS unsigned*)(lds + (bufoff) + ldsw + _i * 8192), 16, 0, 0); } while (0)
; #define PG8_LDA(dst, b, h) do { _Pragma("unroll") for (int m = 0; m < 4; ++m) _Pragma("unroll") for (int k = 0; k < 2; ++k) dst[m][k] = *(const PG8_LAS bf16x8*)(lds + PG8_SA(b, h) + aoff + m * 2048 + k * 1024); } while (0)
; #define PG8_LDB(dst, b, h) do { _Pragma("unroll") for (int n = 0; n < 2; ++n) _Pragma("unroll") for (int k = 0; k < 2; ++k) dst[n][k] = *(const PG8_LAS bf16x8*)(lds + PG8_SB(b, h) + boff + n * 2048 + k * 1024); } while (0)
; #define PG8_MMA(ai, bj, At, Bt) do { __builtin_amdgcn_s_setprio(1); _Pragma("unroll") for (int m = 0; m < 4; ++m) _Pragma("unroll") for (int n = 0; n < 2; ++n) _Pragma("unroll") for (int k = 0; k < 2; ++k) \
;         acc[ai][bj][m][n] = __builtin_amdgcn_mfma_f32_16x16x32_bf16(Bt[n][k], At[m][k], acc[ai][bj][m][n], 0, 0, 0); __builtin_amdgcn_s_setprio(0); } while (0)
; #define PG8_WAIT_V(n) asm volatile("s_waitcnt vmcnt(" #n ")" ::: "memory")
; #define PG8_WAIT_L(n) asm volatile("s_waitcnt lgkmcnt(" #n ")" ::: "memory")
; #define PG8_BAR __builtin_amdgcn_s_barrier()
; #define PG8_SCHED __builtin_amdgcn_sched_barrier(0)
; template <class Epi, class Sched, bool ALIGN_EPI = false, bool SP2 = false>
; __device__ __forceinline__ void gemm_phase(PG8_LAS unsigned char* lds, const Gemm g, const Sched& S, const Epi& E, const int tid_in) {
;     ...
;             PG8_LDB(B0, 0, 0); PG8_LDB(B1, 0, 1); PG8_SCHED; PG8_LDA(At, 0, 0); PG8_STAGE(PG8_SA(1, 1), a1 + hstepA, voffA);
;             PG8_WAIT_V(8); PG8_WAIT_L(0); PG8_BAR; PG8_MMA(0, 0, At, B0); PG8_MMA(0, 1, At, B1); PG8_BAR; PG8_SCHED;
;             PG8_LDA(At, 0, 1); PG8_STAGE(PG8_SB(0, 0), b2, voffB); PG8_STAGE(PG8_SB(0, 1), b2 + hstepB, voffB); PG8_STAGE(PG8_SA(0, 0), a2, voffA);
;             PG8_WAIT_V(8); PG8_WAIT_L(0); PG8_BAR; PG8_MMA(1, 0, At, B0); PG8_MMA(1, 1, At, B1); PG8_BAR; PG8_SCHED;
;             PG8_LDB(B0, 1, 0); PG8_LDB(B1, 1, 1); PG8_SCHED; PG8_LDA(At, 1, 0); PG8_STAGE(PG8_SA(0, 1), a2 + hstepA, voffA);
;             PG8_WAIT_V(8); PG8_WAIT_L(0); PG8_BAR; PG8_MMA(0, 0, At, B0); PG8_MMA(0, 1, At, B1); PG8_BAR; PG8_SCHED;
	s_setprio 1
	s_waitcnt lgkmcnt(0)
	v_mfma_f32_16x16x32_bf16 v[152:155], v[88:91], v[160:163], v[152:155]
	v_mfma_f32_16x16x32_bf16 v[148:151], v[112:115], v[160:163], v[148:151]
	v_mfma_f32_16x16x32_bf16 v[124:127], v[88:91], v[168:171], v[124:127]
	v_mfma_f32_16x16x32_bf16 v[120:123], v[112:115], v[168:171], v[120:123]
	v_mfma_f32_16x16x32_bf16 v[100:103], v[88:91], v[176:179], v[100:103]
	v_mfma_f32_16x16x32_bf16 v[96:99], v[112:115], v[176:179], v[96:99]
	v_mfma_f32_16x16x32_bf16 v[76:79], v[88:91], v[184:187], v[76:79]
	v_mfma_f32_16x16x32_bf16 v[72:75], v[112:115], v[184:187], v[72:75]
	v_mfma_f32_16x16x32_bf16 v[152:155], v[92:95], v[164:167], v[152:155]
	v_mfma_f32_16x16x32_bf16 v[148:151], v[116:119], v[164:167], v[148:151]
	v_mfma_f32_16x16x32_bf16 v[124:127], v[92:95], v[172:175], v[124:127]
	v_mfma_f32_16x16x32_bf16 v[120:123], v[116:119], v[172:175], v[120:123]
	v_mfma_f32_16x16x32_bf16 v[100:103], v[92:95], v[180:183], v[100:103]
	v_mfma_f32_16x16x32_bf16 v[96:99], v[116:119], v[180:183], v[96:99]
	v_mfma_f32_16x16x32_bf16 v[76:79], v[92:95], v[194:197], v[76:79]
	v_mfma_f32_16x16x32_bf16 v[72:75], v[116:119], v[194:197], v[72:75]
	v_mfma_f32_16x16x32_bf16 v[136:139], v[132:135], v[160:163], v[136:139]
	v_mfma_f32_16x16x32_bf16 v[128:131], v[144:147], v[160:163], v[128:131]
	v_mfma_f32_16x16x32_bf16 v[108:111], v[132:135], v[168:171], v[108:111]
	v_mfma_f32_16x16x32_bf16 v[104:107], v[144:147], v[168:171], v[104:107]
	v_mfma_f32_16x16x32_bf16 v[84:87], v[132:135], v[176:179], v[84:87]
	v_mfma_f32_16x16x32_bf16 v[80:83], v[144:147], v[176:179], v[80:83]
	v_mfma_f32_16x16x32_bf16 v[68:71], v[132:135], v[184:187], v[68:71]
	v_mfma_f32_16x16x32_bf16 v[64:67], v[144:147], v[184:187], v[64:67]
	v_mfma_f32_16x16x32_bf16 v[136:139], v[140:143], v[164:167], v[136:139]
	v_mfma_f32_16x16x32_bf16 v[128:131], v[156:159], v[164:167], v[128:131]
	v_mfma_f32_16x16x32_bf16 v[108:111], v[140:143], v[172:175], v[108:111]
	v_mfma_f32_16x16x32_bf16 v[104:107], v[156:159], v[172:175], v[104:107]
	v_mfma_f32_16x16x32_bf16 v[84:87], v[140:143], v[180:183], v[84:87]
	v_mfma_f32_16x16x32_bf16 v[80:83], v[156:159], v[180:183], v[80:83]
	v_mfma_f32_16x16x32_bf16 v[68:71], v[140:143], v[194:197], v[68:71]
	v_mfma_f32_16x16x32_bf16 v[64:67], v[156:159], v[194:197], v[64:67]
	s_setprio 0
	s_barrier
	s_add_i32 s12, s12, s61
	v_lshl_add_u64 v[204:205], s[56:57], 0, v[192:193]
	s_mov_b32 m0, s12
	ds_read_b128 v[160:163], v230 offset:16384
	ds_read_b128 v[164:167], v230 offset:17408
	ds_read_b128 v[168:171], v230 offset:18432
	ds_read_b128 v[172:175], v230 offset:19456
	ds_read_b128 v[176:179], v230 offset:20480
	ds_read_b128 v[180:183], v230 offset:21504
	ds_read_b128 v[184:187], v230 offset:22528
	ds_read_b128 v[194:197], v230 offset:23552
	global_load_lds_dwordx4 v[204:205], off
	s_add_i32 m0, s12, 0x2000
	s_add_u32 s12, s56, 0x200000
	v_lshl_add_u64 v[206:207], s[56:57], 0, v[198:199]
	s_addc_u32 s13, s57, 0
	s_add_i32 s54, s76, s61
	global_load_lds_dwordx4 v[206:207], off
	v_lshl_add_u64 v[208:209], s[12:13], 0, v[192:193]
	s_mov_b32 m0, s54
	v_lshl_add_u64 v[210:211], s[58:59], 0, v[190:191]
	global_load_lds_dwordx4 v[208:209], off
	v_lshl_add_u64 v[208:209], s[12:13], 0, v[198:199]
	s_add_i32 m0, s54, 0x2000
	s_nop 0
	global_load_lds_dwordx4 v[208:209], off
	v_lshl_add_u64 v[208:209], s[58:59], 0, v[188:189]
	s_mov_b32 m0, s64
	s_nop 0
	global_load_lds_dwordx4 v[208:209], off
	s_mov_b32 m0, s65
	s_nop 0
	global_load_lds_dwordx4 v[210:211], off
	s_waitcnt vmcnt(8)
	s_waitcnt lgkmcnt(0)
	s_barrier
	s_setprio 1
	s_waitcnt lgkmcnt(0)
	v_mfma_f32_16x16x32_bf16 v[60:63], v[88:91], v[160:163], v[60:63]
	v_mfma_f32_16x16x32_bf16 v[56:59], v[112:115], v[160:163], v[56:59]
	v_mfma_f32_16x16x32_bf16 v[44:47], v[88:91], v[168:171], v[44:47]
	v_mfma_f32_16x16x32_bf16 v[40:43], v[112:115], v[168:171], v[40:43]
	v_mfma_f32_16x16x32_bf16 v[28:31], v[88:91], v[176:179], v[28:31]
	v_mfma_f32_16x16x32_bf16 v[24:27], v[112:115], v[176:179], v[24:27]
	v_mfma_f32_16x16x32_bf16 v[12:15], v[88:91], v[184:187], v[12:15]
	v_mfma_f32_16x16x32_bf16 v[8:11], v[112:115], v[184:187], v[8:11]
	v_mfma_f32_16x16x32_bf16 v[60:63], v[92:95], v[164:167], v[60:63]
	v_mfma_f32_16x16x32_bf16 v[56:59], v[116:119], v[164:167], v[56:59]
	v_mfma_f32_16x16x32_bf16 v[44:47], v[92:95], v[172:175], v[44:47]
	v_mfma_f32_16x16x32_bf16 v[40:43], v[116:119], v[172:175], v[40:43]
	v_mfma_f32_16x16x32_bf16 v[28:31], v[92:95], v[180:183], v[28:31]
	v_mfma_f32_16x16x32_bf16 v[24:27], v[116:119], v[180:183], v[24:27]
	v_mfma_f32_16x16x32_bf16 v[12:15], v[92:95], v[194:197], v[12:15]
	v_mfma_f32_16x16x32_bf16 v[8:11], v[116:119], v[194:197], v[8:11]
	v_mfma_f32_16x16x32_bf16 v[52:55], v[132:135], v[160:163], v[52:55]
	v_mfma_f32_16x16x32_bf16 v[48:51], v[144:147], v[160:163], v[48:51]
	v_mfma_f32_16x16x32_bf16 v[36:39], v[132:135], v[168:171], v[36:39]
	v_mfma_f32_16x16x32_bf16 v[32:35], v[144:147], v[168:171], v[32:35]
	v_mfma_f32_16x16x32_bf16 v[20:23], v[132:135], v[176:179], v[20:23]
	v_mfma_f32_16x16x32_bf16 v[16:19], v[144:147], v[176:179], v[16:19]
	v_mfma_f32_16x16x32_bf16 v[4:7], v[132:135], v[184:187], v[4:7]
	v_mfma_f32_16x16x32_bf16 v[0:3], v[144:147], v[184:187], v[0:3]
	v_mfma_f32_16x16x32_bf16 v[52:55], v[140:143], v[164:167], v[52:55]
	v_mfma_f32_16x16x32_bf16 v[48:51], v[156:159], v[164:167], v[48:51]
	v_mfma_f32_16x16x32_bf16 v[36:39], v[140:143], v[172:175], v[36:39]
	v_mfma_f32_16x16x32_bf16 v[32:35], v[156:159], v[172:175], v[32:35]
	v_mfma_f32_16x16x32_bf16 v[20:23], v[140:143], v[180:183], v[20:23]
	v_mfma_f32_16x16x32_bf16 v[16:19], v[156:159], v[180:183], v[16:19]
	v_mfma_f32_16x16x32_bf16 v[4:7], v[140:143], v[194:197], v[4:7]
	v_mfma_f32_16x16x32_bf16 v[0:3], v[156:159], v[194:197], v[0:3]
	s_setprio 0
	s_barrier
; #define PG8_STAGE(bufoff, gbase, voff) do { _Pragma("unroll") for (int _i = 0; _i < 2; ++_i) \
;         __builtin_amdgcn_global_load_lds((const unsigned*)((const char*)(gbase) + (voff)[_i]), (PG8_LAS unsigned*)(lds + (bufoff) + ldsw + _i * 8192), 16, 0, 0); } while (0)
; #define PG8_LDA(dst, b, h) do { _Pragma("unroll") for (int m = 0; m < 4; ++m) _Pragma("unroll") for (int k = 0; k < 2; ++k) dst[m][k] = *(const PG8_LAS bf16x8*)(lds + PG8_SA(b, h) + aoff + m * 2048 + k * 1024); } while (0)
; #define PG8_LDB(dst, b, h) do { _Pragma("unroll") for (int n = 0; n < 2; ++n) _Pragma("unroll") for (int k = 0; k < 2; ++k) dst[n][k] = *(const PG8_LAS bf16x8*)(lds + PG8_SB(b, h) + boff + n * 2048 + k * 1024); } while (0)
; #define PG8_MMA(ai, bj, At, Bt) do { __builtin_amdgcn_s_setprio(1); _Pragma("unroll") for (int m = 0; m < 4; ++m) _Pragma("unroll") for (int n = 0; n < 2; ++n) _Pragma("unroll") for (int k = 0; k < 2; ++k) \
;         acc[ai][bj][m][n] = __builtin_amdgcn_mfma_f32_16x16x32_bf16(Bt[n][k], At[m][k], acc[ai][bj][m][n], 0, 0, 0); __builtin_amdgcn_s_setprio(0); } while (0)
; #define PG8_WAIT_V(n) asm volatile("s_waitcnt vmcnt(" #n ")" ::: "memory")
; #define PG8_WAIT_L(n) asm volatile("s_waitcnt lgkmcnt(" #n ")" ::: "memory")
; #define PG8_BAR __builtin_amdgcn_s_barrier()
; #define PG8_SCHED __builtin_amdgcn_sched_barrier(0)
; template <class Epi, class Sched, bool ALIGN_EPI = false, bool SP2 = false>
; __device__ __forceinline__ void gemm_phase(PG8_LAS unsigned char* lds, const Gemm g, const Sched& S, const Epi& E, const int tid_in) {
;     ...
;             PG8_LDB(B0, 1, 0); PG8_LDB(B1, 1, 1); PG8_SCHED; PG8_LDA(At, 1, 0); PG8_STAGE(PG8_SA(0, 1), a2 + hstepA, voffA);
;             PG8_WAIT_V(8); PG8_WAIT_L(0); PG8_BAR; PG8_MMA(0, 0, At, B0); PG8_MMA(0, 1, At, B1); PG8_BAR; PG8_SCHED;
	s_add_i32 s54, 0, 0x18000
	s_add_i32 s55, 0, 0x1c000
	v_add_u32_e32 v116, s54, v228
	v_add_u32_e32 v156, s55, v228
	ds_read_b128 v[88:91], v116
	ds_read_b128 v[92:95], v116 offset:1024
	ds_read_b128 v[112:115], v116 offset:2048
	ds_read_b128 v[116:119], v116 offset:3072
	ds_read_b128 v[132:135], v156
	ds_read_b128 v[140:143], v156 offset:1024
	ds_read_b128 v[144:147], v156 offset:2048
	ds_read_b128 v[156:159], v156 offset:3072
	s_add_u32 s12, s58, 0xf0000
	s_addc_u32 s13, s59, 0
	s_mov_b32 m0, s66
	v_lshl_add_u64 v[212:213], s[12:13], 0, v[188:189]
	ds_read_b128 v[160:163], v230 offset:32768
	ds_read_b128 v[164:167], v230 offset:33792
	ds_read_b128 v[168:171], v230 offset:34816
	ds_read_b128 v[172:175], v230 offset:35840
	ds_read_b128 v[176:179], v230 offset:36864
	ds_read_b128 v[180:183], v230 offset:37888
	ds_read_b128 v[184:187], v230 offset:38912
	ds_read_b128 v[194:197], v230 offset:39936
	global_load_lds_dwordx4 v[212:213], off
	v_lshl_add_u64 v[212:213], s[12:13], 0, v[190:191]
	s_mov_b32 m0, s67
	s_nop 0
	global_load_lds_dwordx4 v[212:213], off
	s_waitcnt vmcnt(8)
	s_waitcnt lgkmcnt(0)
	s_barrier
	s_setprio 1
	s_waitcnt lgkmcnt(0)
	v_mfma_f32_16x16x32_bf16 v[152:155], v[88:91], v[160:163], v[152:155]
	v_mfma_f32_16x16x32_bf16 v[148:151], v[112:115], v[160:163], v[148:151]
	v_mfma_f32_16x16x32_bf16 v[124:127], v[88:91], v[168:171], v[124:127]
	v_mfma_f32_16x16x32_bf16 v[120:123], v[112:115], v[168:171], v[120:123]
	v_mfma_f32_16x16x32_bf16 v[100:103], v[88:91], v[176:179], v[100:103]
	v_mfma_f32_16x16x32_bf16 v[96:99], v[112:115], v[176:179], v[96:99]
	v_mfma_f32_16x16x32_bf16 v[76:79], v[88:91], v[184:187], v[76:79]
	v_mfma_f32_16x16x32_bf16 v[72:75], v[112:115], v[184:187], v[72:75]
	v_mfma_f32_16x16x32_bf16 v[152:155], v[92:95], v[164:167], v[152:155]
	v_mfma_f32_16x16x32_bf16 v[148:151], v[116:119], v[164:167], v[148:151]
	v_mfma_f32_16x16x32_bf16 v[124:127], v[92:95], v[172:175], v[124:127]
	v_mfma_f32_16x16x32_bf16 v[120:123], v[116:119], v[172:175], v[120:123]
	v_mfma_f32_16x16x32_bf16 v[100:103], v[92:95], v[180:183], v[100:103]
	v_mfma_f32_16x16x32_bf16 v[96:99], v[116:119], v[180:183], v[96:99]
	v_mfma_f32_16x16x32_bf16 v[76:79], v[92:95], v[194:197], v[76:79]
	v_mfma_f32_16x16x32_bf16 v[72:75], v[116:119], v[194:197], v[72:75]
	v_mfma_f32_16x16x32_bf16 v[136:139], v[132:135], v[160:163], v[136:139]
	v_mfma_f32_16x16x32_bf16 v[128:131], v[144:147], v[160:163], v[128:131]
	v_mfma_f32_16x16x32_bf16 v[108:111], v[132:135], v[168:171], v[108:111]
	v_mfma_f32_16x16x32_bf16 v[104:107], v[144:147], v[168:171], v[104:107]
	v_mfma_f32_16x16x32_bf16 v[84:87], v[132:135], v[176:179], v[84:87]
	v_mfma_f32_16x16x32_bf16 v[80:83], v[144:147], v[176:179], v[80:83]
	v_mfma_f32_16x16x32_bf16 v[68:71], v[132:135], v[184:187], v[68:71]
	v_mfma_f32_16x16x32_bf16 v[64:67], v[144:147], v[184:187], v[64:67]
	v_mfma_f32_16x16x32_bf16 v[136:139], v[140:143], v[164:167], v[136:139]
	v_mfma_f32_16x16x32_bf16 v[128:131], v[156:159], v[164:167], v[128:131]
	v_mfma_f32_16x16x32_bf16 v[108:111], v[140:143], v[172:175], v[108:111]
	v_mfma_f32_16x16x32_bf16 v[104:107], v[156:159], v[172:175], v[104:107]
	v_mfma_f32_16x16x32_bf16 v[84:87], v[140:143], v[180:183], v[84:87]
	v_mfma_f32_16x16x32_bf16 v[80:83], v[156:159], v[180:183], v[80:83]
	v_mfma_f32_16x16x32_bf16 v[68:71], v[140:143], v[194:197], v[68:71]
	v_mfma_f32_16x16x32_bf16 v[64:67], v[156:159], v[194:197], v[64:67]
	s_setprio 0
	s_barrier
; #define PG8_STAGE(bufoff, gbase, voff) do { _Pragma("unroll") for (int _i = 0; _i < 2; ++_i) \
;         __builtin_amdgcn_global_load_lds((const unsigned*)((const char*)(gbase) + (voff)[_i]), (PG8_LAS unsigned*)(lds + (bufoff) + ldsw + _i * 8192), 16, 0, 0); } while (0)
; #define PG8_LDA(dst, b, h) do { _Pragma("unroll") for (int m = 0; m < 4; ++m) _Pragma("unroll") for (int k = 0; k < 2; ++k) dst[m][k] = *(const PG8_LAS bf16x8*)(lds + PG8_SA(b, h) + aoff + m * 2048 + k * 1024); } while (0)
; #define PG8_MMA(ai, bj, At, Bt) do { __builtin_amdgcn_s_setprio(1); _Pragma("unroll") for (int m = 0; m < 4; ++m) _Pragma("unroll") for (int n = 0; n < 2; ++n) _Pragma("unroll") for (int k = 0; k < 2; ++k) \
;         acc[ai][bj][m][n] = __builtin_amdgcn_mfma_f32_16x16x32_bf16(Bt[n][k], At[m][k], acc[ai][bj][m][n], 0, 0, 0); __builtin_amdgcn_s_setprio(0); } while (0)
; #define PG8_WAIT_V(n) asm volatile("s_waitcnt vmcnt(" #n ")" ::: "memory")
; #define PG8_WAIT_L(n) asm volatile("s_waitcnt lgkmcnt(" #n ")" ::: "memory")
; #define PG8_BAR __builtin_amdgcn_s_barrier()
; #define PG8_SCHED __builtin_amdgcn_sched_barrier(0)
; template <class Epi, class Sched, bool ALIGN_EPI = false, bool SP2 = false>
; __device__ __forceinline__ void gemm_phase(PG8_LAS unsigned char* lds, const Gemm g, const Sched& S, const Epi& E, const int tid_in) {
;     ...
;             PG8_LDA(At, 1, 1); PG8_STAGE(PG8_SB(1, 0), b3, voffB); PG8_STAGE(PG8_SB(1, 1), b3 + hstepB, voffB); PG8_STAGE(PG8_SA(1, 0), a3, voffA);
;             PG8_WAIT_V(8); PG8_WAIT_L(0); PG8_BAR; PG8_MMA(1, 0, At, B0); PG8_MMA(1, 1, At, B1); PG8_BAR; PG8_SCHED;
;     ...
;         if constexpr (ALIGN_EPI) { if (wr == 0) PG8_BAR; }
	s_add_i32 s12, s54, s61
	v_lshl_add_u64 v[204:205], v[204:205], 0, s[26:27]
	s_mov_b32 m0, s12
	ds_read_b128 v[160:163], v230 offset:49152
	ds_read_b128 v[164:167], v230 offset:50176
	ds_read_b128 v[168:171], v230 offset:51200
	ds_read_b128 v[172:175], v230 offset:52224
	ds_read_b128 v[176:179], v230 offset:53248
	ds_read_b128 v[180:183], v230 offset:54272
	ds_read_b128 v[184:187], v230 offset:55296
	ds_read_b128 v[194:197], v230 offset:56320
	global_load_lds_dwordx4 v[204:205], off
	s_add_i32 m0, s12, 0x2000
	s_add_u32 s12, s56, 0x200080
	v_lshl_add_u64 v[204:205], v[206:207], 0, s[26:27]
	s_addc_u32 s13, s57, 0
	s_add_i32 s54, s55, s61
	global_load_lds_dwordx4 v[204:205], off
	v_lshl_add_u64 v[204:205], s[12:13], 0, v[192:193]
	s_mov_b32 m0, s54
	s_nop 0
	global_load_lds_dwordx4 v[204:205], off
	v_lshl_add_u64 v[204:205], s[12:13], 0, v[198:199]
	s_add_i32 m0, s54, 0x2000
	s_nop 0
	global_load_lds_dwordx4 v[204:205], off
	v_lshl_add_u64 v[204:205], v[208:209], 0, s[26:27]
	s_mov_b32 m0, s69
	s_nop 0
	global_load_lds_dwordx4 v[204:205], off
	v_lshl_add_u64 v[204:205], v[210:211], 0, s[26:27]
	s_mov_b32 m0, s70
	s_nop 0
	global_load_lds_dwordx4 v[204:205], off
	s_waitcnt vmcnt(8)
	s_waitcnt lgkmcnt(0)
	s_barrier
	s_setprio 1
	s_waitcnt lgkmcnt(0)
	v_mfma_f32_16x16x32_bf16 v[60:63], v[88:91], v[160:163], v[60:63]
	v_mfma_f32_16x16x32_bf16 v[56:59], v[112:115], v[160:163], v[56:59]
	v_mfma_f32_16x16x32_bf16 v[44:47], v[88:91], v[168:171], v[44:47]
	v_mfma_f32_16x16x32_bf16 v[40:43], v[112:115], v[168:171], v[40:43]
	v_mfma_f32_16x16x32_bf16 v[28:31], v[88:91], v[176:179], v[28:31]
	v_mfma_f32_16x16x32_bf16 v[24:27], v[112:115], v[176:179], v[24:27]
	v_mfma_f32_16x16x32_bf16 v[12:15], v[88:91], v[184:187], v[12:15]
	v_mfma_f32_16x16x32_bf16 v[8:11], v[112:115], v[184:187], v[8:11]
	v_mfma_f32_16x16x32_bf16 v[60:63], v[92:95], v[164:167], v[60:63]
	v_mfma_f32_16x16x32_bf16 v[56:59], v[116:119], v[164:167], v[56:59]
	v_mfma_f32_16x16x32_bf16 v[44:47], v[92:95], v[172:175], v[44:47]
	v_mfma_f32_16x16x32_bf16 v[40:43], v[116:119], v[172:175], v[40:43]
	v_mfma_f32_16x16x32_bf16 v[28:31], v[92:95], v[180:183], v[28:31]
	v_mfma_f32_16x16x32_bf16 v[24:27], v[116:119], v[180:183], v[24:27]
	v_mfma_f32_16x16x32_bf16 v[12:15], v[92:95], v[194:197], v[12:15]
	v_mfma_f32_16x16x32_bf16 v[8:11], v[116:119], v[194:197], v[8:11]
	v_mfma_f32_16x16x32_bf16 v[52:55], v[132:135], v[160:163], v[52:55]
	v_mfma_f32_16x16x32_bf16 v[48:51], v[144:147], v[160:163], v[48:51]
	v_mfma_f32_16x16x32_bf16 v[36:39], v[132:135], v[168:171], v[36:39]
	v_mfma_f32_16x16x32_bf16 v[32:35], v[144:147], v[168:171], v[32:35]
	v_mfma_f32_16x16x32_bf16 v[20:23], v[132:135], v[176:179], v[20:23]
	v_mfma_f32_16x16x32_bf16 v[16:19], v[144:147], v[176:179], v[16:19]
	v_mfma_f32_16x16x32_bf16 v[4:7], v[132:135], v[184:187], v[4:7]
	v_mfma_f32_16x16x32_bf16 v[0:3], v[144:147], v[184:187], v[0:3]
	v_mfma_f32_16x16x32_bf16 v[52:55], v[140:143], v[164:167], v[52:55]
	v_mfma_f32_16x16x32_bf16 v[48:51], v[156:159], v[164:167], v[48:51]
	v_mfma_f32_16x16x32_bf16 v[36:39], v[140:143], v[172:175], v[36:39]
	v_mfma_f32_16x16x32_bf16 v[32:35], v[156:159], v[172:175], v[32:35]
	v_mfma_f32_16x16x32_bf16 v[20:23], v[140:143], v[180:183], v[20:23]
	v_mfma_f32_16x16x32_bf16 v[16:19], v[156:159], v[180:183], v[16:19]
	v_mfma_f32_16x16x32_bf16 v[4:7], v[140:143], v[194:197], v[4:7]
	v_mfma_f32_16x16x32_bf16 v[0:3], v[156:159], v[194:197], v[0:3]
	s_setprio 0
	s_barrier
	s_add_i32 s75, s75, 2
	s_add_u32 s73, s73, 0x100
	s_addc_u32 s74, s74, 0
	s_cmp_gt_u32 s75, 57
	s_mov_b64 s[54:55], s[38:39]
	s_cbranch_scc0 .LBB0_1561
	s_and_b64 vcc, exec, s[42:43]
	s_cbranch_vccz .LBB0_1564
	s_barrier
